# v81 + GEMM K-loop LDS-DMA loads addressed SGPR base + 32-bit lane offset (16 64-bit VALU adds per iteration removed; M0 compensated for INST.OFFSET)
# speedup vs baseline: 1.0221x; 1.0048x over previous
; #define PG8_STAGE(bufoff, gbase, voff) do { _Pragma("unroll") for (int _i = 0; _i < 2; ++_i) \
;         __builtin_amdgcn_global_load_lds((const unsigned*)((const char*)(gbase) + (voff)[_i]), (LAS unsigned*)(lds + (bufoff) + ldsw + _i * 8192), 16, 0, 0); } while (0)
; #define PG8_LDA(dst, b, h) do { _Pragma("unroll") for (int m = 0; m < 4; ++m) _Pragma("unroll") for (int k = 0; k < 2; ++k) dst[m][k] = *(const LAS bf16x8*)(lds + PG8_SA(b, h) + aoff + m * 2048 + k * 1024); } while (0)
; #define PG8_LDB(dst, b, h) do { _Pragma("unroll") for (int n = 0; n < 2; ++n) _Pragma("unroll") for (int k = 0; k < 2; ++k) dst[n][k] = *(const LAS bf16x8*)(lds + PG8_SB(b, h) + boff + n * 2048 + k * 1024); } while (0)
; #define PG8_SCHED __builtin_amdgcn_sched_barrier(0)
; template <class Epi>
; DI void gemm_phase(LAS unsigned char* lds, int wid, int K, int lda, int ldb, bool bperm, const Sched3& S, const Epi& E) {
;     ...
;         const bool has_next = S.next(ui + 1, nxt);
;         const char* nA = has_next ? nxt.A : cA; const char* nB = has_next ? nxt.B : cB; const size_t nhA = has_next ? (nxt.half ? (size_t)0 : hstepA) : hA; const bool full = (cur.half == 0);
;         for (int t = 0; t < nt; t += 2) {
;             const bool last = (t == nt - 2);
;             const char* a1 = cA + (size_t)(t + 1) * kstep;
;             const char* a2 = last ? nA : cA + (size_t)(t + 2) * kstep; const char* b2 = last ? nB : cB + (size_t)(t + 2) * kstep;
;             const char* a3 = a2 + kstep; const char* b3 = b2 + kstep; const size_t h2 = last ? nhA : hA;
;             PG8_LDB(B0, 0, 0); PG8_SCHED; PG8_LDA(At, 0, 0); PG8_STAGE(PG8_SA(1, 1), a1 + hA, voffA);
.LBB0_326:
	s_xor_b64 s[44:45], s[52:53], -1
	s_and_b64 s[50:51], s[52:53], exec
	s_cselect_b32 s5, s41, s47
	s_cselect_b32 s37, s40, s46
	s_cselect_b32 s39, s43, s49
	s_cselect_b32 s52, s42, s48
	s_add_u32 s46, s46, 0x80080
	s_addc_u32 s47, s47, 0
	s_add_u32 s53, s48, 0x100
	s_nop 0
	s_addc_u32 s54, s49, 0
	s_mov_b32 s55, -2
	s_waitcnt lgkmcnt(0)
	ds_read_b128 v[128:131], v230
	ds_read_b128 v[132:135], v230 offset:1024
	ds_read_b128 v[136:139], v230 offset:2048
	ds_read_b128 v[156:159], v230 offset:3072
	s_add_u32 s48, s46, 0xfff80080
	s_addc_u32 s49, s47, -1
	s_cmp_eq_u32 s55, 28
	s_cselect_b32 s51, s5, s49
	s_cselect_b32 s50, s37, s48
	s_cselect_b32 s49, s39, s54
	s_cselect_b32 s48, s52, s53

; #define PG8_STAGE(bufoff, gbase, voff) do { _Pragma("unroll") for (int _i = 0; _i < 2; ++_i) \
;         __builtin_amdgcn_global_load_lds((const unsigned*)((const char*)(gbase) + (voff)[_i]), (LAS unsigned*)(lds + (bufoff) + ldsw + _i * 8192), 16, 0, 0); } while (0)
; #define PG8_LDA(dst, b, h) do { _Pragma("unroll") for (int m = 0; m < 4; ++m) _Pragma("unroll") for (int k = 0; k < 2; ++k) dst[m][k] = *(const LAS bf16x8*)(lds + PG8_SA(b, h) + aoff + m * 2048 + k * 1024); } while (0)
; #define PG8_LDB(dst, b, h) do { _Pragma("unroll") for (int n = 0; n < 2; ++n) _Pragma("unroll") for (int k = 0; k < 2; ++k) dst[n][k] = *(const LAS bf16x8*)(lds + PG8_SB(b, h) + boff + n * 2048 + k * 1024); } while (0)
; #define PG8_SCHED __builtin_amdgcn_sched_barrier(0)
; template <class Epi>
; DI void gemm_phase(LAS unsigned char* lds, int wid, int K, int lda, int ldb, bool bperm, const Sched3& S, const Epi& E) {
;     ...
;             const bool last = (t == nt - 2);
;             const char* a1 = cA + (size_t)(t + 1) * kstep;
;             const char* a2 = last ? nA : cA + (size_t)(t + 2) * kstep; const char* b2 = last ? nB : cB + (size_t)(t + 2) * kstep;
;             const char* a3 = a2 + kstep; const char* b3 = b2 + kstep; const size_t h2 = last ? nhA : hA;
;             PG8_LDB(B0, 0, 0); PG8_SCHED; PG8_LDA(At, 0, 0); PG8_STAGE(PG8_SA(1, 1), a1 + hA, voffA);
	s_add_i32 m0, s58, 0xc000
	ds_read_b128 v[160:163], v231
	ds_read_b128 v[164:167], v231 offset:1024
	ds_read_b128 v[168:171], v231 offset:2048
	ds_read_b128 v[172:175], v231 offset:3072
	ds_read_b128 v[176:179], v231 offset:4096
	ds_read_b128 v[180:183], v231 offset:5120
	ds_read_b128 v[184:187], v231 offset:6144
	ds_read_b128 v[188:191], v231 offset:7168
	global_load_lds_dwordx4 v148, s[46:47]

; #define PG8_STAGE(bufoff, gbase, voff) do { _Pragma("unroll") for (int _i = 0; _i < 2; ++_i) \
;         __builtin_amdgcn_global_load_lds((const unsigned*)((const char*)(gbase) + (voff)[_i]), (LAS unsigned*)(lds + (bufoff) + ldsw + _i * 8192), 16, 0, 0); } while (0)
; #define PG8_LDA(dst, b, h) do { _Pragma("unroll") for (int m = 0; m < 4; ++m) _Pragma("unroll") for (int k = 0; k < 2; ++k) dst[m][k] = *(const LAS bf16x8*)(lds + PG8_SA(b, h) + aoff + m * 2048 + k * 1024); } while (0)
; #define PG8_LDB(dst, b, h) do { _Pragma("unroll") for (int n = 0; n < 2; ++n) _Pragma("unroll") for (int k = 0; k < 2; ++k) dst[n][k] = *(const LAS bf16x8*)(lds + PG8_SB(b, h) + boff + n * 2048 + k * 1024); } while (0)
; #define PG8_MMA(ai, bj, At, Bt) do { __builtin_amdgcn_s_setprio(1); _Pragma("unroll") for (int m = 0; m < 4; ++m) _Pragma("unroll") for (int n = 0; n < 2; ++n) _Pragma("unroll") for (int k = 0; k < 2; ++k) \
;         acc[ai][bj][m][n] = __builtin_amdgcn_mfma_f32_16x16x32_bf16(Bt[n][k], At[m][k], acc[ai][bj][m][n], 0, 0, 0); __builtin_amdgcn_s_setprio(0); } while (0)
; #define PG8_WAIT_L(n) asm volatile("s_waitcnt lgkmcnt(" #n ")" ::: "memory")
; #define PG8_BAR __builtin_amdgcn_s_barrier()
; #define PG8_SCHED __builtin_amdgcn_sched_barrier(0)
; template <class Epi>
; DI void gemm_phase(LAS unsigned char* lds, int wid, int K, int lda, int ldb, bool bperm, const Sched3& S, const Epi& E) {
;     ...
;             PG8_LDB(B0, 0, 0); PG8_SCHED; PG8_LDA(At, 0, 0); PG8_STAGE(PG8_SA(1, 1), a1 + hA, voffA);
;             PG8_WAIT_L(8); PG8_BAR; PG8_WAIT_L(0); PG8_MMA(0, 0, At, B0); PG8_BAR; PG8_SCHED;
	s_add_i32 m0, s58, 0xe000
	s_nop 0
	global_load_lds_dwordx4 v150, s[46:47]
	s_waitcnt lgkmcnt(8)
	s_barrier
	s_waitcnt lgkmcnt(0)
	s_setprio 1
	s_waitcnt lgkmcnt(0)
	v_mfma_f32_16x16x32_bf16 v[124:127], v[128:131], v[160:163], 0
	v_mfma_f32_16x16x32_bf16 v[120:123], v[136:139], v[160:163], 0
	v_mfma_f32_16x16x32_bf16 v[108:111], v[128:131], v[168:171], 0
	v_mfma_f32_16x16x32_bf16 v[104:107], v[136:139], v[168:171], 0
	v_mfma_f32_16x16x32_bf16 v[92:95], v[128:131], v[176:179], 0
	v_mfma_f32_16x16x32_bf16 v[88:91], v[136:139], v[176:179], 0
	v_mfma_f32_16x16x32_bf16 v[76:79], v[128:131], v[184:187], 0
	v_mfma_f32_16x16x32_bf16 v[72:75], v[136:139], v[184:187], 0
	v_mfma_f32_16x16x32_bf16 v[124:127], v[132:135], v[164:167], v[124:127]
	v_mfma_f32_16x16x32_bf16 v[120:123], v[156:159], v[164:167], v[120:123]
	v_mfma_f32_16x16x32_bf16 v[108:111], v[132:135], v[172:175], v[108:111]
	v_mfma_f32_16x16x32_bf16 v[104:107], v[156:159], v[172:175], v[104:107]
	v_mfma_f32_16x16x32_bf16 v[92:95], v[132:135], v[180:183], v[92:95]
	v_mfma_f32_16x16x32_bf16 v[88:91], v[156:159], v[180:183], v[88:91]
	v_mfma_f32_16x16x32_bf16 v[76:79], v[132:135], v[188:191], v[76:79]
	v_mfma_f32_16x16x32_bf16 v[72:75], v[156:159], v[188:191], v[72:75]
	s_setprio 0
	s_barrier
	s_add_i32 s75, s67, s57

; #define PG8_STAGE(bufoff, gbase, voff) do { _Pragma("unroll") for (int _i = 0; _i < 2; ++_i) \
;         __builtin_amdgcn_global_load_lds((const unsigned*)((const char*)(gbase) + (voff)[_i]), (LAS unsigned*)(lds + (bufoff) + ldsw + _i * 8192), 16, 0, 0); } while (0)
; #define PG8_LDB(dst, b, h) do { _Pragma("unroll") for (int n = 0; n < 2; ++n) _Pragma("unroll") for (int k = 0; k < 2; ++k) dst[n][k] = *(const LAS bf16x8*)(lds + PG8_SB(b, h) + boff + n * 2048 + k * 1024); } while (0)
; template <class Epi>
; DI void gemm_phase(LAS unsigned char* lds, int wid, int K, int lda, int ldb, bool bperm, const Sched3& S, const Epi& E) {
;     ...
;             PG8_LDB(B1, 0, 1); PG8_STAGE(PG8_SB(0, 0), b2, voffB);
	s_mov_b32 m0, s75
	ds_read_b128 v[192:195], v232
	ds_read_b128 v[196:199], v232 offset:1024
	ds_read_b128 v[200:203], v232 offset:2048
	ds_read_b128 v[204:207], v232 offset:3072
	global_load_lds_dwordx4 v142, s[48:49]

; #define PG8_STAGE(bufoff, gbase, voff) do { _Pragma("unroll") for (int _i = 0; _i < 2; ++_i) \
;         __builtin_amdgcn_global_load_lds((const unsigned*)((const char*)(gbase) + (voff)[_i]), (LAS unsigned*)(lds + (bufoff) + ldsw + _i * 8192), 16, 0, 0); } while (0)
; #define PG8_LDA(dst, b, h) do { _Pragma("unroll") for (int m = 0; m < 4; ++m) _Pragma("unroll") for (int k = 0; k < 2; ++k) dst[m][k] = *(const LAS bf16x8*)(lds + PG8_SA(b, h) + aoff + m * 2048 + k * 1024); } while (0)
; #define PG8_LDB(dst, b, h) do { _Pragma("unroll") for (int n = 0; n < 2; ++n) _Pragma("unroll") for (int k = 0; k < 2; ++k) dst[n][k] = *(const LAS bf16x8*)(lds + PG8_SB(b, h) + boff + n * 2048 + k * 1024); } while (0)
; #define PG8_MMA(ai, bj, At, Bt) do { __builtin_amdgcn_s_setprio(1); _Pragma("unroll") for (int m = 0; m < 4; ++m) _Pragma("unroll") for (int n = 0; n < 2; ++n) _Pragma("unroll") for (int k = 0; k < 2; ++k) \
;         acc[ai][bj][m][n] = __builtin_amdgcn_mfma_f32_16x16x32_bf16(Bt[n][k], At[m][k], acc[ai][bj][m][n], 0, 0, 0); __builtin_amdgcn_s_setprio(0); } while (0)
; #define PG8_WAIT_L(n) asm volatile("s_waitcnt lgkmcnt(" #n ")" ::: "memory")
; #define PG8_BAR __builtin_amdgcn_s_barrier()
; #define PG8_SCHED __builtin_amdgcn_sched_barrier(0)
; template <class Epi>
; DI void gemm_phase(LAS unsigned char* lds, int wid, int K, int lda, int ldb, bool bperm, const Sched3& S, const Epi& E) {
;     ...
;             PG8_LDB(B1, 0, 1); PG8_STAGE(PG8_SB(0, 0), b2, voffB);
;             PG8_BAR; PG8_WAIT_L(0); PG8_MMA(0, 1, At, B1); PG8_BAR;
;             PG8_LDA(At, 0, 1); PG8_STAGE(PG8_SA(0, 0), a2, voffA);
;             PG8_BAR; PG8_WAIT_L(0); if (full) PG8_MMA(1, 0, At, B0); PG8_BAR; PG8_SCHED;
;             PG8_STAGE(PG8_SB(0, 1), b2 + hstepB, voffB);
	s_add_i32 m0, s75, 0x2000
	s_nop 0
	global_load_lds_dwordx4 v146, s[48:49]
	s_barrier
	s_waitcnt lgkmcnt(0)
	s_setprio 1
	s_waitcnt lgkmcnt(0)
	v_mfma_f32_16x16x32_bf16 v[116:119], v[192:195], v[160:163], 0
	v_mfma_f32_16x16x32_bf16 v[112:115], v[200:203], v[160:163], 0
	v_mfma_f32_16x16x32_bf16 v[100:103], v[192:195], v[168:171], 0
	v_mfma_f32_16x16x32_bf16 v[96:99], v[200:203], v[168:171], 0
	v_mfma_f32_16x16x32_bf16 v[84:87], v[192:195], v[176:179], 0
	v_mfma_f32_16x16x32_bf16 v[80:83], v[200:203], v[176:179], 0
	v_mfma_f32_16x16x32_bf16 v[68:71], v[192:195], v[184:187], 0
	v_mfma_f32_16x16x32_bf16 v[64:67], v[200:203], v[184:187], 0
	v_mfma_f32_16x16x32_bf16 v[116:119], v[196:199], v[164:167], v[116:119]
	v_mfma_f32_16x16x32_bf16 v[112:115], v[204:207], v[164:167], v[112:115]
	v_mfma_f32_16x16x32_bf16 v[100:103], v[196:199], v[172:175], v[100:103]
	v_mfma_f32_16x16x32_bf16 v[96:99], v[204:207], v[172:175], v[96:99]
	v_mfma_f32_16x16x32_bf16 v[84:87], v[196:199], v[180:183], v[84:87]
	v_mfma_f32_16x16x32_bf16 v[80:83], v[204:207], v[180:183], v[80:83]
	v_mfma_f32_16x16x32_bf16 v[68:71], v[196:199], v[188:191], v[68:71]
	v_mfma_f32_16x16x32_bf16 v[64:67], v[204:207], v[188:191], v[64:67]
	s_setprio 0
	s_mov_b32 m0, s58
	s_mov_b64 s[100:101], s[50:51]
	s_barrier
	ds_read_b128 v[160:163], v231 offset:16384
	ds_read_b128 v[164:167], v231 offset:17408
	ds_read_b128 v[168:171], v231 offset:18432
	ds_read_b128 v[172:175], v231 offset:19456
	ds_read_b128 v[176:179], v231 offset:20480
	ds_read_b128 v[180:183], v231 offset:21504
	ds_read_b128 v[184:187], v231 offset:22528
	ds_read_b128 v[188:191], v231 offset:23552
	global_load_lds_dwordx4 v140, s[50:51]
	s_mov_b64 s[100:101], s[50:51]
	s_mov_b32 m0, s59
	s_nop 0
	global_load_lds_dwordx4 v144, s[50:51]
	s_barrier
	s_waitcnt lgkmcnt(0)
	s_setprio 1
	s_waitcnt lgkmcnt(0)
	v_mfma_f32_16x16x32_bf16 v[60:63], v[128:131], v[160:163], 0
	v_mfma_f32_16x16x32_bf16 v[56:59], v[136:139], v[160:163], 0
	v_mfma_f32_16x16x32_bf16 v[44:47], v[128:131], v[168:171], 0
	v_mfma_f32_16x16x32_bf16 v[40:43], v[136:139], v[168:171], 0
	v_mfma_f32_16x16x32_bf16 v[28:31], v[128:131], v[176:179], 0
	v_mfma_f32_16x16x32_bf16 v[24:27], v[136:139], v[176:179], 0
	v_mfma_f32_16x16x32_bf16 v[12:15], v[128:131], v[184:187], 0
	v_mfma_f32_16x16x32_bf16 v[8:11], v[136:139], v[184:187], 0
	v_mfma_f32_16x16x32_bf16 v[60:63], v[132:135], v[164:167], v[60:63]
	v_mfma_f32_16x16x32_bf16 v[56:59], v[156:159], v[164:167], v[56:59]
	v_mfma_f32_16x16x32_bf16 v[44:47], v[132:135], v[172:175], v[44:47]
	v_mfma_f32_16x16x32_bf16 v[40:43], v[156:159], v[172:175], v[40:43]
	v_mfma_f32_16x16x32_bf16 v[28:31], v[132:135], v[180:183], v[28:31]
	v_mfma_f32_16x16x32_bf16 v[24:27], v[156:159], v[180:183], v[24:27]
	v_mfma_f32_16x16x32_bf16 v[12:15], v[132:135], v[188:191], v[12:15]
	v_mfma_f32_16x16x32_bf16 v[8:11], v[156:159], v[188:191], v[8:11]
	s_setprio 0
	s_barrier
	s_add_u32 s76, s48, 0x80000
	s_addc_u32 s77, s49, 0
	s_add_i32 s75, s68, s57

; #define PG8_STAGE(bufoff, gbase, voff) do { _Pragma("unroll") for (int _i = 0; _i < 2; ++_i) \
;         __builtin_amdgcn_global_load_lds((const unsigned*)((const char*)(gbase) + (voff)[_i]), (LAS unsigned*)(lds + (bufoff) + ldsw + _i * 8192), 16, 0, 0); } while (0)
; template <class Epi>
; DI void gemm_phase(LAS unsigned char* lds, int wid, int K, int lda, int ldb, bool bperm, const Sched3& S, const Epi& E) {
;     ...
;             PG8_STAGE(PG8_SB(0, 1), b2 + hstepB, voffB);
	s_mov_b32 m0, s75
	s_nop 0
	global_load_lds_dwordx4 v142, s[76:77]

; #define PG8_STAGE(bufoff, gbase, voff) do { _Pragma("unroll") for (int _i = 0; _i < 2; ++_i) \
;         __builtin_amdgcn_global_load_lds((const unsigned*)((const char*)(gbase) + (voff)[_i]), (LAS unsigned*)(lds + (bufoff) + ldsw + _i * 8192), 16, 0, 0); } while (0)
; #define PG8_LDA(dst, b, h) do { _Pragma("unroll") for (int m = 0; m < 4; ++m) _Pragma("unroll") for (int k = 0; k < 2; ++k) dst[m][k] = *(const LAS bf16x8*)(lds + PG8_SA(b, h) + aoff + m * 2048 + k * 1024); } while (0)
; #define PG8_LDB(dst, b, h) do { _Pragma("unroll") for (int n = 0; n < 2; ++n) _Pragma("unroll") for (int k = 0; k < 2; ++k) dst[n][k] = *(const LAS bf16x8*)(lds + PG8_SB(b, h) + boff + n * 2048 + k * 1024); } while (0)
; #define PG8_MMA(ai, bj, At, Bt) do { __builtin_amdgcn_s_setprio(1); _Pragma("unroll") for (int m = 0; m < 4; ++m) _Pragma("unroll") for (int n = 0; n < 2; ++n) _Pragma("unroll") for (int k = 0; k < 2; ++k) \
;         acc[ai][bj][m][n] = __builtin_amdgcn_mfma_f32_16x16x32_bf16(Bt[n][k], At[m][k], acc[ai][bj][m][n], 0, 0, 0); __builtin_amdgcn_s_setprio(0); } while (0)
; #define PG8_WAIT_V(n) asm volatile("s_waitcnt vmcnt(" #n ")" ::: "memory")
; #define PG8_BAR __builtin_amdgcn_s_barrier()
; #define PG8_SCHED __builtin_amdgcn_sched_barrier(0)
; template <class Epi>
; DI void gemm_phase(LAS unsigned char* lds, int wid, int K, int lda, int ldb, bool bperm, const Sched3& S, const Epi& E) {
;     ...
;             PG8_WAIT_V(6); PG8_BAR; if (full) PG8_MMA(1, 1, At, B1); PG8_BAR;
;             PG8_LDB(B0, 1, 0); PG8_SCHED; PG8_LDA(At, 1, 0); PG8_STAGE(PG8_SA(0, 1), a2 + h2, voffA);
	s_add_i32 m0, s75, 0x2000
	s_nop 0
	global_load_lds_dwordx4 v146, s[76:77]
	s_waitcnt vmcnt(6)
	s_barrier
	s_setprio 1
	v_mfma_f32_16x16x32_bf16 v[52:55], v[192:195], v[160:163], 0
	v_mfma_f32_16x16x32_bf16 v[48:51], v[200:203], v[160:163], 0
	v_mfma_f32_16x16x32_bf16 v[36:39], v[192:195], v[168:171], 0
	v_mfma_f32_16x16x32_bf16 v[32:35], v[200:203], v[168:171], 0
	v_mfma_f32_16x16x32_bf16 v[20:23], v[192:195], v[176:179], 0
	v_mfma_f32_16x16x32_bf16 v[16:19], v[200:203], v[176:179], 0
	v_mfma_f32_16x16x32_bf16 v[4:7], v[192:195], v[184:187], 0
	v_mfma_f32_16x16x32_bf16 v[0:3], v[200:203], v[184:187], 0
	v_mfma_f32_16x16x32_bf16 v[52:55], v[196:199], v[164:167], v[52:55]
	v_mfma_f32_16x16x32_bf16 v[48:51], v[204:207], v[164:167], v[48:51]
	v_mfma_f32_16x16x32_bf16 v[36:39], v[196:199], v[172:175], v[36:39]
	v_mfma_f32_16x16x32_bf16 v[32:35], v[204:207], v[172:175], v[32:35]
	v_mfma_f32_16x16x32_bf16 v[20:23], v[196:199], v[180:183], v[20:23]
	v_mfma_f32_16x16x32_bf16 v[16:19], v[204:207], v[180:183], v[16:19]
	v_mfma_f32_16x16x32_bf16 v[4:7], v[196:199], v[188:191], v[4:7]
	v_mfma_f32_16x16x32_bf16 v[0:3], v[204:207], v[188:191], v[0:3]
	s_setprio 0
	s_add_i32 s75, 0, 0x18000
	v_add_u32_e32 v156, s75, v224
	s_barrier
	ds_read_b128 v[128:131], v156
	ds_read_b128 v[132:135], v156 offset:1024
	ds_read_b128 v[136:139], v156 offset:2048
	ds_read_b128 v[156:159], v156 offset:3072
	s_add_u32 s50, s50, 0x80000
	s_addc_u32 s51, s51, 0
	s_mov_b32 m0, s60

; #define PG8_STAGE(bufoff, gbase, voff) do { _Pragma("unroll") for (int _i = 0; _i < 2; ++_i) \
;         __builtin_amdgcn_global_load_lds((const unsigned*)((const char*)(gbase) + (voff)[_i]), (LAS unsigned*)(lds + (bufoff) + ldsw + _i * 8192), 16, 0, 0); } while (0)
; #define PG8_LDA(dst, b, h) do { _Pragma("unroll") for (int m = 0; m < 4; ++m) _Pragma("unroll") for (int k = 0; k < 2; ++k) dst[m][k] = *(const LAS bf16x8*)(lds + PG8_SA(b, h) + aoff + m * 2048 + k * 1024); } while (0)
; #define PG8_LDB(dst, b, h) do { _Pragma("unroll") for (int n = 0; n < 2; ++n) _Pragma("unroll") for (int k = 0; k < 2; ++k) dst[n][k] = *(const LAS bf16x8*)(lds + PG8_SB(b, h) + boff + n * 2048 + k * 1024); } while (0)
; #define PG8_SCHED __builtin_amdgcn_sched_barrier(0)
; template <class Epi>
; DI void gemm_phase(LAS unsigned char* lds, int wid, int K, int lda, int ldb, bool bperm, const Sched3& S, const Epi& E) {
;     ...
;             PG8_LDB(B0, 1, 0); PG8_SCHED; PG8_LDA(At, 1, 0); PG8_STAGE(PG8_SA(0, 1), a2 + h2, voffA);
	ds_read_b128 v[160:163], v231 offset:32768
	ds_read_b128 v[164:167], v231 offset:33792
	ds_read_b128 v[168:171], v231 offset:34816
	ds_read_b128 v[172:175], v231 offset:35840
	ds_read_b128 v[176:179], v231 offset:36864
	ds_read_b128 v[180:183], v231 offset:37888
	ds_read_b128 v[184:187], v231 offset:38912
	ds_read_b128 v[188:191], v231 offset:39936
	global_load_lds_dwordx4 v140, s[50:51]

; #define PG8_STAGE(bufoff, gbase, voff) do { _Pragma("unroll") for (int _i = 0; _i < 2; ++_i) \
;         __builtin_amdgcn_global_load_lds((const unsigned*)((const char*)(gbase) + (voff)[_i]), (LAS unsigned*)(lds + (bufoff) + ldsw + _i * 8192), 16, 0, 0); } while (0)
; #define PG8_LDB(dst, b, h) do { _Pragma("unroll") for (int n = 0; n < 2; ++n) _Pragma("unroll") for (int k = 0; k < 2; ++k) dst[n][k] = *(const LAS bf16x8*)(lds + PG8_SB(b, h) + boff + n * 2048 + k * 1024); } while (0)
; #define PG8_MMA(ai, bj, At, Bt) do { __builtin_amdgcn_s_setprio(1); _Pragma("unroll") for (int m = 0; m < 4; ++m) _Pragma("unroll") for (int n = 0; n < 2; ++n) _Pragma("unroll") for (int k = 0; k < 2; ++k) \
;         acc[ai][bj][m][n] = __builtin_amdgcn_mfma_f32_16x16x32_bf16(Bt[n][k], At[m][k], acc[ai][bj][m][n], 0, 0, 0); __builtin_amdgcn_s_setprio(0); } while (0)
; #define PG8_WAIT_L(n) asm volatile("s_waitcnt lgkmcnt(" #n ")" ::: "memory")
; #define PG8_BAR __builtin_amdgcn_s_barrier()
; #define PG8_SCHED __builtin_amdgcn_sched_barrier(0)
; template <class Epi>
; DI void gemm_phase(LAS unsigned char* lds, int wid, int K, int lda, int ldb, bool bperm, const Sched3& S, const Epi& E) {
;     ...
;             PG8_WAIT_L(8); PG8_BAR; PG8_WAIT_L(0); PG8_MMA(0, 0, At, B0); PG8_BAR; PG8_SCHED;
;             PG8_LDB(B1, 1, 1); PG8_STAGE(PG8_SB(1, 0), b3, voffB);
	s_mov_b32 m0, s61
	s_nop 0
	global_load_lds_dwordx4 v144, s[50:51]
	s_waitcnt lgkmcnt(8)
	s_barrier
	s_waitcnt lgkmcnt(0)
	s_setprio 1
	s_waitcnt lgkmcnt(0)
	v_mfma_f32_16x16x32_bf16 v[124:127], v[128:131], v[160:163], v[124:127]
	v_mfma_f32_16x16x32_bf16 v[120:123], v[136:139], v[160:163], v[120:123]
	v_mfma_f32_16x16x32_bf16 v[108:111], v[128:131], v[168:171], v[108:111]
	v_mfma_f32_16x16x32_bf16 v[104:107], v[136:139], v[168:171], v[104:107]
	v_mfma_f32_16x16x32_bf16 v[92:95], v[128:131], v[176:179], v[92:95]
	v_mfma_f32_16x16x32_bf16 v[88:91], v[136:139], v[176:179], v[88:91]
	v_mfma_f32_16x16x32_bf16 v[76:79], v[128:131], v[184:187], v[76:79]
	v_mfma_f32_16x16x32_bf16 v[72:75], v[136:139], v[184:187], v[72:75]
	v_mfma_f32_16x16x32_bf16 v[124:127], v[132:135], v[164:167], v[124:127]
	v_mfma_f32_16x16x32_bf16 v[120:123], v[156:159], v[164:167], v[120:123]
	v_mfma_f32_16x16x32_bf16 v[108:111], v[132:135], v[172:175], v[108:111]
	v_mfma_f32_16x16x32_bf16 v[104:107], v[156:159], v[172:175], v[104:107]
	v_mfma_f32_16x16x32_bf16 v[92:95], v[132:135], v[180:183], v[92:95]
	v_mfma_f32_16x16x32_bf16 v[88:91], v[156:159], v[180:183], v[88:91]
	v_mfma_f32_16x16x32_bf16 v[76:79], v[132:135], v[188:191], v[76:79]
	v_mfma_f32_16x16x32_bf16 v[72:75], v[156:159], v[188:191], v[72:75]
	s_setprio 0
	s_barrier
	s_add_i32 s50, 0, 0x1c000
	s_add_i32 s51, s75, s57
	v_add_u32_e32 v204, s50, v224

; #define PG8_STAGE(bufoff, gbase, voff) do { _Pragma("unroll") for (int _i = 0; _i < 2; ++_i) \
;         __builtin_amdgcn_global_load_lds((const unsigned*)((const char*)(gbase) + (voff)[_i]), (LAS unsigned*)(lds + (bufoff) + ldsw + _i * 8192), 16, 0, 0); } while (0)
; #define PG8_LDB(dst, b, h) do { _Pragma("unroll") for (int n = 0; n < 2; ++n) _Pragma("unroll") for (int k = 0; k < 2; ++k) dst[n][k] = *(const LAS bf16x8*)(lds + PG8_SB(b, h) + boff + n * 2048 + k * 1024); } while (0)
; template <class Epi>
; DI void gemm_phase(LAS unsigned char* lds, int wid, int K, int lda, int ldb, bool bperm, const Sched3& S, const Epi& E) {
;     ...
;             PG8_LDB(B1, 1, 1); PG8_STAGE(PG8_SB(1, 0), b3, voffB);
	s_sub_i32 m0, s51, 0x80
	ds_read_b128 v[192:195], v204
	ds_read_b128 v[196:199], v204 offset:1024
	ds_read_b128 v[200:203], v204 offset:2048
	ds_read_b128 v[204:207], v204 offset:3072
	global_load_lds_dwordx4 v142, s[48:49] offset:128

; #define PG8_STAGE(bufoff, gbase, voff) do { _Pragma("unroll") for (int _i = 0; _i < 2; ++_i) \
;         __builtin_amdgcn_global_load_lds((const unsigned*)((const char*)(gbase) + (voff)[_i]), (LAS unsigned*)(lds + (bufoff) + ldsw + _i * 8192), 16, 0, 0); } while (0)
; #define PG8_LDA(dst, b, h) do { _Pragma("unroll") for (int m = 0; m < 4; ++m) _Pragma("unroll") for (int k = 0; k < 2; ++k) dst[m][k] = *(const LAS bf16x8*)(lds + PG8_SA(b, h) + aoff + m * 2048 + k * 1024); } while (0)
; #define PG8_LDB(dst, b, h) do { _Pragma("unroll") for (int n = 0; n < 2; ++n) _Pragma("unroll") for (int k = 0; k < 2; ++k) dst[n][k] = *(const LAS bf16x8*)(lds + PG8_SB(b, h) + boff + n * 2048 + k * 1024); } while (0)
; #define PG8_MMA(ai, bj, At, Bt) do { __builtin_amdgcn_s_setprio(1); _Pragma("unroll") for (int m = 0; m < 4; ++m) _Pragma("unroll") for (int n = 0; n < 2; ++n) _Pragma("unroll") for (int k = 0; k < 2; ++k) \
;         acc[ai][bj][m][n] = __builtin_amdgcn_mfma_f32_16x16x32_bf16(Bt[n][k], At[m][k], acc[ai][bj][m][n], 0, 0, 0); __builtin_amdgcn_s_setprio(0); } while (0)
; #define PG8_WAIT_L(n) asm volatile("s_waitcnt lgkmcnt(" #n ")" ::: "memory")
; #define PG8_BAR __builtin_amdgcn_s_barrier()
; template <class Epi>
; DI void gemm_phase(LAS unsigned char* lds, int wid, int K, int lda, int ldb, bool bperm, const Sched3& S, const Epi& E) {
;     ...
;             PG8_LDB(B1, 1, 1); PG8_STAGE(PG8_SB(1, 0), b3, voffB);
;             PG8_BAR; PG8_WAIT_L(0); PG8_MMA(0, 1, At, B1); PG8_BAR;
;             PG8_LDA(At, 1, 1); PG8_STAGE(PG8_SA(1, 0), a3, voffA);
	s_add_i32 m0, s51, 0x1f80
	s_nop 0
	global_load_lds_dwordx4 v146, s[48:49] offset:128
	s_barrier
	s_waitcnt lgkmcnt(0)
	s_setprio 1
	s_waitcnt lgkmcnt(0)
	v_mfma_f32_16x16x32_bf16 v[116:119], v[192:195], v[160:163], v[116:119]
	v_mfma_f32_16x16x32_bf16 v[112:115], v[200:203], v[160:163], v[112:115]
	v_mfma_f32_16x16x32_bf16 v[100:103], v[192:195], v[168:171], v[100:103]
	v_mfma_f32_16x16x32_bf16 v[96:99], v[200:203], v[168:171], v[96:99]
	v_mfma_f32_16x16x32_bf16 v[84:87], v[192:195], v[176:179], v[84:87]
	v_mfma_f32_16x16x32_bf16 v[80:83], v[200:203], v[176:179], v[80:83]
	v_mfma_f32_16x16x32_bf16 v[68:71], v[192:195], v[184:187], v[68:71]
	v_mfma_f32_16x16x32_bf16 v[64:67], v[200:203], v[184:187], v[64:67]
	v_mfma_f32_16x16x32_bf16 v[116:119], v[196:199], v[164:167], v[116:119]
	v_mfma_f32_16x16x32_bf16 v[112:115], v[204:207], v[164:167], v[112:115]
	v_mfma_f32_16x16x32_bf16 v[100:103], v[196:199], v[172:175], v[100:103]
	v_mfma_f32_16x16x32_bf16 v[96:99], v[204:207], v[172:175], v[96:99]
	v_mfma_f32_16x16x32_bf16 v[84:87], v[196:199], v[180:183], v[84:87]
	v_mfma_f32_16x16x32_bf16 v[80:83], v[204:207], v[180:183], v[80:83]
	v_mfma_f32_16x16x32_bf16 v[68:71], v[196:199], v[188:191], v[68:71]
	v_mfma_f32_16x16x32_bf16 v[64:67], v[204:207], v[188:191], v[64:67]
	s_setprio 0
	s_sub_i32 m0, s63, 0x80

; #define PG8_STAGE(bufoff, gbase, voff) do { _Pragma("unroll") for (int _i = 0; _i < 2; ++_i) \
;         __builtin_amdgcn_global_load_lds((const unsigned*)((const char*)(gbase) + (voff)[_i]), (LAS unsigned*)(lds + (bufoff) + ldsw + _i * 8192), 16, 0, 0); } while (0)
; #define PG8_LDA(dst, b, h) do { _Pragma("unroll") for (int m = 0; m < 4; ++m) _Pragma("unroll") for (int k = 0; k < 2; ++k) dst[m][k] = *(const LAS bf16x8*)(lds + PG8_SA(b, h) + aoff + m * 2048 + k * 1024); } while (0)
; template <class Epi>
; DI void gemm_phase(LAS unsigned char* lds, int wid, int K, int lda, int ldb, bool bperm, const Sched3& S, const Epi& E) {
;     ...
;             PG8_LDA(At, 1, 1); PG8_STAGE(PG8_SA(1, 0), a3, voffA);
	s_barrier
	ds_read_b128 v[160:163], v231 offset:49152
	ds_read_b128 v[164:167], v231 offset:50176
	ds_read_b128 v[168:171], v231 offset:51200
	ds_read_b128 v[172:175], v231 offset:52224
	ds_read_b128 v[176:179], v231 offset:53248
	ds_read_b128 v[180:183], v231 offset:54272
	ds_read_b128 v[184:187], v231 offset:55296
	ds_read_b128 v[188:191], v231 offset:56320
	global_load_lds_dwordx4 v140, s[100:101] offset:128

; #define PG8_STAGE(bufoff, gbase, voff) do { _Pragma("unroll") for (int _i = 0; _i < 2; ++_i) \
;         __builtin_amdgcn_global_load_lds((const unsigned*)((const char*)(gbase) + (voff)[_i]), (LAS unsigned*)(lds + (bufoff) + ldsw + _i * 8192), 16, 0, 0); } while (0)
; #define PG8_LDA(dst, b, h) do { _Pragma("unroll") for (int m = 0; m < 4; ++m) _Pragma("unroll") for (int k = 0; k < 2; ++k) dst[m][k] = *(const LAS bf16x8*)(lds + PG8_SA(b, h) + aoff + m * 2048 + k * 1024); } while (0)
; #define PG8_MMA(ai, bj, At, Bt) do { __builtin_amdgcn_s_setprio(1); _Pragma("unroll") for (int m = 0; m < 4; ++m) _Pragma("unroll") for (int n = 0; n < 2; ++n) _Pragma("unroll") for (int k = 0; k < 2; ++k) \
;         acc[ai][bj][m][n] = __builtin_amdgcn_mfma_f32_16x16x32_bf16(Bt[n][k], At[m][k], acc[ai][bj][m][n], 0, 0, 0); __builtin_amdgcn_s_setprio(0); } while (0)
; #define PG8_WAIT_L(n) asm volatile("s_waitcnt lgkmcnt(" #n ")" ::: "memory")
; #define PG8_BAR __builtin_amdgcn_s_barrier()
; #define PG8_SCHED __builtin_amdgcn_sched_barrier(0)
; template <class Epi>
; DI void gemm_phase(LAS unsigned char* lds, int wid, int K, int lda, int ldb, bool bperm, const Sched3& S, const Epi& E) {
;     ...
;             PG8_LDA(At, 1, 1); PG8_STAGE(PG8_SA(1, 0), a3, voffA);
;             PG8_BAR; PG8_WAIT_L(0); if (full) PG8_MMA(1, 0, At, B0); PG8_BAR; PG8_SCHED;
;             PG8_STAGE(PG8_SB(1, 1), b3 + hstepB, voffB);
	s_sub_i32 m0, s64, 0x80
	s_nop 0
	global_load_lds_dwordx4 v144, s[100:101] offset:128
	s_barrier
	s_waitcnt lgkmcnt(0)
	s_setprio 1
	s_waitcnt lgkmcnt(0)
	v_mfma_f32_16x16x32_bf16 v[60:63], v[128:131], v[160:163], v[60:63]
	v_mfma_f32_16x16x32_bf16 v[56:59], v[136:139], v[160:163], v[56:59]
	v_mfma_f32_16x16x32_bf16 v[44:47], v[128:131], v[168:171], v[44:47]
	v_mfma_f32_16x16x32_bf16 v[40:43], v[136:139], v[168:171], v[40:43]
	v_mfma_f32_16x16x32_bf16 v[28:31], v[128:131], v[176:179], v[28:31]
	v_mfma_f32_16x16x32_bf16 v[24:27], v[136:139], v[176:179], v[24:27]
	v_mfma_f32_16x16x32_bf16 v[12:15], v[128:131], v[184:187], v[12:15]
	v_mfma_f32_16x16x32_bf16 v[8:11], v[136:139], v[184:187], v[8:11]
	v_mfma_f32_16x16x32_bf16 v[60:63], v[132:135], v[164:167], v[60:63]
	v_mfma_f32_16x16x32_bf16 v[56:59], v[156:159], v[164:167], v[56:59]
	v_mfma_f32_16x16x32_bf16 v[44:47], v[132:135], v[172:175], v[44:47]
	v_mfma_f32_16x16x32_bf16 v[40:43], v[156:159], v[172:175], v[40:43]
	v_mfma_f32_16x16x32_bf16 v[28:31], v[132:135], v[180:183], v[28:31]
	v_mfma_f32_16x16x32_bf16 v[24:27], v[156:159], v[180:183], v[24:27]
	v_mfma_f32_16x16x32_bf16 v[12:15], v[132:135], v[188:191], v[12:15]
	v_mfma_f32_16x16x32_bf16 v[8:11], v[156:159], v[188:191], v[8:11]
	s_setprio 0
	s_barrier
	s_add_u32 s48, s48, 0x80080
	s_addc_u32 s49, s49, 0
	s_add_i32 s50, s50, s57

; #define PG8_STAGE(bufoff, gbase, voff) do { _Pragma("unroll") for (int _i = 0; _i < 2; ++_i) \
;         __builtin_amdgcn_global_load_lds((const unsigned*)((const char*)(gbase) + (voff)[_i]), (LAS unsigned*)(lds + (bufoff) + ldsw + _i * 8192), 16, 0, 0); } while (0)
; template <class Epi>
; DI void gemm_phase(LAS unsigned char* lds, int wid, int K, int lda, int ldb, bool bperm, const Sched3& S, const Epi& E) {
;     ...
;             PG8_STAGE(PG8_SB(1, 1), b3 + hstepB, voffB);
	s_mov_b32 m0, s50
	s_nop 0
	global_load_lds_dwordx4 v142, s[48:49]

; #define PG8_STAGE(bufoff, gbase, voff) do { _Pragma("unroll") for (int _i = 0; _i < 2; ++_i) \
;         __builtin_amdgcn_global_load_lds((const unsigned*)((const char*)(gbase) + (voff)[_i]), (LAS unsigned*)(lds + (bufoff) + ldsw + _i * 8192), 16, 0, 0); } while (0)
; #define PG8_LDA(dst, b, h) do { _Pragma("unroll") for (int m = 0; m < 4; ++m) _Pragma("unroll") for (int k = 0; k < 2; ++k) dst[m][k] = *(const LAS bf16x8*)(lds + PG8_SA(b, h) + aoff + m * 2048 + k * 1024); } while (0)
; #define PG8_LDB(dst, b, h) do { _Pragma("unroll") for (int n = 0; n < 2; ++n) _Pragma("unroll") for (int k = 0; k < 2; ++k) dst[n][k] = *(const LAS bf16x8*)(lds + PG8_SB(b, h) + boff + n * 2048 + k * 1024); } while (0)
; #define PG8_MMA(ai, bj, At, Bt) do { __builtin_amdgcn_s_setprio(1); _Pragma("unroll") for (int m = 0; m < 4; ++m) _Pragma("unroll") for (int n = 0; n < 2; ++n) _Pragma("unroll") for (int k = 0; k < 2; ++k) \
;         acc[ai][bj][m][n] = __builtin_amdgcn_mfma_f32_16x16x32_bf16(Bt[n][k], At[m][k], acc[ai][bj][m][n], 0, 0, 0); __builtin_amdgcn_s_setprio(0); } while (0)
; #define PG8_WAIT_V(n) asm volatile("s_waitcnt vmcnt(" #n ")" ::: "memory")
; #define PG8_BAR __builtin_amdgcn_s_barrier()
; #define PG8_SCHED __builtin_amdgcn_sched_barrier(0)
; template <class Epi>
; DI void gemm_phase(LAS unsigned char* lds, int wid, int K, int lda, int ldb, bool bperm, const Sched3& S, const Epi& E) {
;     ...
;         const bool has_next = S.next(ui + 1, nxt);
;         const char* nA = has_next ? nxt.A : cA; const char* nB = has_next ? nxt.B : cB; const size_t nhA = has_next ? (nxt.half ? (size_t)0 : hstepA) : hA; const bool full = (cur.half == 0);
;         for (int t = 0; t < nt; t += 2) {
;             const bool last = (t == nt - 2);
;             const char* a1 = cA + (size_t)(t + 1) * kstep;
;             const char* a2 = last ? nA : cA + (size_t)(t + 2) * kstep; const char* b2 = last ? nB : cB + (size_t)(t + 2) * kstep;
;             const char* a3 = a2 + kstep; const char* b3 = b2 + kstep; const size_t h2 = last ? nhA : hA;
;             PG8_LDB(B0, 0, 0); PG8_SCHED; PG8_LDA(At, 0, 0); PG8_STAGE(PG8_SA(1, 1), a1 + hA, voffA);
;     ...
;             PG8_STAGE(PG8_SB(1, 1), b3 + hstepB, voffB);
;             PG8_WAIT_V(6); PG8_BAR; if (full) PG8_MMA(1, 1, At, B1); PG8_BAR;
	s_add_i32 m0, s50, 0x2000
	s_nop 0
	global_load_lds_dwordx4 v146, s[48:49]
	s_waitcnt vmcnt(6)
	s_barrier
	s_setprio 1
	v_mfma_f32_16x16x32_bf16 v[52:55], v[192:195], v[160:163], v[52:55]
	v_mfma_f32_16x16x32_bf16 v[48:51], v[200:203], v[160:163], v[48:51]
	v_mfma_f32_16x16x32_bf16 v[36:39], v[192:195], v[168:171], v[36:39]
	v_mfma_f32_16x16x32_bf16 v[32:35], v[200:203], v[168:171], v[32:35]
	v_mfma_f32_16x16x32_bf16 v[20:23], v[192:195], v[176:179], v[20:23]
	v_mfma_f32_16x16x32_bf16 v[16:19], v[200:203], v[176:179], v[16:19]
	v_mfma_f32_16x16x32_bf16 v[4:7], v[192:195], v[184:187], v[4:7]
	v_mfma_f32_16x16x32_bf16 v[0:3], v[200:203], v[184:187], v[0:3]
	v_mfma_f32_16x16x32_bf16 v[52:55], v[196:199], v[164:167], v[52:55]
	v_mfma_f32_16x16x32_bf16 v[48:51], v[204:207], v[164:167], v[48:51]
	v_mfma_f32_16x16x32_bf16 v[36:39], v[196:199], v[172:175], v[36:39]
	v_mfma_f32_16x16x32_bf16 v[32:35], v[204:207], v[172:175], v[32:35]
	v_mfma_f32_16x16x32_bf16 v[20:23], v[196:199], v[180:183], v[20:23]
	v_mfma_f32_16x16x32_bf16 v[16:19], v[204:207], v[180:183], v[16:19]
	v_mfma_f32_16x16x32_bf16 v[4:7], v[196:199], v[188:191], v[4:7]
	v_mfma_f32_16x16x32_bf16 v[0:3], v[204:207], v[188:191], v[0:3]
	s_setprio 0
	s_add_i32 s55, s55, 2
	s_add_u32 s46, s46, 0x100
	s_addc_u32 s47, s47, 0
	s_add_u32 s53, s53, 0x100
	s_addc_u32 s54, s54, 0
	s_cmp_gt_u32 s55, 29
	s_barrier
	s_cbranch_scc0 .LBB0_327
	s_branch .Lpeel_0_exit
.LBB0_327:
	s_waitcnt lgkmcnt(0)
	ds_read_b128 v[128:131], v230
	ds_read_b128 v[132:135], v230 offset:1024
	ds_read_b128 v[136:139], v230 offset:2048
	ds_read_b128 v[156:159], v230 offset:3072
	s_add_u32 s48, s46, 0xfff80080
	s_addc_u32 s49, s47, -1
	s_cmp_eq_u32 s55, 28
	s_cselect_b32 s51, s5, s49
	s_cselect_b32 s50, s37, s48
	s_cselect_b32 s49, s39, s54
	s_cselect_b32 s48, s52, s53

; #define PG8_STAGE(bufoff, gbase, voff) do { _Pragma("unroll") for (int _i = 0; _i < 2; ++_i) \
;         __builtin_amdgcn_global_load_lds((const unsigned*)((const char*)(gbase) + (voff)[_i]), (LAS unsigned*)(lds + (bufoff) + ldsw + _i * 8192), 16, 0, 0); } while (0)
; #define PG8_LDA(dst, b, h) do { _Pragma("unroll") for (int m = 0; m < 4; ++m) _Pragma("unroll") for (int k = 0; k < 2; ++k) dst[m][k] = *(const LAS bf16x8*)(lds + PG8_SA(b, h) + aoff + m * 2048 + k * 1024); } while (0)
; #define PG8_LDB(dst, b, h) do { _Pragma("unroll") for (int n = 0; n < 2; ++n) _Pragma("unroll") for (int k = 0; k < 2; ++k) dst[n][k] = *(const LAS bf16x8*)(lds + PG8_SB(b, h) + boff + n * 2048 + k * 1024); } while (0)
; #define PG8_SCHED __builtin_amdgcn_sched_barrier(0)
; template <class Epi>
; DI void gemm_phase(LAS unsigned char* lds, int wid, int K, int lda, int ldb, bool bperm, const Sched3& S, const Epi& E) {
;     ...
;             const bool last = (t == nt - 2);
;             const char* a1 = cA + (size_t)(t + 1) * kstep;
;             const char* a2 = last ? nA : cA + (size_t)(t + 2) * kstep; const char* b2 = last ? nB : cB + (size_t)(t + 2) * kstep;
;             const char* a3 = a2 + kstep; const char* b3 = b2 + kstep; const size_t h2 = last ? nhA : hA;
;             PG8_LDB(B0, 0, 0); PG8_SCHED; PG8_LDA(At, 0, 0); PG8_STAGE(PG8_SA(1, 1), a1 + hA, voffA);
	s_add_i32 m0, s58, 0xc000
	ds_read_b128 v[160:163], v231
	ds_read_b128 v[164:167], v231 offset:1024
	ds_read_b128 v[168:171], v231 offset:2048
	ds_read_b128 v[172:175], v231 offset:3072
	ds_read_b128 v[176:179], v231 offset:4096
	ds_read_b128 v[180:183], v231 offset:5120
	ds_read_b128 v[184:187], v231 offset:6144
	ds_read_b128 v[188:191], v231 offset:7168
	global_load_lds_dwordx4 v148, s[46:47]

; #define PG8_STAGE(bufoff, gbase, voff) do { _Pragma("unroll") for (int _i = 0; _i < 2; ++_i) \
;         __builtin_amdgcn_global_load_lds((const unsigned*)((const char*)(gbase) + (voff)[_i]), (LAS unsigned*)(lds + (bufoff) + ldsw + _i * 8192), 16, 0, 0); } while (0)
; #define PG8_LDA(dst, b, h) do { _Pragma("unroll") for (int m = 0; m < 4; ++m) _Pragma("unroll") for (int k = 0; k < 2; ++k) dst[m][k] = *(const LAS bf16x8*)(lds + PG8_SA(b, h) + aoff + m * 2048 + k * 1024); } while (0)
; #define PG8_LDB(dst, b, h) do { _Pragma("unroll") for (int n = 0; n < 2; ++n) _Pragma("unroll") for (int k = 0; k < 2; ++k) dst[n][k] = *(const LAS bf16x8*)(lds + PG8_SB(b, h) + boff + n * 2048 + k * 1024); } while (0)
; #define PG8_MMA(ai, bj, At, Bt) do { __builtin_amdgcn_s_setprio(1); _Pragma("unroll") for (int m = 0; m < 4; ++m) _Pragma("unroll") for (int n = 0; n < 2; ++n) _Pragma("unroll") for (int k = 0; k < 2; ++k) \
;         acc[ai][bj][m][n] = __builtin_amdgcn_mfma_f32_16x16x32_bf16(Bt[n][k], At[m][k], acc[ai][bj][m][n], 0, 0, 0); __builtin_amdgcn_s_setprio(0); } while (0)
; #define PG8_WAIT_L(n) asm volatile("s_waitcnt lgkmcnt(" #n ")" ::: "memory")
; #define PG8_BAR __builtin_amdgcn_s_barrier()
; #define PG8_SCHED __builtin_amdgcn_sched_barrier(0)
; template <class Epi>
; DI void gemm_phase(LAS unsigned char* lds, int wid, int K, int lda, int ldb, bool bperm, const Sched3& S, const Epi& E) {
;     ...
;             PG8_LDB(B0, 0, 0); PG8_SCHED; PG8_LDA(At, 0, 0); PG8_STAGE(PG8_SA(1, 1), a1 + hA, voffA);
;             PG8_WAIT_L(8); PG8_BAR; PG8_WAIT_L(0); PG8_MMA(0, 0, At, B0); PG8_BAR; PG8_SCHED;
	s_add_i32 m0, s58, 0xe000
	s_nop 0
	global_load_lds_dwordx4 v150, s[46:47]
	s_waitcnt lgkmcnt(8)
	s_barrier
	s_waitcnt lgkmcnt(0)
	s_setprio 1
	s_waitcnt lgkmcnt(0)
	v_mfma_f32_16x16x32_bf16 v[124:127], v[128:131], v[160:163], v[124:127]
	v_mfma_f32_16x16x32_bf16 v[120:123], v[136:139], v[160:163], v[120:123]
	v_mfma_f32_16x16x32_bf16 v[108:111], v[128:131], v[168:171], v[108:111]
	v_mfma_f32_16x16x32_bf16 v[104:107], v[136:139], v[168:171], v[104:107]
	v_mfma_f32_16x16x32_bf16 v[92:95], v[128:131], v[176:179], v[92:95]
	v_mfma_f32_16x16x32_bf16 v[88:91], v[136:139], v[176:179], v[88:91]
	v_mfma_f32_16x16x32_bf16 v[76:79], v[128:131], v[184:187], v[76:79]
	v_mfma_f32_16x16x32_bf16 v[72:75], v[136:139], v[184:187], v[72:75]
	v_mfma_f32_16x16x32_bf16 v[124:127], v[132:135], v[164:167], v[124:127]
	v_mfma_f32_16x16x32_bf16 v[120:123], v[156:159], v[164:167], v[120:123]
	v_mfma_f32_16x16x32_bf16 v[108:111], v[132:135], v[172:175], v[108:111]
	v_mfma_f32_16x16x32_bf16 v[104:107], v[156:159], v[172:175], v[104:107]
	v_mfma_f32_16x16x32_bf16 v[92:95], v[132:135], v[180:183], v[92:95]
	v_mfma_f32_16x16x32_bf16 v[88:91], v[156:159], v[180:183], v[88:91]
	v_mfma_f32_16x16x32_bf16 v[76:79], v[132:135], v[188:191], v[76:79]
	v_mfma_f32_16x16x32_bf16 v[72:75], v[156:159], v[188:191], v[72:75]
	s_setprio 0
	s_barrier
	s_add_i32 s75, s67, s57

; #define PG8_STAGE(bufoff, gbase, voff) do { _Pragma("unroll") for (int _i = 0; _i < 2; ++_i) \
;         __builtin_amdgcn_global_load_lds((const unsigned*)((const char*)(gbase) + (voff)[_i]), (LAS unsigned*)(lds + (bufoff) + ldsw + _i * 8192), 16, 0, 0); } while (0)
; #define PG8_LDB(dst, b, h) do { _Pragma("unroll") for (int n = 0; n < 2; ++n) _Pragma("unroll") for (int k = 0; k < 2; ++k) dst[n][k] = *(const LAS bf16x8*)(lds + PG8_SB(b, h) + boff + n * 2048 + k * 1024); } while (0)
; template <class Epi>
; DI void gemm_phase(LAS unsigned char* lds, int wid, int K, int lda, int ldb, bool bperm, const Sched3& S, const Epi& E) {
;     ...
;             PG8_LDB(B1, 0, 1); PG8_STAGE(PG8_SB(0, 0), b2, voffB);
	s_mov_b32 m0, s75
	ds_read_b128 v[192:195], v232
	ds_read_b128 v[196:199], v232 offset:1024
	ds_read_b128 v[200:203], v232 offset:2048
	ds_read_b128 v[204:207], v232 offset:3072
	global_load_lds_dwordx4 v142, s[48:49]

; #define PG8_STAGE(bufoff, gbase, voff) do { _Pragma("unroll") for (int _i = 0; _i < 2; ++_i) \
;         __builtin_amdgcn_global_load_lds((const unsigned*)((const char*)(gbase) + (voff)[_i]), (LAS unsigned*)(lds + (bufoff) + ldsw + _i * 8192), 16, 0, 0); } while (0)
; #define PG8_LDA(dst, b, h) do { _Pragma("unroll") for (int m = 0; m < 4; ++m) _Pragma("unroll") for (int k = 0; k < 2; ++k) dst[m][k] = *(const LAS bf16x8*)(lds + PG8_SA(b, h) + aoff + m * 2048 + k * 1024); } while (0)
; #define PG8_LDB(dst, b, h) do { _Pragma("unroll") for (int n = 0; n < 2; ++n) _Pragma("unroll") for (int k = 0; k < 2; ++k) dst[n][k] = *(const LAS bf16x8*)(lds + PG8_SB(b, h) + boff + n * 2048 + k * 1024); } while (0)
; #define PG8_MMA(ai, bj, At, Bt) do { __builtin_amdgcn_s_setprio(1); _Pragma("unroll") for (int m = 0; m < 4; ++m) _Pragma("unroll") for (int n = 0; n < 2; ++n) _Pragma("unroll") for (int k = 0; k < 2; ++k) \
;         acc[ai][bj][m][n] = __builtin_amdgcn_mfma_f32_16x16x32_bf16(Bt[n][k], At[m][k], acc[ai][bj][m][n], 0, 0, 0); __builtin_amdgcn_s_setprio(0); } while (0)
; #define PG8_WAIT_L(n) asm volatile("s_waitcnt lgkmcnt(" #n ")" ::: "memory")
; #define PG8_BAR __builtin_amdgcn_s_barrier()
; #define PG8_SCHED __builtin_amdgcn_sched_barrier(0)
; template <class Epi>
; DI void gemm_phase(LAS unsigned char* lds, int wid, int K, int lda, int ldb, bool bperm, const Sched3& S, const Epi& E) {
;     ...
;             PG8_LDB(B1, 0, 1); PG8_STAGE(PG8_SB(0, 0), b2, voffB);
;             PG8_BAR; PG8_WAIT_L(0); PG8_MMA(0, 1, At, B1); PG8_BAR;
;             PG8_LDA(At, 0, 1); PG8_STAGE(PG8_SA(0, 0), a2, voffA);
;             PG8_BAR; PG8_WAIT_L(0); if (full) PG8_MMA(1, 0, At, B0); PG8_BAR; PG8_SCHED;
;             PG8_STAGE(PG8_SB(0, 1), b2 + hstepB, voffB);
	s_add_i32 m0, s75, 0x2000
	s_nop 0
	global_load_lds_dwordx4 v146, s[48:49]
	s_barrier
	s_waitcnt lgkmcnt(0)
	s_setprio 1
	s_waitcnt lgkmcnt(0)
	v_mfma_f32_16x16x32_bf16 v[116:119], v[192:195], v[160:163], v[116:119]
	v_mfma_f32_16x16x32_bf16 v[112:115], v[200:203], v[160:163], v[112:115]
	v_mfma_f32_16x16x32_bf16 v[100:103], v[192:195], v[168:171], v[100:103]
	v_mfma_f32_16x16x32_bf16 v[96:99], v[200:203], v[168:171], v[96:99]
	v_mfma_f32_16x16x32_bf16 v[84:87], v[192:195], v[176:179], v[84:87]
	v_mfma_f32_16x16x32_bf16 v[80:83], v[200:203], v[176:179], v[80:83]
	v_mfma_f32_16x16x32_bf16 v[68:71], v[192:195], v[184:187], v[68:71]
	v_mfma_f32_16x16x32_bf16 v[64:67], v[200:203], v[184:187], v[64:67]
	v_mfma_f32_16x16x32_bf16 v[116:119], v[196:199], v[164:167], v[116:119]
	v_mfma_f32_16x16x32_bf16 v[112:115], v[204:207], v[164:167], v[112:115]
	v_mfma_f32_16x16x32_bf16 v[100:103], v[196:199], v[172:175], v[100:103]
	v_mfma_f32_16x16x32_bf16 v[96:99], v[204:207], v[172:175], v[96:99]
	v_mfma_f32_16x16x32_bf16 v[84:87], v[196:199], v[180:183], v[84:87]
	v_mfma_f32_16x16x32_bf16 v[80:83], v[204:207], v[180:183], v[80:83]
	v_mfma_f32_16x16x32_bf16 v[68:71], v[196:199], v[188:191], v[68:71]
	v_mfma_f32_16x16x32_bf16 v[64:67], v[204:207], v[188:191], v[64:67]
	s_setprio 0
	s_mov_b32 m0, s58
	s_mov_b64 s[100:101], s[50:51]
	s_barrier
	ds_read_b128 v[160:163], v231 offset:16384
	ds_read_b128 v[164:167], v231 offset:17408
	ds_read_b128 v[168:171], v231 offset:18432
	ds_read_b128 v[172:175], v231 offset:19456
	ds_read_b128 v[176:179], v231 offset:20480
	ds_read_b128 v[180:183], v231 offset:21504
	ds_read_b128 v[184:187], v231 offset:22528
	ds_read_b128 v[188:191], v231 offset:23552
	global_load_lds_dwordx4 v140, s[50:51]
	s_mov_b64 s[100:101], s[50:51]
	s_mov_b32 m0, s59
	s_nop 0
	global_load_lds_dwordx4 v144, s[50:51]
	s_barrier
	s_waitcnt lgkmcnt(0)
	s_setprio 1
	s_waitcnt lgkmcnt(0)
	v_mfma_f32_16x16x32_bf16 v[60:63], v[128:131], v[160:163], v[60:63]
	v_mfma_f32_16x16x32_bf16 v[56:59], v[136:139], v[160:163], v[56:59]
	v_mfma_f32_16x16x32_bf16 v[44:47], v[128:131], v[168:171], v[44:47]
	v_mfma_f32_16x16x32_bf16 v[40:43], v[136:139], v[168:171], v[40:43]
	v_mfma_f32_16x16x32_bf16 v[28:31], v[128:131], v[176:179], v[28:31]
	v_mfma_f32_16x16x32_bf16 v[24:27], v[136:139], v[176:179], v[24:27]
	v_mfma_f32_16x16x32_bf16 v[12:15], v[128:131], v[184:187], v[12:15]
	v_mfma_f32_16x16x32_bf16 v[8:11], v[136:139], v[184:187], v[8:11]
	v_mfma_f32_16x16x32_bf16 v[60:63], v[132:135], v[164:167], v[60:63]
	v_mfma_f32_16x16x32_bf16 v[56:59], v[156:159], v[164:167], v[56:59]
	v_mfma_f32_16x16x32_bf16 v[44:47], v[132:135], v[172:175], v[44:47]
	v_mfma_f32_16x16x32_bf16 v[40:43], v[156:159], v[172:175], v[40:43]
	v_mfma_f32_16x16x32_bf16 v[28:31], v[132:135], v[180:183], v[28:31]
	v_mfma_f32_16x16x32_bf16 v[24:27], v[156:159], v[180:183], v[24:27]
	v_mfma_f32_16x16x32_bf16 v[12:15], v[132:135], v[188:191], v[12:15]
	v_mfma_f32_16x16x32_bf16 v[8:11], v[156:159], v[188:191], v[8:11]
	s_setprio 0
	s_barrier
	s_add_u32 s76, s48, 0x80000
	s_addc_u32 s77, s49, 0
	s_add_i32 s75, s68, s57

; #define PG8_STAGE(bufoff, gbase, voff) do { _Pragma("unroll") for (int _i = 0; _i < 2; ++_i) \
;         __builtin_amdgcn_global_load_lds((const unsigned*)((const char*)(gbase) + (voff)[_i]), (LAS unsigned*)(lds + (bufoff) + ldsw + _i * 8192), 16, 0, 0); } while (0)
; template <class Epi>
; DI void gemm_phase(LAS unsigned char* lds, int wid, int K, int lda, int ldb, bool bperm, const Sched3& S, const Epi& E) {
;     ...
;             PG8_STAGE(PG8_SB(0, 1), b2 + hstepB, voffB);
	s_mov_b32 m0, s75
	s_nop 0
	global_load_lds_dwordx4 v142, s[76:77]

; #define PG8_STAGE(bufoff, gbase, voff) do { _Pragma("unroll") for (int _i = 0; _i < 2; ++_i) \
;         __builtin_amdgcn_global_load_lds((const unsigned*)((const char*)(gbase) + (voff)[_i]), (LAS unsigned*)(lds + (bufoff) + ldsw + _i * 8192), 16, 0, 0); } while (0)
; #define PG8_LDA(dst, b, h) do { _Pragma("unroll") for (int m = 0; m < 4; ++m) _Pragma("unroll") for (int k = 0; k < 2; ++k) dst[m][k] = *(const LAS bf16x8*)(lds + PG8_SA(b, h) + aoff + m * 2048 + k * 1024); } while (0)
; #define PG8_LDB(dst, b, h) do { _Pragma("unroll") for (int n = 0; n < 2; ++n) _Pragma("unroll") for (int k = 0; k < 2; ++k) dst[n][k] = *(const LAS bf16x8*)(lds + PG8_SB(b, h) + boff + n * 2048 + k * 1024); } while (0)
; #define PG8_MMA(ai, bj, At, Bt) do { __builtin_amdgcn_s_setprio(1); _Pragma("unroll") for (int m = 0; m < 4; ++m) _Pragma("unroll") for (int n = 0; n < 2; ++n) _Pragma("unroll") for (int k = 0; k < 2; ++k) \
;         acc[ai][bj][m][n] = __builtin_amdgcn_mfma_f32_16x16x32_bf16(Bt[n][k], At[m][k], acc[ai][bj][m][n], 0, 0, 0); __builtin_amdgcn_s_setprio(0); } while (0)
; #define PG8_WAIT_V(n) asm volatile("s_waitcnt vmcnt(" #n ")" ::: "memory")
; #define PG8_BAR __builtin_amdgcn_s_barrier()
; #define PG8_SCHED __builtin_amdgcn_sched_barrier(0)
; template <class Epi>
; DI void gemm_phase(LAS unsigned char* lds, int wid, int K, int lda, int ldb, bool bperm, const Sched3& S, const Epi& E) {
;     ...
;             PG8_WAIT_V(6); PG8_BAR; if (full) PG8_MMA(1, 1, At, B1); PG8_BAR;
;             PG8_LDB(B0, 1, 0); PG8_SCHED; PG8_LDA(At, 1, 0); PG8_STAGE(PG8_SA(0, 1), a2 + h2, voffA);
	s_add_i32 m0, s75, 0x2000
	s_nop 0
	global_load_lds_dwordx4 v146, s[76:77]
	s_waitcnt vmcnt(6)
	s_barrier
	s_setprio 1
	v_mfma_f32_16x16x32_bf16 v[52:55], v[192:195], v[160:163], v[52:55]
	v_mfma_f32_16x16x32_bf16 v[48:51], v[200:203], v[160:163], v[48:51]
	v_mfma_f32_16x16x32_bf16 v[36:39], v[192:195], v[168:171], v[36:39]
	v_mfma_f32_16x16x32_bf16 v[32:35], v[200:203], v[168:171], v[32:35]
	v_mfma_f32_16x16x32_bf16 v[20:23], v[192:195], v[176:179], v[20:23]
	v_mfma_f32_16x16x32_bf16 v[16:19], v[200:203], v[176:179], v[16:19]
	v_mfma_f32_16x16x32_bf16 v[4:7], v[192:195], v[184:187], v[4:7]
	v_mfma_f32_16x16x32_bf16 v[0:3], v[200:203], v[184:187], v[0:3]
	v_mfma_f32_16x16x32_bf16 v[52:55], v[196:199], v[164:167], v[52:55]
	v_mfma_f32_16x16x32_bf16 v[48:51], v[204:207], v[164:167], v[48:51]
	v_mfma_f32_16x16x32_bf16 v[36:39], v[196:199], v[172:175], v[36:39]
	v_mfma_f32_16x16x32_bf16 v[32:35], v[204:207], v[172:175], v[32:35]
	v_mfma_f32_16x16x32_bf16 v[20:23], v[196:199], v[180:183], v[20:23]
	v_mfma_f32_16x16x32_bf16 v[16:19], v[204:207], v[180:183], v[16:19]
	v_mfma_f32_16x16x32_bf16 v[4:7], v[196:199], v[188:191], v[4:7]
	v_mfma_f32_16x16x32_bf16 v[0:3], v[204:207], v[188:191], v[0:3]
	s_setprio 0
	s_add_i32 s75, 0, 0x18000
	v_add_u32_e32 v156, s75, v224
	s_barrier
	ds_read_b128 v[128:131], v156
	ds_read_b128 v[132:135], v156 offset:1024
	ds_read_b128 v[136:139], v156 offset:2048
	ds_read_b128 v[156:159], v156 offset:3072
	s_add_u32 s50, s50, 0x80000
	s_addc_u32 s51, s51, 0
	s_mov_b32 m0, s60

; #define PG8_STAGE(bufoff, gbase, voff) do { _Pragma("unroll") for (int _i = 0; _i < 2; ++_i) \
;         __builtin_amdgcn_global_load_lds((const unsigned*)((const char*)(gbase) + (voff)[_i]), (LAS unsigned*)(lds + (bufoff) + ldsw + _i * 8192), 16, 0, 0); } while (0)
; #define PG8_LDA(dst, b, h) do { _Pragma("unroll") for (int m = 0; m < 4; ++m) _Pragma("unroll") for (int k = 0; k < 2; ++k) dst[m][k] = *(const LAS bf16x8*)(lds + PG8_SA(b, h) + aoff + m * 2048 + k * 1024); } while (0)
; #define PG8_LDB(dst, b, h) do { _Pragma("unroll") for (int n = 0; n < 2; ++n) _Pragma("unroll") for (int k = 0; k < 2; ++k) dst[n][k] = *(const LAS bf16x8*)(lds + PG8_SB(b, h) + boff + n * 2048 + k * 1024); } while (0)
; #define PG8_SCHED __builtin_amdgcn_sched_barrier(0)
; template <class Epi>
; DI void gemm_phase(LAS unsigned char* lds, int wid, int K, int lda, int ldb, bool bperm, const Sched3& S, const Epi& E) {
;     ...
;             PG8_LDB(B0, 1, 0); PG8_SCHED; PG8_LDA(At, 1, 0); PG8_STAGE(PG8_SA(0, 1), a2 + h2, voffA);
	ds_read_b128 v[160:163], v231 offset:32768
	ds_read_b128 v[164:167], v231 offset:33792
	ds_read_b128 v[168:171], v231 offset:34816
	ds_read_b128 v[172:175], v231 offset:35840
	ds_read_b128 v[176:179], v231 offset:36864
	ds_read_b128 v[180:183], v231 offset:37888
	ds_read_b128 v[184:187], v231 offset:38912
	ds_read_b128 v[188:191], v231 offset:39936
	global_load_lds_dwordx4 v140, s[50:51]

; #define PG8_STAGE(bufoff, gbase, voff) do { _Pragma("unroll") for (int _i = 0; _i < 2; ++_i) \
;         __builtin_amdgcn_global_load_lds((const unsigned*)((const char*)(gbase) + (voff)[_i]), (LAS unsigned*)(lds + (bufoff) + ldsw + _i * 8192), 16, 0, 0); } while (0)
; #define PG8_LDB(dst, b, h) do { _Pragma("unroll") for (int n = 0; n < 2; ++n) _Pragma("unroll") for (int k = 0; k < 2; ++k) dst[n][k] = *(const LAS bf16x8*)(lds + PG8_SB(b, h) + boff + n * 2048 + k * 1024); } while (0)
; #define PG8_MMA(ai, bj, At, Bt) do { __builtin_amdgcn_s_setprio(1); _Pragma("unroll") for (int m = 0; m < 4; ++m) _Pragma("unroll") for (int n = 0; n < 2; ++n) _Pragma("unroll") for (int k = 0; k < 2; ++k) \
;         acc[ai][bj][m][n] = __builtin_amdgcn_mfma_f32_16x16x32_bf16(Bt[n][k], At[m][k], acc[ai][bj][m][n], 0, 0, 0); __builtin_amdgcn_s_setprio(0); } while (0)
; #define PG8_WAIT_L(n) asm volatile("s_waitcnt lgkmcnt(" #n ")" ::: "memory")
; #define PG8_BAR __builtin_amdgcn_s_barrier()
; #define PG8_SCHED __builtin_amdgcn_sched_barrier(0)
; template <class Epi>
; DI void gemm_phase(LAS unsigned char* lds, int wid, int K, int lda, int ldb, bool bperm, const Sched3& S, const Epi& E) {
;     ...
;             PG8_WAIT_L(8); PG8_BAR; PG8_WAIT_L(0); PG8_MMA(0, 0, At, B0); PG8_BAR; PG8_SCHED;
;             PG8_LDB(B1, 1, 1); PG8_STAGE(PG8_SB(1, 0), b3, voffB);
	s_mov_b32 m0, s61
	s_nop 0
	global_load_lds_dwordx4 v144, s[50:51]
	s_waitcnt lgkmcnt(8)
	s_barrier
	s_waitcnt lgkmcnt(0)
	s_setprio 1
	s_waitcnt lgkmcnt(0)
	v_mfma_f32_16x16x32_bf16 v[124:127], v[128:131], v[160:163], v[124:127]
	v_mfma_f32_16x16x32_bf16 v[120:123], v[136:139], v[160:163], v[120:123]
	v_mfma_f32_16x16x32_bf16 v[108:111], v[128:131], v[168:171], v[108:111]
	v_mfma_f32_16x16x32_bf16 v[104:107], v[136:139], v[168:171], v[104:107]
	v_mfma_f32_16x16x32_bf16 v[92:95], v[128:131], v[176:179], v[92:95]
	v_mfma_f32_16x16x32_bf16 v[88:91], v[136:139], v[176:179], v[88:91]
	v_mfma_f32_16x16x32_bf16 v[76:79], v[128:131], v[184:187], v[76:79]
	v_mfma_f32_16x16x32_bf16 v[72:75], v[136:139], v[184:187], v[72:75]
	v_mfma_f32_16x16x32_bf16 v[124:127], v[132:135], v[164:167], v[124:127]
	v_mfma_f32_16x16x32_bf16 v[120:123], v[156:159], v[164:167], v[120:123]
	v_mfma_f32_16x16x32_bf16 v[108:111], v[132:135], v[172:175], v[108:111]
	v_mfma_f32_16x16x32_bf16 v[104:107], v[156:159], v[172:175], v[104:107]
	v_mfma_f32_16x16x32_bf16 v[92:95], v[132:135], v[180:183], v[92:95]
	v_mfma_f32_16x16x32_bf16 v[88:91], v[156:159], v[180:183], v[88:91]
	v_mfma_f32_16x16x32_bf16 v[76:79], v[132:135], v[188:191], v[76:79]
	v_mfma_f32_16x16x32_bf16 v[72:75], v[156:159], v[188:191], v[72:75]
	s_setprio 0
	s_barrier
	s_add_i32 s50, 0, 0x1c000
	s_add_i32 s51, s75, s57
	v_add_u32_e32 v204, s50, v224

; #define PG8_STAGE(bufoff, gbase, voff) do { _Pragma("unroll") for (int _i = 0; _i < 2; ++_i) \
;         __builtin_amdgcn_global_load_lds((const unsigned*)((const char*)(gbase) + (voff)[_i]), (LAS unsigned*)(lds + (bufoff) + ldsw + _i * 8192), 16, 0, 0); } while (0)
; #define PG8_LDB(dst, b, h) do { _Pragma("unroll") for (int n = 0; n < 2; ++n) _Pragma("unroll") for (int k = 0; k < 2; ++k) dst[n][k] = *(const LAS bf16x8*)(lds + PG8_SB(b, h) + boff + n * 2048 + k * 1024); } while (0)
; template <class Epi>
; DI void gemm_phase(LAS unsigned char* lds, int wid, int K, int lda, int ldb, bool bperm, const Sched3& S, const Epi& E) {
;     ...
;             PG8_LDB(B1, 1, 1); PG8_STAGE(PG8_SB(1, 0), b3, voffB);
	s_sub_i32 m0, s51, 0x80
	ds_read_b128 v[192:195], v204
	ds_read_b128 v[196:199], v204 offset:1024
	ds_read_b128 v[200:203], v204 offset:2048
	ds_read_b128 v[204:207], v204 offset:3072
	global_load_lds_dwordx4 v142, s[48:49] offset:128

; #define PG8_STAGE(bufoff, gbase, voff) do { _Pragma("unroll") for (int _i = 0; _i < 2; ++_i) \
;         __builtin_amdgcn_global_load_lds((const unsigned*)((const char*)(gbase) + (voff)[_i]), (LAS unsigned*)(lds + (bufoff) + ldsw + _i * 8192), 16, 0, 0); } while (0)
; #define PG8_LDA(dst, b, h) do { _Pragma("unroll") for (int m = 0; m < 4; ++m) _Pragma("unroll") for (int k = 0; k < 2; ++k) dst[m][k] = *(const LAS bf16x8*)(lds + PG8_SA(b, h) + aoff + m * 2048 + k * 1024); } while (0)
; #define PG8_LDB(dst, b, h) do { _Pragma("unroll") for (int n = 0; n < 2; ++n) _Pragma("unroll") for (int k = 0; k < 2; ++k) dst[n][k] = *(const LAS bf16x8*)(lds + PG8_SB(b, h) + boff + n * 2048 + k * 1024); } while (0)
; #define PG8_MMA(ai, bj, At, Bt) do { __builtin_amdgcn_s_setprio(1); _Pragma("unroll") for (int m = 0; m < 4; ++m) _Pragma("unroll") for (int n = 0; n < 2; ++n) _Pragma("unroll") for (int k = 0; k < 2; ++k) \
;         acc[ai][bj][m][n] = __builtin_amdgcn_mfma_f32_16x16x32_bf16(Bt[n][k], At[m][k], acc[ai][bj][m][n], 0, 0, 0); __builtin_amdgcn_s_setprio(0); } while (0)
; #define PG8_WAIT_L(n) asm volatile("s_waitcnt lgkmcnt(" #n ")" ::: "memory")
; #define PG8_BAR __builtin_amdgcn_s_barrier()
; template <class Epi>
; DI void gemm_phase(LAS unsigned char* lds, int wid, int K, int lda, int ldb, bool bperm, const Sched3& S, const Epi& E) {
;     ...
;             PG8_LDB(B1, 1, 1); PG8_STAGE(PG8_SB(1, 0), b3, voffB);
;             PG8_BAR; PG8_WAIT_L(0); PG8_MMA(0, 1, At, B1); PG8_BAR;
;             PG8_LDA(At, 1, 1); PG8_STAGE(PG8_SA(1, 0), a3, voffA);
	s_add_i32 m0, s51, 0x1f80
	s_nop 0
	global_load_lds_dwordx4 v146, s[48:49] offset:128
	s_barrier
	s_waitcnt lgkmcnt(0)
	s_setprio 1
	s_waitcnt lgkmcnt(0)
	v_mfma_f32_16x16x32_bf16 v[116:119], v[192:195], v[160:163], v[116:119]
	v_mfma_f32_16x16x32_bf16 v[112:115], v[200:203], v[160:163], v[112:115]
	v_mfma_f32_16x16x32_bf16 v[100:103], v[192:195], v[168:171], v[100:103]
	v_mfma_f32_16x16x32_bf16 v[96:99], v[200:203], v[168:171], v[96:99]
	v_mfma_f32_16x16x32_bf16 v[84:87], v[192:195], v[176:179], v[84:87]
	v_mfma_f32_16x16x32_bf16 v[80:83], v[200:203], v[176:179], v[80:83]
	v_mfma_f32_16x16x32_bf16 v[68:71], v[192:195], v[184:187], v[68:71]
	v_mfma_f32_16x16x32_bf16 v[64:67], v[200:203], v[184:187], v[64:67]
	v_mfma_f32_16x16x32_bf16 v[116:119], v[196:199], v[164:167], v[116:119]
	v_mfma_f32_16x16x32_bf16 v[112:115], v[204:207], v[164:167], v[112:115]
	v_mfma_f32_16x16x32_bf16 v[100:103], v[196:199], v[172:175], v[100:103]
	v_mfma_f32_16x16x32_bf16 v[96:99], v[204:207], v[172:175], v[96:99]
	v_mfma_f32_16x16x32_bf16 v[84:87], v[196:199], v[180:183], v[84:87]
	v_mfma_f32_16x16x32_bf16 v[80:83], v[204:207], v[180:183], v[80:83]
	v_mfma_f32_16x16x32_bf16 v[68:71], v[196:199], v[188:191], v[68:71]
	v_mfma_f32_16x16x32_bf16 v[64:67], v[204:207], v[188:191], v[64:67]
	s_setprio 0
	s_sub_i32 m0, s63, 0x80

; #define PG8_STAGE(bufoff, gbase, voff) do { _Pragma("unroll") for (int _i = 0; _i < 2; ++_i) \
;         __builtin_amdgcn_global_load_lds((const unsigned*)((const char*)(gbase) + (voff)[_i]), (LAS unsigned*)(lds + (bufoff) + ldsw + _i * 8192), 16, 0, 0); } while (0)
; #define PG8_LDA(dst, b, h) do { _Pragma("unroll") for (int m = 0; m < 4; ++m) _Pragma("unroll") for (int k = 0; k < 2; ++k) dst[m][k] = *(const LAS bf16x8*)(lds + PG8_SA(b, h) + aoff + m * 2048 + k * 1024); } while (0)
; template <class Epi>
; DI void gemm_phase(LAS unsigned char* lds, int wid, int K, int lda, int ldb, bool bperm, const Sched3& S, const Epi& E) {
;     ...
;             PG8_LDA(At, 1, 1); PG8_STAGE(PG8_SA(1, 0), a3, voffA);
	s_barrier
	ds_read_b128 v[160:163], v231 offset:49152
	ds_read_b128 v[164:167], v231 offset:50176
	ds_read_b128 v[168:171], v231 offset:51200
	ds_read_b128 v[172:175], v231 offset:52224
	ds_read_b128 v[176:179], v231 offset:53248
	ds_read_b128 v[180:183], v231 offset:54272
	ds_read_b128 v[184:187], v231 offset:55296
	ds_read_b128 v[188:191], v231 offset:56320
	global_load_lds_dwordx4 v140, s[100:101] offset:128

; #define PG8_STAGE(bufoff, gbase, voff) do { _Pragma("unroll") for (int _i = 0; _i < 2; ++_i) \
;         __builtin_amdgcn_global_load_lds((const unsigned*)((const char*)(gbase) + (voff)[_i]), (LAS unsigned*)(lds + (bufoff) + ldsw + _i * 8192), 16, 0, 0); } while (0)
; #define PG8_LDA(dst, b, h) do { _Pragma("unroll") for (int m = 0; m < 4; ++m) _Pragma("unroll") for (int k = 0; k < 2; ++k) dst[m][k] = *(const LAS bf16x8*)(lds + PG8_SA(b, h) + aoff + m * 2048 + k * 1024); } while (0)
; #define PG8_MMA(ai, bj, At, Bt) do { __builtin_amdgcn_s_setprio(1); _Pragma("unroll") for (int m = 0; m < 4; ++m) _Pragma("unroll") for (int n = 0; n < 2; ++n) _Pragma("unroll") for (int k = 0; k < 2; ++k) \
;         acc[ai][bj][m][n] = __builtin_amdgcn_mfma_f32_16x16x32_bf16(Bt[n][k], At[m][k], acc[ai][bj][m][n], 0, 0, 0); __builtin_amdgcn_s_setprio(0); } while (0)
; #define PG8_WAIT_L(n) asm volatile("s_waitcnt lgkmcnt(" #n ")" ::: "memory")
; #define PG8_BAR __builtin_amdgcn_s_barrier()
; #define PG8_SCHED __builtin_amdgcn_sched_barrier(0)
; template <class Epi>
; DI void gemm_phase(LAS unsigned char* lds, int wid, int K, int lda, int ldb, bool bperm, const Sched3& S, const Epi& E) {
;     ...
;             PG8_LDA(At, 1, 1); PG8_STAGE(PG8_SA(1, 0), a3, voffA);
;             PG8_BAR; PG8_WAIT_L(0); if (full) PG8_MMA(1, 0, At, B0); PG8_BAR; PG8_SCHED;
;             PG8_STAGE(PG8_SB(1, 1), b3 + hstepB, voffB);
	s_sub_i32 m0, s64, 0x80
	s_nop 0
	global_load_lds_dwordx4 v144, s[100:101] offset:128
	s_barrier
	s_waitcnt lgkmcnt(0)
	s_setprio 1
	s_waitcnt lgkmcnt(0)
	v_mfma_f32_16x16x32_bf16 v[60:63], v[128:131], v[160:163], v[60:63]
	v_mfma_f32_16x16x32_bf16 v[56:59], v[136:139], v[160:163], v[56:59]
	v_mfma_f32_16x16x32_bf16 v[44:47], v[128:131], v[168:171], v[44:47]
	v_mfma_f32_16x16x32_bf16 v[40:43], v[136:139], v[168:171], v[40:43]
	v_mfma_f32_16x16x32_bf16 v[28:31], v[128:131], v[176:179], v[28:31]
	v_mfma_f32_16x16x32_bf16 v[24:27], v[136:139], v[176:179], v[24:27]
	v_mfma_f32_16x16x32_bf16 v[12:15], v[128:131], v[184:187], v[12:15]
	v_mfma_f32_16x16x32_bf16 v[8:11], v[136:139], v[184:187], v[8:11]
	v_mfma_f32_16x16x32_bf16 v[60:63], v[132:135], v[164:167], v[60:63]
	v_mfma_f32_16x16x32_bf16 v[56:59], v[156:159], v[164:167], v[56:59]
	v_mfma_f32_16x16x32_bf16 v[44:47], v[132:135], v[172:175], v[44:47]
	v_mfma_f32_16x16x32_bf16 v[40:43], v[156:159], v[172:175], v[40:43]
	v_mfma_f32_16x16x32_bf16 v[28:31], v[132:135], v[180:183], v[28:31]
	v_mfma_f32_16x16x32_bf16 v[24:27], v[156:159], v[180:183], v[24:27]
	v_mfma_f32_16x16x32_bf16 v[12:15], v[132:135], v[188:191], v[12:15]
	v_mfma_f32_16x16x32_bf16 v[8:11], v[156:159], v[188:191], v[8:11]
	s_setprio 0
	s_barrier
	s_add_u32 s48, s48, 0x80080
	s_addc_u32 s49, s49, 0
	s_add_i32 s50, s50, s57

; #define PG8_STAGE(bufoff, gbase, voff) do { _Pragma("unroll") for (int _i = 0; _i < 2; ++_i) \
;         __builtin_amdgcn_global_load_lds((const unsigned*)((const char*)(gbase) + (voff)[_i]), (LAS unsigned*)(lds + (bufoff) + ldsw + _i * 8192), 16, 0, 0); } while (0)
; template <class Epi>
; DI void gemm_phase(LAS unsigned char* lds, int wid, int K, int lda, int ldb, bool bperm, const Sched3& S, const Epi& E) {
;     ...
;             PG8_STAGE(PG8_SB(1, 1), b3 + hstepB, voffB);
	s_mov_b32 m0, s50
	s_nop 0
	global_load_lds_dwordx4 v142, s[48:49]

; #define PG8_STAGE(bufoff, gbase, voff) do { _Pragma("unroll") for (int _i = 0; _i < 2; ++_i) \
;         __builtin_amdgcn_global_load_lds((const unsigned*)((const char*)(gbase) + (voff)[_i]), (LAS unsigned*)(lds + (bufoff) + ldsw + _i * 8192), 16, 0, 0); } while (0)
; #define PG8_MMA(ai, bj, At, Bt) do { __builtin_amdgcn_s_setprio(1); _Pragma("unroll") for (int m = 0; m < 4; ++m) _Pragma("unroll") for (int n = 0; n < 2; ++n) _Pragma("unroll") for (int k = 0; k < 2; ++k) \
;         acc[ai][bj][m][n] = __builtin_amdgcn_mfma_f32_16x16x32_bf16(Bt[n][k], At[m][k], acc[ai][bj][m][n], 0, 0, 0); __builtin_amdgcn_s_setprio(0); } while (0)
; #define PG8_WAIT_V(n) asm volatile("s_waitcnt vmcnt(" #n ")" ::: "memory")
; #define PG8_BAR __builtin_amdgcn_s_barrier()
; template <class Epi>
; DI void gemm_phase(LAS unsigned char* lds, int wid, int K, int lda, int ldb, bool bperm, const Sched3& S, const Epi& E) {
;     ...
;             PG8_STAGE(PG8_SB(1, 1), b3 + hstepB, voffB);
;             PG8_WAIT_V(6); PG8_BAR; if (full) PG8_MMA(1, 1, At, B1); PG8_BAR;
	s_add_i32 m0, s50, 0x2000
	s_nop 0
	global_load_lds_dwordx4 v146, s[48:49]
	s_waitcnt vmcnt(6)
	s_barrier
	s_setprio 1
	v_mfma_f32_16x16x32_bf16 v[52:55], v[192:195], v[160:163], v[52:55]
	v_mfma_f32_16x16x32_bf16 v[48:51], v[200:203], v[160:163], v[48:51]
	v_mfma_f32_16x16x32_bf16 v[36:39], v[192:195], v[168:171], v[36:39]
	v_mfma_f32_16x16x32_bf16 v[32:35], v[200:203], v[168:171], v[32:35]
	v_mfma_f32_16x16x32_bf16 v[20:23], v[192:195], v[176:179], v[20:23]
	v_mfma_f32_16x16x32_bf16 v[16:19], v[200:203], v[176:179], v[16:19]
	v_mfma_f32_16x16x32_bf16 v[4:7], v[192:195], v[184:187], v[4:7]
	v_mfma_f32_16x16x32_bf16 v[0:3], v[200:203], v[184:187], v[0:3]
	v_mfma_f32_16x16x32_bf16 v[52:55], v[196:199], v[164:167], v[52:55]
	v_mfma_f32_16x16x32_bf16 v[48:51], v[204:207], v[164:167], v[48:51]
	v_mfma_f32_16x16x32_bf16 v[36:39], v[196:199], v[172:175], v[36:39]
	v_mfma_f32_16x16x32_bf16 v[32:35], v[204:207], v[172:175], v[32:35]
	v_mfma_f32_16x16x32_bf16 v[20:23], v[196:199], v[180:183], v[20:23]
	v_mfma_f32_16x16x32_bf16 v[16:19], v[204:207], v[180:183], v[16:19]
	v_mfma_f32_16x16x32_bf16 v[4:7], v[196:199], v[188:191], v[4:7]
	v_mfma_f32_16x16x32_bf16 v[0:3], v[204:207], v[188:191], v[0:3]
	s_setprio 0
	s_add_i32 s55, s55, 2
	s_add_u32 s46, s46, 0x100
	s_addc_u32 s47, s47, 0
	s_add_u32 s53, s53, 0x100
	s_addc_u32 s54, s54, 0
	s_cmp_gt_u32 s55, 29
	s_barrier
	s_cbranch_scc0 .LBB0_327

; #define PG8_STAGE(bufoff, gbase, voff) do { _Pragma("unroll") for (int _i = 0; _i < 2; ++_i) \
;         __builtin_amdgcn_global_load_lds((const unsigned*)((const char*)(gbase) + (voff)[_i]), (LAS unsigned*)(lds + (bufoff) + ldsw + _i * 8192), 16, 0, 0); } while (0)
; #define PG8_LDA(dst, b, h) do { _Pragma("unroll") for (int m = 0; m < 4; ++m) _Pragma("unroll") for (int k = 0; k < 2; ++k) dst[m][k] = *(const LAS bf16x8*)(lds + PG8_SA(b, h) + aoff + m * 2048 + k * 1024); } while (0)
; #define PG8_LDB(dst, b, h) do { _Pragma("unroll") for (int n = 0; n < 2; ++n) _Pragma("unroll") for (int k = 0; k < 2; ++k) dst[n][k] = *(const LAS bf16x8*)(lds + PG8_SB(b, h) + boff + n * 2048 + k * 1024); } while (0)
; #define PG8_SCHED __builtin_amdgcn_sched_barrier(0)
; template <class Epi>
; DI void gemm_phase(LAS unsigned char* lds, int wid, int K, int lda, int ldb, bool bperm, const Sched3& S, const Epi& E) {
;     ...
;         const bool has_next = S.next(ui + 1, nxt);
;         const char* nA = has_next ? nxt.A : cA; const char* nB = has_next ? nxt.B : cB; const size_t nhA = has_next ? (nxt.half ? (size_t)0 : hstepA) : hA; const bool full = (cur.half == 0);
;         for (int t = 0; t < nt; t += 2) {
;             const bool last = (t == nt - 2);
;             const char* a1 = cA + (size_t)(t + 1) * kstep;
;             const char* a2 = last ? nA : cA + (size_t)(t + 2) * kstep; const char* b2 = last ? nB : cB + (size_t)(t + 2) * kstep;
;             const char* a3 = a2 + kstep; const char* b3 = b2 + kstep; const size_t h2 = last ? nhA : hA;
;             PG8_LDB(B0, 0, 0); PG8_SCHED; PG8_LDA(At, 0, 0); PG8_STAGE(PG8_SA(1, 1), a1 + hA, voffA);
.LBB0_620:
	s_add_u32 s38, s38, 0x80080
	s_addc_u32 s39, s39, 0
	s_add_u32 s21, s40, 0x100
	s_nop 0
	s_addc_u32 s23, s41, 0
	s_mov_b32 s29, -2
	s_waitcnt lgkmcnt(0)
	ds_read_b128 v[128:131], v203
	ds_read_b128 v[132:135], v203 offset:1024
	ds_read_b128 v[136:139], v203 offset:2048
	ds_read_b128 v[140:143], v203 offset:3072
	s_add_u32 s40, s38, 0xfff80080
	s_addc_u32 s41, s39, -1
	s_cmp_eq_u32 s29, 28
	s_cselect_b32 s43, s31, s41
	s_cselect_b32 s42, s30, s40
	s_cselect_b32 s41, s37, s23
	s_cselect_b32 s40, s36, s21

; #define PG8_STAGE(bufoff, gbase, voff) do { _Pragma("unroll") for (int _i = 0; _i < 2; ++_i) \
;         __builtin_amdgcn_global_load_lds((const unsigned*)((const char*)(gbase) + (voff)[_i]), (LAS unsigned*)(lds + (bufoff) + ldsw + _i * 8192), 16, 0, 0); } while (0)
; #define PG8_LDA(dst, b, h) do { _Pragma("unroll") for (int m = 0; m < 4; ++m) _Pragma("unroll") for (int k = 0; k < 2; ++k) dst[m][k] = *(const LAS bf16x8*)(lds + PG8_SA(b, h) + aoff + m * 2048 + k * 1024); } while (0)
; #define PG8_LDB(dst, b, h) do { _Pragma("unroll") for (int n = 0; n < 2; ++n) _Pragma("unroll") for (int k = 0; k < 2; ++k) dst[n][k] = *(const LAS bf16x8*)(lds + PG8_SB(b, h) + boff + n * 2048 + k * 1024); } while (0)
; #define PG8_SCHED __builtin_amdgcn_sched_barrier(0)
; template <class Epi>
; DI void gemm_phase(LAS unsigned char* lds, int wid, int K, int lda, int ldb, bool bperm, const Sched3& S, const Epi& E) {
;     ...
;             const bool last = (t == nt - 2);
;             const char* a1 = cA + (size_t)(t + 1) * kstep;
;             const char* a2 = last ? nA : cA + (size_t)(t + 2) * kstep; const char* b2 = last ? nB : cB + (size_t)(t + 2) * kstep;
;             const char* a3 = a2 + kstep; const char* b3 = b2 + kstep; const size_t h2 = last ? nhA : hA;
;             PG8_LDB(B0, 0, 0); PG8_SCHED; PG8_LDA(At, 0, 0); PG8_STAGE(PG8_SA(1, 1), a1 + hA, voffA);
	s_add_i32 m0, s50, 0xc000
	ds_read_b128 v[144:147], v204
	ds_read_b128 v[148:151], v204 offset:1024
	ds_read_b128 v[152:155], v204 offset:2048
	ds_read_b128 v[156:159], v204 offset:3072
	ds_read_b128 v[160:163], v204 offset:4096
	ds_read_b128 v[164:167], v204 offset:5120
	ds_read_b128 v[168:171], v204 offset:6144
	ds_read_b128 v[172:175], v204 offset:7168
	global_load_lds_dwordx4 v180, s[38:39]

; #define PG8_STAGE(bufoff, gbase, voff) do { _Pragma("unroll") for (int _i = 0; _i < 2; ++_i) \
;         __builtin_amdgcn_global_load_lds((const unsigned*)((const char*)(gbase) + (voff)[_i]), (LAS unsigned*)(lds + (bufoff) + ldsw + _i * 8192), 16, 0, 0); } while (0)
; #define PG8_LDA(dst, b, h) do { _Pragma("unroll") for (int m = 0; m < 4; ++m) _Pragma("unroll") for (int k = 0; k < 2; ++k) dst[m][k] = *(const LAS bf16x8*)(lds + PG8_SA(b, h) + aoff + m * 2048 + k * 1024); } while (0)
; #define PG8_LDB(dst, b, h) do { _Pragma("unroll") for (int n = 0; n < 2; ++n) _Pragma("unroll") for (int k = 0; k < 2; ++k) dst[n][k] = *(const LAS bf16x8*)(lds + PG8_SB(b, h) + boff + n * 2048 + k * 1024); } while (0)
; #define PG8_MMA(ai, bj, At, Bt) do { __builtin_amdgcn_s_setprio(1); _Pragma("unroll") for (int m = 0; m < 4; ++m) _Pragma("unroll") for (int n = 0; n < 2; ++n) _Pragma("unroll") for (int k = 0; k < 2; ++k) \
;         acc[ai][bj][m][n] = __builtin_amdgcn_mfma_f32_16x16x32_bf16(Bt[n][k], At[m][k], acc[ai][bj][m][n], 0, 0, 0); __builtin_amdgcn_s_setprio(0); } while (0)
; #define PG8_WAIT_L(n) asm volatile("s_waitcnt lgkmcnt(" #n ")" ::: "memory")
; #define PG8_BAR __builtin_amdgcn_s_barrier()
; #define PG8_SCHED __builtin_amdgcn_sched_barrier(0)
; template <class Epi>
; DI void gemm_phase(LAS unsigned char* lds, int wid, int K, int lda, int ldb, bool bperm, const Sched3& S, const Epi& E) {
;     ...
;             PG8_LDB(B0, 0, 0); PG8_SCHED; PG8_LDA(At, 0, 0); PG8_STAGE(PG8_SA(1, 1), a1 + hA, voffA);
;             PG8_WAIT_L(8); PG8_BAR; PG8_WAIT_L(0); PG8_MMA(0, 0, At, B0); PG8_BAR; PG8_SCHED;
	s_add_i32 m0, s50, 0xe000
	s_nop 0
	global_load_lds_dwordx4 v182, s[38:39]
	s_waitcnt lgkmcnt(8)
	s_barrier
	s_waitcnt lgkmcnt(0)
	s_setprio 1
	s_waitcnt lgkmcnt(0)
	v_mfma_f32_16x16x32_bf16 v[124:127], v[128:131], v[144:147], 0
	v_mfma_f32_16x16x32_bf16 v[120:123], v[136:139], v[144:147], 0
	v_mfma_f32_16x16x32_bf16 v[108:111], v[128:131], v[152:155], 0
	v_mfma_f32_16x16x32_bf16 v[104:107], v[136:139], v[152:155], 0
	v_mfma_f32_16x16x32_bf16 v[92:95], v[128:131], v[160:163], 0
	v_mfma_f32_16x16x32_bf16 v[88:91], v[136:139], v[160:163], 0
	v_mfma_f32_16x16x32_bf16 v[76:79], v[128:131], v[168:171], 0
	v_mfma_f32_16x16x32_bf16 v[72:75], v[136:139], v[168:171], 0
	v_mfma_f32_16x16x32_bf16 v[124:127], v[132:135], v[148:151], v[124:127]
	v_mfma_f32_16x16x32_bf16 v[120:123], v[140:143], v[148:151], v[120:123]
	v_mfma_f32_16x16x32_bf16 v[108:111], v[132:135], v[156:159], v[108:111]
	v_mfma_f32_16x16x32_bf16 v[104:107], v[140:143], v[156:159], v[104:107]
	v_mfma_f32_16x16x32_bf16 v[92:95], v[132:135], v[164:167], v[92:95]
	v_mfma_f32_16x16x32_bf16 v[88:91], v[140:143], v[164:167], v[88:91]
	v_mfma_f32_16x16x32_bf16 v[76:79], v[132:135], v[172:175], v[76:79]
	v_mfma_f32_16x16x32_bf16 v[72:75], v[140:143], v[172:175], v[72:75]
	s_setprio 0
	s_barrier
	s_add_i32 s63, s59, s49

; #define PG8_STAGE(bufoff, gbase, voff) do { _Pragma("unroll") for (int _i = 0; _i < 2; ++_i) \
;         __builtin_amdgcn_global_load_lds((const unsigned*)((const char*)(gbase) + (voff)[_i]), (LAS unsigned*)(lds + (bufoff) + ldsw + _i * 8192), 16, 0, 0); } while (0)
; #define PG8_LDB(dst, b, h) do { _Pragma("unroll") for (int n = 0; n < 2; ++n) _Pragma("unroll") for (int k = 0; k < 2; ++k) dst[n][k] = *(const LAS bf16x8*)(lds + PG8_SB(b, h) + boff + n * 2048 + k * 1024); } while (0)
; template <class Epi>
; DI void gemm_phase(LAS unsigned char* lds, int wid, int K, int lda, int ldb, bool bperm, const Sched3& S, const Epi& E) {
;     ...
;             PG8_LDB(B1, 0, 1); PG8_STAGE(PG8_SB(0, 0), b2, voffB);
	s_mov_b32 m0, s63
	ds_read_b128 v[186:189], v205
	ds_read_b128 v[190:193], v205 offset:1024
	ds_read_b128 v[194:197], v205 offset:2048
	ds_read_b128 v[206:209], v205 offset:3072
	global_load_lds_dwordx4 v176, s[40:41]

; #define PG8_STAGE(bufoff, gbase, voff) do { _Pragma("unroll") for (int _i = 0; _i < 2; ++_i) \
;         __builtin_amdgcn_global_load_lds((const unsigned*)((const char*)(gbase) + (voff)[_i]), (LAS unsigned*)(lds + (bufoff) + ldsw + _i * 8192), 16, 0, 0); } while (0)
; #define PG8_LDA(dst, b, h) do { _Pragma("unroll") for (int m = 0; m < 4; ++m) _Pragma("unroll") for (int k = 0; k < 2; ++k) dst[m][k] = *(const LAS bf16x8*)(lds + PG8_SA(b, h) + aoff + m * 2048 + k * 1024); } while (0)
; #define PG8_LDB(dst, b, h) do { _Pragma("unroll") for (int n = 0; n < 2; ++n) _Pragma("unroll") for (int k = 0; k < 2; ++k) dst[n][k] = *(const LAS bf16x8*)(lds + PG8_SB(b, h) + boff + n * 2048 + k * 1024); } while (0)
; #define PG8_MMA(ai, bj, At, Bt) do { __builtin_amdgcn_s_setprio(1); _Pragma("unroll") for (int m = 0; m < 4; ++m) _Pragma("unroll") for (int n = 0; n < 2; ++n) _Pragma("unroll") for (int k = 0; k < 2; ++k) \
;         acc[ai][bj][m][n] = __builtin_amdgcn_mfma_f32_16x16x32_bf16(Bt[n][k], At[m][k], acc[ai][bj][m][n], 0, 0, 0); __builtin_amdgcn_s_setprio(0); } while (0)
; #define PG8_WAIT_L(n) asm volatile("s_waitcnt lgkmcnt(" #n ")" ::: "memory")
; #define PG8_BAR __builtin_amdgcn_s_barrier()
; #define PG8_SCHED __builtin_amdgcn_sched_barrier(0)
; template <class Epi>
; DI void gemm_phase(LAS unsigned char* lds, int wid, int K, int lda, int ldb, bool bperm, const Sched3& S, const Epi& E) {
;     ...
;             PG8_LDB(B1, 0, 1); PG8_STAGE(PG8_SB(0, 0), b2, voffB);
;             PG8_BAR; PG8_WAIT_L(0); PG8_MMA(0, 1, At, B1); PG8_BAR;
;             PG8_LDA(At, 0, 1); PG8_STAGE(PG8_SA(0, 0), a2, voffA);
;             PG8_BAR; PG8_WAIT_L(0); if (full) PG8_MMA(1, 0, At, B0); PG8_BAR; PG8_SCHED;
;             PG8_STAGE(PG8_SB(0, 1), b2 + hstepB, voffB);
	s_add_i32 m0, s63, 0x2000
	s_nop 0
	global_load_lds_dwordx4 v178, s[40:41]
	s_barrier
	s_waitcnt lgkmcnt(0)
	s_setprio 1
	s_waitcnt lgkmcnt(0)
	v_mfma_f32_16x16x32_bf16 v[116:119], v[186:189], v[144:147], 0
	v_mfma_f32_16x16x32_bf16 v[112:115], v[194:197], v[144:147], 0
	v_mfma_f32_16x16x32_bf16 v[100:103], v[186:189], v[152:155], 0
	v_mfma_f32_16x16x32_bf16 v[96:99], v[194:197], v[152:155], 0
	v_mfma_f32_16x16x32_bf16 v[84:87], v[186:189], v[160:163], 0
	v_mfma_f32_16x16x32_bf16 v[80:83], v[194:197], v[160:163], 0
	v_mfma_f32_16x16x32_bf16 v[68:71], v[186:189], v[168:171], 0
	v_mfma_f32_16x16x32_bf16 v[64:67], v[194:197], v[168:171], 0
	v_mfma_f32_16x16x32_bf16 v[116:119], v[190:193], v[148:151], v[116:119]
	v_mfma_f32_16x16x32_bf16 v[112:115], v[206:209], v[148:151], v[112:115]
	v_mfma_f32_16x16x32_bf16 v[100:103], v[190:193], v[156:159], v[100:103]
	v_mfma_f32_16x16x32_bf16 v[96:99], v[206:209], v[156:159], v[96:99]
	v_mfma_f32_16x16x32_bf16 v[84:87], v[190:193], v[164:167], v[84:87]
	v_mfma_f32_16x16x32_bf16 v[80:83], v[206:209], v[164:167], v[80:83]
	v_mfma_f32_16x16x32_bf16 v[68:71], v[190:193], v[172:175], v[68:71]
	v_mfma_f32_16x16x32_bf16 v[64:67], v[206:209], v[172:175], v[64:67]
	s_setprio 0
	s_mov_b32 m0, s50
	s_mov_b64 s[100:101], s[42:43]
	s_barrier
	ds_read_b128 v[144:147], v204 offset:16384
	ds_read_b128 v[148:151], v204 offset:17408
	ds_read_b128 v[152:155], v204 offset:18432
	ds_read_b128 v[156:159], v204 offset:19456
	ds_read_b128 v[160:163], v204 offset:20480
	ds_read_b128 v[164:167], v204 offset:21504
	ds_read_b128 v[168:171], v204 offset:22528
	ds_read_b128 v[172:175], v204 offset:23552
	global_load_lds_dwordx4 v176, s[42:43]
	s_mov_b64 s[100:101], s[42:43]
	s_mov_b32 m0, s51
	s_nop 0
	global_load_lds_dwordx4 v178, s[42:43]
	s_barrier
	s_waitcnt lgkmcnt(0)
	s_setprio 1
	s_waitcnt lgkmcnt(0)
	v_mfma_f32_16x16x32_bf16 v[60:63], v[128:131], v[144:147], 0
	v_mfma_f32_16x16x32_bf16 v[56:59], v[136:139], v[144:147], 0
	v_mfma_f32_16x16x32_bf16 v[44:47], v[128:131], v[152:155], 0
	v_mfma_f32_16x16x32_bf16 v[40:43], v[136:139], v[152:155], 0
	v_mfma_f32_16x16x32_bf16 v[28:31], v[128:131], v[160:163], 0
	v_mfma_f32_16x16x32_bf16 v[24:27], v[136:139], v[160:163], 0
	v_mfma_f32_16x16x32_bf16 v[12:15], v[128:131], v[168:171], 0
	v_mfma_f32_16x16x32_bf16 v[8:11], v[136:139], v[168:171], 0
	v_mfma_f32_16x16x32_bf16 v[60:63], v[132:135], v[148:151], v[60:63]
	v_mfma_f32_16x16x32_bf16 v[56:59], v[140:143], v[148:151], v[56:59]
	v_mfma_f32_16x16x32_bf16 v[44:47], v[132:135], v[156:159], v[44:47]
	v_mfma_f32_16x16x32_bf16 v[40:43], v[140:143], v[156:159], v[40:43]
	v_mfma_f32_16x16x32_bf16 v[28:31], v[132:135], v[164:167], v[28:31]
	v_mfma_f32_16x16x32_bf16 v[24:27], v[140:143], v[164:167], v[24:27]
	v_mfma_f32_16x16x32_bf16 v[12:15], v[132:135], v[172:175], v[12:15]
	v_mfma_f32_16x16x32_bf16 v[8:11], v[140:143], v[172:175], v[8:11]
	s_setprio 0
	s_barrier
	s_add_u32 s64, s40, 0x80000
	s_addc_u32 s65, s41, 0
	s_add_i32 s63, s60, s49

; #define PG8_STAGE(bufoff, gbase, voff) do { _Pragma("unroll") for (int _i = 0; _i < 2; ++_i) \
;         __builtin_amdgcn_global_load_lds((const unsigned*)((const char*)(gbase) + (voff)[_i]), (LAS unsigned*)(lds + (bufoff) + ldsw + _i * 8192), 16, 0, 0); } while (0)
; template <class Epi>
; DI void gemm_phase(LAS unsigned char* lds, int wid, int K, int lda, int ldb, bool bperm, const Sched3& S, const Epi& E) {
;     ...
;             PG8_STAGE(PG8_SB(0, 1), b2 + hstepB, voffB);
	s_mov_b32 m0, s63
	s_nop 0
	global_load_lds_dwordx4 v176, s[64:65]

; #define PG8_STAGE(bufoff, gbase, voff) do { _Pragma("unroll") for (int _i = 0; _i < 2; ++_i) \
;         __builtin_amdgcn_global_load_lds((const unsigned*)((const char*)(gbase) + (voff)[_i]), (LAS unsigned*)(lds + (bufoff) + ldsw + _i * 8192), 16, 0, 0); } while (0)
; #define PG8_LDA(dst, b, h) do { _Pragma("unroll") for (int m = 0; m < 4; ++m) _Pragma("unroll") for (int k = 0; k < 2; ++k) dst[m][k] = *(const LAS bf16x8*)(lds + PG8_SA(b, h) + aoff + m * 2048 + k * 1024); } while (0)
; #define PG8_LDB(dst, b, h) do { _Pragma("unroll") for (int n = 0; n < 2; ++n) _Pragma("unroll") for (int k = 0; k < 2; ++k) dst[n][k] = *(const LAS bf16x8*)(lds + PG8_SB(b, h) + boff + n * 2048 + k * 1024); } while (0)
; #define PG8_MMA(ai, bj, At, Bt) do { __builtin_amdgcn_s_setprio(1); _Pragma("unroll") for (int m = 0; m < 4; ++m) _Pragma("unroll") for (int n = 0; n < 2; ++n) _Pragma("unroll") for (int k = 0; k < 2; ++k) \
;         acc[ai][bj][m][n] = __builtin_amdgcn_mfma_f32_16x16x32_bf16(Bt[n][k], At[m][k], acc[ai][bj][m][n], 0, 0, 0); __builtin_amdgcn_s_setprio(0); } while (0)
; #define PG8_WAIT_V(n) asm volatile("s_waitcnt vmcnt(" #n ")" ::: "memory")
; #define PG8_BAR __builtin_amdgcn_s_barrier()
; #define PG8_SCHED __builtin_amdgcn_sched_barrier(0)
; template <class Epi>
; DI void gemm_phase(LAS unsigned char* lds, int wid, int K, int lda, int ldb, bool bperm, const Sched3& S, const Epi& E) {
;     ...
;             PG8_WAIT_V(6); PG8_BAR; if (full) PG8_MMA(1, 1, At, B1); PG8_BAR;
;             PG8_LDB(B0, 1, 0); PG8_SCHED; PG8_LDA(At, 1, 0); PG8_STAGE(PG8_SA(0, 1), a2 + h2, voffA);
	s_add_i32 m0, s63, 0x2000
	s_nop 0
	global_load_lds_dwordx4 v178, s[64:65]
	s_waitcnt vmcnt(6)
	s_barrier
	s_setprio 1
	v_mfma_f32_16x16x32_bf16 v[52:55], v[186:189], v[144:147], 0
	v_mfma_f32_16x16x32_bf16 v[48:51], v[194:197], v[144:147], 0
	v_mfma_f32_16x16x32_bf16 v[36:39], v[186:189], v[152:155], 0
	v_mfma_f32_16x16x32_bf16 v[32:35], v[194:197], v[152:155], 0
	v_mfma_f32_16x16x32_bf16 v[20:23], v[186:189], v[160:163], 0
	v_mfma_f32_16x16x32_bf16 v[16:19], v[194:197], v[160:163], 0
	v_mfma_f32_16x16x32_bf16 v[4:7], v[186:189], v[168:171], 0
	v_mfma_f32_16x16x32_bf16 v[0:3], v[194:197], v[168:171], 0
	v_mfma_f32_16x16x32_bf16 v[52:55], v[190:193], v[148:151], v[52:55]
	v_mfma_f32_16x16x32_bf16 v[48:51], v[206:209], v[148:151], v[48:51]
	v_mfma_f32_16x16x32_bf16 v[36:39], v[190:193], v[156:159], v[36:39]
	v_mfma_f32_16x16x32_bf16 v[32:35], v[206:209], v[156:159], v[32:35]
	v_mfma_f32_16x16x32_bf16 v[20:23], v[190:193], v[164:167], v[20:23]
	v_mfma_f32_16x16x32_bf16 v[16:19], v[206:209], v[164:167], v[16:19]
	v_mfma_f32_16x16x32_bf16 v[4:7], v[190:193], v[172:175], v[4:7]
	v_mfma_f32_16x16x32_bf16 v[0:3], v[206:209], v[172:175], v[0:3]
	s_setprio 0
	s_add_i32 s63, 0, 0x18000
	v_add_u32_e32 v140, s63, v199
	s_barrier
	ds_read_b128 v[128:131], v140
	ds_read_b128 v[132:135], v140 offset:1024
	ds_read_b128 v[136:139], v140 offset:2048
	ds_read_b128 v[140:143], v140 offset:3072
	s_add_u32 s42, s42, 0x80000
	s_addc_u32 s43, s43, 0
	s_mov_b32 m0, s52

; #define PG8_STAGE(bufoff, gbase, voff) do { _Pragma("unroll") for (int _i = 0; _i < 2; ++_i) \
;         __builtin_amdgcn_global_load_lds((const unsigned*)((const char*)(gbase) + (voff)[_i]), (LAS unsigned*)(lds + (bufoff) + ldsw + _i * 8192), 16, 0, 0); } while (0)
; #define PG8_LDA(dst, b, h) do { _Pragma("unroll") for (int m = 0; m < 4; ++m) _Pragma("unroll") for (int k = 0; k < 2; ++k) dst[m][k] = *(const LAS bf16x8*)(lds + PG8_SA(b, h) + aoff + m * 2048 + k * 1024); } while (0)
; #define PG8_LDB(dst, b, h) do { _Pragma("unroll") for (int n = 0; n < 2; ++n) _Pragma("unroll") for (int k = 0; k < 2; ++k) dst[n][k] = *(const LAS bf16x8*)(lds + PG8_SB(b, h) + boff + n * 2048 + k * 1024); } while (0)
; #define PG8_SCHED __builtin_amdgcn_sched_barrier(0)
; template <class Epi>
; DI void gemm_phase(LAS unsigned char* lds, int wid, int K, int lda, int ldb, bool bperm, const Sched3& S, const Epi& E) {
;     ...
;             PG8_LDB(B0, 1, 0); PG8_SCHED; PG8_LDA(At, 1, 0); PG8_STAGE(PG8_SA(0, 1), a2 + h2, voffA);
	ds_read_b128 v[144:147], v204 offset:32768
	ds_read_b128 v[148:151], v204 offset:33792
	ds_read_b128 v[152:155], v204 offset:34816
	ds_read_b128 v[156:159], v204 offset:35840
	ds_read_b128 v[160:163], v204 offset:36864
	ds_read_b128 v[164:167], v204 offset:37888
	ds_read_b128 v[168:171], v204 offset:38912
	ds_read_b128 v[172:175], v204 offset:39936
	global_load_lds_dwordx4 v176, s[42:43]

; #define PG8_STAGE(bufoff, gbase, voff) do { _Pragma("unroll") for (int _i = 0; _i < 2; ++_i) \
;         __builtin_amdgcn_global_load_lds((const unsigned*)((const char*)(gbase) + (voff)[_i]), (LAS unsigned*)(lds + (bufoff) + ldsw + _i * 8192), 16, 0, 0); } while (0)
; #define PG8_LDB(dst, b, h) do { _Pragma("unroll") for (int n = 0; n < 2; ++n) _Pragma("unroll") for (int k = 0; k < 2; ++k) dst[n][k] = *(const LAS bf16x8*)(lds + PG8_SB(b, h) + boff + n * 2048 + k * 1024); } while (0)
; #define PG8_MMA(ai, bj, At, Bt) do { __builtin_amdgcn_s_setprio(1); _Pragma("unroll") for (int m = 0; m < 4; ++m) _Pragma("unroll") for (int n = 0; n < 2; ++n) _Pragma("unroll") for (int k = 0; k < 2; ++k) \
;         acc[ai][bj][m][n] = __builtin_amdgcn_mfma_f32_16x16x32_bf16(Bt[n][k], At[m][k], acc[ai][bj][m][n], 0, 0, 0); __builtin_amdgcn_s_setprio(0); } while (0)
; #define PG8_WAIT_L(n) asm volatile("s_waitcnt lgkmcnt(" #n ")" ::: "memory")
; #define PG8_BAR __builtin_amdgcn_s_barrier()
; #define PG8_SCHED __builtin_amdgcn_sched_barrier(0)
; template <class Epi>
; DI void gemm_phase(LAS unsigned char* lds, int wid, int K, int lda, int ldb, bool bperm, const Sched3& S, const Epi& E) {
;     ...
;             PG8_WAIT_L(8); PG8_BAR; PG8_WAIT_L(0); PG8_MMA(0, 0, At, B0); PG8_BAR; PG8_SCHED;
;             PG8_LDB(B1, 1, 1); PG8_STAGE(PG8_SB(1, 0), b3, voffB);
	s_mov_b32 m0, s53
	s_nop 0
	global_load_lds_dwordx4 v178, s[42:43]
	s_waitcnt lgkmcnt(8)
	s_barrier
	s_waitcnt lgkmcnt(0)
	s_setprio 1
	s_waitcnt lgkmcnt(0)
	v_mfma_f32_16x16x32_bf16 v[124:127], v[128:131], v[144:147], v[124:127]
	v_mfma_f32_16x16x32_bf16 v[120:123], v[136:139], v[144:147], v[120:123]
	v_mfma_f32_16x16x32_bf16 v[108:111], v[128:131], v[152:155], v[108:111]
	v_mfma_f32_16x16x32_bf16 v[104:107], v[136:139], v[152:155], v[104:107]
	v_mfma_f32_16x16x32_bf16 v[92:95], v[128:131], v[160:163], v[92:95]
	v_mfma_f32_16x16x32_bf16 v[88:91], v[136:139], v[160:163], v[88:91]
	v_mfma_f32_16x16x32_bf16 v[76:79], v[128:131], v[168:171], v[76:79]
	v_mfma_f32_16x16x32_bf16 v[72:75], v[136:139], v[168:171], v[72:75]
	v_mfma_f32_16x16x32_bf16 v[124:127], v[132:135], v[148:151], v[124:127]
	v_mfma_f32_16x16x32_bf16 v[120:123], v[140:143], v[148:151], v[120:123]
	v_mfma_f32_16x16x32_bf16 v[108:111], v[132:135], v[156:159], v[108:111]
	v_mfma_f32_16x16x32_bf16 v[104:107], v[140:143], v[156:159], v[104:107]
	v_mfma_f32_16x16x32_bf16 v[92:95], v[132:135], v[164:167], v[92:95]
	v_mfma_f32_16x16x32_bf16 v[88:91], v[140:143], v[164:167], v[88:91]
	v_mfma_f32_16x16x32_bf16 v[76:79], v[132:135], v[172:175], v[76:79]
	v_mfma_f32_16x16x32_bf16 v[72:75], v[140:143], v[172:175], v[72:75]
	s_setprio 0
	s_barrier
	s_add_i32 s42, 0, 0x1c000
	s_add_i32 s43, s63, s49
	v_add_u32_e32 v206, s42, v199

; #define PG8_STAGE(bufoff, gbase, voff) do { _Pragma("unroll") for (int _i = 0; _i < 2; ++_i) \
;         __builtin_amdgcn_global_load_lds((const unsigned*)((const char*)(gbase) + (voff)[_i]), (LAS unsigned*)(lds + (bufoff) + ldsw + _i * 8192), 16, 0, 0); } while (0)
; #define PG8_LDB(dst, b, h) do { _Pragma("unroll") for (int n = 0; n < 2; ++n) _Pragma("unroll") for (int k = 0; k < 2; ++k) dst[n][k] = *(const LAS bf16x8*)(lds + PG8_SB(b, h) + boff + n * 2048 + k * 1024); } while (0)
; template <class Epi>
; DI void gemm_phase(LAS unsigned char* lds, int wid, int K, int lda, int ldb, bool bperm, const Sched3& S, const Epi& E) {
;     ...
;             PG8_LDB(B1, 1, 1); PG8_STAGE(PG8_SB(1, 0), b3, voffB);
	s_sub_i32 m0, s43, 0x80
	ds_read_b128 v[186:189], v206
	ds_read_b128 v[190:193], v206 offset:1024
	ds_read_b128 v[194:197], v206 offset:2048
	ds_read_b128 v[206:209], v206 offset:3072
	global_load_lds_dwordx4 v176, s[40:41] offset:128

; #define PG8_STAGE(bufoff, gbase, voff) do { _Pragma("unroll") for (int _i = 0; _i < 2; ++_i) \
;         __builtin_amdgcn_global_load_lds((const unsigned*)((const char*)(gbase) + (voff)[_i]), (LAS unsigned*)(lds + (bufoff) + ldsw + _i * 8192), 16, 0, 0); } while (0)
; #define PG8_LDA(dst, b, h) do { _Pragma("unroll") for (int m = 0; m < 4; ++m) _Pragma("unroll") for (int k = 0; k < 2; ++k) dst[m][k] = *(const LAS bf16x8*)(lds + PG8_SA(b, h) + aoff + m * 2048 + k * 1024); } while (0)
; #define PG8_LDB(dst, b, h) do { _Pragma("unroll") for (int n = 0; n < 2; ++n) _Pragma("unroll") for (int k = 0; k < 2; ++k) dst[n][k] = *(const LAS bf16x8*)(lds + PG8_SB(b, h) + boff + n * 2048 + k * 1024); } while (0)
; #define PG8_MMA(ai, bj, At, Bt) do { __builtin_amdgcn_s_setprio(1); _Pragma("unroll") for (int m = 0; m < 4; ++m) _Pragma("unroll") for (int n = 0; n < 2; ++n) _Pragma("unroll") for (int k = 0; k < 2; ++k) \
;         acc[ai][bj][m][n] = __builtin_amdgcn_mfma_f32_16x16x32_bf16(Bt[n][k], At[m][k], acc[ai][bj][m][n], 0, 0, 0); __builtin_amdgcn_s_setprio(0); } while (0)
; #define PG8_WAIT_L(n) asm volatile("s_waitcnt lgkmcnt(" #n ")" ::: "memory")
; #define PG8_BAR __builtin_amdgcn_s_barrier()
; template <class Epi>
; DI void gemm_phase(LAS unsigned char* lds, int wid, int K, int lda, int ldb, bool bperm, const Sched3& S, const Epi& E) {
;     ...
;             PG8_LDB(B1, 1, 1); PG8_STAGE(PG8_SB(1, 0), b3, voffB);
;             PG8_BAR; PG8_WAIT_L(0); PG8_MMA(0, 1, At, B1); PG8_BAR;
;             PG8_LDA(At, 1, 1); PG8_STAGE(PG8_SA(1, 0), a3, voffA);
	s_add_i32 m0, s43, 0x1f80
	s_nop 0
	global_load_lds_dwordx4 v178, s[40:41] offset:128
	s_barrier
	s_waitcnt lgkmcnt(0)
	s_setprio 1
	s_waitcnt lgkmcnt(0)
	v_mfma_f32_16x16x32_bf16 v[116:119], v[186:189], v[144:147], v[116:119]
	v_mfma_f32_16x16x32_bf16 v[112:115], v[194:197], v[144:147], v[112:115]
	v_mfma_f32_16x16x32_bf16 v[100:103], v[186:189], v[152:155], v[100:103]
	v_mfma_f32_16x16x32_bf16 v[96:99], v[194:197], v[152:155], v[96:99]
	v_mfma_f32_16x16x32_bf16 v[84:87], v[186:189], v[160:163], v[84:87]
	v_mfma_f32_16x16x32_bf16 v[80:83], v[194:197], v[160:163], v[80:83]
	v_mfma_f32_16x16x32_bf16 v[68:71], v[186:189], v[168:171], v[68:71]
	v_mfma_f32_16x16x32_bf16 v[64:67], v[194:197], v[168:171], v[64:67]
	v_mfma_f32_16x16x32_bf16 v[116:119], v[190:193], v[148:151], v[116:119]
	v_mfma_f32_16x16x32_bf16 v[112:115], v[206:209], v[148:151], v[112:115]
	v_mfma_f32_16x16x32_bf16 v[100:103], v[190:193], v[156:159], v[100:103]
	v_mfma_f32_16x16x32_bf16 v[96:99], v[206:209], v[156:159], v[96:99]
	v_mfma_f32_16x16x32_bf16 v[84:87], v[190:193], v[164:167], v[84:87]
	v_mfma_f32_16x16x32_bf16 v[80:83], v[206:209], v[164:167], v[80:83]
	v_mfma_f32_16x16x32_bf16 v[68:71], v[190:193], v[172:175], v[68:71]
	v_mfma_f32_16x16x32_bf16 v[64:67], v[206:209], v[172:175], v[64:67]
	s_setprio 0
	s_sub_i32 m0, s55, 0x80

; #define PG8_STAGE(bufoff, gbase, voff) do { _Pragma("unroll") for (int _i = 0; _i < 2; ++_i) \
;         __builtin_amdgcn_global_load_lds((const unsigned*)((const char*)(gbase) + (voff)[_i]), (LAS unsigned*)(lds + (bufoff) + ldsw + _i * 8192), 16, 0, 0); } while (0)
; #define PG8_LDA(dst, b, h) do { _Pragma("unroll") for (int m = 0; m < 4; ++m) _Pragma("unroll") for (int k = 0; k < 2; ++k) dst[m][k] = *(const LAS bf16x8*)(lds + PG8_SA(b, h) + aoff + m * 2048 + k * 1024); } while (0)
; template <class Epi>
; DI void gemm_phase(LAS unsigned char* lds, int wid, int K, int lda, int ldb, bool bperm, const Sched3& S, const Epi& E) {
;     ...
;             PG8_LDA(At, 1, 1); PG8_STAGE(PG8_SA(1, 0), a3, voffA);
	s_barrier
	ds_read_b128 v[144:147], v204 offset:49152
	ds_read_b128 v[148:151], v204 offset:50176
	ds_read_b128 v[152:155], v204 offset:51200
	ds_read_b128 v[156:159], v204 offset:52224
	ds_read_b128 v[160:163], v204 offset:53248
	ds_read_b128 v[164:167], v204 offset:54272
	ds_read_b128 v[168:171], v204 offset:55296
	ds_read_b128 v[172:175], v204 offset:56320
	global_load_lds_dwordx4 v176, s[100:101] offset:128

; #define PG8_STAGE(bufoff, gbase, voff) do { _Pragma("unroll") for (int _i = 0; _i < 2; ++_i) \
;         __builtin_amdgcn_global_load_lds((const unsigned*)((const char*)(gbase) + (voff)[_i]), (LAS unsigned*)(lds + (bufoff) + ldsw + _i * 8192), 16, 0, 0); } while (0)
; #define PG8_LDA(dst, b, h) do { _Pragma("unroll") for (int m = 0; m < 4; ++m) _Pragma("unroll") for (int k = 0; k < 2; ++k) dst[m][k] = *(const LAS bf16x8*)(lds + PG8_SA(b, h) + aoff + m * 2048 + k * 1024); } while (0)
; #define PG8_MMA(ai, bj, At, Bt) do { __builtin_amdgcn_s_setprio(1); _Pragma("unroll") for (int m = 0; m < 4; ++m) _Pragma("unroll") for (int n = 0; n < 2; ++n) _Pragma("unroll") for (int k = 0; k < 2; ++k) \
;         acc[ai][bj][m][n] = __builtin_amdgcn_mfma_f32_16x16x32_bf16(Bt[n][k], At[m][k], acc[ai][bj][m][n], 0, 0, 0); __builtin_amdgcn_s_setprio(0); } while (0)
; #define PG8_WAIT_L(n) asm volatile("s_waitcnt lgkmcnt(" #n ")" ::: "memory")
; #define PG8_BAR __builtin_amdgcn_s_barrier()
; #define PG8_SCHED __builtin_amdgcn_sched_barrier(0)
; template <class Epi>
; DI void gemm_phase(LAS unsigned char* lds, int wid, int K, int lda, int ldb, bool bperm, const Sched3& S, const Epi& E) {
;     ...
;             PG8_LDA(At, 1, 1); PG8_STAGE(PG8_SA(1, 0), a3, voffA);
;             PG8_BAR; PG8_WAIT_L(0); if (full) PG8_MMA(1, 0, At, B0); PG8_BAR; PG8_SCHED;
;             PG8_STAGE(PG8_SB(1, 1), b3 + hstepB, voffB);
	s_sub_i32 m0, s56, 0x80
	s_nop 0
	global_load_lds_dwordx4 v178, s[100:101] offset:128
	s_barrier
	s_waitcnt lgkmcnt(0)
	s_setprio 1
	s_waitcnt lgkmcnt(0)
	v_mfma_f32_16x16x32_bf16 v[60:63], v[128:131], v[144:147], v[60:63]
	v_mfma_f32_16x16x32_bf16 v[56:59], v[136:139], v[144:147], v[56:59]
	v_mfma_f32_16x16x32_bf16 v[44:47], v[128:131], v[152:155], v[44:47]
	v_mfma_f32_16x16x32_bf16 v[40:43], v[136:139], v[152:155], v[40:43]
	v_mfma_f32_16x16x32_bf16 v[28:31], v[128:131], v[160:163], v[28:31]
	v_mfma_f32_16x16x32_bf16 v[24:27], v[136:139], v[160:163], v[24:27]
	v_mfma_f32_16x16x32_bf16 v[12:15], v[128:131], v[168:171], v[12:15]
	v_mfma_f32_16x16x32_bf16 v[8:11], v[136:139], v[168:171], v[8:11]
	v_mfma_f32_16x16x32_bf16 v[60:63], v[132:135], v[148:151], v[60:63]
	v_mfma_f32_16x16x32_bf16 v[56:59], v[140:143], v[148:151], v[56:59]
	v_mfma_f32_16x16x32_bf16 v[44:47], v[132:135], v[156:159], v[44:47]
	v_mfma_f32_16x16x32_bf16 v[40:43], v[140:143], v[156:159], v[40:43]
	v_mfma_f32_16x16x32_bf16 v[28:31], v[132:135], v[164:167], v[28:31]
	v_mfma_f32_16x16x32_bf16 v[24:27], v[140:143], v[164:167], v[24:27]
	v_mfma_f32_16x16x32_bf16 v[12:15], v[132:135], v[172:175], v[12:15]
	v_mfma_f32_16x16x32_bf16 v[8:11], v[140:143], v[172:175], v[8:11]
	s_setprio 0
	s_barrier
	s_add_u32 s40, s40, 0x80080
	s_addc_u32 s41, s41, 0
	s_add_i32 s42, s42, s49

; #define PG8_STAGE(bufoff, gbase, voff) do { _Pragma("unroll") for (int _i = 0; _i < 2; ++_i) \
;         __builtin_amdgcn_global_load_lds((const unsigned*)((const char*)(gbase) + (voff)[_i]), (LAS unsigned*)(lds + (bufoff) + ldsw + _i * 8192), 16, 0, 0); } while (0)
; template <class Epi>
; DI void gemm_phase(LAS unsigned char* lds, int wid, int K, int lda, int ldb, bool bperm, const Sched3& S, const Epi& E) {
;     ...
;             PG8_STAGE(PG8_SB(1, 1), b3 + hstepB, voffB);
	s_mov_b32 m0, s42
	s_nop 0
	global_load_lds_dwordx4 v176, s[40:41]

; #define PG8_STAGE(bufoff, gbase, voff) do { _Pragma("unroll") for (int _i = 0; _i < 2; ++_i) \
;         __builtin_amdgcn_global_load_lds((const unsigned*)((const char*)(gbase) + (voff)[_i]), (LAS unsigned*)(lds + (bufoff) + ldsw + _i * 8192), 16, 0, 0); } while (0)
; #define PG8_LDA(dst, b, h) do { _Pragma("unroll") for (int m = 0; m < 4; ++m) _Pragma("unroll") for (int k = 0; k < 2; ++k) dst[m][k] = *(const LAS bf16x8*)(lds + PG8_SA(b, h) + aoff + m * 2048 + k * 1024); } while (0)
; #define PG8_LDB(dst, b, h) do { _Pragma("unroll") for (int n = 0; n < 2; ++n) _Pragma("unroll") for (int k = 0; k < 2; ++k) dst[n][k] = *(const LAS bf16x8*)(lds + PG8_SB(b, h) + boff + n * 2048 + k * 1024); } while (0)
; #define PG8_MMA(ai, bj, At, Bt) do { __builtin_amdgcn_s_setprio(1); _Pragma("unroll") for (int m = 0; m < 4; ++m) _Pragma("unroll") for (int n = 0; n < 2; ++n) _Pragma("unroll") for (int k = 0; k < 2; ++k) \
;         acc[ai][bj][m][n] = __builtin_amdgcn_mfma_f32_16x16x32_bf16(Bt[n][k], At[m][k], acc[ai][bj][m][n], 0, 0, 0); __builtin_amdgcn_s_setprio(0); } while (0)
; #define PG8_WAIT_V(n) asm volatile("s_waitcnt vmcnt(" #n ")" ::: "memory")
; #define PG8_BAR __builtin_amdgcn_s_barrier()
; #define PG8_SCHED __builtin_amdgcn_sched_barrier(0)
; template <class Epi>
; DI void gemm_phase(LAS unsigned char* lds, int wid, int K, int lda, int ldb, bool bperm, const Sched3& S, const Epi& E) {
;     ...
;             const bool last = (t == nt - 2);
;             const char* a1 = cA + (size_t)(t + 1) * kstep;
;             const char* a2 = last ? nA : cA + (size_t)(t + 2) * kstep; const char* b2 = last ? nB : cB + (size_t)(t + 2) * kstep;
;             const char* a3 = a2 + kstep; const char* b3 = b2 + kstep; const size_t h2 = last ? nhA : hA;
;             PG8_LDB(B0, 0, 0); PG8_SCHED; PG8_LDA(At, 0, 0); PG8_STAGE(PG8_SA(1, 1), a1 + hA, voffA);
;     ...
;             PG8_STAGE(PG8_SB(1, 1), b3 + hstepB, voffB);
;             PG8_WAIT_V(6); PG8_BAR; if (full) PG8_MMA(1, 1, At, B1); PG8_BAR;
	s_add_i32 m0, s42, 0x2000
	s_nop 0
	global_load_lds_dwordx4 v178, s[40:41]
	s_waitcnt vmcnt(6)
	s_barrier
	s_setprio 1
	v_mfma_f32_16x16x32_bf16 v[52:55], v[186:189], v[144:147], v[52:55]
	v_mfma_f32_16x16x32_bf16 v[48:51], v[194:197], v[144:147], v[48:51]
	v_mfma_f32_16x16x32_bf16 v[36:39], v[186:189], v[152:155], v[36:39]
	v_mfma_f32_16x16x32_bf16 v[32:35], v[194:197], v[152:155], v[32:35]
	v_mfma_f32_16x16x32_bf16 v[20:23], v[186:189], v[160:163], v[20:23]
	v_mfma_f32_16x16x32_bf16 v[16:19], v[194:197], v[160:163], v[16:19]
	v_mfma_f32_16x16x32_bf16 v[4:7], v[186:189], v[168:171], v[4:7]
	v_mfma_f32_16x16x32_bf16 v[0:3], v[194:197], v[168:171], v[0:3]
	v_mfma_f32_16x16x32_bf16 v[52:55], v[190:193], v[148:151], v[52:55]
	v_mfma_f32_16x16x32_bf16 v[48:51], v[206:209], v[148:151], v[48:51]
	v_mfma_f32_16x16x32_bf16 v[36:39], v[190:193], v[156:159], v[36:39]
	v_mfma_f32_16x16x32_bf16 v[32:35], v[206:209], v[156:159], v[32:35]
	v_mfma_f32_16x16x32_bf16 v[20:23], v[190:193], v[164:167], v[20:23]
	v_mfma_f32_16x16x32_bf16 v[16:19], v[206:209], v[164:167], v[16:19]
	v_mfma_f32_16x16x32_bf16 v[4:7], v[190:193], v[172:175], v[4:7]
	v_mfma_f32_16x16x32_bf16 v[0:3], v[206:209], v[172:175], v[0:3]
	s_setprio 0
	s_add_i32 s29, s29, 2
	s_add_u32 s38, s38, 0x100
	s_addc_u32 s39, s39, 0
	s_add_u32 s21, s21, 0x100
	s_addc_u32 s23, s23, 0
	s_cmp_gt_u32 s29, 29
	s_barrier
	s_cbranch_scc0 .LBB0_621
	s_branch .Lpeel_1_exit
.LBB0_621:
	ds_read_b128 v[128:131], v203
	ds_read_b128 v[132:135], v203 offset:1024
	ds_read_b128 v[136:139], v203 offset:2048
	ds_read_b128 v[140:143], v203 offset:3072
	s_add_u32 s40, s38, 0xfff80080
	s_addc_u32 s41, s39, -1
	s_cmp_eq_u32 s29, 28
	s_cselect_b32 s43, s31, s41
	s_cselect_b32 s42, s30, s40
	s_cselect_b32 s41, s37, s23
	s_cselect_b32 s40, s36, s21

; #define PG8_STAGE(bufoff, gbase, voff) do { _Pragma("unroll") for (int _i = 0; _i < 2; ++_i) \
;         __builtin_amdgcn_global_load_lds((const unsigned*)((const char*)(gbase) + (voff)[_i]), (LAS unsigned*)(lds + (bufoff) + ldsw + _i * 8192), 16, 0, 0); } while (0)
; #define PG8_LDA(dst, b, h) do { _Pragma("unroll") for (int m = 0; m < 4; ++m) _Pragma("unroll") for (int k = 0; k < 2; ++k) dst[m][k] = *(const LAS bf16x8*)(lds + PG8_SA(b, h) + aoff + m * 2048 + k * 1024); } while (0)
; #define PG8_LDB(dst, b, h) do { _Pragma("unroll") for (int n = 0; n < 2; ++n) _Pragma("unroll") for (int k = 0; k < 2; ++k) dst[n][k] = *(const LAS bf16x8*)(lds + PG8_SB(b, h) + boff + n * 2048 + k * 1024); } while (0)
; #define PG8_SCHED __builtin_amdgcn_sched_barrier(0)
; template <class Epi>
; DI void gemm_phase(LAS unsigned char* lds, int wid, int K, int lda, int ldb, bool bperm, const Sched3& S, const Epi& E) {
;     ...
;             PG8_LDB(B0, 0, 0); PG8_SCHED; PG8_LDA(At, 0, 0); PG8_STAGE(PG8_SA(1, 1), a1 + hA, voffA);
	s_add_i32 m0, s50, 0xc000
	ds_read_b128 v[144:147], v204
	ds_read_b128 v[148:151], v204 offset:1024
	ds_read_b128 v[152:155], v204 offset:2048
	ds_read_b128 v[156:159], v204 offset:3072
	ds_read_b128 v[160:163], v204 offset:4096
	ds_read_b128 v[164:167], v204 offset:5120
	ds_read_b128 v[168:171], v204 offset:6144
	ds_read_b128 v[172:175], v204 offset:7168
	global_load_lds_dwordx4 v180, s[38:39]

; #define PG8_STAGE(bufoff, gbase, voff) do { _Pragma("unroll") for (int _i = 0; _i < 2; ++_i) \
;         __builtin_amdgcn_global_load_lds((const unsigned*)((const char*)(gbase) + (voff)[_i]), (LAS unsigned*)(lds + (bufoff) + ldsw + _i * 8192), 16, 0, 0); } while (0)
; #define PG8_LDA(dst, b, h) do { _Pragma("unroll") for (int m = 0; m < 4; ++m) _Pragma("unroll") for (int k = 0; k < 2; ++k) dst[m][k] = *(const LAS bf16x8*)(lds + PG8_SA(b, h) + aoff + m * 2048 + k * 1024); } while (0)
; #define PG8_LDB(dst, b, h) do { _Pragma("unroll") for (int n = 0; n < 2; ++n) _Pragma("unroll") for (int k = 0; k < 2; ++k) dst[n][k] = *(const LAS bf16x8*)(lds + PG8_SB(b, h) + boff + n * 2048 + k * 1024); } while (0)
; #define PG8_MMA(ai, bj, At, Bt) do { __builtin_amdgcn_s_setprio(1); _Pragma("unroll") for (int m = 0; m < 4; ++m) _Pragma("unroll") for (int n = 0; n < 2; ++n) _Pragma("unroll") for (int k = 0; k < 2; ++k) \
;         acc[ai][bj][m][n] = __builtin_amdgcn_mfma_f32_16x16x32_bf16(Bt[n][k], At[m][k], acc[ai][bj][m][n], 0, 0, 0); __builtin_amdgcn_s_setprio(0); } while (0)
; #define PG8_WAIT_L(n) asm volatile("s_waitcnt lgkmcnt(" #n ")" ::: "memory")
; #define PG8_BAR __builtin_amdgcn_s_barrier()
; #define PG8_SCHED __builtin_amdgcn_sched_barrier(0)
; template <class Epi>
; DI void gemm_phase(LAS unsigned char* lds, int wid, int K, int lda, int ldb, bool bperm, const Sched3& S, const Epi& E) {
;     ...
;             PG8_LDB(B0, 0, 0); PG8_SCHED; PG8_LDA(At, 0, 0); PG8_STAGE(PG8_SA(1, 1), a1 + hA, voffA);
;             PG8_WAIT_L(8); PG8_BAR; PG8_WAIT_L(0); PG8_MMA(0, 0, At, B0); PG8_BAR; PG8_SCHED;
	s_add_i32 m0, s50, 0xe000
	s_nop 0
	global_load_lds_dwordx4 v182, s[38:39]
	s_waitcnt lgkmcnt(8)
	s_barrier
	s_waitcnt lgkmcnt(0)
	s_setprio 1
	s_waitcnt lgkmcnt(0)
	v_mfma_f32_16x16x32_bf16 v[124:127], v[128:131], v[144:147], v[124:127]
	v_mfma_f32_16x16x32_bf16 v[120:123], v[136:139], v[144:147], v[120:123]
	v_mfma_f32_16x16x32_bf16 v[108:111], v[128:131], v[152:155], v[108:111]
	v_mfma_f32_16x16x32_bf16 v[104:107], v[136:139], v[152:155], v[104:107]
	v_mfma_f32_16x16x32_bf16 v[92:95], v[128:131], v[160:163], v[92:95]
	v_mfma_f32_16x16x32_bf16 v[88:91], v[136:139], v[160:163], v[88:91]
	v_mfma_f32_16x16x32_bf16 v[76:79], v[128:131], v[168:171], v[76:79]
	v_mfma_f32_16x16x32_bf16 v[72:75], v[136:139], v[168:171], v[72:75]
	v_mfma_f32_16x16x32_bf16 v[124:127], v[132:135], v[148:151], v[124:127]
	v_mfma_f32_16x16x32_bf16 v[120:123], v[140:143], v[148:151], v[120:123]
	v_mfma_f32_16x16x32_bf16 v[108:111], v[132:135], v[156:159], v[108:111]
	v_mfma_f32_16x16x32_bf16 v[104:107], v[140:143], v[156:159], v[104:107]
	v_mfma_f32_16x16x32_bf16 v[92:95], v[132:135], v[164:167], v[92:95]
	v_mfma_f32_16x16x32_bf16 v[88:91], v[140:143], v[164:167], v[88:91]
	v_mfma_f32_16x16x32_bf16 v[76:79], v[132:135], v[172:175], v[76:79]
	v_mfma_f32_16x16x32_bf16 v[72:75], v[140:143], v[172:175], v[72:75]
	s_setprio 0
	s_barrier
	s_add_i32 s63, s59, s49

; #define PG8_STAGE(bufoff, gbase, voff) do { _Pragma("unroll") for (int _i = 0; _i < 2; ++_i) \
;         __builtin_amdgcn_global_load_lds((const unsigned*)((const char*)(gbase) + (voff)[_i]), (LAS unsigned*)(lds + (bufoff) + ldsw + _i * 8192), 16, 0, 0); } while (0)
; #define PG8_LDB(dst, b, h) do { _Pragma("unroll") for (int n = 0; n < 2; ++n) _Pragma("unroll") for (int k = 0; k < 2; ++k) dst[n][k] = *(const LAS bf16x8*)(lds + PG8_SB(b, h) + boff + n * 2048 + k * 1024); } while (0)
; template <class Epi>
; DI void gemm_phase(LAS unsigned char* lds, int wid, int K, int lda, int ldb, bool bperm, const Sched3& S, const Epi& E) {
;     ...
;             PG8_LDB(B1, 0, 1); PG8_STAGE(PG8_SB(0, 0), b2, voffB);
	s_mov_b32 m0, s63
	ds_read_b128 v[186:189], v205
	ds_read_b128 v[190:193], v205 offset:1024
	ds_read_b128 v[194:197], v205 offset:2048
	ds_read_b128 v[206:209], v205 offset:3072
	global_load_lds_dwordx4 v176, s[40:41]

; #define PG8_STAGE(bufoff, gbase, voff) do { _Pragma("unroll") for (int _i = 0; _i < 2; ++_i) \
;         __builtin_amdgcn_global_load_lds((const unsigned*)((const char*)(gbase) + (voff)[_i]), (LAS unsigned*)(lds + (bufoff) + ldsw + _i * 8192), 16, 0, 0); } while (0)
; #define PG8_LDA(dst, b, h) do { _Pragma("unroll") for (int m = 0; m < 4; ++m) _Pragma("unroll") for (int k = 0; k < 2; ++k) dst[m][k] = *(const LAS bf16x8*)(lds + PG8_SA(b, h) + aoff + m * 2048 + k * 1024); } while (0)
; #define PG8_LDB(dst, b, h) do { _Pragma("unroll") for (int n = 0; n < 2; ++n) _Pragma("unroll") for (int k = 0; k < 2; ++k) dst[n][k] = *(const LAS bf16x8*)(lds + PG8_SB(b, h) + boff + n * 2048 + k * 1024); } while (0)
; #define PG8_MMA(ai, bj, At, Bt) do { __builtin_amdgcn_s_setprio(1); _Pragma("unroll") for (int m = 0; m < 4; ++m) _Pragma("unroll") for (int n = 0; n < 2; ++n) _Pragma("unroll") for (int k = 0; k < 2; ++k) \
;         acc[ai][bj][m][n] = __builtin_amdgcn_mfma_f32_16x16x32_bf16(Bt[n][k], At[m][k], acc[ai][bj][m][n], 0, 0, 0); __builtin_amdgcn_s_setprio(0); } while (0)
; #define PG8_WAIT_L(n) asm volatile("s_waitcnt lgkmcnt(" #n ")" ::: "memory")
; #define PG8_BAR __builtin_amdgcn_s_barrier()
; #define PG8_SCHED __builtin_amdgcn_sched_barrier(0)
; template <class Epi>
; DI void gemm_phase(LAS unsigned char* lds, int wid, int K, int lda, int ldb, bool bperm, const Sched3& S, const Epi& E) {
;     ...
;             PG8_LDB(B1, 0, 1); PG8_STAGE(PG8_SB(0, 0), b2, voffB);
;             PG8_BAR; PG8_WAIT_L(0); PG8_MMA(0, 1, At, B1); PG8_BAR;
;             PG8_LDA(At, 0, 1); PG8_STAGE(PG8_SA(0, 0), a2, voffA);
;             PG8_BAR; PG8_WAIT_L(0); if (full) PG8_MMA(1, 0, At, B0); PG8_BAR; PG8_SCHED;
	s_add_i32 m0, s63, 0x2000
	s_nop 0
	global_load_lds_dwordx4 v178, s[40:41]
	s_barrier
	s_waitcnt lgkmcnt(0)
	s_setprio 1
	s_waitcnt lgkmcnt(0)
	v_mfma_f32_16x16x32_bf16 v[116:119], v[186:189], v[144:147], v[116:119]
	v_mfma_f32_16x16x32_bf16 v[112:115], v[194:197], v[144:147], v[112:115]
	v_mfma_f32_16x16x32_bf16 v[100:103], v[186:189], v[152:155], v[100:103]
	v_mfma_f32_16x16x32_bf16 v[96:99], v[194:197], v[152:155], v[96:99]
	v_mfma_f32_16x16x32_bf16 v[84:87], v[186:189], v[160:163], v[84:87]
	v_mfma_f32_16x16x32_bf16 v[80:83], v[194:197], v[160:163], v[80:83]
	v_mfma_f32_16x16x32_bf16 v[68:71], v[186:189], v[168:171], v[68:71]
	v_mfma_f32_16x16x32_bf16 v[64:67], v[194:197], v[168:171], v[64:67]
	v_mfma_f32_16x16x32_bf16 v[116:119], v[190:193], v[148:151], v[116:119]
	v_mfma_f32_16x16x32_bf16 v[112:115], v[206:209], v[148:151], v[112:115]
	v_mfma_f32_16x16x32_bf16 v[100:103], v[190:193], v[156:159], v[100:103]
	v_mfma_f32_16x16x32_bf16 v[96:99], v[206:209], v[156:159], v[96:99]
	v_mfma_f32_16x16x32_bf16 v[84:87], v[190:193], v[164:167], v[84:87]
	v_mfma_f32_16x16x32_bf16 v[80:83], v[206:209], v[164:167], v[80:83]
	v_mfma_f32_16x16x32_bf16 v[68:71], v[190:193], v[172:175], v[68:71]
	v_mfma_f32_16x16x32_bf16 v[64:67], v[206:209], v[172:175], v[64:67]
	s_setprio 0
	s_mov_b32 m0, s50
	s_mov_b64 s[100:101], s[42:43]
	s_barrier
	ds_read_b128 v[144:147], v204 offset:16384
	ds_read_b128 v[148:151], v204 offset:17408
	ds_read_b128 v[152:155], v204 offset:18432
	ds_read_b128 v[156:159], v204 offset:19456
	ds_read_b128 v[160:163], v204 offset:20480
	ds_read_b128 v[164:167], v204 offset:21504
	ds_read_b128 v[168:171], v204 offset:22528
	ds_read_b128 v[172:175], v204 offset:23552
	global_load_lds_dwordx4 v176, s[42:43]
	s_mov_b64 s[100:101], s[42:43]
	s_mov_b32 m0, s51
	s_nop 0
	global_load_lds_dwordx4 v178, s[42:43]
	s_barrier
	s_waitcnt lgkmcnt(0)
	s_setprio 1
	s_waitcnt lgkmcnt(0)
	v_mfma_f32_16x16x32_bf16 v[60:63], v[128:131], v[144:147], v[60:63]
	v_mfma_f32_16x16x32_bf16 v[56:59], v[136:139], v[144:147], v[56:59]
	v_mfma_f32_16x16x32_bf16 v[44:47], v[128:131], v[152:155], v[44:47]
	v_mfma_f32_16x16x32_bf16 v[40:43], v[136:139], v[152:155], v[40:43]
	v_mfma_f32_16x16x32_bf16 v[28:31], v[128:131], v[160:163], v[28:31]
	v_mfma_f32_16x16x32_bf16 v[24:27], v[136:139], v[160:163], v[24:27]
	v_mfma_f32_16x16x32_bf16 v[12:15], v[128:131], v[168:171], v[12:15]
	v_mfma_f32_16x16x32_bf16 v[8:11], v[136:139], v[168:171], v[8:11]
	v_mfma_f32_16x16x32_bf16 v[60:63], v[132:135], v[148:151], v[60:63]
	v_mfma_f32_16x16x32_bf16 v[56:59], v[140:143], v[148:151], v[56:59]
	v_mfma_f32_16x16x32_bf16 v[44:47], v[132:135], v[156:159], v[44:47]
	v_mfma_f32_16x16x32_bf16 v[40:43], v[140:143], v[156:159], v[40:43]
	v_mfma_f32_16x16x32_bf16 v[28:31], v[132:135], v[164:167], v[28:31]
	v_mfma_f32_16x16x32_bf16 v[24:27], v[140:143], v[164:167], v[24:27]
	v_mfma_f32_16x16x32_bf16 v[12:15], v[132:135], v[172:175], v[12:15]
	v_mfma_f32_16x16x32_bf16 v[8:11], v[140:143], v[172:175], v[8:11]
	s_setprio 0
	s_barrier
	s_add_u32 s64, s40, 0x80000
	s_addc_u32 s65, s41, 0
	s_add_i32 s63, s60, s49

; #define PG8_STAGE(bufoff, gbase, voff) do { _Pragma("unroll") for (int _i = 0; _i < 2; ++_i) \
;         __builtin_amdgcn_global_load_lds((const unsigned*)((const char*)(gbase) + (voff)[_i]), (LAS unsigned*)(lds + (bufoff) + ldsw + _i * 8192), 16, 0, 0); } while (0)
; template <class Epi>
; DI void gemm_phase(LAS unsigned char* lds, int wid, int K, int lda, int ldb, bool bperm, const Sched3& S, const Epi& E) {
;     ...
;             PG8_STAGE(PG8_SB(0, 1), b2 + hstepB, voffB);
	s_mov_b32 m0, s63
	s_nop 0
	global_load_lds_dwordx4 v176, s[64:65]

; #define PG8_STAGE(bufoff, gbase, voff) do { _Pragma("unroll") for (int _i = 0; _i < 2; ++_i) \
;         __builtin_amdgcn_global_load_lds((const unsigned*)((const char*)(gbase) + (voff)[_i]), (LAS unsigned*)(lds + (bufoff) + ldsw + _i * 8192), 16, 0, 0); } while (0)
; #define PG8_LDA(dst, b, h) do { _Pragma("unroll") for (int m = 0; m < 4; ++m) _Pragma("unroll") for (int k = 0; k < 2; ++k) dst[m][k] = *(const LAS bf16x8*)(lds + PG8_SA(b, h) + aoff + m * 2048 + k * 1024); } while (0)
; #define PG8_LDB(dst, b, h) do { _Pragma("unroll") for (int n = 0; n < 2; ++n) _Pragma("unroll") for (int k = 0; k < 2; ++k) dst[n][k] = *(const LAS bf16x8*)(lds + PG8_SB(b, h) + boff + n * 2048 + k * 1024); } while (0)
; #define PG8_MMA(ai, bj, At, Bt) do { __builtin_amdgcn_s_setprio(1); _Pragma("unroll") for (int m = 0; m < 4; ++m) _Pragma("unroll") for (int n = 0; n < 2; ++n) _Pragma("unroll") for (int k = 0; k < 2; ++k) \
;         acc[ai][bj][m][n] = __builtin_amdgcn_mfma_f32_16x16x32_bf16(Bt[n][k], At[m][k], acc[ai][bj][m][n], 0, 0, 0); __builtin_amdgcn_s_setprio(0); } while (0)
; #define PG8_WAIT_V(n) asm volatile("s_waitcnt vmcnt(" #n ")" ::: "memory")
; #define PG8_BAR __builtin_amdgcn_s_barrier()
; #define PG8_SCHED __builtin_amdgcn_sched_barrier(0)
; template <class Epi>
; DI void gemm_phase(LAS unsigned char* lds, int wid, int K, int lda, int ldb, bool bperm, const Sched3& S, const Epi& E) {
;     ...
;             PG8_STAGE(PG8_SB(0, 1), b2 + hstepB, voffB);
;             PG8_WAIT_V(6); PG8_BAR; if (full) PG8_MMA(1, 1, At, B1); PG8_BAR;
;             PG8_LDB(B0, 1, 0); PG8_SCHED; PG8_LDA(At, 1, 0); PG8_STAGE(PG8_SA(0, 1), a2 + h2, voffA);
	s_add_i32 m0, s63, 0x2000
	s_nop 0
	global_load_lds_dwordx4 v178, s[64:65]
	s_waitcnt vmcnt(6)
	s_barrier
	s_setprio 1
	v_mfma_f32_16x16x32_bf16 v[52:55], v[186:189], v[144:147], v[52:55]
	v_mfma_f32_16x16x32_bf16 v[48:51], v[194:197], v[144:147], v[48:51]
	v_mfma_f32_16x16x32_bf16 v[36:39], v[186:189], v[152:155], v[36:39]
	v_mfma_f32_16x16x32_bf16 v[32:35], v[194:197], v[152:155], v[32:35]
	v_mfma_f32_16x16x32_bf16 v[20:23], v[186:189], v[160:163], v[20:23]
	v_mfma_f32_16x16x32_bf16 v[16:19], v[194:197], v[160:163], v[16:19]
	v_mfma_f32_16x16x32_bf16 v[4:7], v[186:189], v[168:171], v[4:7]
	v_mfma_f32_16x16x32_bf16 v[0:3], v[194:197], v[168:171], v[0:3]
	v_mfma_f32_16x16x32_bf16 v[52:55], v[190:193], v[148:151], v[52:55]
	v_mfma_f32_16x16x32_bf16 v[48:51], v[206:209], v[148:151], v[48:51]
	v_mfma_f32_16x16x32_bf16 v[36:39], v[190:193], v[156:159], v[36:39]
	v_mfma_f32_16x16x32_bf16 v[32:35], v[206:209], v[156:159], v[32:35]
	v_mfma_f32_16x16x32_bf16 v[20:23], v[190:193], v[164:167], v[20:23]
	v_mfma_f32_16x16x32_bf16 v[16:19], v[206:209], v[164:167], v[16:19]
	v_mfma_f32_16x16x32_bf16 v[4:7], v[190:193], v[172:175], v[4:7]
	v_mfma_f32_16x16x32_bf16 v[0:3], v[206:209], v[172:175], v[0:3]
	s_setprio 0
	s_add_i32 s63, 0, 0x18000
	v_add_u32_e32 v140, s63, v199
	s_barrier
	ds_read_b128 v[128:131], v140
	ds_read_b128 v[132:135], v140 offset:1024
	ds_read_b128 v[136:139], v140 offset:2048
	ds_read_b128 v[140:143], v140 offset:3072
	s_add_u32 s42, s42, 0x80000
	s_addc_u32 s43, s43, 0
	s_mov_b32 m0, s52

; #define PG8_STAGE(bufoff, gbase, voff) do { _Pragma("unroll") for (int _i = 0; _i < 2; ++_i) \
;         __builtin_amdgcn_global_load_lds((const unsigned*)((const char*)(gbase) + (voff)[_i]), (LAS unsigned*)(lds + (bufoff) + ldsw + _i * 8192), 16, 0, 0); } while (0)
; #define PG8_LDA(dst, b, h) do { _Pragma("unroll") for (int m = 0; m < 4; ++m) _Pragma("unroll") for (int k = 0; k < 2; ++k) dst[m][k] = *(const LAS bf16x8*)(lds + PG8_SA(b, h) + aoff + m * 2048 + k * 1024); } while (0)
; #define PG8_LDB(dst, b, h) do { _Pragma("unroll") for (int n = 0; n < 2; ++n) _Pragma("unroll") for (int k = 0; k < 2; ++k) dst[n][k] = *(const LAS bf16x8*)(lds + PG8_SB(b, h) + boff + n * 2048 + k * 1024); } while (0)
; #define PG8_SCHED __builtin_amdgcn_sched_barrier(0)
; template <class Epi>
; DI void gemm_phase(LAS unsigned char* lds, int wid, int K, int lda, int ldb, bool bperm, const Sched3& S, const Epi& E) {
;     ...
;             PG8_LDB(B0, 1, 0); PG8_SCHED; PG8_LDA(At, 1, 0); PG8_STAGE(PG8_SA(0, 1), a2 + h2, voffA);
	ds_read_b128 v[144:147], v204 offset:32768
	ds_read_b128 v[148:151], v204 offset:33792
	ds_read_b128 v[152:155], v204 offset:34816
	ds_read_b128 v[156:159], v204 offset:35840
	ds_read_b128 v[160:163], v204 offset:36864
	ds_read_b128 v[164:167], v204 offset:37888
	ds_read_b128 v[168:171], v204 offset:38912
	ds_read_b128 v[172:175], v204 offset:39936
	global_load_lds_dwordx4 v176, s[42:43]

; #define PG8_STAGE(bufoff, gbase, voff) do { _Pragma("unroll") for (int _i = 0; _i < 2; ++_i) \
;         __builtin_amdgcn_global_load_lds((const unsigned*)((const char*)(gbase) + (voff)[_i]), (LAS unsigned*)(lds + (bufoff) + ldsw + _i * 8192), 16, 0, 0); } while (0)
; #define PG8_LDA(dst, b, h) do { _Pragma("unroll") for (int m = 0; m < 4; ++m) _Pragma("unroll") for (int k = 0; k < 2; ++k) dst[m][k] = *(const LAS bf16x8*)(lds + PG8_SA(b, h) + aoff + m * 2048 + k * 1024); } while (0)
; #define PG8_LDB(dst, b, h) do { _Pragma("unroll") for (int n = 0; n < 2; ++n) _Pragma("unroll") for (int k = 0; k < 2; ++k) dst[n][k] = *(const LAS bf16x8*)(lds + PG8_SB(b, h) + boff + n * 2048 + k * 1024); } while (0)
; #define PG8_MMA(ai, bj, At, Bt) do { __builtin_amdgcn_s_setprio(1); _Pragma("unroll") for (int m = 0; m < 4; ++m) _Pragma("unroll") for (int n = 0; n < 2; ++n) _Pragma("unroll") for (int k = 0; k < 2; ++k) \
;         acc[ai][bj][m][n] = __builtin_amdgcn_mfma_f32_16x16x32_bf16(Bt[n][k], At[m][k], acc[ai][bj][m][n], 0, 0, 0); __builtin_amdgcn_s_setprio(0); } while (0)
; #define PG8_WAIT_L(n) asm volatile("s_waitcnt lgkmcnt(" #n ")" ::: "memory")
; #define PG8_BAR __builtin_amdgcn_s_barrier()
; #define PG8_SCHED __builtin_amdgcn_sched_barrier(0)
; template <class Epi>
; DI void gemm_phase(LAS unsigned char* lds, int wid, int K, int lda, int ldb, bool bperm, const Sched3& S, const Epi& E) {
;     ...
;             PG8_LDB(B0, 1, 0); PG8_SCHED; PG8_LDA(At, 1, 0); PG8_STAGE(PG8_SA(0, 1), a2 + h2, voffA);
;             PG8_WAIT_L(8); PG8_BAR; PG8_WAIT_L(0); PG8_MMA(0, 0, At, B0); PG8_BAR; PG8_SCHED;
;             PG8_LDB(B1, 1, 1); PG8_STAGE(PG8_SB(1, 0), b3, voffB);
	s_mov_b32 m0, s53
	s_nop 0
	global_load_lds_dwordx4 v178, s[42:43]
	s_waitcnt lgkmcnt(8)
	s_barrier
	s_waitcnt lgkmcnt(0)
	s_setprio 1
	s_waitcnt lgkmcnt(0)
	v_mfma_f32_16x16x32_bf16 v[124:127], v[128:131], v[144:147], v[124:127]
	v_mfma_f32_16x16x32_bf16 v[120:123], v[136:139], v[144:147], v[120:123]
	v_mfma_f32_16x16x32_bf16 v[108:111], v[128:131], v[152:155], v[108:111]
	v_mfma_f32_16x16x32_bf16 v[104:107], v[136:139], v[152:155], v[104:107]
	v_mfma_f32_16x16x32_bf16 v[92:95], v[128:131], v[160:163], v[92:95]
	v_mfma_f32_16x16x32_bf16 v[88:91], v[136:139], v[160:163], v[88:91]
	v_mfma_f32_16x16x32_bf16 v[76:79], v[128:131], v[168:171], v[76:79]
	v_mfma_f32_16x16x32_bf16 v[72:75], v[136:139], v[168:171], v[72:75]
	v_mfma_f32_16x16x32_bf16 v[124:127], v[132:135], v[148:151], v[124:127]
	v_mfma_f32_16x16x32_bf16 v[120:123], v[140:143], v[148:151], v[120:123]
	v_mfma_f32_16x16x32_bf16 v[108:111], v[132:135], v[156:159], v[108:111]
	v_mfma_f32_16x16x32_bf16 v[104:107], v[140:143], v[156:159], v[104:107]
	v_mfma_f32_16x16x32_bf16 v[92:95], v[132:135], v[164:167], v[92:95]
	v_mfma_f32_16x16x32_bf16 v[88:91], v[140:143], v[164:167], v[88:91]
	v_mfma_f32_16x16x32_bf16 v[76:79], v[132:135], v[172:175], v[76:79]
	v_mfma_f32_16x16x32_bf16 v[72:75], v[140:143], v[172:175], v[72:75]
	s_setprio 0
	s_barrier
	s_add_i32 s42, 0, 0x1c000
	s_add_i32 s43, s63, s49
	v_add_u32_e32 v206, s42, v199

; #define PG8_STAGE(bufoff, gbase, voff) do { _Pragma("unroll") for (int _i = 0; _i < 2; ++_i) \
;         __builtin_amdgcn_global_load_lds((const unsigned*)((const char*)(gbase) + (voff)[_i]), (LAS unsigned*)(lds + (bufoff) + ldsw + _i * 8192), 16, 0, 0); } while (0)
; #define PG8_LDB(dst, b, h) do { _Pragma("unroll") for (int n = 0; n < 2; ++n) _Pragma("unroll") for (int k = 0; k < 2; ++k) dst[n][k] = *(const LAS bf16x8*)(lds + PG8_SB(b, h) + boff + n * 2048 + k * 1024); } while (0)
; template <class Epi>
; DI void gemm_phase(LAS unsigned char* lds, int wid, int K, int lda, int ldb, bool bperm, const Sched3& S, const Epi& E) {
;     ...
;             PG8_LDB(B1, 1, 1); PG8_STAGE(PG8_SB(1, 0), b3, voffB);
	s_sub_i32 m0, s43, 0x80
	ds_read_b128 v[186:189], v206
	ds_read_b128 v[190:193], v206 offset:1024
	ds_read_b128 v[194:197], v206 offset:2048
	ds_read_b128 v[206:209], v206 offset:3072
	global_load_lds_dwordx4 v176, s[40:41] offset:128

; #define PG8_STAGE(bufoff, gbase, voff) do { _Pragma("unroll") for (int _i = 0; _i < 2; ++_i) \
;         __builtin_amdgcn_global_load_lds((const unsigned*)((const char*)(gbase) + (voff)[_i]), (LAS unsigned*)(lds + (bufoff) + ldsw + _i * 8192), 16, 0, 0); } while (0)
; #define PG8_LDA(dst, b, h) do { _Pragma("unroll") for (int m = 0; m < 4; ++m) _Pragma("unroll") for (int k = 0; k < 2; ++k) dst[m][k] = *(const LAS bf16x8*)(lds + PG8_SA(b, h) + aoff + m * 2048 + k * 1024); } while (0)
; #define PG8_LDB(dst, b, h) do { _Pragma("unroll") for (int n = 0; n < 2; ++n) _Pragma("unroll") for (int k = 0; k < 2; ++k) dst[n][k] = *(const LAS bf16x8*)(lds + PG8_SB(b, h) + boff + n * 2048 + k * 1024); } while (0)
; #define PG8_MMA(ai, bj, At, Bt) do { __builtin_amdgcn_s_setprio(1); _Pragma("unroll") for (int m = 0; m < 4; ++m) _Pragma("unroll") for (int n = 0; n < 2; ++n) _Pragma("unroll") for (int k = 0; k < 2; ++k) \
;         acc[ai][bj][m][n] = __builtin_amdgcn_mfma_f32_16x16x32_bf16(Bt[n][k], At[m][k], acc[ai][bj][m][n], 0, 0, 0); __builtin_amdgcn_s_setprio(0); } while (0)
; #define PG8_WAIT_L(n) asm volatile("s_waitcnt lgkmcnt(" #n ")" ::: "memory")
; #define PG8_BAR __builtin_amdgcn_s_barrier()
; template <class Epi>
; DI void gemm_phase(LAS unsigned char* lds, int wid, int K, int lda, int ldb, bool bperm, const Sched3& S, const Epi& E) {
;     ...
;             PG8_LDB(B1, 1, 1); PG8_STAGE(PG8_SB(1, 0), b3, voffB);
;             PG8_BAR; PG8_WAIT_L(0); PG8_MMA(0, 1, At, B1); PG8_BAR;
;             PG8_LDA(At, 1, 1); PG8_STAGE(PG8_SA(1, 0), a3, voffA);
	s_add_i32 m0, s43, 0x1f80
	s_nop 0
	global_load_lds_dwordx4 v178, s[40:41] offset:128
	s_barrier
	s_waitcnt lgkmcnt(0)
	s_setprio 1
	s_waitcnt lgkmcnt(0)
	v_mfma_f32_16x16x32_bf16 v[116:119], v[186:189], v[144:147], v[116:119]
	v_mfma_f32_16x16x32_bf16 v[112:115], v[194:197], v[144:147], v[112:115]
	v_mfma_f32_16x16x32_bf16 v[100:103], v[186:189], v[152:155], v[100:103]
	v_mfma_f32_16x16x32_bf16 v[96:99], v[194:197], v[152:155], v[96:99]
	v_mfma_f32_16x16x32_bf16 v[84:87], v[186:189], v[160:163], v[84:87]
	v_mfma_f32_16x16x32_bf16 v[80:83], v[194:197], v[160:163], v[80:83]
	v_mfma_f32_16x16x32_bf16 v[68:71], v[186:189], v[168:171], v[68:71]
	v_mfma_f32_16x16x32_bf16 v[64:67], v[194:197], v[168:171], v[64:67]
	v_mfma_f32_16x16x32_bf16 v[116:119], v[190:193], v[148:151], v[116:119]
	v_mfma_f32_16x16x32_bf16 v[112:115], v[206:209], v[148:151], v[112:115]
	v_mfma_f32_16x16x32_bf16 v[100:103], v[190:193], v[156:159], v[100:103]
	v_mfma_f32_16x16x32_bf16 v[96:99], v[206:209], v[156:159], v[96:99]
	v_mfma_f32_16x16x32_bf16 v[84:87], v[190:193], v[164:167], v[84:87]
	v_mfma_f32_16x16x32_bf16 v[80:83], v[206:209], v[164:167], v[80:83]
	v_mfma_f32_16x16x32_bf16 v[68:71], v[190:193], v[172:175], v[68:71]
	v_mfma_f32_16x16x32_bf16 v[64:67], v[206:209], v[172:175], v[64:67]
	s_setprio 0
	s_sub_i32 m0, s55, 0x80

; #define PG8_STAGE(bufoff, gbase, voff) do { _Pragma("unroll") for (int _i = 0; _i < 2; ++_i) \
;         __builtin_amdgcn_global_load_lds((const unsigned*)((const char*)(gbase) + (voff)[_i]), (LAS unsigned*)(lds + (bufoff) + ldsw + _i * 8192), 16, 0, 0); } while (0)
; #define PG8_LDA(dst, b, h) do { _Pragma("unroll") for (int m = 0; m < 4; ++m) _Pragma("unroll") for (int k = 0; k < 2; ++k) dst[m][k] = *(const LAS bf16x8*)(lds + PG8_SA(b, h) + aoff + m * 2048 + k * 1024); } while (0)
; template <class Epi>
; DI void gemm_phase(LAS unsigned char* lds, int wid, int K, int lda, int ldb, bool bperm, const Sched3& S, const Epi& E) {
;     ...
;             PG8_LDA(At, 1, 1); PG8_STAGE(PG8_SA(1, 0), a3, voffA);
	s_barrier
	ds_read_b128 v[144:147], v204 offset:49152
	ds_read_b128 v[148:151], v204 offset:50176
	ds_read_b128 v[152:155], v204 offset:51200
	ds_read_b128 v[156:159], v204 offset:52224
	ds_read_b128 v[160:163], v204 offset:53248
	ds_read_b128 v[164:167], v204 offset:54272
	ds_read_b128 v[168:171], v204 offset:55296
	ds_read_b128 v[172:175], v204 offset:56320
	global_load_lds_dwordx4 v176, s[100:101] offset:128

; #define PG8_STAGE(bufoff, gbase, voff) do { _Pragma("unroll") for (int _i = 0; _i < 2; ++_i) \
;         __builtin_amdgcn_global_load_lds((const unsigned*)((const char*)(gbase) + (voff)[_i]), (LAS unsigned*)(lds + (bufoff) + ldsw + _i * 8192), 16, 0, 0); } while (0)
; #define PG8_LDA(dst, b, h) do { _Pragma("unroll") for (int m = 0; m < 4; ++m) _Pragma("unroll") for (int k = 0; k < 2; ++k) dst[m][k] = *(const LAS bf16x8*)(lds + PG8_SA(b, h) + aoff + m * 2048 + k * 1024); } while (0)
; #define PG8_MMA(ai, bj, At, Bt) do { __builtin_amdgcn_s_setprio(1); _Pragma("unroll") for (int m = 0; m < 4; ++m) _Pragma("unroll") for (int n = 0; n < 2; ++n) _Pragma("unroll") for (int k = 0; k < 2; ++k) \
;         acc[ai][bj][m][n] = __builtin_amdgcn_mfma_f32_16x16x32_bf16(Bt[n][k], At[m][k], acc[ai][bj][m][n], 0, 0, 0); __builtin_amdgcn_s_setprio(0); } while (0)
; #define PG8_WAIT_L(n) asm volatile("s_waitcnt lgkmcnt(" #n ")" ::: "memory")
; #define PG8_BAR __builtin_amdgcn_s_barrier()
; #define PG8_SCHED __builtin_amdgcn_sched_barrier(0)
; template <class Epi>
; DI void gemm_phase(LAS unsigned char* lds, int wid, int K, int lda, int ldb, bool bperm, const Sched3& S, const Epi& E) {
;     ...
;             PG8_LDA(At, 1, 1); PG8_STAGE(PG8_SA(1, 0), a3, voffA);
;             PG8_BAR; PG8_WAIT_L(0); if (full) PG8_MMA(1, 0, At, B0); PG8_BAR; PG8_SCHED;
;             PG8_STAGE(PG8_SB(1, 1), b3 + hstepB, voffB);
	s_sub_i32 m0, s56, 0x80
	s_nop 0
	global_load_lds_dwordx4 v178, s[100:101] offset:128
	s_barrier
	s_waitcnt lgkmcnt(0)
	s_setprio 1
	s_waitcnt lgkmcnt(0)
	v_mfma_f32_16x16x32_bf16 v[60:63], v[128:131], v[144:147], v[60:63]
	v_mfma_f32_16x16x32_bf16 v[56:59], v[136:139], v[144:147], v[56:59]
	v_mfma_f32_16x16x32_bf16 v[44:47], v[128:131], v[152:155], v[44:47]
	v_mfma_f32_16x16x32_bf16 v[40:43], v[136:139], v[152:155], v[40:43]
	v_mfma_f32_16x16x32_bf16 v[28:31], v[128:131], v[160:163], v[28:31]
	v_mfma_f32_16x16x32_bf16 v[24:27], v[136:139], v[160:163], v[24:27]
	v_mfma_f32_16x16x32_bf16 v[12:15], v[128:131], v[168:171], v[12:15]
	v_mfma_f32_16x16x32_bf16 v[8:11], v[136:139], v[168:171], v[8:11]
	v_mfma_f32_16x16x32_bf16 v[60:63], v[132:135], v[148:151], v[60:63]
	v_mfma_f32_16x16x32_bf16 v[56:59], v[140:143], v[148:151], v[56:59]
	v_mfma_f32_16x16x32_bf16 v[44:47], v[132:135], v[156:159], v[44:47]
	v_mfma_f32_16x16x32_bf16 v[40:43], v[140:143], v[156:159], v[40:43]
	v_mfma_f32_16x16x32_bf16 v[28:31], v[132:135], v[164:167], v[28:31]
	v_mfma_f32_16x16x32_bf16 v[24:27], v[140:143], v[164:167], v[24:27]
	v_mfma_f32_16x16x32_bf16 v[12:15], v[132:135], v[172:175], v[12:15]
	v_mfma_f32_16x16x32_bf16 v[8:11], v[140:143], v[172:175], v[8:11]
	s_setprio 0
	s_barrier
	s_add_u32 s40, s40, 0x80080
	s_addc_u32 s41, s41, 0
	s_add_i32 s42, s42, s49

; #define PG8_STAGE(bufoff, gbase, voff) do { _Pragma("unroll") for (int _i = 0; _i < 2; ++_i) \
;         __builtin_amdgcn_global_load_lds((const unsigned*)((const char*)(gbase) + (voff)[_i]), (LAS unsigned*)(lds + (bufoff) + ldsw + _i * 8192), 16, 0, 0); } while (0)
; template <class Epi>
; DI void gemm_phase(LAS unsigned char* lds, int wid, int K, int lda, int ldb, bool bperm, const Sched3& S, const Epi& E) {
;     ...
;             PG8_STAGE(PG8_SB(1, 1), b3 + hstepB, voffB);
	s_mov_b32 m0, s42
	s_nop 0
	global_load_lds_dwordx4 v176, s[40:41]

; #define PG8_STAGE(bufoff, gbase, voff) do { _Pragma("unroll") for (int _i = 0; _i < 2; ++_i) \
;         __builtin_amdgcn_global_load_lds((const unsigned*)((const char*)(gbase) + (voff)[_i]), (LAS unsigned*)(lds + (bufoff) + ldsw + _i * 8192), 16, 0, 0); } while (0)
; #define PG8_MMA(ai, bj, At, Bt) do { __builtin_amdgcn_s_setprio(1); _Pragma("unroll") for (int m = 0; m < 4; ++m) _Pragma("unroll") for (int n = 0; n < 2; ++n) _Pragma("unroll") for (int k = 0; k < 2; ++k) \
;         acc[ai][bj][m][n] = __builtin_amdgcn_mfma_f32_16x16x32_bf16(Bt[n][k], At[m][k], acc[ai][bj][m][n], 0, 0, 0); __builtin_amdgcn_s_setprio(0); } while (0)
; #define PG8_WAIT_V(n) asm volatile("s_waitcnt vmcnt(" #n ")" ::: "memory")
; #define PG8_BAR __builtin_amdgcn_s_barrier()
; template <class Epi>
; DI void gemm_phase(LAS unsigned char* lds, int wid, int K, int lda, int ldb, bool bperm, const Sched3& S, const Epi& E) {
;     ...
;             PG8_STAGE(PG8_SB(1, 1), b3 + hstepB, voffB);
;             PG8_WAIT_V(6); PG8_BAR; if (full) PG8_MMA(1, 1, At, B1); PG8_BAR;
	s_add_i32 m0, s42, 0x2000
	s_nop 0
	global_load_lds_dwordx4 v178, s[40:41]
	s_waitcnt vmcnt(6)
	s_barrier
	s_setprio 1
	v_mfma_f32_16x16x32_bf16 v[52:55], v[186:189], v[144:147], v[52:55]
	v_mfma_f32_16x16x32_bf16 v[48:51], v[194:197], v[144:147], v[48:51]
	v_mfma_f32_16x16x32_bf16 v[36:39], v[186:189], v[152:155], v[36:39]
	v_mfma_f32_16x16x32_bf16 v[32:35], v[194:197], v[152:155], v[32:35]
	v_mfma_f32_16x16x32_bf16 v[20:23], v[186:189], v[160:163], v[20:23]
	v_mfma_f32_16x16x32_bf16 v[16:19], v[194:197], v[160:163], v[16:19]
	v_mfma_f32_16x16x32_bf16 v[4:7], v[186:189], v[168:171], v[4:7]
	v_mfma_f32_16x16x32_bf16 v[0:3], v[194:197], v[168:171], v[0:3]
	v_mfma_f32_16x16x32_bf16 v[52:55], v[190:193], v[148:151], v[52:55]
	v_mfma_f32_16x16x32_bf16 v[48:51], v[206:209], v[148:151], v[48:51]
	v_mfma_f32_16x16x32_bf16 v[36:39], v[190:193], v[156:159], v[36:39]
	v_mfma_f32_16x16x32_bf16 v[32:35], v[206:209], v[156:159], v[32:35]
	v_mfma_f32_16x16x32_bf16 v[20:23], v[190:193], v[164:167], v[20:23]
	v_mfma_f32_16x16x32_bf16 v[16:19], v[206:209], v[164:167], v[16:19]
	v_mfma_f32_16x16x32_bf16 v[4:7], v[190:193], v[172:175], v[4:7]
	v_mfma_f32_16x16x32_bf16 v[0:3], v[206:209], v[172:175], v[0:3]
	s_setprio 0
	s_add_i32 s29, s29, 2
	s_add_u32 s38, s38, 0x100
	s_addc_u32 s39, s39, 0
	s_add_u32 s21, s21, 0x100
	s_addc_u32 s23, s23, 0
	s_cmp_gt_u32 s29, 29
	s_barrier
	s_cbranch_scc0 .LBB0_621

; #define PG8_STAGE(bufoff, gbase, voff) do { _Pragma("unroll") for (int _i = 0; _i < 2; ++_i) \
;         __builtin_amdgcn_global_load_lds((const unsigned*)((const char*)(gbase) + (voff)[_i]), (LAS unsigned*)(lds + (bufoff) + ldsw + _i * 8192), 16, 0, 0); } while (0)
; #define PG8_LDA(dst, b, h) do { _Pragma("unroll") for (int m = 0; m < 4; ++m) _Pragma("unroll") for (int k = 0; k < 2; ++k) dst[m][k] = *(const LAS bf16x8*)(lds + PG8_SA(b, h) + aoff + m * 2048 + k * 1024); } while (0)
; #define PG8_LDB(dst, b, h) do { _Pragma("unroll") for (int n = 0; n < 2; ++n) _Pragma("unroll") for (int k = 0; k < 2; ++k) dst[n][k] = *(const LAS bf16x8*)(lds + PG8_SB(b, h) + boff + n * 2048 + k * 1024); } while (0)
; #define PG8_SCHED __builtin_amdgcn_sched_barrier(0)
; template <class Epi>
; DI void gemm_phase(LAS unsigned char* lds, int wid, int K, int lda, int ldb, bool bperm, const Sched3& S, const Epi& E) {
;     ...
;             const bool last = (t == nt - 2);
;             const char* a1 = cA + (size_t)(t + 1) * kstep;
;             const char* a2 = last ? nA : cA + (size_t)(t + 2) * kstep; const char* b2 = last ? nB : cB + (size_t)(t + 2) * kstep;
;             const char* a3 = a2 + kstep; const char* b3 = b2 + kstep; const size_t h2 = last ? nhA : hA;
;             PG8_LDB(B0, 0, 0); PG8_SCHED; PG8_LDA(At, 0, 0); PG8_STAGE(PG8_SA(1, 1), a1 + hA, voffA);
.LBB0_704:
	v_lshl_add_u32 v218, s22, 8, v155
	v_lshlrev_b32_e32 v218, 2, v218
	global_load_dword v220, v218, s[10:11]
	global_load_dword v221, v218, s[10:11] offset:64
	global_load_dword v222, v218, s[10:11] offset:128
	global_load_dword v223, v218, s[10:11] offset:192
	global_load_dword v224, v218, s[10:11] offset:512
	global_load_dword v225, v218, s[10:11] offset:576
	global_load_dword v226, v218, s[10:11] offset:640
	global_load_dword v227, v218, s[10:11] offset:704
	s_add_u32 s28, s28, 0x80080
	s_addc_u32 s29, s29, 0
	s_add_u32 s15, s30, 0x100
	s_nop 0
	s_addc_u32 s17, s31, 0
	s_mov_b32 s57, -2
	ds_read_b128 v[138:141], v160
	ds_read_b128 v[142:145], v160 offset:1024
	ds_read_b128 v[146:149], v160 offset:2048
	ds_read_b128 v[150:153], v160 offset:3072
	s_add_u32 s30, s28, 0xfff80080
	s_addc_u32 s31, s29, -1
	s_cmp_eq_u32 s57, 28
	s_cselect_b32 s37, s25, s31
	s_cselect_b32 s36, s24, s30
	s_cselect_b32 s31, s27, s17
	s_cselect_b32 s30, s26, s15

; #define PG8_STAGE(bufoff, gbase, voff) do { _Pragma("unroll") for (int _i = 0; _i < 2; ++_i) \
;         __builtin_amdgcn_global_load_lds((const unsigned*)((const char*)(gbase) + (voff)[_i]), (LAS unsigned*)(lds + (bufoff) + ldsw + _i * 8192), 16, 0, 0); } while (0)
; #define PG8_LDA(dst, b, h) do { _Pragma("unroll") for (int m = 0; m < 4; ++m) _Pragma("unroll") for (int k = 0; k < 2; ++k) dst[m][k] = *(const LAS bf16x8*)(lds + PG8_SA(b, h) + aoff + m * 2048 + k * 1024); } while (0)
; #define PG8_LDB(dst, b, h) do { _Pragma("unroll") for (int n = 0; n < 2; ++n) _Pragma("unroll") for (int k = 0; k < 2; ++k) dst[n][k] = *(const LAS bf16x8*)(lds + PG8_SB(b, h) + boff + n * 2048 + k * 1024); } while (0)
; #define PG8_SCHED __builtin_amdgcn_sched_barrier(0)
; template <class Epi>
; DI void gemm_phase(LAS unsigned char* lds, int wid, int K, int lda, int ldb, bool bperm, const Sched3& S, const Epi& E) {
;     ...
;             PG8_LDB(B0, 0, 0); PG8_SCHED; PG8_LDA(At, 0, 0); PG8_STAGE(PG8_SA(1, 1), a1 + hA, voffA);
	s_add_i32 m0, s23, 0xc000
	ds_read_b128 v[164:167], v161
	ds_read_b128 v[168:171], v161 offset:1024
	ds_read_b128 v[172:175], v161 offset:2048
	ds_read_b128 v[176:179], v161 offset:3072
	ds_read_b128 v[180:183], v161 offset:4096
	ds_read_b128 v[184:187], v161 offset:5120
	ds_read_b128 v[188:191], v161 offset:6144
	ds_read_b128 v[192:195], v161 offset:7168
	global_load_lds_dwordx4 v132, s[28:29]

; #define PG8_STAGE(bufoff, gbase, voff) do { _Pragma("unroll") for (int _i = 0; _i < 2; ++_i) \
;         __builtin_amdgcn_global_load_lds((const unsigned*)((const char*)(gbase) + (voff)[_i]), (LAS unsigned*)(lds + (bufoff) + ldsw + _i * 8192), 16, 0, 0); } while (0)
; #define PG8_LDA(dst, b, h) do { _Pragma("unroll") for (int m = 0; m < 4; ++m) _Pragma("unroll") for (int k = 0; k < 2; ++k) dst[m][k] = *(const LAS bf16x8*)(lds + PG8_SA(b, h) + aoff + m * 2048 + k * 1024); } while (0)
; #define PG8_LDB(dst, b, h) do { _Pragma("unroll") for (int n = 0; n < 2; ++n) _Pragma("unroll") for (int k = 0; k < 2; ++k) dst[n][k] = *(const LAS bf16x8*)(lds + PG8_SB(b, h) + boff + n * 2048 + k * 1024); } while (0)
; #define PG8_MMA(ai, bj, At, Bt) do { __builtin_amdgcn_s_setprio(1); _Pragma("unroll") for (int m = 0; m < 4; ++m) _Pragma("unroll") for (int n = 0; n < 2; ++n) _Pragma("unroll") for (int k = 0; k < 2; ++k) \
;         acc[ai][bj][m][n] = __builtin_amdgcn_mfma_f32_16x16x32_bf16(Bt[n][k], At[m][k], acc[ai][bj][m][n], 0, 0, 0); __builtin_amdgcn_s_setprio(0); } while (0)
; #define PG8_WAIT_L(n) asm volatile("s_waitcnt lgkmcnt(" #n ")" ::: "memory")
; #define PG8_BAR __builtin_amdgcn_s_barrier()
; #define PG8_SCHED __builtin_amdgcn_sched_barrier(0)
; template <class Epi>
; DI void gemm_phase(LAS unsigned char* lds, int wid, int K, int lda, int ldb, bool bperm, const Sched3& S, const Epi& E) {
;     ...
;             PG8_LDB(B0, 0, 0); PG8_SCHED; PG8_LDA(At, 0, 0); PG8_STAGE(PG8_SA(1, 1), a1 + hA, voffA);
;             PG8_WAIT_L(8); PG8_BAR; PG8_WAIT_L(0); PG8_MMA(0, 0, At, B0); PG8_BAR; PG8_SCHED;
	s_add_i32 m0, s23, 0xe000
	s_nop 0
	global_load_lds_dwordx4 v134, s[28:29]
	s_waitcnt lgkmcnt(8)
	s_barrier
	s_waitcnt lgkmcnt(0)
	s_setprio 1
	s_waitcnt lgkmcnt(0)
	v_mfma_f32_16x16x32_bf16 v[124:127], v[138:141], v[164:167], 0
	v_mfma_f32_16x16x32_bf16 v[120:123], v[146:149], v[164:167], 0
	v_mfma_f32_16x16x32_bf16 v[116:119], v[138:141], v[172:175], 0
	v_mfma_f32_16x16x32_bf16 v[104:107], v[146:149], v[172:175], 0
	v_mfma_f32_16x16x32_bf16 v[96:99], v[138:141], v[180:183], 0
	v_mfma_f32_16x16x32_bf16 v[88:91], v[146:149], v[180:183], 0
	v_mfma_f32_16x16x32_bf16 v[80:83], v[138:141], v[188:191], 0
	v_mfma_f32_16x16x32_bf16 v[72:75], v[146:149], v[188:191], 0
	v_mfma_f32_16x16x32_bf16 v[124:127], v[142:145], v[168:171], v[124:127]
	v_mfma_f32_16x16x32_bf16 v[120:123], v[150:153], v[168:171], v[120:123]
	v_mfma_f32_16x16x32_bf16 v[116:119], v[142:145], v[176:179], v[116:119]
	v_mfma_f32_16x16x32_bf16 v[104:107], v[150:153], v[176:179], v[104:107]
	v_mfma_f32_16x16x32_bf16 v[96:99], v[142:145], v[184:187], v[96:99]
	v_mfma_f32_16x16x32_bf16 v[88:91], v[150:153], v[184:187], v[88:91]
	v_mfma_f32_16x16x32_bf16 v[80:83], v[142:145], v[192:195], v[80:83]
	v_mfma_f32_16x16x32_bf16 v[72:75], v[150:153], v[192:195], v[72:75]
	s_setprio 0
	s_barrier
	s_add_i32 s58, s53, s43

; #define PG8_STAGE(bufoff, gbase, voff) do { _Pragma("unroll") for (int _i = 0; _i < 2; ++_i) \
;         __builtin_amdgcn_global_load_lds((const unsigned*)((const char*)(gbase) + (voff)[_i]), (LAS unsigned*)(lds + (bufoff) + ldsw + _i * 8192), 16, 0, 0); } while (0)
; #define PG8_LDB(dst, b, h) do { _Pragma("unroll") for (int n = 0; n < 2; ++n) _Pragma("unroll") for (int k = 0; k < 2; ++k) dst[n][k] = *(const LAS bf16x8*)(lds + PG8_SB(b, h) + boff + n * 2048 + k * 1024); } while (0)
; template <class Epi>
; DI void gemm_phase(LAS unsigned char* lds, int wid, int K, int lda, int ldb, bool bperm, const Sched3& S, const Epi& E) {
;     ...
;             PG8_LDB(B1, 0, 1); PG8_STAGE(PG8_SB(0, 0), b2, voffB);
	s_mov_b32 m0, s58
	ds_read_b128 v[196:199], v162
	ds_read_b128 v[200:203], v162 offset:1024
	ds_read_b128 v[204:207], v162 offset:2048
	ds_read_b128 v[208:211], v162 offset:3072
	global_load_lds_dwordx4 v130, s[30:31]

; #define PG8_STAGE(bufoff, gbase, voff) do { _Pragma("unroll") for (int _i = 0; _i < 2; ++_i) \
;         __builtin_amdgcn_global_load_lds((const unsigned*)((const char*)(gbase) + (voff)[_i]), (LAS unsigned*)(lds + (bufoff) + ldsw + _i * 8192), 16, 0, 0); } while (0)
; #define PG8_LDA(dst, b, h) do { _Pragma("unroll") for (int m = 0; m < 4; ++m) _Pragma("unroll") for (int k = 0; k < 2; ++k) dst[m][k] = *(const LAS bf16x8*)(lds + PG8_SA(b, h) + aoff + m * 2048 + k * 1024); } while (0)
; #define PG8_LDB(dst, b, h) do { _Pragma("unroll") for (int n = 0; n < 2; ++n) _Pragma("unroll") for (int k = 0; k < 2; ++k) dst[n][k] = *(const LAS bf16x8*)(lds + PG8_SB(b, h) + boff + n * 2048 + k * 1024); } while (0)
; #define PG8_MMA(ai, bj, At, Bt) do { __builtin_amdgcn_s_setprio(1); _Pragma("unroll") for (int m = 0; m < 4; ++m) _Pragma("unroll") for (int n = 0; n < 2; ++n) _Pragma("unroll") for (int k = 0; k < 2; ++k) \
;         acc[ai][bj][m][n] = __builtin_amdgcn_mfma_f32_16x16x32_bf16(Bt[n][k], At[m][k], acc[ai][bj][m][n], 0, 0, 0); __builtin_amdgcn_s_setprio(0); } while (0)
; #define PG8_WAIT_L(n) asm volatile("s_waitcnt lgkmcnt(" #n ")" ::: "memory")
; #define PG8_BAR __builtin_amdgcn_s_barrier()
; #define PG8_SCHED __builtin_amdgcn_sched_barrier(0)
; template <class Epi>
; DI void gemm_phase(LAS unsigned char* lds, int wid, int K, int lda, int ldb, bool bperm, const Sched3& S, const Epi& E) {
;     ...
;             PG8_LDB(B1, 0, 1); PG8_STAGE(PG8_SB(0, 0), b2, voffB);
;             PG8_BAR; PG8_WAIT_L(0); PG8_MMA(0, 1, At, B1); PG8_BAR;
;             PG8_LDA(At, 0, 1); PG8_STAGE(PG8_SA(0, 0), a2, voffA);
;             PG8_BAR; PG8_WAIT_L(0); if (full) PG8_MMA(1, 0, At, B0); PG8_BAR; PG8_SCHED;
	s_add_i32 m0, s58, 0x2000
	s_nop 0
	global_load_lds_dwordx4 v128, s[30:31]
	s_barrier
	s_waitcnt lgkmcnt(0)
	s_setprio 1
	s_waitcnt lgkmcnt(0)
	v_mfma_f32_16x16x32_bf16 v[112:115], v[196:199], v[164:167], 0
	v_mfma_f32_16x16x32_bf16 v[108:111], v[204:207], v[164:167], 0
	v_mfma_f32_16x16x32_bf16 v[100:103], v[196:199], v[172:175], 0
	v_mfma_f32_16x16x32_bf16 v[92:95], v[204:207], v[172:175], 0
	v_mfma_f32_16x16x32_bf16 v[84:87], v[196:199], v[180:183], 0
	v_mfma_f32_16x16x32_bf16 v[76:79], v[204:207], v[180:183], 0
	v_mfma_f32_16x16x32_bf16 v[68:71], v[196:199], v[188:191], 0
	v_mfma_f32_16x16x32_bf16 v[64:67], v[204:207], v[188:191], 0
	v_mfma_f32_16x16x32_bf16 v[112:115], v[200:203], v[168:171], v[112:115]
	v_mfma_f32_16x16x32_bf16 v[108:111], v[208:211], v[168:171], v[108:111]
	v_mfma_f32_16x16x32_bf16 v[100:103], v[200:203], v[176:179], v[100:103]
	v_mfma_f32_16x16x32_bf16 v[92:95], v[208:211], v[176:179], v[92:95]
	v_mfma_f32_16x16x32_bf16 v[84:87], v[200:203], v[184:187], v[84:87]
	v_mfma_f32_16x16x32_bf16 v[76:79], v[208:211], v[184:187], v[76:79]
	v_mfma_f32_16x16x32_bf16 v[68:71], v[200:203], v[192:195], v[68:71]
	v_mfma_f32_16x16x32_bf16 v[64:67], v[208:211], v[192:195], v[64:67]
	s_setprio 0
	s_mov_b32 m0, s23
	s_mov_b64 s[100:101], s[36:37]
	s_barrier
	ds_read_b128 v[164:167], v161 offset:16384
	ds_read_b128 v[168:171], v161 offset:17408
	ds_read_b128 v[172:175], v161 offset:18432
	ds_read_b128 v[176:179], v161 offset:19456
	ds_read_b128 v[180:183], v161 offset:20480
	ds_read_b128 v[184:187], v161 offset:21504
	ds_read_b128 v[188:191], v161 offset:22528
	ds_read_b128 v[192:195], v161 offset:23552
	global_load_lds_dwordx4 v130, s[36:37]
	s_mov_b64 s[100:101], s[36:37]
	s_mov_b32 m0, s46
	s_nop 0
	global_load_lds_dwordx4 v128, s[36:37]
	s_barrier
	s_waitcnt lgkmcnt(0)
	s_setprio 1
	s_waitcnt lgkmcnt(0)
	v_mfma_f32_16x16x32_bf16 v[60:63], v[138:141], v[164:167], 0
	v_mfma_f32_16x16x32_bf16 v[56:59], v[146:149], v[164:167], 0
	v_mfma_f32_16x16x32_bf16 v[48:51], v[138:141], v[172:175], 0
	v_mfma_f32_16x16x32_bf16 v[40:43], v[146:149], v[172:175], 0
	v_mfma_f32_16x16x32_bf16 v[32:35], v[138:141], v[180:183], 0
	v_mfma_f32_16x16x32_bf16 v[24:27], v[146:149], v[180:183], 0
	v_mfma_f32_16x16x32_bf16 v[16:19], v[138:141], v[188:191], 0
	v_mfma_f32_16x16x32_bf16 v[8:11], v[146:149], v[188:191], 0
	v_mfma_f32_16x16x32_bf16 v[60:63], v[142:145], v[168:171], v[60:63]
	v_mfma_f32_16x16x32_bf16 v[56:59], v[150:153], v[168:171], v[56:59]
	v_mfma_f32_16x16x32_bf16 v[48:51], v[142:145], v[176:179], v[48:51]
	v_mfma_f32_16x16x32_bf16 v[40:43], v[150:153], v[176:179], v[40:43]
	v_mfma_f32_16x16x32_bf16 v[32:35], v[142:145], v[184:187], v[32:35]
	v_mfma_f32_16x16x32_bf16 v[24:27], v[150:153], v[184:187], v[24:27]
	v_mfma_f32_16x16x32_bf16 v[16:19], v[142:145], v[192:195], v[16:19]
	v_mfma_f32_16x16x32_bf16 v[8:11], v[150:153], v[192:195], v[8:11]
	s_setprio 0
	s_barrier
	s_add_u32 s58, s30, 0x80000
	s_addc_u32 s59, s31, 0
	s_add_i32 s60, s54, s43

; #define PG8_STAGE(bufoff, gbase, voff) do { _Pragma("unroll") for (int _i = 0; _i < 2; ++_i) \
;         __builtin_amdgcn_global_load_lds((const unsigned*)((const char*)(gbase) + (voff)[_i]), (LAS unsigned*)(lds + (bufoff) + ldsw + _i * 8192), 16, 0, 0); } while (0)
; template <class Epi>
; DI void gemm_phase(LAS unsigned char* lds, int wid, int K, int lda, int ldb, bool bperm, const Sched3& S, const Epi& E) {
;     ...
;             PG8_STAGE(PG8_SB(0, 1), b2 + hstepB, voffB);
	s_mov_b32 m0, s60
	s_nop 0
	global_load_lds_dwordx4 v130, s[58:59]

; #define PG8_STAGE(bufoff, gbase, voff) do { _Pragma("unroll") for (int _i = 0; _i < 2; ++_i) \
;         __builtin_amdgcn_global_load_lds((const unsigned*)((const char*)(gbase) + (voff)[_i]), (LAS unsigned*)(lds + (bufoff) + ldsw + _i * 8192), 16, 0, 0); } while (0)
; #define PG8_LDA(dst, b, h) do { _Pragma("unroll") for (int m = 0; m < 4; ++m) _Pragma("unroll") for (int k = 0; k < 2; ++k) dst[m][k] = *(const LAS bf16x8*)(lds + PG8_SA(b, h) + aoff + m * 2048 + k * 1024); } while (0)
; #define PG8_LDB(dst, b, h) do { _Pragma("unroll") for (int n = 0; n < 2; ++n) _Pragma("unroll") for (int k = 0; k < 2; ++k) dst[n][k] = *(const LAS bf16x8*)(lds + PG8_SB(b, h) + boff + n * 2048 + k * 1024); } while (0)
; #define PG8_MMA(ai, bj, At, Bt) do { __builtin_amdgcn_s_setprio(1); _Pragma("unroll") for (int m = 0; m < 4; ++m) _Pragma("unroll") for (int n = 0; n < 2; ++n) _Pragma("unroll") for (int k = 0; k < 2; ++k) \
;         acc[ai][bj][m][n] = __builtin_amdgcn_mfma_f32_16x16x32_bf16(Bt[n][k], At[m][k], acc[ai][bj][m][n], 0, 0, 0); __builtin_amdgcn_s_setprio(0); } while (0)
; #define PG8_WAIT_V(n) asm volatile("s_waitcnt vmcnt(" #n ")" ::: "memory")
; #define PG8_BAR __builtin_amdgcn_s_barrier()
; #define PG8_SCHED __builtin_amdgcn_sched_barrier(0)
; template <class Epi>
; DI void gemm_phase(LAS unsigned char* lds, int wid, int K, int lda, int ldb, bool bperm, const Sched3& S, const Epi& E) {
;     ...
;             PG8_STAGE(PG8_SB(0, 1), b2 + hstepB, voffB);
;             PG8_WAIT_V(6); PG8_BAR; if (full) PG8_MMA(1, 1, At, B1); PG8_BAR;
;             PG8_LDB(B0, 1, 0); PG8_SCHED; PG8_LDA(At, 1, 0); PG8_STAGE(PG8_SA(0, 1), a2 + h2, voffA);
	s_add_i32 m0, s60, 0x2000
	s_nop 0
	global_load_lds_dwordx4 v128, s[58:59]
	s_waitcnt vmcnt(6)
	s_barrier
	s_setprio 1
	v_mfma_f32_16x16x32_bf16 v[52:55], v[196:199], v[164:167], 0
	v_mfma_f32_16x16x32_bf16 v[44:47], v[204:207], v[164:167], 0
	v_mfma_f32_16x16x32_bf16 v[36:39], v[196:199], v[172:175], 0
	v_mfma_f32_16x16x32_bf16 v[28:31], v[204:207], v[172:175], 0
	v_mfma_f32_16x16x32_bf16 v[20:23], v[196:199], v[180:183], 0
	v_mfma_f32_16x16x32_bf16 v[12:15], v[204:207], v[180:183], 0
	v_mfma_f32_16x16x32_bf16 v[4:7], v[196:199], v[188:191], 0
	v_mfma_f32_16x16x32_bf16 v[0:3], v[204:207], v[188:191], 0
	v_mfma_f32_16x16x32_bf16 v[52:55], v[200:203], v[168:171], v[52:55]
	v_mfma_f32_16x16x32_bf16 v[44:47], v[208:211], v[168:171], v[44:47]
	v_mfma_f32_16x16x32_bf16 v[36:39], v[200:203], v[176:179], v[36:39]
	v_mfma_f32_16x16x32_bf16 v[28:31], v[208:211], v[176:179], v[28:31]
	v_mfma_f32_16x16x32_bf16 v[20:23], v[200:203], v[184:187], v[20:23]
	v_mfma_f32_16x16x32_bf16 v[12:15], v[208:211], v[184:187], v[12:15]
	v_mfma_f32_16x16x32_bf16 v[4:7], v[200:203], v[192:195], v[4:7]
	v_mfma_f32_16x16x32_bf16 v[0:3], v[208:211], v[192:195], v[0:3]
	s_setprio 0
	s_add_i32 s58, 0, 0x18000
	v_add_u32_e32 v150, s58, v158
	s_barrier
	ds_read_b128 v[138:141], v150
	ds_read_b128 v[142:145], v150 offset:1024
	ds_read_b128 v[146:149], v150 offset:2048
	ds_read_b128 v[150:153], v150 offset:3072
	s_add_u32 s36, s36, 0x80000
	s_addc_u32 s37, s37, 0
	s_mov_b32 m0, s47

; #define PG8_STAGE(bufoff, gbase, voff) do { _Pragma("unroll") for (int _i = 0; _i < 2; ++_i) \
;         __builtin_amdgcn_global_load_lds((const unsigned*)((const char*)(gbase) + (voff)[_i]), (LAS unsigned*)(lds + (bufoff) + ldsw + _i * 8192), 16, 0, 0); } while (0)
; #define PG8_LDA(dst, b, h) do { _Pragma("unroll") for (int m = 0; m < 4; ++m) _Pragma("unroll") for (int k = 0; k < 2; ++k) dst[m][k] = *(const LAS bf16x8*)(lds + PG8_SA(b, h) + aoff + m * 2048 + k * 1024); } while (0)
; #define PG8_LDB(dst, b, h) do { _Pragma("unroll") for (int n = 0; n < 2; ++n) _Pragma("unroll") for (int k = 0; k < 2; ++k) dst[n][k] = *(const LAS bf16x8*)(lds + PG8_SB(b, h) + boff + n * 2048 + k * 1024); } while (0)
; #define PG8_SCHED __builtin_amdgcn_sched_barrier(0)
; template <class Epi>
; DI void gemm_phase(LAS unsigned char* lds, int wid, int K, int lda, int ldb, bool bperm, const Sched3& S, const Epi& E) {
;     ...
;             PG8_LDB(B0, 1, 0); PG8_SCHED; PG8_LDA(At, 1, 0); PG8_STAGE(PG8_SA(0, 1), a2 + h2, voffA);
	ds_read_b128 v[164:167], v161 offset:32768
	ds_read_b128 v[168:171], v161 offset:33792
	ds_read_b128 v[172:175], v161 offset:34816
	ds_read_b128 v[176:179], v161 offset:35840
	ds_read_b128 v[180:183], v161 offset:36864
	ds_read_b128 v[184:187], v161 offset:37888
	ds_read_b128 v[188:191], v161 offset:38912
	ds_read_b128 v[192:195], v161 offset:39936
	global_load_lds_dwordx4 v130, s[36:37]

; #define PG8_STAGE(bufoff, gbase, voff) do { _Pragma("unroll") for (int _i = 0; _i < 2; ++_i) \
;         __builtin_amdgcn_global_load_lds((const unsigned*)((const char*)(gbase) + (voff)[_i]), (LAS unsigned*)(lds + (bufoff) + ldsw + _i * 8192), 16, 0, 0); } while (0)
; #define PG8_LDA(dst, b, h) do { _Pragma("unroll") for (int m = 0; m < 4; ++m) _Pragma("unroll") for (int k = 0; k < 2; ++k) dst[m][k] = *(const LAS bf16x8*)(lds + PG8_SA(b, h) + aoff + m * 2048 + k * 1024); } while (0)
; #define PG8_LDB(dst, b, h) do { _Pragma("unroll") for (int n = 0; n < 2; ++n) _Pragma("unroll") for (int k = 0; k < 2; ++k) dst[n][k] = *(const LAS bf16x8*)(lds + PG8_SB(b, h) + boff + n * 2048 + k * 1024); } while (0)
; #define PG8_MMA(ai, bj, At, Bt) do { __builtin_amdgcn_s_setprio(1); _Pragma("unroll") for (int m = 0; m < 4; ++m) _Pragma("unroll") for (int n = 0; n < 2; ++n) _Pragma("unroll") for (int k = 0; k < 2; ++k) \
;         acc[ai][bj][m][n] = __builtin_amdgcn_mfma_f32_16x16x32_bf16(Bt[n][k], At[m][k], acc[ai][bj][m][n], 0, 0, 0); __builtin_amdgcn_s_setprio(0); } while (0)
; #define PG8_WAIT_L(n) asm volatile("s_waitcnt lgkmcnt(" #n ")" ::: "memory")
; #define PG8_BAR __builtin_amdgcn_s_barrier()
; #define PG8_SCHED __builtin_amdgcn_sched_barrier(0)
; template <class Epi>
; DI void gemm_phase(LAS unsigned char* lds, int wid, int K, int lda, int ldb, bool bperm, const Sched3& S, const Epi& E) {
;     ...
;             PG8_LDB(B0, 1, 0); PG8_SCHED; PG8_LDA(At, 1, 0); PG8_STAGE(PG8_SA(0, 1), a2 + h2, voffA);
;             PG8_WAIT_L(8); PG8_BAR; PG8_WAIT_L(0); PG8_MMA(0, 0, At, B0); PG8_BAR; PG8_SCHED;
;             PG8_LDB(B1, 1, 1); PG8_STAGE(PG8_SB(1, 0), b3, voffB);
	s_mov_b32 m0, s48
	s_nop 0
	global_load_lds_dwordx4 v128, s[36:37]
	s_waitcnt lgkmcnt(8)
	s_barrier
	s_waitcnt lgkmcnt(0)
	s_setprio 1
	s_waitcnt lgkmcnt(0)
	v_mfma_f32_16x16x32_bf16 v[124:127], v[138:141], v[164:167], v[124:127]
	v_mfma_f32_16x16x32_bf16 v[120:123], v[146:149], v[164:167], v[120:123]
	v_mfma_f32_16x16x32_bf16 v[116:119], v[138:141], v[172:175], v[116:119]
	v_mfma_f32_16x16x32_bf16 v[104:107], v[146:149], v[172:175], v[104:107]
	v_mfma_f32_16x16x32_bf16 v[96:99], v[138:141], v[180:183], v[96:99]
	v_mfma_f32_16x16x32_bf16 v[88:91], v[146:149], v[180:183], v[88:91]
	v_mfma_f32_16x16x32_bf16 v[80:83], v[138:141], v[188:191], v[80:83]
	v_mfma_f32_16x16x32_bf16 v[72:75], v[146:149], v[188:191], v[72:75]
	v_mfma_f32_16x16x32_bf16 v[124:127], v[142:145], v[168:171], v[124:127]
	v_mfma_f32_16x16x32_bf16 v[120:123], v[150:153], v[168:171], v[120:123]
	v_mfma_f32_16x16x32_bf16 v[116:119], v[142:145], v[176:179], v[116:119]
	v_mfma_f32_16x16x32_bf16 v[104:107], v[150:153], v[176:179], v[104:107]
	v_mfma_f32_16x16x32_bf16 v[96:99], v[142:145], v[184:187], v[96:99]
	v_mfma_f32_16x16x32_bf16 v[88:91], v[150:153], v[184:187], v[88:91]
	v_mfma_f32_16x16x32_bf16 v[80:83], v[142:145], v[192:195], v[80:83]
	v_mfma_f32_16x16x32_bf16 v[72:75], v[150:153], v[192:195], v[72:75]
	s_setprio 0
	s_barrier
	s_add_i32 s36, 0, 0x1c000
	s_add_i32 s37, s58, s43
	v_add_u32_e32 v154, s36, v158

; #define PG8_STAGE(bufoff, gbase, voff) do { _Pragma("unroll") for (int _i = 0; _i < 2; ++_i) \
;         __builtin_amdgcn_global_load_lds((const unsigned*)((const char*)(gbase) + (voff)[_i]), (LAS unsigned*)(lds + (bufoff) + ldsw + _i * 8192), 16, 0, 0); } while (0)
; #define PG8_LDB(dst, b, h) do { _Pragma("unroll") for (int n = 0; n < 2; ++n) _Pragma("unroll") for (int k = 0; k < 2; ++k) dst[n][k] = *(const LAS bf16x8*)(lds + PG8_SB(b, h) + boff + n * 2048 + k * 1024); } while (0)
; template <class Epi>
; DI void gemm_phase(LAS unsigned char* lds, int wid, int K, int lda, int ldb, bool bperm, const Sched3& S, const Epi& E) {
;     ...
;             PG8_LDB(B1, 1, 1); PG8_STAGE(PG8_SB(1, 0), b3, voffB);
	s_sub_i32 m0, s37, 0x80
	ds_read_b128 v[196:199], v154
	ds_read_b128 v[200:203], v154 offset:1024
	ds_read_b128 v[204:207], v154 offset:2048
	ds_read_b128 v[208:211], v154 offset:3072
	global_load_lds_dwordx4 v130, s[30:31] offset:128

; #define PG8_STAGE(bufoff, gbase, voff) do { _Pragma("unroll") for (int _i = 0; _i < 2; ++_i) \
;         __builtin_amdgcn_global_load_lds((const unsigned*)((const char*)(gbase) + (voff)[_i]), (LAS unsigned*)(lds + (bufoff) + ldsw + _i * 8192), 16, 0, 0); } while (0)
; #define PG8_LDA(dst, b, h) do { _Pragma("unroll") for (int m = 0; m < 4; ++m) _Pragma("unroll") for (int k = 0; k < 2; ++k) dst[m][k] = *(const LAS bf16x8*)(lds + PG8_SA(b, h) + aoff + m * 2048 + k * 1024); } while (0)
; #define PG8_LDB(dst, b, h) do { _Pragma("unroll") for (int n = 0; n < 2; ++n) _Pragma("unroll") for (int k = 0; k < 2; ++k) dst[n][k] = *(const LAS bf16x8*)(lds + PG8_SB(b, h) + boff + n * 2048 + k * 1024); } while (0)
; #define PG8_MMA(ai, bj, At, Bt) do { __builtin_amdgcn_s_setprio(1); _Pragma("unroll") for (int m = 0; m < 4; ++m) _Pragma("unroll") for (int n = 0; n < 2; ++n) _Pragma("unroll") for (int k = 0; k < 2; ++k) \
;         acc[ai][bj][m][n] = __builtin_amdgcn_mfma_f32_16x16x32_bf16(Bt[n][k], At[m][k], acc[ai][bj][m][n], 0, 0, 0); __builtin_amdgcn_s_setprio(0); } while (0)
; #define PG8_WAIT_L(n) asm volatile("s_waitcnt lgkmcnt(" #n ")" ::: "memory")
; #define PG8_BAR __builtin_amdgcn_s_barrier()
; template <class Epi>
; DI void gemm_phase(LAS unsigned char* lds, int wid, int K, int lda, int ldb, bool bperm, const Sched3& S, const Epi& E) {
;     ...
;             PG8_LDB(B1, 1, 1); PG8_STAGE(PG8_SB(1, 0), b3, voffB);
;             PG8_BAR; PG8_WAIT_L(0); PG8_MMA(0, 1, At, B1); PG8_BAR;
;             PG8_LDA(At, 1, 1); PG8_STAGE(PG8_SA(1, 0), a3, voffA);
	s_add_i32 m0, s37, 0x1f80
	s_nop 0
	global_load_lds_dwordx4 v128, s[30:31] offset:128
	s_barrier
	s_waitcnt lgkmcnt(0)
	s_setprio 1
	s_waitcnt lgkmcnt(0)
	v_mfma_f32_16x16x32_bf16 v[112:115], v[196:199], v[164:167], v[112:115]
	v_mfma_f32_16x16x32_bf16 v[108:111], v[204:207], v[164:167], v[108:111]
	v_mfma_f32_16x16x32_bf16 v[100:103], v[196:199], v[172:175], v[100:103]
	v_mfma_f32_16x16x32_bf16 v[92:95], v[204:207], v[172:175], v[92:95]
	v_mfma_f32_16x16x32_bf16 v[84:87], v[196:199], v[180:183], v[84:87]
	v_mfma_f32_16x16x32_bf16 v[76:79], v[204:207], v[180:183], v[76:79]
	v_mfma_f32_16x16x32_bf16 v[68:71], v[196:199], v[188:191], v[68:71]
	v_mfma_f32_16x16x32_bf16 v[64:67], v[204:207], v[188:191], v[64:67]
	v_mfma_f32_16x16x32_bf16 v[112:115], v[200:203], v[168:171], v[112:115]
	v_mfma_f32_16x16x32_bf16 v[108:111], v[208:211], v[168:171], v[108:111]
	v_mfma_f32_16x16x32_bf16 v[100:103], v[200:203], v[176:179], v[100:103]
	v_mfma_f32_16x16x32_bf16 v[92:95], v[208:211], v[176:179], v[92:95]
	v_mfma_f32_16x16x32_bf16 v[84:87], v[200:203], v[184:187], v[84:87]
	v_mfma_f32_16x16x32_bf16 v[76:79], v[208:211], v[184:187], v[76:79]
	v_mfma_f32_16x16x32_bf16 v[68:71], v[200:203], v[192:195], v[68:71]
	v_mfma_f32_16x16x32_bf16 v[64:67], v[208:211], v[192:195], v[64:67]
	s_setprio 0
	s_sub_i32 m0, s49, 0x80

; #define PG8_STAGE(bufoff, gbase, voff) do { _Pragma("unroll") for (int _i = 0; _i < 2; ++_i) \
;         __builtin_amdgcn_global_load_lds((const unsigned*)((const char*)(gbase) + (voff)[_i]), (LAS unsigned*)(lds + (bufoff) + ldsw + _i * 8192), 16, 0, 0); } while (0)
; #define PG8_LDA(dst, b, h) do { _Pragma("unroll") for (int m = 0; m < 4; ++m) _Pragma("unroll") for (int k = 0; k < 2; ++k) dst[m][k] = *(const LAS bf16x8*)(lds + PG8_SA(b, h) + aoff + m * 2048 + k * 1024); } while (0)
; template <class Epi>
; DI void gemm_phase(LAS unsigned char* lds, int wid, int K, int lda, int ldb, bool bperm, const Sched3& S, const Epi& E) {
;     ...
;             PG8_LDA(At, 1, 1); PG8_STAGE(PG8_SA(1, 0), a3, voffA);
	s_barrier
	ds_read_b128 v[164:167], v161 offset:49152
	ds_read_b128 v[168:171], v161 offset:50176
	ds_read_b128 v[172:175], v161 offset:51200
	ds_read_b128 v[176:179], v161 offset:52224
	ds_read_b128 v[180:183], v161 offset:53248
	ds_read_b128 v[184:187], v161 offset:54272
	ds_read_b128 v[188:191], v161 offset:55296
	ds_read_b128 v[192:195], v161 offset:56320
	global_load_lds_dwordx4 v130, s[100:101] offset:128

; #define PG8_STAGE(bufoff, gbase, voff) do { _Pragma("unroll") for (int _i = 0; _i < 2; ++_i) \
;         __builtin_amdgcn_global_load_lds((const unsigned*)((const char*)(gbase) + (voff)[_i]), (LAS unsigned*)(lds + (bufoff) + ldsw + _i * 8192), 16, 0, 0); } while (0)
; #define PG8_LDA(dst, b, h) do { _Pragma("unroll") for (int m = 0; m < 4; ++m) _Pragma("unroll") for (int k = 0; k < 2; ++k) dst[m][k] = *(const LAS bf16x8*)(lds + PG8_SA(b, h) + aoff + m * 2048 + k * 1024); } while (0)
; #define PG8_MMA(ai, bj, At, Bt) do { __builtin_amdgcn_s_setprio(1); _Pragma("unroll") for (int m = 0; m < 4; ++m) _Pragma("unroll") for (int n = 0; n < 2; ++n) _Pragma("unroll") for (int k = 0; k < 2; ++k) \
;         acc[ai][bj][m][n] = __builtin_amdgcn_mfma_f32_16x16x32_bf16(Bt[n][k], At[m][k], acc[ai][bj][m][n], 0, 0, 0); __builtin_amdgcn_s_setprio(0); } while (0)
; #define PG8_WAIT_L(n) asm volatile("s_waitcnt lgkmcnt(" #n ")" ::: "memory")
; #define PG8_BAR __builtin_amdgcn_s_barrier()
; #define PG8_SCHED __builtin_amdgcn_sched_barrier(0)
; template <class Epi>
; DI void gemm_phase(LAS unsigned char* lds, int wid, int K, int lda, int ldb, bool bperm, const Sched3& S, const Epi& E) {
;     ...
;             PG8_LDA(At, 1, 1); PG8_STAGE(PG8_SA(1, 0), a3, voffA);
;             PG8_BAR; PG8_WAIT_L(0); if (full) PG8_MMA(1, 0, At, B0); PG8_BAR; PG8_SCHED;
;             PG8_STAGE(PG8_SB(1, 1), b3 + hstepB, voffB);
	s_sub_i32 m0, s50, 0x80
	s_nop 0
	global_load_lds_dwordx4 v128, s[100:101] offset:128
	s_barrier
	s_waitcnt lgkmcnt(0)
	s_setprio 1
	s_waitcnt lgkmcnt(0)
	v_mfma_f32_16x16x32_bf16 v[60:63], v[138:141], v[164:167], v[60:63]
	v_mfma_f32_16x16x32_bf16 v[56:59], v[146:149], v[164:167], v[56:59]
	v_mfma_f32_16x16x32_bf16 v[48:51], v[138:141], v[172:175], v[48:51]
	v_mfma_f32_16x16x32_bf16 v[40:43], v[146:149], v[172:175], v[40:43]
	v_mfma_f32_16x16x32_bf16 v[32:35], v[138:141], v[180:183], v[32:35]
	v_mfma_f32_16x16x32_bf16 v[24:27], v[146:149], v[180:183], v[24:27]
	v_mfma_f32_16x16x32_bf16 v[16:19], v[138:141], v[188:191], v[16:19]
	v_mfma_f32_16x16x32_bf16 v[8:11], v[146:149], v[188:191], v[8:11]
	v_mfma_f32_16x16x32_bf16 v[60:63], v[142:145], v[168:171], v[60:63]
	v_mfma_f32_16x16x32_bf16 v[56:59], v[150:153], v[168:171], v[56:59]
	v_mfma_f32_16x16x32_bf16 v[48:51], v[142:145], v[176:179], v[48:51]
	v_mfma_f32_16x16x32_bf16 v[40:43], v[150:153], v[176:179], v[40:43]
	v_mfma_f32_16x16x32_bf16 v[32:35], v[142:145], v[184:187], v[32:35]
	v_mfma_f32_16x16x32_bf16 v[24:27], v[150:153], v[184:187], v[24:27]
	v_mfma_f32_16x16x32_bf16 v[16:19], v[142:145], v[192:195], v[16:19]
	v_mfma_f32_16x16x32_bf16 v[8:11], v[150:153], v[192:195], v[8:11]
	s_setprio 0
	s_barrier
	s_add_u32 s30, s30, 0x80080
	s_addc_u32 s31, s31, 0
	s_add_i32 s36, s36, s43

; #define PG8_STAGE(bufoff, gbase, voff) do { _Pragma("unroll") for (int _i = 0; _i < 2; ++_i) \
;         __builtin_amdgcn_global_load_lds((const unsigned*)((const char*)(gbase) + (voff)[_i]), (LAS unsigned*)(lds + (bufoff) + ldsw + _i * 8192), 16, 0, 0); } while (0)
; template <class Epi>
; DI void gemm_phase(LAS unsigned char* lds, int wid, int K, int lda, int ldb, bool bperm, const Sched3& S, const Epi& E) {
;     ...
;             PG8_STAGE(PG8_SB(1, 1), b3 + hstepB, voffB);
	s_mov_b32 m0, s36
	s_nop 0
	global_load_lds_dwordx4 v130, s[30:31]

; #define PG8_STAGE(bufoff, gbase, voff) do { _Pragma("unroll") for (int _i = 0; _i < 2; ++_i) \
;         __builtin_amdgcn_global_load_lds((const unsigned*)((const char*)(gbase) + (voff)[_i]), (LAS unsigned*)(lds + (bufoff) + ldsw + _i * 8192), 16, 0, 0); } while (0)
; #define PG8_LDA(dst, b, h) do { _Pragma("unroll") for (int m = 0; m < 4; ++m) _Pragma("unroll") for (int k = 0; k < 2; ++k) dst[m][k] = *(const LAS bf16x8*)(lds + PG8_SA(b, h) + aoff + m * 2048 + k * 1024); } while (0)
; #define PG8_LDB(dst, b, h) do { _Pragma("unroll") for (int n = 0; n < 2; ++n) _Pragma("unroll") for (int k = 0; k < 2; ++k) dst[n][k] = *(const LAS bf16x8*)(lds + PG8_SB(b, h) + boff + n * 2048 + k * 1024); } while (0)
; #define PG8_MMA(ai, bj, At, Bt) do { __builtin_amdgcn_s_setprio(1); _Pragma("unroll") for (int m = 0; m < 4; ++m) _Pragma("unroll") for (int n = 0; n < 2; ++n) _Pragma("unroll") for (int k = 0; k < 2; ++k) \
;         acc[ai][bj][m][n] = __builtin_amdgcn_mfma_f32_16x16x32_bf16(Bt[n][k], At[m][k], acc[ai][bj][m][n], 0, 0, 0); __builtin_amdgcn_s_setprio(0); } while (0)
; #define PG8_WAIT_V(n) asm volatile("s_waitcnt vmcnt(" #n ")" ::: "memory")
; #define PG8_BAR __builtin_amdgcn_s_barrier()
; #define PG8_SCHED __builtin_amdgcn_sched_barrier(0)
; template <class Epi>
; DI void gemm_phase(LAS unsigned char* lds, int wid, int K, int lda, int ldb, bool bperm, const Sched3& S, const Epi& E) {
;     ...
;             const bool last = (t == nt - 2);
;             const char* a1 = cA + (size_t)(t + 1) * kstep;
;             const char* a2 = last ? nA : cA + (size_t)(t + 2) * kstep; const char* b2 = last ? nB : cB + (size_t)(t + 2) * kstep;
;             const char* a3 = a2 + kstep; const char* b3 = b2 + kstep; const size_t h2 = last ? nhA : hA;
;             PG8_LDB(B0, 0, 0); PG8_SCHED; PG8_LDA(At, 0, 0); PG8_STAGE(PG8_SA(1, 1), a1 + hA, voffA);
;     ...
;             PG8_STAGE(PG8_SB(1, 1), b3 + hstepB, voffB);
;             PG8_WAIT_V(6); PG8_BAR; if (full) PG8_MMA(1, 1, At, B1); PG8_BAR;
	s_add_i32 m0, s36, 0x2000
	s_nop 0
	global_load_lds_dwordx4 v128, s[30:31]
	s_waitcnt vmcnt(6)
	s_barrier
	s_setprio 1
	v_mfma_f32_16x16x32_bf16 v[52:55], v[196:199], v[164:167], v[52:55]
	v_mfma_f32_16x16x32_bf16 v[44:47], v[204:207], v[164:167], v[44:47]
	v_mfma_f32_16x16x32_bf16 v[36:39], v[196:199], v[172:175], v[36:39]
	v_mfma_f32_16x16x32_bf16 v[28:31], v[204:207], v[172:175], v[28:31]
	v_mfma_f32_16x16x32_bf16 v[20:23], v[196:199], v[180:183], v[20:23]
	v_mfma_f32_16x16x32_bf16 v[12:15], v[204:207], v[180:183], v[12:15]
	v_mfma_f32_16x16x32_bf16 v[4:7], v[196:199], v[188:191], v[4:7]
	v_mfma_f32_16x16x32_bf16 v[0:3], v[204:207], v[188:191], v[0:3]
	v_mfma_f32_16x16x32_bf16 v[52:55], v[200:203], v[168:171], v[52:55]
	v_mfma_f32_16x16x32_bf16 v[44:47], v[208:211], v[168:171], v[44:47]
	v_mfma_f32_16x16x32_bf16 v[36:39], v[200:203], v[176:179], v[36:39]
	v_mfma_f32_16x16x32_bf16 v[28:31], v[208:211], v[176:179], v[28:31]
	v_mfma_f32_16x16x32_bf16 v[20:23], v[200:203], v[184:187], v[20:23]
	v_mfma_f32_16x16x32_bf16 v[12:15], v[208:211], v[184:187], v[12:15]
	v_mfma_f32_16x16x32_bf16 v[4:7], v[200:203], v[192:195], v[4:7]
	v_mfma_f32_16x16x32_bf16 v[0:3], v[208:211], v[192:195], v[0:3]
	s_setprio 0
	s_add_i32 s57, s57, 2
	s_add_u32 s28, s28, 0x100
	s_addc_u32 s29, s29, 0
	s_add_u32 s15, s15, 0x100
	s_addc_u32 s17, s17, 0
	s_cmp_gt_u32 s57, 29
	s_barrier
	s_cbranch_scc0 .LBB0_705
	s_branch .Lpeel_2_exit
.LBB0_705:
	ds_read_b128 v[138:141], v160
	ds_read_b128 v[142:145], v160 offset:1024
	ds_read_b128 v[146:149], v160 offset:2048
	ds_read_b128 v[150:153], v160 offset:3072
	s_add_u32 s30, s28, 0xfff80080
	s_addc_u32 s31, s29, -1
	s_cmp_eq_u32 s57, 28
	s_cselect_b32 s37, s25, s31
	s_cselect_b32 s36, s24, s30
	s_cselect_b32 s31, s27, s17
	s_cselect_b32 s30, s26, s15

; #define PG8_STAGE(bufoff, gbase, voff) do { _Pragma("unroll") for (int _i = 0; _i < 2; ++_i) \
;         __builtin_amdgcn_global_load_lds((const unsigned*)((const char*)(gbase) + (voff)[_i]), (LAS unsigned*)(lds + (bufoff) + ldsw + _i * 8192), 16, 0, 0); } while (0)
; #define PG8_LDA(dst, b, h) do { _Pragma("unroll") for (int m = 0; m < 4; ++m) _Pragma("unroll") for (int k = 0; k < 2; ++k) dst[m][k] = *(const LAS bf16x8*)(lds + PG8_SA(b, h) + aoff + m * 2048 + k * 1024); } while (0)
; #define PG8_LDB(dst, b, h) do { _Pragma("unroll") for (int n = 0; n < 2; ++n) _Pragma("unroll") for (int k = 0; k < 2; ++k) dst[n][k] = *(const LAS bf16x8*)(lds + PG8_SB(b, h) + boff + n * 2048 + k * 1024); } while (0)
; #define PG8_SCHED __builtin_amdgcn_sched_barrier(0)
; template <class Epi>
; DI void gemm_phase(LAS unsigned char* lds, int wid, int K, int lda, int ldb, bool bperm, const Sched3& S, const Epi& E) {
;     ...
;             PG8_LDB(B0, 0, 0); PG8_SCHED; PG8_LDA(At, 0, 0); PG8_STAGE(PG8_SA(1, 1), a1 + hA, voffA);
	s_add_i32 m0, s23, 0xc000
	ds_read_b128 v[164:167], v161
	ds_read_b128 v[168:171], v161 offset:1024
	ds_read_b128 v[172:175], v161 offset:2048
	ds_read_b128 v[176:179], v161 offset:3072
	ds_read_b128 v[180:183], v161 offset:4096
	ds_read_b128 v[184:187], v161 offset:5120
	ds_read_b128 v[188:191], v161 offset:6144
	ds_read_b128 v[192:195], v161 offset:7168
	global_load_lds_dwordx4 v132, s[28:29]

; #define PG8_STAGE(bufoff, gbase, voff) do { _Pragma("unroll") for (int _i = 0; _i < 2; ++_i) \
;         __builtin_amdgcn_global_load_lds((const unsigned*)((const char*)(gbase) + (voff)[_i]), (LAS unsigned*)(lds + (bufoff) + ldsw + _i * 8192), 16, 0, 0); } while (0)
; #define PG8_LDA(dst, b, h) do { _Pragma("unroll") for (int m = 0; m < 4; ++m) _Pragma("unroll") for (int k = 0; k < 2; ++k) dst[m][k] = *(const LAS bf16x8*)(lds + PG8_SA(b, h) + aoff + m * 2048 + k * 1024); } while (0)
; #define PG8_LDB(dst, b, h) do { _Pragma("unroll") for (int n = 0; n < 2; ++n) _Pragma("unroll") for (int k = 0; k < 2; ++k) dst[n][k] = *(const LAS bf16x8*)(lds + PG8_SB(b, h) + boff + n * 2048 + k * 1024); } while (0)
; #define PG8_MMA(ai, bj, At, Bt) do { __builtin_amdgcn_s_setprio(1); _Pragma("unroll") for (int m = 0; m < 4; ++m) _Pragma("unroll") for (int n = 0; n < 2; ++n) _Pragma("unroll") for (int k = 0; k < 2; ++k) \
;         acc[ai][bj][m][n] = __builtin_amdgcn_mfma_f32_16x16x32_bf16(Bt[n][k], At[m][k], acc[ai][bj][m][n], 0, 0, 0); __builtin_amdgcn_s_setprio(0); } while (0)
; #define PG8_WAIT_L(n) asm volatile("s_waitcnt lgkmcnt(" #n ")" ::: "memory")
; #define PG8_BAR __builtin_amdgcn_s_barrier()
; #define PG8_SCHED __builtin_amdgcn_sched_barrier(0)
; template <class Epi>
; DI void gemm_phase(LAS unsigned char* lds, int wid, int K, int lda, int ldb, bool bperm, const Sched3& S, const Epi& E) {
;     ...
;             PG8_LDB(B0, 0, 0); PG8_SCHED; PG8_LDA(At, 0, 0); PG8_STAGE(PG8_SA(1, 1), a1 + hA, voffA);
;             PG8_WAIT_L(8); PG8_BAR; PG8_WAIT_L(0); PG8_MMA(0, 0, At, B0); PG8_BAR; PG8_SCHED;
	s_add_i32 m0, s23, 0xe000
	s_nop 0
	global_load_lds_dwordx4 v134, s[28:29]
	s_waitcnt lgkmcnt(8)
	s_barrier
	s_waitcnt lgkmcnt(0)
	s_setprio 1
	s_waitcnt lgkmcnt(0)
	v_mfma_f32_16x16x32_bf16 v[124:127], v[138:141], v[164:167], v[124:127]
	v_mfma_f32_16x16x32_bf16 v[120:123], v[146:149], v[164:167], v[120:123]
	v_mfma_f32_16x16x32_bf16 v[116:119], v[138:141], v[172:175], v[116:119]
	v_mfma_f32_16x16x32_bf16 v[104:107], v[146:149], v[172:175], v[104:107]
	v_mfma_f32_16x16x32_bf16 v[96:99], v[138:141], v[180:183], v[96:99]
	v_mfma_f32_16x16x32_bf16 v[88:91], v[146:149], v[180:183], v[88:91]
	v_mfma_f32_16x16x32_bf16 v[80:83], v[138:141], v[188:191], v[80:83]
	v_mfma_f32_16x16x32_bf16 v[72:75], v[146:149], v[188:191], v[72:75]
	v_mfma_f32_16x16x32_bf16 v[124:127], v[142:145], v[168:171], v[124:127]
	v_mfma_f32_16x16x32_bf16 v[120:123], v[150:153], v[168:171], v[120:123]
	v_mfma_f32_16x16x32_bf16 v[116:119], v[142:145], v[176:179], v[116:119]
	v_mfma_f32_16x16x32_bf16 v[104:107], v[150:153], v[176:179], v[104:107]
	v_mfma_f32_16x16x32_bf16 v[96:99], v[142:145], v[184:187], v[96:99]
	v_mfma_f32_16x16x32_bf16 v[88:91], v[150:153], v[184:187], v[88:91]
	v_mfma_f32_16x16x32_bf16 v[80:83], v[142:145], v[192:195], v[80:83]
	v_mfma_f32_16x16x32_bf16 v[72:75], v[150:153], v[192:195], v[72:75]
	s_setprio 0
	s_barrier
	s_add_i32 s58, s53, s43

; #define PG8_STAGE(bufoff, gbase, voff) do { _Pragma("unroll") for (int _i = 0; _i < 2; ++_i) \
;         __builtin_amdgcn_global_load_lds((const unsigned*)((const char*)(gbase) + (voff)[_i]), (LAS unsigned*)(lds + (bufoff) + ldsw + _i * 8192), 16, 0, 0); } while (0)
; #define PG8_LDB(dst, b, h) do { _Pragma("unroll") for (int n = 0; n < 2; ++n) _Pragma("unroll") for (int k = 0; k < 2; ++k) dst[n][k] = *(const LAS bf16x8*)(lds + PG8_SB(b, h) + boff + n * 2048 + k * 1024); } while (0)
; template <class Epi>
; DI void gemm_phase(LAS unsigned char* lds, int wid, int K, int lda, int ldb, bool bperm, const Sched3& S, const Epi& E) {
;     ...
;             PG8_LDB(B1, 0, 1); PG8_STAGE(PG8_SB(0, 0), b2, voffB);
	s_mov_b32 m0, s58
	ds_read_b128 v[196:199], v162
	ds_read_b128 v[200:203], v162 offset:1024
	ds_read_b128 v[204:207], v162 offset:2048
	ds_read_b128 v[208:211], v162 offset:3072
	global_load_lds_dwordx4 v130, s[30:31]

; #define PG8_STAGE(bufoff, gbase, voff) do { _Pragma("unroll") for (int _i = 0; _i < 2; ++_i) \
;         __builtin_amdgcn_global_load_lds((const unsigned*)((const char*)(gbase) + (voff)[_i]), (LAS unsigned*)(lds + (bufoff) + ldsw + _i * 8192), 16, 0, 0); } while (0)
; #define PG8_LDA(dst, b, h) do { _Pragma("unroll") for (int m = 0; m < 4; ++m) _Pragma("unroll") for (int k = 0; k < 2; ++k) dst[m][k] = *(const LAS bf16x8*)(lds + PG8_SA(b, h) + aoff + m * 2048 + k * 1024); } while (0)
; #define PG8_LDB(dst, b, h) do { _Pragma("unroll") for (int n = 0; n < 2; ++n) _Pragma("unroll") for (int k = 0; k < 2; ++k) dst[n][k] = *(const LAS bf16x8*)(lds + PG8_SB(b, h) + boff + n * 2048 + k * 1024); } while (0)
; #define PG8_MMA(ai, bj, At, Bt) do { __builtin_amdgcn_s_setprio(1); _Pragma("unroll") for (int m = 0; m < 4; ++m) _Pragma("unroll") for (int n = 0; n < 2; ++n) _Pragma("unroll") for (int k = 0; k < 2; ++k) \
;         acc[ai][bj][m][n] = __builtin_amdgcn_mfma_f32_16x16x32_bf16(Bt[n][k], At[m][k], acc[ai][bj][m][n], 0, 0, 0); __builtin_amdgcn_s_setprio(0); } while (0)
; #define PG8_WAIT_L(n) asm volatile("s_waitcnt lgkmcnt(" #n ")" ::: "memory")
; #define PG8_BAR __builtin_amdgcn_s_barrier()
; #define PG8_SCHED __builtin_amdgcn_sched_barrier(0)
; template <class Epi>
; DI void gemm_phase(LAS unsigned char* lds, int wid, int K, int lda, int ldb, bool bperm, const Sched3& S, const Epi& E) {
;     ...
;             PG8_LDB(B1, 0, 1); PG8_STAGE(PG8_SB(0, 0), b2, voffB);
;             PG8_BAR; PG8_WAIT_L(0); PG8_MMA(0, 1, At, B1); PG8_BAR;
;             PG8_LDA(At, 0, 1); PG8_STAGE(PG8_SA(0, 0), a2, voffA);
;             PG8_BAR; PG8_WAIT_L(0); if (full) PG8_MMA(1, 0, At, B0); PG8_BAR; PG8_SCHED;
	s_add_i32 m0, s58, 0x2000
	s_nop 0
	global_load_lds_dwordx4 v128, s[30:31]
	s_barrier
	s_waitcnt lgkmcnt(0)
	s_setprio 1
	s_waitcnt lgkmcnt(0)
	v_mfma_f32_16x16x32_bf16 v[112:115], v[196:199], v[164:167], v[112:115]
	v_mfma_f32_16x16x32_bf16 v[108:111], v[204:207], v[164:167], v[108:111]
	v_mfma_f32_16x16x32_bf16 v[100:103], v[196:199], v[172:175], v[100:103]
	v_mfma_f32_16x16x32_bf16 v[92:95], v[204:207], v[172:175], v[92:95]
	v_mfma_f32_16x16x32_bf16 v[84:87], v[196:199], v[180:183], v[84:87]
	v_mfma_f32_16x16x32_bf16 v[76:79], v[204:207], v[180:183], v[76:79]
	v_mfma_f32_16x16x32_bf16 v[68:71], v[196:199], v[188:191], v[68:71]
	v_mfma_f32_16x16x32_bf16 v[64:67], v[204:207], v[188:191], v[64:67]
	v_mfma_f32_16x16x32_bf16 v[112:115], v[200:203], v[168:171], v[112:115]
	v_mfma_f32_16x16x32_bf16 v[108:111], v[208:211], v[168:171], v[108:111]
	v_mfma_f32_16x16x32_bf16 v[100:103], v[200:203], v[176:179], v[100:103]
	v_mfma_f32_16x16x32_bf16 v[92:95], v[208:211], v[176:179], v[92:95]
	v_mfma_f32_16x16x32_bf16 v[84:87], v[200:203], v[184:187], v[84:87]
	v_mfma_f32_16x16x32_bf16 v[76:79], v[208:211], v[184:187], v[76:79]
	v_mfma_f32_16x16x32_bf16 v[68:71], v[200:203], v[192:195], v[68:71]
	v_mfma_f32_16x16x32_bf16 v[64:67], v[208:211], v[192:195], v[64:67]
	s_setprio 0
	s_mov_b32 m0, s23
	s_mov_b64 s[100:101], s[36:37]
	s_barrier
	ds_read_b128 v[164:167], v161 offset:16384
	ds_read_b128 v[168:171], v161 offset:17408
	ds_read_b128 v[172:175], v161 offset:18432
	ds_read_b128 v[176:179], v161 offset:19456
	ds_read_b128 v[180:183], v161 offset:20480
	ds_read_b128 v[184:187], v161 offset:21504
	ds_read_b128 v[188:191], v161 offset:22528
	ds_read_b128 v[192:195], v161 offset:23552
	global_load_lds_dwordx4 v130, s[36:37]
	s_mov_b64 s[100:101], s[36:37]
	s_mov_b32 m0, s46
	s_nop 0
	global_load_lds_dwordx4 v128, s[36:37]
	s_barrier
	s_waitcnt lgkmcnt(0)
	s_setprio 1
	s_waitcnt lgkmcnt(0)
	v_mfma_f32_16x16x32_bf16 v[60:63], v[138:141], v[164:167], v[60:63]
	v_mfma_f32_16x16x32_bf16 v[56:59], v[146:149], v[164:167], v[56:59]
	v_mfma_f32_16x16x32_bf16 v[48:51], v[138:141], v[172:175], v[48:51]
	v_mfma_f32_16x16x32_bf16 v[40:43], v[146:149], v[172:175], v[40:43]
	v_mfma_f32_16x16x32_bf16 v[32:35], v[138:141], v[180:183], v[32:35]
	v_mfma_f32_16x16x32_bf16 v[24:27], v[146:149], v[180:183], v[24:27]
	v_mfma_f32_16x16x32_bf16 v[16:19], v[138:141], v[188:191], v[16:19]
	v_mfma_f32_16x16x32_bf16 v[8:11], v[146:149], v[188:191], v[8:11]
	v_mfma_f32_16x16x32_bf16 v[60:63], v[142:145], v[168:171], v[60:63]
	v_mfma_f32_16x16x32_bf16 v[56:59], v[150:153], v[168:171], v[56:59]
	v_mfma_f32_16x16x32_bf16 v[48:51], v[142:145], v[176:179], v[48:51]
	v_mfma_f32_16x16x32_bf16 v[40:43], v[150:153], v[176:179], v[40:43]
	v_mfma_f32_16x16x32_bf16 v[32:35], v[142:145], v[184:187], v[32:35]
	v_mfma_f32_16x16x32_bf16 v[24:27], v[150:153], v[184:187], v[24:27]
	v_mfma_f32_16x16x32_bf16 v[16:19], v[142:145], v[192:195], v[16:19]
	v_mfma_f32_16x16x32_bf16 v[8:11], v[150:153], v[192:195], v[8:11]
	s_setprio 0
	s_barrier
	s_add_u32 s58, s30, 0x80000
	s_addc_u32 s59, s31, 0
	s_add_i32 s60, s54, s43

; #define PG8_STAGE(bufoff, gbase, voff) do { _Pragma("unroll") for (int _i = 0; _i < 2; ++_i) \
;         __builtin_amdgcn_global_load_lds((const unsigned*)((const char*)(gbase) + (voff)[_i]), (LAS unsigned*)(lds + (bufoff) + ldsw + _i * 8192), 16, 0, 0); } while (0)
; template <class Epi>
; DI void gemm_phase(LAS unsigned char* lds, int wid, int K, int lda, int ldb, bool bperm, const Sched3& S, const Epi& E) {
;     ...
;             PG8_STAGE(PG8_SB(0, 1), b2 + hstepB, voffB);
	s_mov_b32 m0, s60
	s_nop 0
	global_load_lds_dwordx4 v130, s[58:59]

; #define PG8_STAGE(bufoff, gbase, voff) do { _Pragma("unroll") for (int _i = 0; _i < 2; ++_i) \
;         __builtin_amdgcn_global_load_lds((const unsigned*)((const char*)(gbase) + (voff)[_i]), (LAS unsigned*)(lds + (bufoff) + ldsw + _i * 8192), 16, 0, 0); } while (0)
; #define PG8_LDA(dst, b, h) do { _Pragma("unroll") for (int m = 0; m < 4; ++m) _Pragma("unroll") for (int k = 0; k < 2; ++k) dst[m][k] = *(const LAS bf16x8*)(lds + PG8_SA(b, h) + aoff + m * 2048 + k * 1024); } while (0)
; #define PG8_LDB(dst, b, h) do { _Pragma("unroll") for (int n = 0; n < 2; ++n) _Pragma("unroll") for (int k = 0; k < 2; ++k) dst[n][k] = *(const LAS bf16x8*)(lds + PG8_SB(b, h) + boff + n * 2048 + k * 1024); } while (0)
; #define PG8_MMA(ai, bj, At, Bt) do { __builtin_amdgcn_s_setprio(1); _Pragma("unroll") for (int m = 0; m < 4; ++m) _Pragma("unroll") for (int n = 0; n < 2; ++n) _Pragma("unroll") for (int k = 0; k < 2; ++k) \
;         acc[ai][bj][m][n] = __builtin_amdgcn_mfma_f32_16x16x32_bf16(Bt[n][k], At[m][k], acc[ai][bj][m][n], 0, 0, 0); __builtin_amdgcn_s_setprio(0); } while (0)
; #define PG8_WAIT_V(n) asm volatile("s_waitcnt vmcnt(" #n ")" ::: "memory")
; #define PG8_BAR __builtin_amdgcn_s_barrier()
; #define PG8_SCHED __builtin_amdgcn_sched_barrier(0)
; template <class Epi>
; DI void gemm_phase(LAS unsigned char* lds, int wid, int K, int lda, int ldb, bool bperm, const Sched3& S, const Epi& E) {
;     ...
;             PG8_STAGE(PG8_SB(0, 1), b2 + hstepB, voffB);
;             PG8_WAIT_V(6); PG8_BAR; if (full) PG8_MMA(1, 1, At, B1); PG8_BAR;
;             PG8_LDB(B0, 1, 0); PG8_SCHED; PG8_LDA(At, 1, 0); PG8_STAGE(PG8_SA(0, 1), a2 + h2, voffA);
	s_add_i32 m0, s60, 0x2000
	s_nop 0
	global_load_lds_dwordx4 v128, s[58:59]
	s_waitcnt vmcnt(6)
	s_barrier
	s_setprio 1
	v_mfma_f32_16x16x32_bf16 v[52:55], v[196:199], v[164:167], v[52:55]
	v_mfma_f32_16x16x32_bf16 v[44:47], v[204:207], v[164:167], v[44:47]
	v_mfma_f32_16x16x32_bf16 v[36:39], v[196:199], v[172:175], v[36:39]
	v_mfma_f32_16x16x32_bf16 v[28:31], v[204:207], v[172:175], v[28:31]
	v_mfma_f32_16x16x32_bf16 v[20:23], v[196:199], v[180:183], v[20:23]
	v_mfma_f32_16x16x32_bf16 v[12:15], v[204:207], v[180:183], v[12:15]
	v_mfma_f32_16x16x32_bf16 v[4:7], v[196:199], v[188:191], v[4:7]
	v_mfma_f32_16x16x32_bf16 v[0:3], v[204:207], v[188:191], v[0:3]
	v_mfma_f32_16x16x32_bf16 v[52:55], v[200:203], v[168:171], v[52:55]
	v_mfma_f32_16x16x32_bf16 v[44:47], v[208:211], v[168:171], v[44:47]
	v_mfma_f32_16x16x32_bf16 v[36:39], v[200:203], v[176:179], v[36:39]
	v_mfma_f32_16x16x32_bf16 v[28:31], v[208:211], v[176:179], v[28:31]
	v_mfma_f32_16x16x32_bf16 v[20:23], v[200:203], v[184:187], v[20:23]
	v_mfma_f32_16x16x32_bf16 v[12:15], v[208:211], v[184:187], v[12:15]
	v_mfma_f32_16x16x32_bf16 v[4:7], v[200:203], v[192:195], v[4:7]
	v_mfma_f32_16x16x32_bf16 v[0:3], v[208:211], v[192:195], v[0:3]
	s_setprio 0
	s_add_i32 s58, 0, 0x18000
	v_add_u32_e32 v150, s58, v158
	s_barrier
	ds_read_b128 v[138:141], v150
	ds_read_b128 v[142:145], v150 offset:1024
	ds_read_b128 v[146:149], v150 offset:2048
	ds_read_b128 v[150:153], v150 offset:3072
	s_add_u32 s36, s36, 0x80000
	s_addc_u32 s37, s37, 0
	s_mov_b32 m0, s47

; #define PG8_STAGE(bufoff, gbase, voff) do { _Pragma("unroll") for (int _i = 0; _i < 2; ++_i) \
;         __builtin_amdgcn_global_load_lds((const unsigned*)((const char*)(gbase) + (voff)[_i]), (LAS unsigned*)(lds + (bufoff) + ldsw + _i * 8192), 16, 0, 0); } while (0)
; #define PG8_LDA(dst, b, h) do { _Pragma("unroll") for (int m = 0; m < 4; ++m) _Pragma("unroll") for (int k = 0; k < 2; ++k) dst[m][k] = *(const LAS bf16x8*)(lds + PG8_SA(b, h) + aoff + m * 2048 + k * 1024); } while (0)
; #define PG8_LDB(dst, b, h) do { _Pragma("unroll") for (int n = 0; n < 2; ++n) _Pragma("unroll") for (int k = 0; k < 2; ++k) dst[n][k] = *(const LAS bf16x8*)(lds + PG8_SB(b, h) + boff + n * 2048 + k * 1024); } while (0)
; #define PG8_SCHED __builtin_amdgcn_sched_barrier(0)
; template <class Epi>
; DI void gemm_phase(LAS unsigned char* lds, int wid, int K, int lda, int ldb, bool bperm, const Sched3& S, const Epi& E) {
;     ...
;             PG8_LDB(B0, 1, 0); PG8_SCHED; PG8_LDA(At, 1, 0); PG8_STAGE(PG8_SA(0, 1), a2 + h2, voffA);
	ds_read_b128 v[164:167], v161 offset:32768
	ds_read_b128 v[168:171], v161 offset:33792
	ds_read_b128 v[172:175], v161 offset:34816
	ds_read_b128 v[176:179], v161 offset:35840
	ds_read_b128 v[180:183], v161 offset:36864
	ds_read_b128 v[184:187], v161 offset:37888
	ds_read_b128 v[188:191], v161 offset:38912
	ds_read_b128 v[192:195], v161 offset:39936
	global_load_lds_dwordx4 v130, s[36:37]

; #define PG8_STAGE(bufoff, gbase, voff) do { _Pragma("unroll") for (int _i = 0; _i < 2; ++_i) \
;         __builtin_amdgcn_global_load_lds((const unsigned*)((const char*)(gbase) + (voff)[_i]), (LAS unsigned*)(lds + (bufoff) + ldsw + _i * 8192), 16, 0, 0); } while (0)
; #define PG8_LDA(dst, b, h) do { _Pragma("unroll") for (int m = 0; m < 4; ++m) _Pragma("unroll") for (int k = 0; k < 2; ++k) dst[m][k] = *(const LAS bf16x8*)(lds + PG8_SA(b, h) + aoff + m * 2048 + k * 1024); } while (0)
; #define PG8_LDB(dst, b, h) do { _Pragma("unroll") for (int n = 0; n < 2; ++n) _Pragma("unroll") for (int k = 0; k < 2; ++k) dst[n][k] = *(const LAS bf16x8*)(lds + PG8_SB(b, h) + boff + n * 2048 + k * 1024); } while (0)
; #define PG8_MMA(ai, bj, At, Bt) do { __builtin_amdgcn_s_setprio(1); _Pragma("unroll") for (int m = 0; m < 4; ++m) _Pragma("unroll") for (int n = 0; n < 2; ++n) _Pragma("unroll") for (int k = 0; k < 2; ++k) \
;         acc[ai][bj][m][n] = __builtin_amdgcn_mfma_f32_16x16x32_bf16(Bt[n][k], At[m][k], acc[ai][bj][m][n], 0, 0, 0); __builtin_amdgcn_s_setprio(0); } while (0)
; #define PG8_WAIT_L(n) asm volatile("s_waitcnt lgkmcnt(" #n ")" ::: "memory")
; #define PG8_BAR __builtin_amdgcn_s_barrier()
; #define PG8_SCHED __builtin_amdgcn_sched_barrier(0)
; template <class Epi>
; DI void gemm_phase(LAS unsigned char* lds, int wid, int K, int lda, int ldb, bool bperm, const Sched3& S, const Epi& E) {
;     ...
;             PG8_LDB(B0, 1, 0); PG8_SCHED; PG8_LDA(At, 1, 0); PG8_STAGE(PG8_SA(0, 1), a2 + h2, voffA);
;             PG8_WAIT_L(8); PG8_BAR; PG8_WAIT_L(0); PG8_MMA(0, 0, At, B0); PG8_BAR; PG8_SCHED;
;             PG8_LDB(B1, 1, 1); PG8_STAGE(PG8_SB(1, 0), b3, voffB);
	s_mov_b32 m0, s48
	s_nop 0
	global_load_lds_dwordx4 v128, s[36:37]
	s_waitcnt lgkmcnt(8)
	s_barrier
	s_waitcnt lgkmcnt(0)
	s_setprio 1
	s_waitcnt lgkmcnt(0)
	v_mfma_f32_16x16x32_bf16 v[124:127], v[138:141], v[164:167], v[124:127]
	v_mfma_f32_16x16x32_bf16 v[120:123], v[146:149], v[164:167], v[120:123]
	v_mfma_f32_16x16x32_bf16 v[116:119], v[138:141], v[172:175], v[116:119]
	v_mfma_f32_16x16x32_bf16 v[104:107], v[146:149], v[172:175], v[104:107]
	v_mfma_f32_16x16x32_bf16 v[96:99], v[138:141], v[180:183], v[96:99]
	v_mfma_f32_16x16x32_bf16 v[88:91], v[146:149], v[180:183], v[88:91]
	v_mfma_f32_16x16x32_bf16 v[80:83], v[138:141], v[188:191], v[80:83]
	v_mfma_f32_16x16x32_bf16 v[72:75], v[146:149], v[188:191], v[72:75]
	v_mfma_f32_16x16x32_bf16 v[124:127], v[142:145], v[168:171], v[124:127]
	v_mfma_f32_16x16x32_bf16 v[120:123], v[150:153], v[168:171], v[120:123]
	v_mfma_f32_16x16x32_bf16 v[116:119], v[142:145], v[176:179], v[116:119]
	v_mfma_f32_16x16x32_bf16 v[104:107], v[150:153], v[176:179], v[104:107]
	v_mfma_f32_16x16x32_bf16 v[96:99], v[142:145], v[184:187], v[96:99]
	v_mfma_f32_16x16x32_bf16 v[88:91], v[150:153], v[184:187], v[88:91]
	v_mfma_f32_16x16x32_bf16 v[80:83], v[142:145], v[192:195], v[80:83]
	v_mfma_f32_16x16x32_bf16 v[72:75], v[150:153], v[192:195], v[72:75]
	s_setprio 0
	s_barrier
	s_add_i32 s36, 0, 0x1c000
	s_add_i32 s37, s58, s43
	v_add_u32_e32 v154, s36, v158

; #define PG8_STAGE(bufoff, gbase, voff) do { _Pragma("unroll") for (int _i = 0; _i < 2; ++_i) \
;         __builtin_amdgcn_global_load_lds((const unsigned*)((const char*)(gbase) + (voff)[_i]), (LAS unsigned*)(lds + (bufoff) + ldsw + _i * 8192), 16, 0, 0); } while (0)
; #define PG8_LDB(dst, b, h) do { _Pragma("unroll") for (int n = 0; n < 2; ++n) _Pragma("unroll") for (int k = 0; k < 2; ++k) dst[n][k] = *(const LAS bf16x8*)(lds + PG8_SB(b, h) + boff + n * 2048 + k * 1024); } while (0)
; template <class Epi>
; DI void gemm_phase(LAS unsigned char* lds, int wid, int K, int lda, int ldb, bool bperm, const Sched3& S, const Epi& E) {
;     ...
;             PG8_LDB(B1, 1, 1); PG8_STAGE(PG8_SB(1, 0), b3, voffB);
	s_sub_i32 m0, s37, 0x80
	ds_read_b128 v[196:199], v154
	ds_read_b128 v[200:203], v154 offset:1024
	ds_read_b128 v[204:207], v154 offset:2048
	ds_read_b128 v[208:211], v154 offset:3072
	global_load_lds_dwordx4 v130, s[30:31] offset:128

; #define PG8_STAGE(bufoff, gbase, voff) do { _Pragma("unroll") for (int _i = 0; _i < 2; ++_i) \
;         __builtin_amdgcn_global_load_lds((const unsigned*)((const char*)(gbase) + (voff)[_i]), (LAS unsigned*)(lds + (bufoff) + ldsw + _i * 8192), 16, 0, 0); } while (0)
; #define PG8_LDA(dst, b, h) do { _Pragma("unroll") for (int m = 0; m < 4; ++m) _Pragma("unroll") for (int k = 0; k < 2; ++k) dst[m][k] = *(const LAS bf16x8*)(lds + PG8_SA(b, h) + aoff + m * 2048 + k * 1024); } while (0)
; #define PG8_LDB(dst, b, h) do { _Pragma("unroll") for (int n = 0; n < 2; ++n) _Pragma("unroll") for (int k = 0; k < 2; ++k) dst[n][k] = *(const LAS bf16x8*)(lds + PG8_SB(b, h) + boff + n * 2048 + k * 1024); } while (0)
; #define PG8_MMA(ai, bj, At, Bt) do { __builtin_amdgcn_s_setprio(1); _Pragma("unroll") for (int m = 0; m < 4; ++m) _Pragma("unroll") for (int n = 0; n < 2; ++n) _Pragma("unroll") for (int k = 0; k < 2; ++k) \
;         acc[ai][bj][m][n] = __builtin_amdgcn_mfma_f32_16x16x32_bf16(Bt[n][k], At[m][k], acc[ai][bj][m][n], 0, 0, 0); __builtin_amdgcn_s_setprio(0); } while (0)
; #define PG8_WAIT_L(n) asm volatile("s_waitcnt lgkmcnt(" #n ")" ::: "memory")
; #define PG8_BAR __builtin_amdgcn_s_barrier()
; template <class Epi>
; DI void gemm_phase(LAS unsigned char* lds, int wid, int K, int lda, int ldb, bool bperm, const Sched3& S, const Epi& E) {
;     ...
;             PG8_LDB(B1, 1, 1); PG8_STAGE(PG8_SB(1, 0), b3, voffB);
;             PG8_BAR; PG8_WAIT_L(0); PG8_MMA(0, 1, At, B1); PG8_BAR;
;             PG8_LDA(At, 1, 1); PG8_STAGE(PG8_SA(1, 0), a3, voffA);
	s_add_i32 m0, s37, 0x1f80
	s_nop 0
	global_load_lds_dwordx4 v128, s[30:31] offset:128
	s_barrier
	s_waitcnt lgkmcnt(0)
	s_setprio 1
	s_waitcnt lgkmcnt(0)
	v_mfma_f32_16x16x32_bf16 v[112:115], v[196:199], v[164:167], v[112:115]
	v_mfma_f32_16x16x32_bf16 v[108:111], v[204:207], v[164:167], v[108:111]
	v_mfma_f32_16x16x32_bf16 v[100:103], v[196:199], v[172:175], v[100:103]
	v_mfma_f32_16x16x32_bf16 v[92:95], v[204:207], v[172:175], v[92:95]
	v_mfma_f32_16x16x32_bf16 v[84:87], v[196:199], v[180:183], v[84:87]
	v_mfma_f32_16x16x32_bf16 v[76:79], v[204:207], v[180:183], v[76:79]
	v_mfma_f32_16x16x32_bf16 v[68:71], v[196:199], v[188:191], v[68:71]
	v_mfma_f32_16x16x32_bf16 v[64:67], v[204:207], v[188:191], v[64:67]
	v_mfma_f32_16x16x32_bf16 v[112:115], v[200:203], v[168:171], v[112:115]
	v_mfma_f32_16x16x32_bf16 v[108:111], v[208:211], v[168:171], v[108:111]
	v_mfma_f32_16x16x32_bf16 v[100:103], v[200:203], v[176:179], v[100:103]
	v_mfma_f32_16x16x32_bf16 v[92:95], v[208:211], v[176:179], v[92:95]
	v_mfma_f32_16x16x32_bf16 v[84:87], v[200:203], v[184:187], v[84:87]
	v_mfma_f32_16x16x32_bf16 v[76:79], v[208:211], v[184:187], v[76:79]
	v_mfma_f32_16x16x32_bf16 v[68:71], v[200:203], v[192:195], v[68:71]
	v_mfma_f32_16x16x32_bf16 v[64:67], v[208:211], v[192:195], v[64:67]
	s_setprio 0
	s_sub_i32 m0, s49, 0x80

; #define PG8_STAGE(bufoff, gbase, voff) do { _Pragma("unroll") for (int _i = 0; _i < 2; ++_i) \
;         __builtin_amdgcn_global_load_lds((const unsigned*)((const char*)(gbase) + (voff)[_i]), (LAS unsigned*)(lds + (bufoff) + ldsw + _i * 8192), 16, 0, 0); } while (0)
; #define PG8_LDA(dst, b, h) do { _Pragma("unroll") for (int m = 0; m < 4; ++m) _Pragma("unroll") for (int k = 0; k < 2; ++k) dst[m][k] = *(const LAS bf16x8*)(lds + PG8_SA(b, h) + aoff + m * 2048 + k * 1024); } while (0)
; template <class Epi>
; DI void gemm_phase(LAS unsigned char* lds, int wid, int K, int lda, int ldb, bool bperm, const Sched3& S, const Epi& E) {
;     ...
;             PG8_LDA(At, 1, 1); PG8_STAGE(PG8_SA(1, 0), a3, voffA);
	s_barrier
	ds_read_b128 v[164:167], v161 offset:49152
	ds_read_b128 v[168:171], v161 offset:50176
	ds_read_b128 v[172:175], v161 offset:51200
	ds_read_b128 v[176:179], v161 offset:52224
	ds_read_b128 v[180:183], v161 offset:53248
	ds_read_b128 v[184:187], v161 offset:54272
	ds_read_b128 v[188:191], v161 offset:55296
	ds_read_b128 v[192:195], v161 offset:56320
	global_load_lds_dwordx4 v130, s[100:101] offset:128

; #define PG8_STAGE(bufoff, gbase, voff) do { _Pragma("unroll") for (int _i = 0; _i < 2; ++_i) \
;         __builtin_amdgcn_global_load_lds((const unsigned*)((const char*)(gbase) + (voff)[_i]), (LAS unsigned*)(lds + (bufoff) + ldsw + _i * 8192), 16, 0, 0); } while (0)
; #define PG8_LDA(dst, b, h) do { _Pragma("unroll") for (int m = 0; m < 4; ++m) _Pragma("unroll") for (int k = 0; k < 2; ++k) dst[m][k] = *(const LAS bf16x8*)(lds + PG8_SA(b, h) + aoff + m * 2048 + k * 1024); } while (0)
; #define PG8_MMA(ai, bj, At, Bt) do { __builtin_amdgcn_s_setprio(1); _Pragma("unroll") for (int m = 0; m < 4; ++m) _Pragma("unroll") for (int n = 0; n < 2; ++n) _Pragma("unroll") for (int k = 0; k < 2; ++k) \
;         acc[ai][bj][m][n] = __builtin_amdgcn_mfma_f32_16x16x32_bf16(Bt[n][k], At[m][k], acc[ai][bj][m][n], 0, 0, 0); __builtin_amdgcn_s_setprio(0); } while (0)
; #define PG8_WAIT_L(n) asm volatile("s_waitcnt lgkmcnt(" #n ")" ::: "memory")
; #define PG8_BAR __builtin_amdgcn_s_barrier()
; #define PG8_SCHED __builtin_amdgcn_sched_barrier(0)
; template <class Epi>
; DI void gemm_phase(LAS unsigned char* lds, int wid, int K, int lda, int ldb, bool bperm, const Sched3& S, const Epi& E) {
;     ...
;             PG8_LDA(At, 1, 1); PG8_STAGE(PG8_SA(1, 0), a3, voffA);
;             PG8_BAR; PG8_WAIT_L(0); if (full) PG8_MMA(1, 0, At, B0); PG8_BAR; PG8_SCHED;
;             PG8_STAGE(PG8_SB(1, 1), b3 + hstepB, voffB);
	s_sub_i32 m0, s50, 0x80
	s_nop 0
	global_load_lds_dwordx4 v128, s[100:101] offset:128
	s_barrier
	s_waitcnt lgkmcnt(0)
	s_setprio 1
	s_waitcnt lgkmcnt(0)
	v_mfma_f32_16x16x32_bf16 v[60:63], v[138:141], v[164:167], v[60:63]
	v_mfma_f32_16x16x32_bf16 v[56:59], v[146:149], v[164:167], v[56:59]
	v_mfma_f32_16x16x32_bf16 v[48:51], v[138:141], v[172:175], v[48:51]
	v_mfma_f32_16x16x32_bf16 v[40:43], v[146:149], v[172:175], v[40:43]
	v_mfma_f32_16x16x32_bf16 v[32:35], v[138:141], v[180:183], v[32:35]
	v_mfma_f32_16x16x32_bf16 v[24:27], v[146:149], v[180:183], v[24:27]
	v_mfma_f32_16x16x32_bf16 v[16:19], v[138:141], v[188:191], v[16:19]
	v_mfma_f32_16x16x32_bf16 v[8:11], v[146:149], v[188:191], v[8:11]
	v_mfma_f32_16x16x32_bf16 v[60:63], v[142:145], v[168:171], v[60:63]
	v_mfma_f32_16x16x32_bf16 v[56:59], v[150:153], v[168:171], v[56:59]
	v_mfma_f32_16x16x32_bf16 v[48:51], v[142:145], v[176:179], v[48:51]
	v_mfma_f32_16x16x32_bf16 v[40:43], v[150:153], v[176:179], v[40:43]
	v_mfma_f32_16x16x32_bf16 v[32:35], v[142:145], v[184:187], v[32:35]
	v_mfma_f32_16x16x32_bf16 v[24:27], v[150:153], v[184:187], v[24:27]
	v_mfma_f32_16x16x32_bf16 v[16:19], v[142:145], v[192:195], v[16:19]
	v_mfma_f32_16x16x32_bf16 v[8:11], v[150:153], v[192:195], v[8:11]
	s_setprio 0
	s_barrier
	s_add_u32 s30, s30, 0x80080
	s_addc_u32 s31, s31, 0
	s_add_i32 s36, s36, s43

; #define PG8_STAGE(bufoff, gbase, voff) do { _Pragma("unroll") for (int _i = 0; _i < 2; ++_i) \
;         __builtin_amdgcn_global_load_lds((const unsigned*)((const char*)(gbase) + (voff)[_i]), (LAS unsigned*)(lds + (bufoff) + ldsw + _i * 8192), 16, 0, 0); } while (0)
; template <class Epi>
; DI void gemm_phase(LAS unsigned char* lds, int wid, int K, int lda, int ldb, bool bperm, const Sched3& S, const Epi& E) {
;     ...
;             PG8_STAGE(PG8_SB(1, 1), b3 + hstepB, voffB);
	s_mov_b32 m0, s36
	s_nop 0
	global_load_lds_dwordx4 v130, s[30:31]

; #define PG8_STAGE(bufoff, gbase, voff) do { _Pragma("unroll") for (int _i = 0; _i < 2; ++_i) \
;         __builtin_amdgcn_global_load_lds((const unsigned*)((const char*)(gbase) + (voff)[_i]), (LAS unsigned*)(lds + (bufoff) + ldsw + _i * 8192), 16, 0, 0); } while (0)
; #define PG8_MMA(ai, bj, At, Bt) do { __builtin_amdgcn_s_setprio(1); _Pragma("unroll") for (int m = 0; m < 4; ++m) _Pragma("unroll") for (int n = 0; n < 2; ++n) _Pragma("unroll") for (int k = 0; k < 2; ++k) \
;         acc[ai][bj][m][n] = __builtin_amdgcn_mfma_f32_16x16x32_bf16(Bt[n][k], At[m][k], acc[ai][bj][m][n], 0, 0, 0); __builtin_amdgcn_s_setprio(0); } while (0)
; #define PG8_WAIT_V(n) asm volatile("s_waitcnt vmcnt(" #n ")" ::: "memory")
; #define PG8_BAR __builtin_amdgcn_s_barrier()
; template <class Epi>
; DI void gemm_phase(LAS unsigned char* lds, int wid, int K, int lda, int ldb, bool bperm, const Sched3& S, const Epi& E) {
;     ...
;             PG8_STAGE(PG8_SB(1, 1), b3 + hstepB, voffB);
;             PG8_WAIT_V(6); PG8_BAR; if (full) PG8_MMA(1, 1, At, B1); PG8_BAR;
	s_add_i32 m0, s36, 0x2000
	s_nop 0
	global_load_lds_dwordx4 v128, s[30:31]
	s_waitcnt vmcnt(6)
	s_barrier
	s_setprio 1
	v_mfma_f32_16x16x32_bf16 v[52:55], v[196:199], v[164:167], v[52:55]
	v_mfma_f32_16x16x32_bf16 v[44:47], v[204:207], v[164:167], v[44:47]
	v_mfma_f32_16x16x32_bf16 v[36:39], v[196:199], v[172:175], v[36:39]
	v_mfma_f32_16x16x32_bf16 v[28:31], v[204:207], v[172:175], v[28:31]
	v_mfma_f32_16x16x32_bf16 v[20:23], v[196:199], v[180:183], v[20:23]
	v_mfma_f32_16x16x32_bf16 v[12:15], v[204:207], v[180:183], v[12:15]
	v_mfma_f32_16x16x32_bf16 v[4:7], v[196:199], v[188:191], v[4:7]
	v_mfma_f32_16x16x32_bf16 v[0:3], v[204:207], v[188:191], v[0:3]
	v_mfma_f32_16x16x32_bf16 v[52:55], v[200:203], v[168:171], v[52:55]
	v_mfma_f32_16x16x32_bf16 v[44:47], v[208:211], v[168:171], v[44:47]
	v_mfma_f32_16x16x32_bf16 v[36:39], v[200:203], v[176:179], v[36:39]
	v_mfma_f32_16x16x32_bf16 v[28:31], v[208:211], v[176:179], v[28:31]
	v_mfma_f32_16x16x32_bf16 v[20:23], v[200:203], v[184:187], v[20:23]
	v_mfma_f32_16x16x32_bf16 v[12:15], v[208:211], v[184:187], v[12:15]
	v_mfma_f32_16x16x32_bf16 v[4:7], v[200:203], v[192:195], v[4:7]
	v_mfma_f32_16x16x32_bf16 v[0:3], v[208:211], v[192:195], v[0:3]
	s_setprio 0
	s_add_i32 s57, s57, 2
	s_add_u32 s28, s28, 0x100
	s_addc_u32 s29, s29, 0
	s_add_u32 s15, s15, 0x100
	s_addc_u32 s17, s17, 0
	s_cmp_gt_u32 s57, 29
	s_barrier
	s_cbranch_scc0 .LBB0_705

; #define PG8_STAGE(bufoff, gbase, voff) do { _Pragma("unroll") for (int _i = 0; _i < 2; ++_i) \
;         __builtin_amdgcn_global_load_lds((const unsigned*)((const char*)(gbase) + (voff)[_i]), (LAS unsigned*)(lds + (bufoff) + ldsw + _i * 8192), 16, 0, 0); } while (0)
; #define PG8_LDA(dst, b, h) do { _Pragma("unroll") for (int m = 0; m < 4; ++m) _Pragma("unroll") for (int k = 0; k < 2; ++k) dst[m][k] = *(const LAS bf16x8*)(lds + PG8_SA(b, h) + aoff + m * 2048 + k * 1024); } while (0)
; #define PG8_LDB(dst, b, h) do { _Pragma("unroll") for (int n = 0; n < 2; ++n) _Pragma("unroll") for (int k = 0; k < 2; ++k) dst[n][k] = *(const LAS bf16x8*)(lds + PG8_SB(b, h) + boff + n * 2048 + k * 1024); } while (0)
; #define PG8_SCHED __builtin_amdgcn_sched_barrier(0)
; template <class Epi>
; DI void gemm_phase(LAS unsigned char* lds, int wid, int K, int lda, int ldb, bool bperm, const Sched3& S, const Epi& E) {
;     ...
;             const bool last = (t == nt - 2);
;             const char* a1 = cA + (size_t)(t + 1) * kstep;
;             const char* a2 = last ? nA : cA + (size_t)(t + 2) * kstep; const char* b2 = last ? nB : cB + (size_t)(t + 2) * kstep;
;             const char* a3 = a2 + kstep; const char* b3 = b2 + kstep; const size_t h2 = last ? nhA : hA;
;             PG8_LDB(B0, 0, 0); PG8_SCHED; PG8_LDA(At, 0, 0); PG8_STAGE(PG8_SA(1, 1), a1 + hA, voffA);
.LBB0_784:
	s_add_u32 s60, s28, 0x100
	s_nop 0
	s_addc_u32 s61, s29, 0
	s_mov_b32 s62, -2
	s_waitcnt lgkmcnt(0)
	ds_read_b128 v[128:131], v185
	ds_read_b128 v[132:135], v185 offset:1024
	ds_read_b128 v[136:139], v185 offset:2048
	ds_read_b128 v[140:143], v185 offset:3072
	s_add_u32 s28, s26, 0x100
	s_addc_u32 s29, s27, 0
	s_cmpk_eq_i32 s62, 0x54
	s_cselect_b32 s37, s23, s29
	s_cselect_b32 s36, s22, s28
	s_cselect_b32 s31, s25, s61
	s_cselect_b32 s30, s24, s60

; #define PG8_STAGE(bufoff, gbase, voff) do { _Pragma("unroll") for (int _i = 0; _i < 2; ++_i) \
;         __builtin_amdgcn_global_load_lds((const unsigned*)((const char*)(gbase) + (voff)[_i]), (LAS unsigned*)(lds + (bufoff) + ldsw + _i * 8192), 16, 0, 0); } while (0)
; #define PG8_LDA(dst, b, h) do { _Pragma("unroll") for (int m = 0; m < 4; ++m) _Pragma("unroll") for (int k = 0; k < 2; ++k) dst[m][k] = *(const LAS bf16x8*)(lds + PG8_SA(b, h) + aoff + m * 2048 + k * 1024); } while (0)
; #define PG8_LDB(dst, b, h) do { _Pragma("unroll") for (int n = 0; n < 2; ++n) _Pragma("unroll") for (int k = 0; k < 2; ++k) dst[n][k] = *(const LAS bf16x8*)(lds + PG8_SB(b, h) + boff + n * 2048 + k * 1024); } while (0)
; #define PG8_SCHED __builtin_amdgcn_sched_barrier(0)
; template <class Epi>
; DI void gemm_phase(LAS unsigned char* lds, int wid, int K, int lda, int ldb, bool bperm, const Sched3& S, const Epi& E) {
;     ...
;             PG8_LDB(B0, 0, 0); PG8_SCHED; PG8_LDA(At, 0, 0); PG8_STAGE(PG8_SA(1, 1), a1 + hA, voffA);
	s_add_i32 m0, s44, 0xc000
	ds_read_b128 v[144:147], v186
	ds_read_b128 v[148:151], v186 offset:1024
	ds_read_b128 v[162:165], v186 offset:2048
	ds_read_b128 v[166:169], v186 offset:3072
	ds_read_b128 v[170:173], v186 offset:4096
	ds_read_b128 v[174:177], v186 offset:5120
	ds_read_b128 v[188:191], v186 offset:6144
	ds_read_b128 v[192:195], v186 offset:7168
	global_load_lds_dwordx4 v156, s[26:27]

; #define PG8_STAGE(bufoff, gbase, voff) do { _Pragma("unroll") for (int _i = 0; _i < 2; ++_i) \
;         __builtin_amdgcn_global_load_lds((const unsigned*)((const char*)(gbase) + (voff)[_i]), (LAS unsigned*)(lds + (bufoff) + ldsw + _i * 8192), 16, 0, 0); } while (0)
; #define PG8_LDA(dst, b, h) do { _Pragma("unroll") for (int m = 0; m < 4; ++m) _Pragma("unroll") for (int k = 0; k < 2; ++k) dst[m][k] = *(const LAS bf16x8*)(lds + PG8_SA(b, h) + aoff + m * 2048 + k * 1024); } while (0)
; #define PG8_LDB(dst, b, h) do { _Pragma("unroll") for (int n = 0; n < 2; ++n) _Pragma("unroll") for (int k = 0; k < 2; ++k) dst[n][k] = *(const LAS bf16x8*)(lds + PG8_SB(b, h) + boff + n * 2048 + k * 1024); } while (0)
; #define PG8_MMA(ai, bj, At, Bt) do { __builtin_amdgcn_s_setprio(1); _Pragma("unroll") for (int m = 0; m < 4; ++m) _Pragma("unroll") for (int n = 0; n < 2; ++n) _Pragma("unroll") for (int k = 0; k < 2; ++k) \
;         acc[ai][bj][m][n] = __builtin_amdgcn_mfma_f32_16x16x32_bf16(Bt[n][k], At[m][k], acc[ai][bj][m][n], 0, 0, 0); __builtin_amdgcn_s_setprio(0); } while (0)
; #define PG8_WAIT_L(n) asm volatile("s_waitcnt lgkmcnt(" #n ")" ::: "memory")
; #define PG8_BAR __builtin_amdgcn_s_barrier()
; #define PG8_SCHED __builtin_amdgcn_sched_barrier(0)
; template <class Epi>
; DI void gemm_phase(LAS unsigned char* lds, int wid, int K, int lda, int ldb, bool bperm, const Sched3& S, const Epi& E) {
;     ...
;             PG8_LDB(B0, 0, 0); PG8_SCHED; PG8_LDA(At, 0, 0); PG8_STAGE(PG8_SA(1, 1), a1 + hA, voffA);
;             PG8_WAIT_L(8); PG8_BAR; PG8_WAIT_L(0); PG8_MMA(0, 0, At, B0); PG8_BAR; PG8_SCHED;
	s_add_i32 m0, s44, 0xe000
	s_nop 0
	global_load_lds_dwordx4 v158, s[26:27]
	s_waitcnt lgkmcnt(8)
	s_barrier
	s_waitcnt lgkmcnt(0)
	s_setprio 1
	s_waitcnt lgkmcnt(0)
	v_mfma_f32_16x16x32_bf16 v[124:127], v[128:131], v[144:147], 0
	v_mfma_f32_16x16x32_bf16 v[120:123], v[136:139], v[144:147], 0
	v_mfma_f32_16x16x32_bf16 v[108:111], v[128:131], v[162:165], 0
	v_mfma_f32_16x16x32_bf16 v[104:107], v[136:139], v[162:165], 0
	v_mfma_f32_16x16x32_bf16 v[92:95], v[128:131], v[170:173], 0
	v_mfma_f32_16x16x32_bf16 v[88:91], v[136:139], v[170:173], 0
	v_mfma_f32_16x16x32_bf16 v[76:79], v[128:131], v[188:191], 0
	v_mfma_f32_16x16x32_bf16 v[72:75], v[136:139], v[188:191], 0
	v_mfma_f32_16x16x32_bf16 v[124:127], v[132:135], v[148:151], v[124:127]
	v_mfma_f32_16x16x32_bf16 v[120:123], v[140:143], v[148:151], v[120:123]
	v_mfma_f32_16x16x32_bf16 v[108:111], v[132:135], v[166:169], v[108:111]
	v_mfma_f32_16x16x32_bf16 v[104:107], v[140:143], v[166:169], v[104:107]
	v_mfma_f32_16x16x32_bf16 v[92:95], v[132:135], v[174:177], v[92:95]
	v_mfma_f32_16x16x32_bf16 v[88:91], v[140:143], v[174:177], v[88:91]
	v_mfma_f32_16x16x32_bf16 v[76:79], v[132:135], v[192:195], v[76:79]
	v_mfma_f32_16x16x32_bf16 v[72:75], v[140:143], v[192:195], v[72:75]
	s_setprio 0
	s_barrier
	s_add_i32 s26, s53, s43

; #define PG8_STAGE(bufoff, gbase, voff) do { _Pragma("unroll") for (int _i = 0; _i < 2; ++_i) \
;         __builtin_amdgcn_global_load_lds((const unsigned*)((const char*)(gbase) + (voff)[_i]), (LAS unsigned*)(lds + (bufoff) + ldsw + _i * 8192), 16, 0, 0); } while (0)
; #define PG8_LDB(dst, b, h) do { _Pragma("unroll") for (int n = 0; n < 2; ++n) _Pragma("unroll") for (int k = 0; k < 2; ++k) dst[n][k] = *(const LAS bf16x8*)(lds + PG8_SB(b, h) + boff + n * 2048 + k * 1024); } while (0)
; template <class Epi>
; DI void gemm_phase(LAS unsigned char* lds, int wid, int K, int lda, int ldb, bool bperm, const Sched3& S, const Epi& E) {
;     ...
;             PG8_LDB(B1, 0, 1); PG8_STAGE(PG8_SB(0, 0), b2, voffB);
	s_mov_b32 m0, s26
	ds_read_b128 v[196:199], v187
	ds_read_b128 v[200:203], v187 offset:1024
	ds_read_b128 v[204:207], v187 offset:2048
	ds_read_b128 v[208:211], v187 offset:3072
	global_load_lds_dwordx4 v152, s[30:31]

; #define PG8_STAGE(bufoff, gbase, voff) do { _Pragma("unroll") for (int _i = 0; _i < 2; ++_i) \
;         __builtin_amdgcn_global_load_lds((const unsigned*)((const char*)(gbase) + (voff)[_i]), (LAS unsigned*)(lds + (bufoff) + ldsw + _i * 8192), 16, 0, 0); } while (0)
; #define PG8_LDA(dst, b, h) do { _Pragma("unroll") for (int m = 0; m < 4; ++m) _Pragma("unroll") for (int k = 0; k < 2; ++k) dst[m][k] = *(const LAS bf16x8*)(lds + PG8_SA(b, h) + aoff + m * 2048 + k * 1024); } while (0)
; #define PG8_LDB(dst, b, h) do { _Pragma("unroll") for (int n = 0; n < 2; ++n) _Pragma("unroll") for (int k = 0; k < 2; ++k) dst[n][k] = *(const LAS bf16x8*)(lds + PG8_SB(b, h) + boff + n * 2048 + k * 1024); } while (0)
; #define PG8_MMA(ai, bj, At, Bt) do { __builtin_amdgcn_s_setprio(1); _Pragma("unroll") for (int m = 0; m < 4; ++m) _Pragma("unroll") for (int n = 0; n < 2; ++n) _Pragma("unroll") for (int k = 0; k < 2; ++k) \
;         acc[ai][bj][m][n] = __builtin_amdgcn_mfma_f32_16x16x32_bf16(Bt[n][k], At[m][k], acc[ai][bj][m][n], 0, 0, 0); __builtin_amdgcn_s_setprio(0); } while (0)
; #define PG8_WAIT_L(n) asm volatile("s_waitcnt lgkmcnt(" #n ")" ::: "memory")
; #define PG8_BAR __builtin_amdgcn_s_barrier()
; #define PG8_SCHED __builtin_amdgcn_sched_barrier(0)
; template <class Epi>
; DI void gemm_phase(LAS unsigned char* lds, int wid, int K, int lda, int ldb, bool bperm, const Sched3& S, const Epi& E) {
;     ...
;             PG8_LDB(B1, 0, 1); PG8_STAGE(PG8_SB(0, 0), b2, voffB);
;             PG8_BAR; PG8_WAIT_L(0); PG8_MMA(0, 1, At, B1); PG8_BAR;
;             PG8_LDA(At, 0, 1); PG8_STAGE(PG8_SA(0, 0), a2, voffA);
;             PG8_BAR; PG8_WAIT_L(0); if (full) PG8_MMA(1, 0, At, B0); PG8_BAR; PG8_SCHED;
	s_add_i32 m0, s26, 0x2000
	s_nop 0
	global_load_lds_dwordx4 v154, s[30:31]
	s_barrier
	s_waitcnt lgkmcnt(0)
	s_setprio 1
	s_waitcnt lgkmcnt(0)
	v_mfma_f32_16x16x32_bf16 v[116:119], v[196:199], v[144:147], 0
	v_mfma_f32_16x16x32_bf16 v[112:115], v[204:207], v[144:147], 0
	v_mfma_f32_16x16x32_bf16 v[100:103], v[196:199], v[162:165], 0
	v_mfma_f32_16x16x32_bf16 v[96:99], v[204:207], v[162:165], 0
	v_mfma_f32_16x16x32_bf16 v[84:87], v[196:199], v[170:173], 0
	v_mfma_f32_16x16x32_bf16 v[80:83], v[204:207], v[170:173], 0
	v_mfma_f32_16x16x32_bf16 v[68:71], v[196:199], v[188:191], 0
	v_mfma_f32_16x16x32_bf16 v[64:67], v[204:207], v[188:191], 0
	v_mfma_f32_16x16x32_bf16 v[116:119], v[200:203], v[148:151], v[116:119]
	v_mfma_f32_16x16x32_bf16 v[112:115], v[208:211], v[148:151], v[112:115]
	v_mfma_f32_16x16x32_bf16 v[100:103], v[200:203], v[166:169], v[100:103]
	v_mfma_f32_16x16x32_bf16 v[96:99], v[208:211], v[166:169], v[96:99]
	v_mfma_f32_16x16x32_bf16 v[84:87], v[200:203], v[174:177], v[84:87]
	v_mfma_f32_16x16x32_bf16 v[80:83], v[208:211], v[174:177], v[80:83]
	v_mfma_f32_16x16x32_bf16 v[68:71], v[200:203], v[192:195], v[68:71]
	v_mfma_f32_16x16x32_bf16 v[64:67], v[208:211], v[192:195], v[64:67]
	s_setprio 0
	s_mov_b32 m0, s44
	s_mov_b64 s[100:101], s[36:37]
	s_barrier
	ds_read_b128 v[144:147], v186 offset:16384
	ds_read_b128 v[148:151], v186 offset:17408
	ds_read_b128 v[162:165], v186 offset:18432
	ds_read_b128 v[166:169], v186 offset:19456
	ds_read_b128 v[170:173], v186 offset:20480
	ds_read_b128 v[174:177], v186 offset:21504
	ds_read_b128 v[188:191], v186 offset:22528
	ds_read_b128 v[192:195], v186 offset:23552
	global_load_lds_dwordx4 v152, s[36:37]
	s_mov_b64 s[100:101], s[36:37]
	s_mov_b32 m0, s45
	s_nop 0
	global_load_lds_dwordx4 v154, s[36:37]
	s_barrier
	s_waitcnt lgkmcnt(0)
	s_setprio 1
	s_waitcnt lgkmcnt(0)
	v_mfma_f32_16x16x32_bf16 v[60:63], v[128:131], v[144:147], 0
	v_mfma_f32_16x16x32_bf16 v[56:59], v[136:139], v[144:147], 0
	v_mfma_f32_16x16x32_bf16 v[44:47], v[128:131], v[162:165], 0
	v_mfma_f32_16x16x32_bf16 v[40:43], v[136:139], v[162:165], 0
	v_mfma_f32_16x16x32_bf16 v[28:31], v[128:131], v[170:173], 0
	v_mfma_f32_16x16x32_bf16 v[24:27], v[136:139], v[170:173], 0
	v_mfma_f32_16x16x32_bf16 v[12:15], v[128:131], v[188:191], 0
	v_mfma_f32_16x16x32_bf16 v[8:11], v[136:139], v[188:191], 0
	v_mfma_f32_16x16x32_bf16 v[60:63], v[132:135], v[148:151], v[60:63]
	v_mfma_f32_16x16x32_bf16 v[56:59], v[140:143], v[148:151], v[56:59]
	v_mfma_f32_16x16x32_bf16 v[44:47], v[132:135], v[166:169], v[44:47]
	v_mfma_f32_16x16x32_bf16 v[40:43], v[140:143], v[166:169], v[40:43]
	v_mfma_f32_16x16x32_bf16 v[28:31], v[132:135], v[174:177], v[28:31]
	v_mfma_f32_16x16x32_bf16 v[24:27], v[140:143], v[174:177], v[24:27]
	v_mfma_f32_16x16x32_bf16 v[12:15], v[132:135], v[192:195], v[12:15]
	v_mfma_f32_16x16x32_bf16 v[8:11], v[140:143], v[192:195], v[8:11]
	s_setprio 0
	s_barrier
	s_add_u32 s26, s30, 0x160000
	s_addc_u32 s27, s31, 0
	s_add_i32 s63, s54, s43

; #define PG8_STAGE(bufoff, gbase, voff) do { _Pragma("unroll") for (int _i = 0; _i < 2; ++_i) \
;         __builtin_amdgcn_global_load_lds((const unsigned*)((const char*)(gbase) + (voff)[_i]), (LAS unsigned*)(lds + (bufoff) + ldsw + _i * 8192), 16, 0, 0); } while (0)
; template <class Epi>
; DI void gemm_phase(LAS unsigned char* lds, int wid, int K, int lda, int ldb, bool bperm, const Sched3& S, const Epi& E) {
;     ...
;             PG8_STAGE(PG8_SB(0, 1), b2 + hstepB, voffB);
	s_mov_b32 m0, s63
	s_nop 0
	global_load_lds_dwordx4 v152, s[26:27]

; #define PG8_STAGE(bufoff, gbase, voff) do { _Pragma("unroll") for (int _i = 0; _i < 2; ++_i) \
;         __builtin_amdgcn_global_load_lds((const unsigned*)((const char*)(gbase) + (voff)[_i]), (LAS unsigned*)(lds + (bufoff) + ldsw + _i * 8192), 16, 0, 0); } while (0)
; #define PG8_LDA(dst, b, h) do { _Pragma("unroll") for (int m = 0; m < 4; ++m) _Pragma("unroll") for (int k = 0; k < 2; ++k) dst[m][k] = *(const LAS bf16x8*)(lds + PG8_SA(b, h) + aoff + m * 2048 + k * 1024); } while (0)
; #define PG8_LDB(dst, b, h) do { _Pragma("unroll") for (int n = 0; n < 2; ++n) _Pragma("unroll") for (int k = 0; k < 2; ++k) dst[n][k] = *(const LAS bf16x8*)(lds + PG8_SB(b, h) + boff + n * 2048 + k * 1024); } while (0)
; #define PG8_MMA(ai, bj, At, Bt) do { __builtin_amdgcn_s_setprio(1); _Pragma("unroll") for (int m = 0; m < 4; ++m) _Pragma("unroll") for (int n = 0; n < 2; ++n) _Pragma("unroll") for (int k = 0; k < 2; ++k) \
;         acc[ai][bj][m][n] = __builtin_amdgcn_mfma_f32_16x16x32_bf16(Bt[n][k], At[m][k], acc[ai][bj][m][n], 0, 0, 0); __builtin_amdgcn_s_setprio(0); } while (0)
; #define PG8_WAIT_V(n) asm volatile("s_waitcnt vmcnt(" #n ")" ::: "memory")
; #define PG8_BAR __builtin_amdgcn_s_barrier()
; #define PG8_SCHED __builtin_amdgcn_sched_barrier(0)
; template <class Epi>
; DI void gemm_phase(LAS unsigned char* lds, int wid, int K, int lda, int ldb, bool bperm, const Sched3& S, const Epi& E) {
;     ...
;             PG8_STAGE(PG8_SB(0, 1), b2 + hstepB, voffB);
;             PG8_WAIT_V(6); PG8_BAR; if (full) PG8_MMA(1, 1, At, B1); PG8_BAR;
;             PG8_LDB(B0, 1, 0); PG8_SCHED; PG8_LDA(At, 1, 0); PG8_STAGE(PG8_SA(0, 1), a2 + h2, voffA);
	s_add_i32 m0, s63, 0x2000
	s_nop 0
	global_load_lds_dwordx4 v154, s[26:27]
	s_waitcnt vmcnt(6)
	s_barrier
	s_setprio 1
	v_mfma_f32_16x16x32_bf16 v[52:55], v[196:199], v[144:147], 0
	v_mfma_f32_16x16x32_bf16 v[48:51], v[204:207], v[144:147], 0
	v_mfma_f32_16x16x32_bf16 v[36:39], v[196:199], v[162:165], 0
	v_mfma_f32_16x16x32_bf16 v[32:35], v[204:207], v[162:165], 0
	v_mfma_f32_16x16x32_bf16 v[20:23], v[196:199], v[170:173], 0
	v_mfma_f32_16x16x32_bf16 v[16:19], v[204:207], v[170:173], 0
	v_mfma_f32_16x16x32_bf16 v[4:7], v[196:199], v[188:191], 0
	v_mfma_f32_16x16x32_bf16 v[0:3], v[204:207], v[188:191], 0
	v_mfma_f32_16x16x32_bf16 v[52:55], v[200:203], v[148:151], v[52:55]
	v_mfma_f32_16x16x32_bf16 v[48:51], v[208:211], v[148:151], v[48:51]
	v_mfma_f32_16x16x32_bf16 v[36:39], v[200:203], v[166:169], v[36:39]
	v_mfma_f32_16x16x32_bf16 v[32:35], v[208:211], v[166:169], v[32:35]
	v_mfma_f32_16x16x32_bf16 v[20:23], v[200:203], v[174:177], v[20:23]
	v_mfma_f32_16x16x32_bf16 v[16:19], v[208:211], v[174:177], v[16:19]
	v_mfma_f32_16x16x32_bf16 v[4:7], v[200:203], v[192:195], v[4:7]
	v_mfma_f32_16x16x32_bf16 v[0:3], v[208:211], v[192:195], v[0:3]
	s_setprio 0
	s_add_i32 s63, 0, 0x18000
	v_add_u32_e32 v140, s63, v181
	s_barrier
	ds_read_b128 v[128:131], v140
	ds_read_b128 v[132:135], v140 offset:1024
	ds_read_b128 v[136:139], v140 offset:2048
	ds_read_b128 v[140:143], v140 offset:3072
	s_add_u32 s26, s36, 0x160000
	s_addc_u32 s27, s37, 0
	s_mov_b32 m0, s46

; #define PG8_STAGE(bufoff, gbase, voff) do { _Pragma("unroll") for (int _i = 0; _i < 2; ++_i) \
;         __builtin_amdgcn_global_load_lds((const unsigned*)((const char*)(gbase) + (voff)[_i]), (LAS unsigned*)(lds + (bufoff) + ldsw + _i * 8192), 16, 0, 0); } while (0)
; #define PG8_LDA(dst, b, h) do { _Pragma("unroll") for (int m = 0; m < 4; ++m) _Pragma("unroll") for (int k = 0; k < 2; ++k) dst[m][k] = *(const LAS bf16x8*)(lds + PG8_SA(b, h) + aoff + m * 2048 + k * 1024); } while (0)
; #define PG8_LDB(dst, b, h) do { _Pragma("unroll") for (int n = 0; n < 2; ++n) _Pragma("unroll") for (int k = 0; k < 2; ++k) dst[n][k] = *(const LAS bf16x8*)(lds + PG8_SB(b, h) + boff + n * 2048 + k * 1024); } while (0)
; #define PG8_SCHED __builtin_amdgcn_sched_barrier(0)
; template <class Epi>
; DI void gemm_phase(LAS unsigned char* lds, int wid, int K, int lda, int ldb, bool bperm, const Sched3& S, const Epi& E) {
;     ...
;             PG8_LDB(B0, 1, 0); PG8_SCHED; PG8_LDA(At, 1, 0); PG8_STAGE(PG8_SA(0, 1), a2 + h2, voffA);
	ds_read_b128 v[144:147], v186 offset:32768
	ds_read_b128 v[148:151], v186 offset:33792
	ds_read_b128 v[162:165], v186 offset:34816
	ds_read_b128 v[166:169], v186 offset:35840
	ds_read_b128 v[170:173], v186 offset:36864
	ds_read_b128 v[174:177], v186 offset:37888
	ds_read_b128 v[188:191], v186 offset:38912
	ds_read_b128 v[192:195], v186 offset:39936
	global_load_lds_dwordx4 v152, s[26:27]

; #define PG8_STAGE(bufoff, gbase, voff) do { _Pragma("unroll") for (int _i = 0; _i < 2; ++_i) \
;         __builtin_amdgcn_global_load_lds((const unsigned*)((const char*)(gbase) + (voff)[_i]), (LAS unsigned*)(lds + (bufoff) + ldsw + _i * 8192), 16, 0, 0); } while (0)
; #define PG8_LDA(dst, b, h) do { _Pragma("unroll") for (int m = 0; m < 4; ++m) _Pragma("unroll") for (int k = 0; k < 2; ++k) dst[m][k] = *(const LAS bf16x8*)(lds + PG8_SA(b, h) + aoff + m * 2048 + k * 1024); } while (0)
; #define PG8_LDB(dst, b, h) do { _Pragma("unroll") for (int n = 0; n < 2; ++n) _Pragma("unroll") for (int k = 0; k < 2; ++k) dst[n][k] = *(const LAS bf16x8*)(lds + PG8_SB(b, h) + boff + n * 2048 + k * 1024); } while (0)
; #define PG8_MMA(ai, bj, At, Bt) do { __builtin_amdgcn_s_setprio(1); _Pragma("unroll") for (int m = 0; m < 4; ++m) _Pragma("unroll") for (int n = 0; n < 2; ++n) _Pragma("unroll") for (int k = 0; k < 2; ++k) \
;         acc[ai][bj][m][n] = __builtin_amdgcn_mfma_f32_16x16x32_bf16(Bt[n][k], At[m][k], acc[ai][bj][m][n], 0, 0, 0); __builtin_amdgcn_s_setprio(0); } while (0)
; #define PG8_WAIT_L(n) asm volatile("s_waitcnt lgkmcnt(" #n ")" ::: "memory")
; #define PG8_BAR __builtin_amdgcn_s_barrier()
; #define PG8_SCHED __builtin_amdgcn_sched_barrier(0)
; template <class Epi>
; DI void gemm_phase(LAS unsigned char* lds, int wid, int K, int lda, int ldb, bool bperm, const Sched3& S, const Epi& E) {
;     ...
;             PG8_LDB(B0, 1, 0); PG8_SCHED; PG8_LDA(At, 1, 0); PG8_STAGE(PG8_SA(0, 1), a2 + h2, voffA);
;             PG8_WAIT_L(8); PG8_BAR; PG8_WAIT_L(0); PG8_MMA(0, 0, At, B0); PG8_BAR; PG8_SCHED;
;             PG8_LDB(B1, 1, 1); PG8_STAGE(PG8_SB(1, 0), b3, voffB);
	s_mov_b32 m0, s47
	s_nop 0
	global_load_lds_dwordx4 v154, s[26:27]
	s_waitcnt lgkmcnt(8)
	s_barrier
	s_waitcnt lgkmcnt(0)
	s_setprio 1
	s_waitcnt lgkmcnt(0)
	v_mfma_f32_16x16x32_bf16 v[124:127], v[128:131], v[144:147], v[124:127]
	v_mfma_f32_16x16x32_bf16 v[120:123], v[136:139], v[144:147], v[120:123]
	v_mfma_f32_16x16x32_bf16 v[108:111], v[128:131], v[162:165], v[108:111]
	v_mfma_f32_16x16x32_bf16 v[104:107], v[136:139], v[162:165], v[104:107]
	v_mfma_f32_16x16x32_bf16 v[92:95], v[128:131], v[170:173], v[92:95]
	v_mfma_f32_16x16x32_bf16 v[88:91], v[136:139], v[170:173], v[88:91]
	v_mfma_f32_16x16x32_bf16 v[76:79], v[128:131], v[188:191], v[76:79]
	v_mfma_f32_16x16x32_bf16 v[72:75], v[136:139], v[188:191], v[72:75]
	v_mfma_f32_16x16x32_bf16 v[124:127], v[132:135], v[148:151], v[124:127]
	v_mfma_f32_16x16x32_bf16 v[120:123], v[140:143], v[148:151], v[120:123]
	v_mfma_f32_16x16x32_bf16 v[108:111], v[132:135], v[166:169], v[108:111]
	v_mfma_f32_16x16x32_bf16 v[104:107], v[140:143], v[166:169], v[104:107]
	v_mfma_f32_16x16x32_bf16 v[92:95], v[132:135], v[174:177], v[92:95]
	v_mfma_f32_16x16x32_bf16 v[88:91], v[140:143], v[174:177], v[88:91]
	v_mfma_f32_16x16x32_bf16 v[76:79], v[132:135], v[192:195], v[76:79]
	v_mfma_f32_16x16x32_bf16 v[72:75], v[140:143], v[192:195], v[72:75]
	s_setprio 0
	s_barrier
	s_add_i32 s36, 0, 0x1c000
	s_add_i32 s26, s63, s43
	v_add_u32_e32 v208, s36, v181

; #define PG8_STAGE(bufoff, gbase, voff) do { _Pragma("unroll") for (int _i = 0; _i < 2; ++_i) \
;         __builtin_amdgcn_global_load_lds((const unsigned*)((const char*)(gbase) + (voff)[_i]), (LAS unsigned*)(lds + (bufoff) + ldsw + _i * 8192), 16, 0, 0); } while (0)
; #define PG8_LDB(dst, b, h) do { _Pragma("unroll") for (int n = 0; n < 2; ++n) _Pragma("unroll") for (int k = 0; k < 2; ++k) dst[n][k] = *(const LAS bf16x8*)(lds + PG8_SB(b, h) + boff + n * 2048 + k * 1024); } while (0)
; template <class Epi>
; DI void gemm_phase(LAS unsigned char* lds, int wid, int K, int lda, int ldb, bool bperm, const Sched3& S, const Epi& E) {
;     ...
;             PG8_LDB(B1, 1, 1); PG8_STAGE(PG8_SB(1, 0), b3, voffB);
	s_sub_i32 m0, s26, 0x80
	ds_read_b128 v[196:199], v208
	ds_read_b128 v[200:203], v208 offset:1024
	ds_read_b128 v[204:207], v208 offset:2048
	ds_read_b128 v[208:211], v208 offset:3072
	global_load_lds_dwordx4 v152, s[30:31] offset:128

; #define PG8_STAGE(bufoff, gbase, voff) do { _Pragma("unroll") for (int _i = 0; _i < 2; ++_i) \
;         __builtin_amdgcn_global_load_lds((const unsigned*)((const char*)(gbase) + (voff)[_i]), (LAS unsigned*)(lds + (bufoff) + ldsw + _i * 8192), 16, 0, 0); } while (0)
; #define PG8_LDA(dst, b, h) do { _Pragma("unroll") for (int m = 0; m < 4; ++m) _Pragma("unroll") for (int k = 0; k < 2; ++k) dst[m][k] = *(const LAS bf16x8*)(lds + PG8_SA(b, h) + aoff + m * 2048 + k * 1024); } while (0)
; #define PG8_LDB(dst, b, h) do { _Pragma("unroll") for (int n = 0; n < 2; ++n) _Pragma("unroll") for (int k = 0; k < 2; ++k) dst[n][k] = *(const LAS bf16x8*)(lds + PG8_SB(b, h) + boff + n * 2048 + k * 1024); } while (0)
; #define PG8_MMA(ai, bj, At, Bt) do { __builtin_amdgcn_s_setprio(1); _Pragma("unroll") for (int m = 0; m < 4; ++m) _Pragma("unroll") for (int n = 0; n < 2; ++n) _Pragma("unroll") for (int k = 0; k < 2; ++k) \
;         acc[ai][bj][m][n] = __builtin_amdgcn_mfma_f32_16x16x32_bf16(Bt[n][k], At[m][k], acc[ai][bj][m][n], 0, 0, 0); __builtin_amdgcn_s_setprio(0); } while (0)
; #define PG8_WAIT_L(n) asm volatile("s_waitcnt lgkmcnt(" #n ")" ::: "memory")
; #define PG8_BAR __builtin_amdgcn_s_barrier()
; template <class Epi>
; DI void gemm_phase(LAS unsigned char* lds, int wid, int K, int lda, int ldb, bool bperm, const Sched3& S, const Epi& E) {
;     ...
;             PG8_LDB(B1, 1, 1); PG8_STAGE(PG8_SB(1, 0), b3, voffB);
;             PG8_BAR; PG8_WAIT_L(0); PG8_MMA(0, 1, At, B1); PG8_BAR;
;             PG8_LDA(At, 1, 1); PG8_STAGE(PG8_SA(1, 0), a3, voffA);
	s_add_i32 m0, s26, 0x1f80
	s_nop 0
	global_load_lds_dwordx4 v154, s[30:31] offset:128
	s_barrier
	s_waitcnt lgkmcnt(0)
	s_setprio 1
	s_waitcnt lgkmcnt(0)
	v_mfma_f32_16x16x32_bf16 v[116:119], v[196:199], v[144:147], v[116:119]
	v_mfma_f32_16x16x32_bf16 v[112:115], v[204:207], v[144:147], v[112:115]
	v_mfma_f32_16x16x32_bf16 v[100:103], v[196:199], v[162:165], v[100:103]
	v_mfma_f32_16x16x32_bf16 v[96:99], v[204:207], v[162:165], v[96:99]
	v_mfma_f32_16x16x32_bf16 v[84:87], v[196:199], v[170:173], v[84:87]
	v_mfma_f32_16x16x32_bf16 v[80:83], v[204:207], v[170:173], v[80:83]
	v_mfma_f32_16x16x32_bf16 v[68:71], v[196:199], v[188:191], v[68:71]
	v_mfma_f32_16x16x32_bf16 v[64:67], v[204:207], v[188:191], v[64:67]
	v_mfma_f32_16x16x32_bf16 v[116:119], v[200:203], v[148:151], v[116:119]
	v_mfma_f32_16x16x32_bf16 v[112:115], v[208:211], v[148:151], v[112:115]
	v_mfma_f32_16x16x32_bf16 v[100:103], v[200:203], v[166:169], v[100:103]
	v_mfma_f32_16x16x32_bf16 v[96:99], v[208:211], v[166:169], v[96:99]
	v_mfma_f32_16x16x32_bf16 v[84:87], v[200:203], v[174:177], v[84:87]
	v_mfma_f32_16x16x32_bf16 v[80:83], v[208:211], v[174:177], v[80:83]
	v_mfma_f32_16x16x32_bf16 v[68:71], v[200:203], v[192:195], v[68:71]
	v_mfma_f32_16x16x32_bf16 v[64:67], v[208:211], v[192:195], v[64:67]
	s_setprio 0
	s_sub_i32 m0, s49, 0x80

; #define PG8_STAGE(bufoff, gbase, voff) do { _Pragma("unroll") for (int _i = 0; _i < 2; ++_i) \
;         __builtin_amdgcn_global_load_lds((const unsigned*)((const char*)(gbase) + (voff)[_i]), (LAS unsigned*)(lds + (bufoff) + ldsw + _i * 8192), 16, 0, 0); } while (0)
; #define PG8_LDA(dst, b, h) do { _Pragma("unroll") for (int m = 0; m < 4; ++m) _Pragma("unroll") for (int k = 0; k < 2; ++k) dst[m][k] = *(const LAS bf16x8*)(lds + PG8_SA(b, h) + aoff + m * 2048 + k * 1024); } while (0)
; template <class Epi>
; DI void gemm_phase(LAS unsigned char* lds, int wid, int K, int lda, int ldb, bool bperm, const Sched3& S, const Epi& E) {
;     ...
;             PG8_LDA(At, 1, 1); PG8_STAGE(PG8_SA(1, 0), a3, voffA);
	s_barrier
	ds_read_b128 v[144:147], v186 offset:49152
	ds_read_b128 v[148:151], v186 offset:50176
	ds_read_b128 v[162:165], v186 offset:51200
	ds_read_b128 v[166:169], v186 offset:52224
	ds_read_b128 v[170:173], v186 offset:53248
	ds_read_b128 v[174:177], v186 offset:54272
	ds_read_b128 v[188:191], v186 offset:55296
	ds_read_b128 v[192:195], v186 offset:56320
	global_load_lds_dwordx4 v152, s[100:101] offset:128

; #define PG8_STAGE(bufoff, gbase, voff) do { _Pragma("unroll") for (int _i = 0; _i < 2; ++_i) \
;         __builtin_amdgcn_global_load_lds((const unsigned*)((const char*)(gbase) + (voff)[_i]), (LAS unsigned*)(lds + (bufoff) + ldsw + _i * 8192), 16, 0, 0); } while (0)
; #define PG8_LDA(dst, b, h) do { _Pragma("unroll") for (int m = 0; m < 4; ++m) _Pragma("unroll") for (int k = 0; k < 2; ++k) dst[m][k] = *(const LAS bf16x8*)(lds + PG8_SA(b, h) + aoff + m * 2048 + k * 1024); } while (0)
; #define PG8_MMA(ai, bj, At, Bt) do { __builtin_amdgcn_s_setprio(1); _Pragma("unroll") for (int m = 0; m < 4; ++m) _Pragma("unroll") for (int n = 0; n < 2; ++n) _Pragma("unroll") for (int k = 0; k < 2; ++k) \
;         acc[ai][bj][m][n] = __builtin_amdgcn_mfma_f32_16x16x32_bf16(Bt[n][k], At[m][k], acc[ai][bj][m][n], 0, 0, 0); __builtin_amdgcn_s_setprio(0); } while (0)
; #define PG8_WAIT_L(n) asm volatile("s_waitcnt lgkmcnt(" #n ")" ::: "memory")
; #define PG8_BAR __builtin_amdgcn_s_barrier()
; #define PG8_SCHED __builtin_amdgcn_sched_barrier(0)
; template <class Epi>
; DI void gemm_phase(LAS unsigned char* lds, int wid, int K, int lda, int ldb, bool bperm, const Sched3& S, const Epi& E) {
;     ...
;             PG8_LDA(At, 1, 1); PG8_STAGE(PG8_SA(1, 0), a3, voffA);
;             PG8_BAR; PG8_WAIT_L(0); if (full) PG8_MMA(1, 0, At, B0); PG8_BAR; PG8_SCHED;
;             PG8_STAGE(PG8_SB(1, 1), b3 + hstepB, voffB);
	s_sub_i32 m0, s50, 0x80
	s_nop 0
	global_load_lds_dwordx4 v154, s[100:101] offset:128
	s_barrier
	s_waitcnt lgkmcnt(0)
	s_setprio 1
	s_waitcnt lgkmcnt(0)
	v_mfma_f32_16x16x32_bf16 v[60:63], v[128:131], v[144:147], v[60:63]
	v_mfma_f32_16x16x32_bf16 v[56:59], v[136:139], v[144:147], v[56:59]
	v_mfma_f32_16x16x32_bf16 v[44:47], v[128:131], v[162:165], v[44:47]
	v_mfma_f32_16x16x32_bf16 v[40:43], v[136:139], v[162:165], v[40:43]
	v_mfma_f32_16x16x32_bf16 v[28:31], v[128:131], v[170:173], v[28:31]
	v_mfma_f32_16x16x32_bf16 v[24:27], v[136:139], v[170:173], v[24:27]
	v_mfma_f32_16x16x32_bf16 v[12:15], v[128:131], v[188:191], v[12:15]
	v_mfma_f32_16x16x32_bf16 v[8:11], v[136:139], v[188:191], v[8:11]
	v_mfma_f32_16x16x32_bf16 v[60:63], v[132:135], v[148:151], v[60:63]
	v_mfma_f32_16x16x32_bf16 v[56:59], v[140:143], v[148:151], v[56:59]
	v_mfma_f32_16x16x32_bf16 v[44:47], v[132:135], v[166:169], v[44:47]
	v_mfma_f32_16x16x32_bf16 v[40:43], v[140:143], v[166:169], v[40:43]
	v_mfma_f32_16x16x32_bf16 v[28:31], v[132:135], v[174:177], v[28:31]
	v_mfma_f32_16x16x32_bf16 v[24:27], v[140:143], v[174:177], v[24:27]
	v_mfma_f32_16x16x32_bf16 v[12:15], v[132:135], v[192:195], v[12:15]
	v_mfma_f32_16x16x32_bf16 v[8:11], v[140:143], v[192:195], v[8:11]
	s_setprio 0
	s_barrier
	s_add_u32 s26, s30, 0x160080
	s_addc_u32 s27, s31, 0
	s_add_i32 s30, s36, s43

; #define PG8_STAGE(bufoff, gbase, voff) do { _Pragma("unroll") for (int _i = 0; _i < 2; ++_i) \
;         __builtin_amdgcn_global_load_lds((const unsigned*)((const char*)(gbase) + (voff)[_i]), (LAS unsigned*)(lds + (bufoff) + ldsw + _i * 8192), 16, 0, 0); } while (0)
; template <class Epi>
; DI void gemm_phase(LAS unsigned char* lds, int wid, int K, int lda, int ldb, bool bperm, const Sched3& S, const Epi& E) {
;     ...
;             PG8_STAGE(PG8_SB(1, 1), b3 + hstepB, voffB);
	s_mov_b32 m0, s30
	s_nop 0
	global_load_lds_dwordx4 v152, s[26:27]

; #define PG8_STAGE(bufoff, gbase, voff) do { _Pragma("unroll") for (int _i = 0; _i < 2; ++_i) \
;         __builtin_amdgcn_global_load_lds((const unsigned*)((const char*)(gbase) + (voff)[_i]), (LAS unsigned*)(lds + (bufoff) + ldsw + _i * 8192), 16, 0, 0); } while (0)
; #define PG8_LDA(dst, b, h) do { _Pragma("unroll") for (int m = 0; m < 4; ++m) _Pragma("unroll") for (int k = 0; k < 2; ++k) dst[m][k] = *(const LAS bf16x8*)(lds + PG8_SA(b, h) + aoff + m * 2048 + k * 1024); } while (0)
; #define PG8_LDB(dst, b, h) do { _Pragma("unroll") for (int n = 0; n < 2; ++n) _Pragma("unroll") for (int k = 0; k < 2; ++k) dst[n][k] = *(const LAS bf16x8*)(lds + PG8_SB(b, h) + boff + n * 2048 + k * 1024); } while (0)
; #define PG8_MMA(ai, bj, At, Bt) do { __builtin_amdgcn_s_setprio(1); _Pragma("unroll") for (int m = 0; m < 4; ++m) _Pragma("unroll") for (int n = 0; n < 2; ++n) _Pragma("unroll") for (int k = 0; k < 2; ++k) \
;         acc[ai][bj][m][n] = __builtin_amdgcn_mfma_f32_16x16x32_bf16(Bt[n][k], At[m][k], acc[ai][bj][m][n], 0, 0, 0); __builtin_amdgcn_s_setprio(0); } while (0)
; #define PG8_WAIT_V(n) asm volatile("s_waitcnt vmcnt(" #n ")" ::: "memory")
; #define PG8_BAR __builtin_amdgcn_s_barrier()
; #define PG8_SCHED __builtin_amdgcn_sched_barrier(0)
; template <class Epi>
; DI void gemm_phase(LAS unsigned char* lds, int wid, int K, int lda, int ldb, bool bperm, const Sched3& S, const Epi& E) {
;     ...
;             const bool last = (t == nt - 2);
;             const char* a1 = cA + (size_t)(t + 1) * kstep;
;             const char* a2 = last ? nA : cA + (size_t)(t + 2) * kstep; const char* b2 = last ? nB : cB + (size_t)(t + 2) * kstep;
;             const char* a3 = a2 + kstep; const char* b3 = b2 + kstep; const size_t h2 = last ? nhA : hA;
;             PG8_LDB(B0, 0, 0); PG8_SCHED; PG8_LDA(At, 0, 0); PG8_STAGE(PG8_SA(1, 1), a1 + hA, voffA);
;     ...
;             PG8_STAGE(PG8_SB(1, 1), b3 + hstepB, voffB);
;             PG8_WAIT_V(6); PG8_BAR; if (full) PG8_MMA(1, 1, At, B1); PG8_BAR;
	s_add_i32 m0, s30, 0x2000
	s_nop 0
	global_load_lds_dwordx4 v154, s[26:27]
	s_waitcnt vmcnt(6)
	s_barrier
	s_setprio 1
	v_mfma_f32_16x16x32_bf16 v[52:55], v[196:199], v[144:147], v[52:55]
	v_mfma_f32_16x16x32_bf16 v[48:51], v[204:207], v[144:147], v[48:51]
	v_mfma_f32_16x16x32_bf16 v[36:39], v[196:199], v[162:165], v[36:39]
	v_mfma_f32_16x16x32_bf16 v[32:35], v[204:207], v[162:165], v[32:35]
	v_mfma_f32_16x16x32_bf16 v[20:23], v[196:199], v[170:173], v[20:23]
	v_mfma_f32_16x16x32_bf16 v[16:19], v[204:207], v[170:173], v[16:19]
	v_mfma_f32_16x16x32_bf16 v[4:7], v[196:199], v[188:191], v[4:7]
	v_mfma_f32_16x16x32_bf16 v[0:3], v[204:207], v[188:191], v[0:3]
	v_mfma_f32_16x16x32_bf16 v[52:55], v[200:203], v[148:151], v[52:55]
	v_mfma_f32_16x16x32_bf16 v[48:51], v[208:211], v[148:151], v[48:51]
	v_mfma_f32_16x16x32_bf16 v[36:39], v[200:203], v[166:169], v[36:39]
	v_mfma_f32_16x16x32_bf16 v[32:35], v[208:211], v[166:169], v[32:35]
	v_mfma_f32_16x16x32_bf16 v[20:23], v[200:203], v[174:177], v[20:23]
	v_mfma_f32_16x16x32_bf16 v[16:19], v[208:211], v[174:177], v[16:19]
	v_mfma_f32_16x16x32_bf16 v[4:7], v[200:203], v[192:195], v[4:7]
	v_mfma_f32_16x16x32_bf16 v[0:3], v[208:211], v[192:195], v[0:3]
	s_setprio 0
	s_add_i32 s62, s62, 2
	s_add_u32 s60, s60, 0x100
	s_addc_u32 s61, s61, 0
	s_cmpk_gt_u32 s62, 0x55
	s_mov_b64 s[26:27], s[28:29]
	s_barrier
	s_cbranch_scc0 .LBB0_785
	s_branch .Lpeel_3_exit
.LBB0_785:
	ds_read_b128 v[128:131], v185
	ds_read_b128 v[132:135], v185 offset:1024
	ds_read_b128 v[136:139], v185 offset:2048
	ds_read_b128 v[140:143], v185 offset:3072
	s_add_u32 s28, s26, 0x100
	s_addc_u32 s29, s27, 0
	s_cmpk_eq_i32 s62, 0x54
	s_cselect_b32 s37, s23, s29
	s_cselect_b32 s36, s22, s28
	s_cselect_b32 s31, s25, s61
	s_cselect_b32 s30, s24, s60

; #define PG8_STAGE(bufoff, gbase, voff) do { _Pragma("unroll") for (int _i = 0; _i < 2; ++_i) \
;         __builtin_amdgcn_global_load_lds((const unsigned*)((const char*)(gbase) + (voff)[_i]), (LAS unsigned*)(lds + (bufoff) + ldsw + _i * 8192), 16, 0, 0); } while (0)
; #define PG8_LDA(dst, b, h) do { _Pragma("unroll") for (int m = 0; m < 4; ++m) _Pragma("unroll") for (int k = 0; k < 2; ++k) dst[m][k] = *(const LAS bf16x8*)(lds + PG8_SA(b, h) + aoff + m * 2048 + k * 1024); } while (0)
; #define PG8_LDB(dst, b, h) do { _Pragma("unroll") for (int n = 0; n < 2; ++n) _Pragma("unroll") for (int k = 0; k < 2; ++k) dst[n][k] = *(const LAS bf16x8*)(lds + PG8_SB(b, h) + boff + n * 2048 + k * 1024); } while (0)
; #define PG8_SCHED __builtin_amdgcn_sched_barrier(0)
; template <class Epi>
; DI void gemm_phase(LAS unsigned char* lds, int wid, int K, int lda, int ldb, bool bperm, const Sched3& S, const Epi& E) {
;     ...
;             PG8_LDB(B0, 0, 0); PG8_SCHED; PG8_LDA(At, 0, 0); PG8_STAGE(PG8_SA(1, 1), a1 + hA, voffA);
	s_add_i32 m0, s44, 0xc000
	ds_read_b128 v[144:147], v186
	ds_read_b128 v[148:151], v186 offset:1024
	ds_read_b128 v[162:165], v186 offset:2048
	ds_read_b128 v[166:169], v186 offset:3072
	ds_read_b128 v[170:173], v186 offset:4096
	ds_read_b128 v[174:177], v186 offset:5120
	ds_read_b128 v[188:191], v186 offset:6144
	ds_read_b128 v[192:195], v186 offset:7168
	global_load_lds_dwordx4 v156, s[26:27]

; #define PG8_STAGE(bufoff, gbase, voff) do { _Pragma("unroll") for (int _i = 0; _i < 2; ++_i) \
;         __builtin_amdgcn_global_load_lds((const unsigned*)((const char*)(gbase) + (voff)[_i]), (LAS unsigned*)(lds + (bufoff) + ldsw + _i * 8192), 16, 0, 0); } while (0)
; #define PG8_LDA(dst, b, h) do { _Pragma("unroll") for (int m = 0; m < 4; ++m) _Pragma("unroll") for (int k = 0; k < 2; ++k) dst[m][k] = *(const LAS bf16x8*)(lds + PG8_SA(b, h) + aoff + m * 2048 + k * 1024); } while (0)
; #define PG8_LDB(dst, b, h) do { _Pragma("unroll") for (int n = 0; n < 2; ++n) _Pragma("unroll") for (int k = 0; k < 2; ++k) dst[n][k] = *(const LAS bf16x8*)(lds + PG8_SB(b, h) + boff + n * 2048 + k * 1024); } while (0)
; #define PG8_MMA(ai, bj, At, Bt) do { __builtin_amdgcn_s_setprio(1); _Pragma("unroll") for (int m = 0; m < 4; ++m) _Pragma("unroll") for (int n = 0; n < 2; ++n) _Pragma("unroll") for (int k = 0; k < 2; ++k) \
;         acc[ai][bj][m][n] = __builtin_amdgcn_mfma_f32_16x16x32_bf16(Bt[n][k], At[m][k], acc[ai][bj][m][n], 0, 0, 0); __builtin_amdgcn_s_setprio(0); } while (0)
; #define PG8_WAIT_L(n) asm volatile("s_waitcnt lgkmcnt(" #n ")" ::: "memory")
; #define PG8_BAR __builtin_amdgcn_s_barrier()
; #define PG8_SCHED __builtin_amdgcn_sched_barrier(0)
; template <class Epi>
; DI void gemm_phase(LAS unsigned char* lds, int wid, int K, int lda, int ldb, bool bperm, const Sched3& S, const Epi& E) {
;     ...
;             PG8_LDB(B0, 0, 0); PG8_SCHED; PG8_LDA(At, 0, 0); PG8_STAGE(PG8_SA(1, 1), a1 + hA, voffA);
;             PG8_WAIT_L(8); PG8_BAR; PG8_WAIT_L(0); PG8_MMA(0, 0, At, B0); PG8_BAR; PG8_SCHED;
;             PG8_LDB(B1, 0, 1); PG8_STAGE(PG8_SB(0, 0), b2, voffB);
	s_add_i32 m0, s44, 0xe000
	s_nop 0
	global_load_lds_dwordx4 v158, s[26:27]
	s_waitcnt lgkmcnt(8)
	s_barrier
	s_waitcnt lgkmcnt(0)
	s_setprio 1
	s_waitcnt lgkmcnt(0)
	v_mfma_f32_16x16x32_bf16 v[124:127], v[128:131], v[144:147], v[124:127]
	v_mfma_f32_16x16x32_bf16 v[120:123], v[136:139], v[144:147], v[120:123]
	v_mfma_f32_16x16x32_bf16 v[108:111], v[128:131], v[162:165], v[108:111]
	v_mfma_f32_16x16x32_bf16 v[104:107], v[136:139], v[162:165], v[104:107]
	v_mfma_f32_16x16x32_bf16 v[92:95], v[128:131], v[170:173], v[92:95]
	v_mfma_f32_16x16x32_bf16 v[88:91], v[136:139], v[170:173], v[88:91]
	v_mfma_f32_16x16x32_bf16 v[76:79], v[128:131], v[188:191], v[76:79]
	v_mfma_f32_16x16x32_bf16 v[72:75], v[136:139], v[188:191], v[72:75]
	v_mfma_f32_16x16x32_bf16 v[124:127], v[132:135], v[148:151], v[124:127]
	v_mfma_f32_16x16x32_bf16 v[120:123], v[140:143], v[148:151], v[120:123]
	v_mfma_f32_16x16x32_bf16 v[108:111], v[132:135], v[166:169], v[108:111]
	v_mfma_f32_16x16x32_bf16 v[104:107], v[140:143], v[166:169], v[104:107]
	v_mfma_f32_16x16x32_bf16 v[92:95], v[132:135], v[174:177], v[92:95]
	v_mfma_f32_16x16x32_bf16 v[88:91], v[140:143], v[174:177], v[88:91]
	v_mfma_f32_16x16x32_bf16 v[76:79], v[132:135], v[192:195], v[76:79]
	v_mfma_f32_16x16x32_bf16 v[72:75], v[140:143], v[192:195], v[72:75]
	s_setprio 0
	s_barrier
	s_add_i32 s26, s53, s43

; #define PG8_STAGE(bufoff, gbase, voff) do { _Pragma("unroll") for (int _i = 0; _i < 2; ++_i) \
;         __builtin_amdgcn_global_load_lds((const unsigned*)((const char*)(gbase) + (voff)[_i]), (LAS unsigned*)(lds + (bufoff) + ldsw + _i * 8192), 16, 0, 0); } while (0)
; #define PG8_LDB(dst, b, h) do { _Pragma("unroll") for (int n = 0; n < 2; ++n) _Pragma("unroll") for (int k = 0; k < 2; ++k) dst[n][k] = *(const LAS bf16x8*)(lds + PG8_SB(b, h) + boff + n * 2048 + k * 1024); } while (0)
; template <class Epi>
; DI void gemm_phase(LAS unsigned char* lds, int wid, int K, int lda, int ldb, bool bperm, const Sched3& S, const Epi& E) {
;     ...
;             PG8_LDB(B1, 0, 1); PG8_STAGE(PG8_SB(0, 0), b2, voffB);
	s_mov_b32 m0, s26
	ds_read_b128 v[196:199], v187
	ds_read_b128 v[200:203], v187 offset:1024
	ds_read_b128 v[204:207], v187 offset:2048
	ds_read_b128 v[208:211], v187 offset:3072
	global_load_lds_dwordx4 v152, s[30:31]

; #define PG8_STAGE(bufoff, gbase, voff) do { _Pragma("unroll") for (int _i = 0; _i < 2; ++_i) \
;         __builtin_amdgcn_global_load_lds((const unsigned*)((const char*)(gbase) + (voff)[_i]), (LAS unsigned*)(lds + (bufoff) + ldsw + _i * 8192), 16, 0, 0); } while (0)
; #define PG8_LDA(dst, b, h) do { _Pragma("unroll") for (int m = 0; m < 4; ++m) _Pragma("unroll") for (int k = 0; k < 2; ++k) dst[m][k] = *(const LAS bf16x8*)(lds + PG8_SA(b, h) + aoff + m * 2048 + k * 1024); } while (0)
; #define PG8_LDB(dst, b, h) do { _Pragma("unroll") for (int n = 0; n < 2; ++n) _Pragma("unroll") for (int k = 0; k < 2; ++k) dst[n][k] = *(const LAS bf16x8*)(lds + PG8_SB(b, h) + boff + n * 2048 + k * 1024); } while (0)
; #define PG8_MMA(ai, bj, At, Bt) do { __builtin_amdgcn_s_setprio(1); _Pragma("unroll") for (int m = 0; m < 4; ++m) _Pragma("unroll") for (int n = 0; n < 2; ++n) _Pragma("unroll") for (int k = 0; k < 2; ++k) \
;         acc[ai][bj][m][n] = __builtin_amdgcn_mfma_f32_16x16x32_bf16(Bt[n][k], At[m][k], acc[ai][bj][m][n], 0, 0, 0); __builtin_amdgcn_s_setprio(0); } while (0)
; #define PG8_WAIT_L(n) asm volatile("s_waitcnt lgkmcnt(" #n ")" ::: "memory")
; #define PG8_BAR __builtin_amdgcn_s_barrier()
; #define PG8_SCHED __builtin_amdgcn_sched_barrier(0)
; template <class Epi>
; DI void gemm_phase(LAS unsigned char* lds, int wid, int K, int lda, int ldb, bool bperm, const Sched3& S, const Epi& E) {
;     ...
;             PG8_LDB(B1, 0, 1); PG8_STAGE(PG8_SB(0, 0), b2, voffB);
;             PG8_BAR; PG8_WAIT_L(0); PG8_MMA(0, 1, At, B1); PG8_BAR;
;             PG8_LDA(At, 0, 1); PG8_STAGE(PG8_SA(0, 0), a2, voffA);
;             PG8_BAR; PG8_WAIT_L(0); if (full) PG8_MMA(1, 0, At, B0); PG8_BAR; PG8_SCHED;
;             PG8_STAGE(PG8_SB(0, 1), b2 + hstepB, voffB);
	s_add_i32 m0, s26, 0x2000
	s_nop 0
	global_load_lds_dwordx4 v154, s[30:31]
	s_barrier
	s_waitcnt lgkmcnt(0)
	s_setprio 1
	s_waitcnt lgkmcnt(0)
	v_mfma_f32_16x16x32_bf16 v[116:119], v[196:199], v[144:147], v[116:119]
	v_mfma_f32_16x16x32_bf16 v[112:115], v[204:207], v[144:147], v[112:115]
	v_mfma_f32_16x16x32_bf16 v[100:103], v[196:199], v[162:165], v[100:103]
	v_mfma_f32_16x16x32_bf16 v[96:99], v[204:207], v[162:165], v[96:99]
	v_mfma_f32_16x16x32_bf16 v[84:87], v[196:199], v[170:173], v[84:87]
	v_mfma_f32_16x16x32_bf16 v[80:83], v[204:207], v[170:173], v[80:83]
	v_mfma_f32_16x16x32_bf16 v[68:71], v[196:199], v[188:191], v[68:71]
	v_mfma_f32_16x16x32_bf16 v[64:67], v[204:207], v[188:191], v[64:67]
	v_mfma_f32_16x16x32_bf16 v[116:119], v[200:203], v[148:151], v[116:119]
	v_mfma_f32_16x16x32_bf16 v[112:115], v[208:211], v[148:151], v[112:115]
	v_mfma_f32_16x16x32_bf16 v[100:103], v[200:203], v[166:169], v[100:103]
	v_mfma_f32_16x16x32_bf16 v[96:99], v[208:211], v[166:169], v[96:99]
	v_mfma_f32_16x16x32_bf16 v[84:87], v[200:203], v[174:177], v[84:87]
	v_mfma_f32_16x16x32_bf16 v[80:83], v[208:211], v[174:177], v[80:83]
	v_mfma_f32_16x16x32_bf16 v[68:71], v[200:203], v[192:195], v[68:71]
	v_mfma_f32_16x16x32_bf16 v[64:67], v[208:211], v[192:195], v[64:67]
	s_setprio 0
	s_mov_b32 m0, s44
	s_mov_b64 s[100:101], s[36:37]
	s_barrier
	ds_read_b128 v[144:147], v186 offset:16384
	ds_read_b128 v[148:151], v186 offset:17408
	ds_read_b128 v[162:165], v186 offset:18432
	ds_read_b128 v[166:169], v186 offset:19456
	ds_read_b128 v[170:173], v186 offset:20480
	ds_read_b128 v[174:177], v186 offset:21504
	ds_read_b128 v[188:191], v186 offset:22528
	ds_read_b128 v[192:195], v186 offset:23552
	global_load_lds_dwordx4 v152, s[36:37]
	s_mov_b64 s[100:101], s[36:37]
	s_mov_b32 m0, s45
	s_nop 0
	global_load_lds_dwordx4 v154, s[36:37]
	s_barrier
	s_waitcnt lgkmcnt(0)
	s_setprio 1
	s_waitcnt lgkmcnt(0)
	v_mfma_f32_16x16x32_bf16 v[60:63], v[128:131], v[144:147], v[60:63]
	v_mfma_f32_16x16x32_bf16 v[56:59], v[136:139], v[144:147], v[56:59]
	v_mfma_f32_16x16x32_bf16 v[44:47], v[128:131], v[162:165], v[44:47]
	v_mfma_f32_16x16x32_bf16 v[40:43], v[136:139], v[162:165], v[40:43]
	v_mfma_f32_16x16x32_bf16 v[28:31], v[128:131], v[170:173], v[28:31]
	v_mfma_f32_16x16x32_bf16 v[24:27], v[136:139], v[170:173], v[24:27]
	v_mfma_f32_16x16x32_bf16 v[12:15], v[128:131], v[188:191], v[12:15]
	v_mfma_f32_16x16x32_bf16 v[8:11], v[136:139], v[188:191], v[8:11]
	v_mfma_f32_16x16x32_bf16 v[60:63], v[132:135], v[148:151], v[60:63]
	v_mfma_f32_16x16x32_bf16 v[56:59], v[140:143], v[148:151], v[56:59]
	v_mfma_f32_16x16x32_bf16 v[44:47], v[132:135], v[166:169], v[44:47]
	v_mfma_f32_16x16x32_bf16 v[40:43], v[140:143], v[166:169], v[40:43]
	v_mfma_f32_16x16x32_bf16 v[28:31], v[132:135], v[174:177], v[28:31]
	v_mfma_f32_16x16x32_bf16 v[24:27], v[140:143], v[174:177], v[24:27]
	v_mfma_f32_16x16x32_bf16 v[12:15], v[132:135], v[192:195], v[12:15]
	v_mfma_f32_16x16x32_bf16 v[8:11], v[140:143], v[192:195], v[8:11]
	s_setprio 0
	s_barrier
	s_add_u32 s26, s30, 0x160000
	s_addc_u32 s27, s31, 0
	s_add_i32 s63, s54, s43

; #define PG8_STAGE(bufoff, gbase, voff) do { _Pragma("unroll") for (int _i = 0; _i < 2; ++_i) \
;         __builtin_amdgcn_global_load_lds((const unsigned*)((const char*)(gbase) + (voff)[_i]), (LAS unsigned*)(lds + (bufoff) + ldsw + _i * 8192), 16, 0, 0); } while (0)
; template <class Epi>
; DI void gemm_phase(LAS unsigned char* lds, int wid, int K, int lda, int ldb, bool bperm, const Sched3& S, const Epi& E) {
;     ...
;             PG8_STAGE(PG8_SB(0, 1), b2 + hstepB, voffB);
	s_mov_b32 m0, s63
	s_nop 0
	global_load_lds_dwordx4 v152, s[26:27]

; #define PG8_STAGE(bufoff, gbase, voff) do { _Pragma("unroll") for (int _i = 0; _i < 2; ++_i) \
;         __builtin_amdgcn_global_load_lds((const unsigned*)((const char*)(gbase) + (voff)[_i]), (LAS unsigned*)(lds + (bufoff) + ldsw + _i * 8192), 16, 0, 0); } while (0)
; #define PG8_LDA(dst, b, h) do { _Pragma("unroll") for (int m = 0; m < 4; ++m) _Pragma("unroll") for (int k = 0; k < 2; ++k) dst[m][k] = *(const LAS bf16x8*)(lds + PG8_SA(b, h) + aoff + m * 2048 + k * 1024); } while (0)
; #define PG8_LDB(dst, b, h) do { _Pragma("unroll") for (int n = 0; n < 2; ++n) _Pragma("unroll") for (int k = 0; k < 2; ++k) dst[n][k] = *(const LAS bf16x8*)(lds + PG8_SB(b, h) + boff + n * 2048 + k * 1024); } while (0)
; #define PG8_MMA(ai, bj, At, Bt) do { __builtin_amdgcn_s_setprio(1); _Pragma("unroll") for (int m = 0; m < 4; ++m) _Pragma("unroll") for (int n = 0; n < 2; ++n) _Pragma("unroll") for (int k = 0; k < 2; ++k) \
;         acc[ai][bj][m][n] = __builtin_amdgcn_mfma_f32_16x16x32_bf16(Bt[n][k], At[m][k], acc[ai][bj][m][n], 0, 0, 0); __builtin_amdgcn_s_setprio(0); } while (0)
; #define PG8_WAIT_V(n) asm volatile("s_waitcnt vmcnt(" #n ")" ::: "memory")
; #define PG8_BAR __builtin_amdgcn_s_barrier()
; #define PG8_SCHED __builtin_amdgcn_sched_barrier(0)
; template <class Epi>
; DI void gemm_phase(LAS unsigned char* lds, int wid, int K, int lda, int ldb, bool bperm, const Sched3& S, const Epi& E) {
;     ...
;             PG8_STAGE(PG8_SB(0, 1), b2 + hstepB, voffB);
;             PG8_WAIT_V(6); PG8_BAR; if (full) PG8_MMA(1, 1, At, B1); PG8_BAR;
;             PG8_LDB(B0, 1, 0); PG8_SCHED; PG8_LDA(At, 1, 0); PG8_STAGE(PG8_SA(0, 1), a2 + h2, voffA);
	s_add_i32 m0, s63, 0x2000
	s_nop 0
	global_load_lds_dwordx4 v154, s[26:27]
	s_waitcnt vmcnt(6)
	s_barrier
	s_setprio 1
	v_mfma_f32_16x16x32_bf16 v[52:55], v[196:199], v[144:147], v[52:55]
	v_mfma_f32_16x16x32_bf16 v[48:51], v[204:207], v[144:147], v[48:51]
	v_mfma_f32_16x16x32_bf16 v[36:39], v[196:199], v[162:165], v[36:39]
	v_mfma_f32_16x16x32_bf16 v[32:35], v[204:207], v[162:165], v[32:35]
	v_mfma_f32_16x16x32_bf16 v[20:23], v[196:199], v[170:173], v[20:23]
	v_mfma_f32_16x16x32_bf16 v[16:19], v[204:207], v[170:173], v[16:19]
	v_mfma_f32_16x16x32_bf16 v[4:7], v[196:199], v[188:191], v[4:7]
	v_mfma_f32_16x16x32_bf16 v[0:3], v[204:207], v[188:191], v[0:3]
	v_mfma_f32_16x16x32_bf16 v[52:55], v[200:203], v[148:151], v[52:55]
	v_mfma_f32_16x16x32_bf16 v[48:51], v[208:211], v[148:151], v[48:51]
	v_mfma_f32_16x16x32_bf16 v[36:39], v[200:203], v[166:169], v[36:39]
	v_mfma_f32_16x16x32_bf16 v[32:35], v[208:211], v[166:169], v[32:35]
	v_mfma_f32_16x16x32_bf16 v[20:23], v[200:203], v[174:177], v[20:23]
	v_mfma_f32_16x16x32_bf16 v[16:19], v[208:211], v[174:177], v[16:19]
	v_mfma_f32_16x16x32_bf16 v[4:7], v[200:203], v[192:195], v[4:7]
	v_mfma_f32_16x16x32_bf16 v[0:3], v[208:211], v[192:195], v[0:3]
	s_setprio 0
	s_add_i32 s63, 0, 0x18000
	v_add_u32_e32 v140, s63, v181
	s_barrier
	ds_read_b128 v[128:131], v140
	ds_read_b128 v[132:135], v140 offset:1024
	ds_read_b128 v[136:139], v140 offset:2048
	ds_read_b128 v[140:143], v140 offset:3072
	s_add_u32 s26, s36, 0x160000
	s_addc_u32 s27, s37, 0
	s_mov_b32 m0, s46

; #define PG8_STAGE(bufoff, gbase, voff) do { _Pragma("unroll") for (int _i = 0; _i < 2; ++_i) \
;         __builtin_amdgcn_global_load_lds((const unsigned*)((const char*)(gbase) + (voff)[_i]), (LAS unsigned*)(lds + (bufoff) + ldsw + _i * 8192), 16, 0, 0); } while (0)
; #define PG8_LDA(dst, b, h) do { _Pragma("unroll") for (int m = 0; m < 4; ++m) _Pragma("unroll") for (int k = 0; k < 2; ++k) dst[m][k] = *(const LAS bf16x8*)(lds + PG8_SA(b, h) + aoff + m * 2048 + k * 1024); } while (0)
; #define PG8_LDB(dst, b, h) do { _Pragma("unroll") for (int n = 0; n < 2; ++n) _Pragma("unroll") for (int k = 0; k < 2; ++k) dst[n][k] = *(const LAS bf16x8*)(lds + PG8_SB(b, h) + boff + n * 2048 + k * 1024); } while (0)
; #define PG8_SCHED __builtin_amdgcn_sched_barrier(0)
; template <class Epi>
; DI void gemm_phase(LAS unsigned char* lds, int wid, int K, int lda, int ldb, bool bperm, const Sched3& S, const Epi& E) {
;     ...
;             PG8_LDB(B0, 1, 0); PG8_SCHED; PG8_LDA(At, 1, 0); PG8_STAGE(PG8_SA(0, 1), a2 + h2, voffA);
	ds_read_b128 v[144:147], v186 offset:32768
	ds_read_b128 v[148:151], v186 offset:33792
	ds_read_b128 v[162:165], v186 offset:34816
	ds_read_b128 v[166:169], v186 offset:35840
	ds_read_b128 v[170:173], v186 offset:36864
	ds_read_b128 v[174:177], v186 offset:37888
	ds_read_b128 v[188:191], v186 offset:38912
	ds_read_b128 v[192:195], v186 offset:39936
	global_load_lds_dwordx4 v152, s[26:27]

; #define PG8_STAGE(bufoff, gbase, voff) do { _Pragma("unroll") for (int _i = 0; _i < 2; ++_i) \
;         __builtin_amdgcn_global_load_lds((const unsigned*)((const char*)(gbase) + (voff)[_i]), (LAS unsigned*)(lds + (bufoff) + ldsw + _i * 8192), 16, 0, 0); } while (0)
; #define PG8_LDA(dst, b, h) do { _Pragma("unroll") for (int m = 0; m < 4; ++m) _Pragma("unroll") for (int k = 0; k < 2; ++k) dst[m][k] = *(const LAS bf16x8*)(lds + PG8_SA(b, h) + aoff + m * 2048 + k * 1024); } while (0)
; #define PG8_LDB(dst, b, h) do { _Pragma("unroll") for (int n = 0; n < 2; ++n) _Pragma("unroll") for (int k = 0; k < 2; ++k) dst[n][k] = *(const LAS bf16x8*)(lds + PG8_SB(b, h) + boff + n * 2048 + k * 1024); } while (0)
; #define PG8_MMA(ai, bj, At, Bt) do { __builtin_amdgcn_s_setprio(1); _Pragma("unroll") for (int m = 0; m < 4; ++m) _Pragma("unroll") for (int n = 0; n < 2; ++n) _Pragma("unroll") for (int k = 0; k < 2; ++k) \
;         acc[ai][bj][m][n] = __builtin_amdgcn_mfma_f32_16x16x32_bf16(Bt[n][k], At[m][k], acc[ai][bj][m][n], 0, 0, 0); __builtin_amdgcn_s_setprio(0); } while (0)
; #define PG8_WAIT_L(n) asm volatile("s_waitcnt lgkmcnt(" #n ")" ::: "memory")
; #define PG8_BAR __builtin_amdgcn_s_barrier()
; #define PG8_SCHED __builtin_amdgcn_sched_barrier(0)
; template <class Epi>
; DI void gemm_phase(LAS unsigned char* lds, int wid, int K, int lda, int ldb, bool bperm, const Sched3& S, const Epi& E) {
;     ...
;             PG8_LDB(B0, 1, 0); PG8_SCHED; PG8_LDA(At, 1, 0); PG8_STAGE(PG8_SA(0, 1), a2 + h2, voffA);
;             PG8_WAIT_L(8); PG8_BAR; PG8_WAIT_L(0); PG8_MMA(0, 0, At, B0); PG8_BAR; PG8_SCHED;
;             PG8_LDB(B1, 1, 1); PG8_STAGE(PG8_SB(1, 0), b3, voffB);
	s_mov_b32 m0, s47
	s_nop 0
	global_load_lds_dwordx4 v154, s[26:27]
	s_waitcnt lgkmcnt(8)
	s_barrier
	s_waitcnt lgkmcnt(0)
	s_setprio 1
	s_waitcnt lgkmcnt(0)
	v_mfma_f32_16x16x32_bf16 v[124:127], v[128:131], v[144:147], v[124:127]
	v_mfma_f32_16x16x32_bf16 v[120:123], v[136:139], v[144:147], v[120:123]
	v_mfma_f32_16x16x32_bf16 v[108:111], v[128:131], v[162:165], v[108:111]
	v_mfma_f32_16x16x32_bf16 v[104:107], v[136:139], v[162:165], v[104:107]
	v_mfma_f32_16x16x32_bf16 v[92:95], v[128:131], v[170:173], v[92:95]
	v_mfma_f32_16x16x32_bf16 v[88:91], v[136:139], v[170:173], v[88:91]
	v_mfma_f32_16x16x32_bf16 v[76:79], v[128:131], v[188:191], v[76:79]
	v_mfma_f32_16x16x32_bf16 v[72:75], v[136:139], v[188:191], v[72:75]
	v_mfma_f32_16x16x32_bf16 v[124:127], v[132:135], v[148:151], v[124:127]
	v_mfma_f32_16x16x32_bf16 v[120:123], v[140:143], v[148:151], v[120:123]
	v_mfma_f32_16x16x32_bf16 v[108:111], v[132:135], v[166:169], v[108:111]
	v_mfma_f32_16x16x32_bf16 v[104:107], v[140:143], v[166:169], v[104:107]
	v_mfma_f32_16x16x32_bf16 v[92:95], v[132:135], v[174:177], v[92:95]
	v_mfma_f32_16x16x32_bf16 v[88:91], v[140:143], v[174:177], v[88:91]
	v_mfma_f32_16x16x32_bf16 v[76:79], v[132:135], v[192:195], v[76:79]
	v_mfma_f32_16x16x32_bf16 v[72:75], v[140:143], v[192:195], v[72:75]
	s_setprio 0
	s_barrier
	s_add_i32 s36, 0, 0x1c000
	s_add_i32 s26, s63, s43
	v_add_u32_e32 v208, s36, v181

; #define PG8_STAGE(bufoff, gbase, voff) do { _Pragma("unroll") for (int _i = 0; _i < 2; ++_i) \
;         __builtin_amdgcn_global_load_lds((const unsigned*)((const char*)(gbase) + (voff)[_i]), (LAS unsigned*)(lds + (bufoff) + ldsw + _i * 8192), 16, 0, 0); } while (0)
; #define PG8_LDB(dst, b, h) do { _Pragma("unroll") for (int n = 0; n < 2; ++n) _Pragma("unroll") for (int k = 0; k < 2; ++k) dst[n][k] = *(const LAS bf16x8*)(lds + PG8_SB(b, h) + boff + n * 2048 + k * 1024); } while (0)
; template <class Epi>
; DI void gemm_phase(LAS unsigned char* lds, int wid, int K, int lda, int ldb, bool bperm, const Sched3& S, const Epi& E) {
;     ...
;             PG8_LDB(B1, 1, 1); PG8_STAGE(PG8_SB(1, 0), b3, voffB);
	s_sub_i32 m0, s26, 0x80
	ds_read_b128 v[196:199], v208
	ds_read_b128 v[200:203], v208 offset:1024
	ds_read_b128 v[204:207], v208 offset:2048
	ds_read_b128 v[208:211], v208 offset:3072
	global_load_lds_dwordx4 v152, s[30:31] offset:128

; #define PG8_STAGE(bufoff, gbase, voff) do { _Pragma("unroll") for (int _i = 0; _i < 2; ++_i) \
;         __builtin_amdgcn_global_load_lds((const unsigned*)((const char*)(gbase) + (voff)[_i]), (LAS unsigned*)(lds + (bufoff) + ldsw + _i * 8192), 16, 0, 0); } while (0)
; #define PG8_LDA(dst, b, h) do { _Pragma("unroll") for (int m = 0; m < 4; ++m) _Pragma("unroll") for (int k = 0; k < 2; ++k) dst[m][k] = *(const LAS bf16x8*)(lds + PG8_SA(b, h) + aoff + m * 2048 + k * 1024); } while (0)
; #define PG8_LDB(dst, b, h) do { _Pragma("unroll") for (int n = 0; n < 2; ++n) _Pragma("unroll") for (int k = 0; k < 2; ++k) dst[n][k] = *(const LAS bf16x8*)(lds + PG8_SB(b, h) + boff + n * 2048 + k * 1024); } while (0)
; #define PG8_MMA(ai, bj, At, Bt) do { __builtin_amdgcn_s_setprio(1); _Pragma("unroll") for (int m = 0; m < 4; ++m) _Pragma("unroll") for (int n = 0; n < 2; ++n) _Pragma("unroll") for (int k = 0; k < 2; ++k) \
;         acc[ai][bj][m][n] = __builtin_amdgcn_mfma_f32_16x16x32_bf16(Bt[n][k], At[m][k], acc[ai][bj][m][n], 0, 0, 0); __builtin_amdgcn_s_setprio(0); } while (0)
; #define PG8_WAIT_L(n) asm volatile("s_waitcnt lgkmcnt(" #n ")" ::: "memory")
; #define PG8_BAR __builtin_amdgcn_s_barrier()
; template <class Epi>
; DI void gemm_phase(LAS unsigned char* lds, int wid, int K, int lda, int ldb, bool bperm, const Sched3& S, const Epi& E) {
;     ...
;             PG8_LDB(B1, 1, 1); PG8_STAGE(PG8_SB(1, 0), b3, voffB);
;             PG8_BAR; PG8_WAIT_L(0); PG8_MMA(0, 1, At, B1); PG8_BAR;
;             PG8_LDA(At, 1, 1); PG8_STAGE(PG8_SA(1, 0), a3, voffA);
	s_add_i32 m0, s26, 0x1f80
	s_nop 0
	global_load_lds_dwordx4 v154, s[30:31] offset:128
	s_barrier
	s_waitcnt lgkmcnt(0)
	s_setprio 1
	s_waitcnt lgkmcnt(0)
	v_mfma_f32_16x16x32_bf16 v[116:119], v[196:199], v[144:147], v[116:119]
	v_mfma_f32_16x16x32_bf16 v[112:115], v[204:207], v[144:147], v[112:115]
	v_mfma_f32_16x16x32_bf16 v[100:103], v[196:199], v[162:165], v[100:103]
	v_mfma_f32_16x16x32_bf16 v[96:99], v[204:207], v[162:165], v[96:99]
	v_mfma_f32_16x16x32_bf16 v[84:87], v[196:199], v[170:173], v[84:87]
	v_mfma_f32_16x16x32_bf16 v[80:83], v[204:207], v[170:173], v[80:83]
	v_mfma_f32_16x16x32_bf16 v[68:71], v[196:199], v[188:191], v[68:71]
	v_mfma_f32_16x16x32_bf16 v[64:67], v[204:207], v[188:191], v[64:67]
	v_mfma_f32_16x16x32_bf16 v[116:119], v[200:203], v[148:151], v[116:119]
	v_mfma_f32_16x16x32_bf16 v[112:115], v[208:211], v[148:151], v[112:115]
	v_mfma_f32_16x16x32_bf16 v[100:103], v[200:203], v[166:169], v[100:103]
	v_mfma_f32_16x16x32_bf16 v[96:99], v[208:211], v[166:169], v[96:99]
	v_mfma_f32_16x16x32_bf16 v[84:87], v[200:203], v[174:177], v[84:87]
	v_mfma_f32_16x16x32_bf16 v[80:83], v[208:211], v[174:177], v[80:83]
	v_mfma_f32_16x16x32_bf16 v[68:71], v[200:203], v[192:195], v[68:71]
	v_mfma_f32_16x16x32_bf16 v[64:67], v[208:211], v[192:195], v[64:67]
	s_setprio 0
	s_sub_i32 m0, s49, 0x80

; #define PG8_STAGE(bufoff, gbase, voff) do { _Pragma("unroll") for (int _i = 0; _i < 2; ++_i) \
;         __builtin_amdgcn_global_load_lds((const unsigned*)((const char*)(gbase) + (voff)[_i]), (LAS unsigned*)(lds + (bufoff) + ldsw + _i * 8192), 16, 0, 0); } while (0)
; #define PG8_LDA(dst, b, h) do { _Pragma("unroll") for (int m = 0; m < 4; ++m) _Pragma("unroll") for (int k = 0; k < 2; ++k) dst[m][k] = *(const LAS bf16x8*)(lds + PG8_SA(b, h) + aoff + m * 2048 + k * 1024); } while (0)
; template <class Epi>
; DI void gemm_phase(LAS unsigned char* lds, int wid, int K, int lda, int ldb, bool bperm, const Sched3& S, const Epi& E) {
;     ...
;             PG8_LDA(At, 1, 1); PG8_STAGE(PG8_SA(1, 0), a3, voffA);
	s_barrier
	ds_read_b128 v[144:147], v186 offset:49152
	ds_read_b128 v[148:151], v186 offset:50176
	ds_read_b128 v[162:165], v186 offset:51200
	ds_read_b128 v[166:169], v186 offset:52224
	ds_read_b128 v[170:173], v186 offset:53248
	ds_read_b128 v[174:177], v186 offset:54272
	ds_read_b128 v[188:191], v186 offset:55296
	ds_read_b128 v[192:195], v186 offset:56320
	global_load_lds_dwordx4 v152, s[100:101] offset:128

; #define PG8_STAGE(bufoff, gbase, voff) do { _Pragma("unroll") for (int _i = 0; _i < 2; ++_i) \
;         __builtin_amdgcn_global_load_lds((const unsigned*)((const char*)(gbase) + (voff)[_i]), (LAS unsigned*)(lds + (bufoff) + ldsw + _i * 8192), 16, 0, 0); } while (0)
; #define PG8_LDA(dst, b, h) do { _Pragma("unroll") for (int m = 0; m < 4; ++m) _Pragma("unroll") for (int k = 0; k < 2; ++k) dst[m][k] = *(const LAS bf16x8*)(lds + PG8_SA(b, h) + aoff + m * 2048 + k * 1024); } while (0)
; #define PG8_MMA(ai, bj, At, Bt) do { __builtin_amdgcn_s_setprio(1); _Pragma("unroll") for (int m = 0; m < 4; ++m) _Pragma("unroll") for (int n = 0; n < 2; ++n) _Pragma("unroll") for (int k = 0; k < 2; ++k) \
;         acc[ai][bj][m][n] = __builtin_amdgcn_mfma_f32_16x16x32_bf16(Bt[n][k], At[m][k], acc[ai][bj][m][n], 0, 0, 0); __builtin_amdgcn_s_setprio(0); } while (0)
; #define PG8_WAIT_L(n) asm volatile("s_waitcnt lgkmcnt(" #n ")" ::: "memory")
; #define PG8_BAR __builtin_amdgcn_s_barrier()
; #define PG8_SCHED __builtin_amdgcn_sched_barrier(0)
; template <class Epi>
; DI void gemm_phase(LAS unsigned char* lds, int wid, int K, int lda, int ldb, bool bperm, const Sched3& S, const Epi& E) {
;     ...
;             PG8_LDA(At, 1, 1); PG8_STAGE(PG8_SA(1, 0), a3, voffA);
;             PG8_BAR; PG8_WAIT_L(0); if (full) PG8_MMA(1, 0, At, B0); PG8_BAR; PG8_SCHED;
;             PG8_STAGE(PG8_SB(1, 1), b3 + hstepB, voffB);
	s_sub_i32 m0, s50, 0x80
	s_nop 0
	global_load_lds_dwordx4 v154, s[100:101] offset:128
	s_barrier
	s_waitcnt lgkmcnt(0)
	s_setprio 1
	s_waitcnt lgkmcnt(0)
	v_mfma_f32_16x16x32_bf16 v[60:63], v[128:131], v[144:147], v[60:63]
	v_mfma_f32_16x16x32_bf16 v[56:59], v[136:139], v[144:147], v[56:59]
	v_mfma_f32_16x16x32_bf16 v[44:47], v[128:131], v[162:165], v[44:47]
	v_mfma_f32_16x16x32_bf16 v[40:43], v[136:139], v[162:165], v[40:43]
	v_mfma_f32_16x16x32_bf16 v[28:31], v[128:131], v[170:173], v[28:31]
	v_mfma_f32_16x16x32_bf16 v[24:27], v[136:139], v[170:173], v[24:27]
	v_mfma_f32_16x16x32_bf16 v[12:15], v[128:131], v[188:191], v[12:15]
	v_mfma_f32_16x16x32_bf16 v[8:11], v[136:139], v[188:191], v[8:11]
	v_mfma_f32_16x16x32_bf16 v[60:63], v[132:135], v[148:151], v[60:63]
	v_mfma_f32_16x16x32_bf16 v[56:59], v[140:143], v[148:151], v[56:59]
	v_mfma_f32_16x16x32_bf16 v[44:47], v[132:135], v[166:169], v[44:47]
	v_mfma_f32_16x16x32_bf16 v[40:43], v[140:143], v[166:169], v[40:43]
	v_mfma_f32_16x16x32_bf16 v[28:31], v[132:135], v[174:177], v[28:31]
	v_mfma_f32_16x16x32_bf16 v[24:27], v[140:143], v[174:177], v[24:27]
	v_mfma_f32_16x16x32_bf16 v[12:15], v[132:135], v[192:195], v[12:15]
	v_mfma_f32_16x16x32_bf16 v[8:11], v[140:143], v[192:195], v[8:11]
	s_setprio 0
	s_barrier
	s_add_u32 s26, s30, 0x160080
	s_addc_u32 s27, s31, 0
	s_add_i32 s30, s36, s43

; #define PG8_STAGE(bufoff, gbase, voff) do { _Pragma("unroll") for (int _i = 0; _i < 2; ++_i) \
;         __builtin_amdgcn_global_load_lds((const unsigned*)((const char*)(gbase) + (voff)[_i]), (LAS unsigned*)(lds + (bufoff) + ldsw + _i * 8192), 16, 0, 0); } while (0)
; template <class Epi>
; DI void gemm_phase(LAS unsigned char* lds, int wid, int K, int lda, int ldb, bool bperm, const Sched3& S, const Epi& E) {
;     ...
;             PG8_STAGE(PG8_SB(1, 1), b3 + hstepB, voffB);
	s_mov_b32 m0, s30
	s_nop 0
	global_load_lds_dwordx4 v152, s[26:27]

; #define PG8_STAGE(bufoff, gbase, voff) do { _Pragma("unroll") for (int _i = 0; _i < 2; ++_i) \
;         __builtin_amdgcn_global_load_lds((const unsigned*)((const char*)(gbase) + (voff)[_i]), (LAS unsigned*)(lds + (bufoff) + ldsw + _i * 8192), 16, 0, 0); } while (0)
; #define PG8_MMA(ai, bj, At, Bt) do { __builtin_amdgcn_s_setprio(1); _Pragma("unroll") for (int m = 0; m < 4; ++m) _Pragma("unroll") for (int n = 0; n < 2; ++n) _Pragma("unroll") for (int k = 0; k < 2; ++k) \
;         acc[ai][bj][m][n] = __builtin_amdgcn_mfma_f32_16x16x32_bf16(Bt[n][k], At[m][k], acc[ai][bj][m][n], 0, 0, 0); __builtin_amdgcn_s_setprio(0); } while (0)
; #define PG8_WAIT_V(n) asm volatile("s_waitcnt vmcnt(" #n ")" ::: "memory")
; #define PG8_BAR __builtin_amdgcn_s_barrier()
; template <class Epi>
; DI void gemm_phase(LAS unsigned char* lds, int wid, int K, int lda, int ldb, bool bperm, const Sched3& S, const Epi& E) {
;     ...
;         for (int t = 0; t < nt; t += 2) {
;     ...
;             PG8_STAGE(PG8_SB(1, 1), b3 + hstepB, voffB);
;             PG8_WAIT_V(6); PG8_BAR; if (full) PG8_MMA(1, 1, At, B1); PG8_BAR;
	s_add_i32 m0, s30, 0x2000
	s_nop 0
	global_load_lds_dwordx4 v154, s[26:27]
	s_waitcnt vmcnt(6)
	s_barrier
	s_setprio 1
	v_mfma_f32_16x16x32_bf16 v[52:55], v[196:199], v[144:147], v[52:55]
	v_mfma_f32_16x16x32_bf16 v[48:51], v[204:207], v[144:147], v[48:51]
	v_mfma_f32_16x16x32_bf16 v[36:39], v[196:199], v[162:165], v[36:39]
	v_mfma_f32_16x16x32_bf16 v[32:35], v[204:207], v[162:165], v[32:35]
	v_mfma_f32_16x16x32_bf16 v[20:23], v[196:199], v[170:173], v[20:23]
	v_mfma_f32_16x16x32_bf16 v[16:19], v[204:207], v[170:173], v[16:19]
	v_mfma_f32_16x16x32_bf16 v[4:7], v[196:199], v[188:191], v[4:7]
	v_mfma_f32_16x16x32_bf16 v[0:3], v[204:207], v[188:191], v[0:3]
	v_mfma_f32_16x16x32_bf16 v[52:55], v[200:203], v[148:151], v[52:55]
	v_mfma_f32_16x16x32_bf16 v[48:51], v[208:211], v[148:151], v[48:51]
	v_mfma_f32_16x16x32_bf16 v[36:39], v[200:203], v[166:169], v[36:39]
	v_mfma_f32_16x16x32_bf16 v[32:35], v[208:211], v[166:169], v[32:35]
	v_mfma_f32_16x16x32_bf16 v[20:23], v[200:203], v[174:177], v[20:23]
	v_mfma_f32_16x16x32_bf16 v[16:19], v[208:211], v[174:177], v[16:19]
	v_mfma_f32_16x16x32_bf16 v[4:7], v[200:203], v[192:195], v[4:7]
	v_mfma_f32_16x16x32_bf16 v[0:3], v[208:211], v[192:195], v[0:3]
	s_setprio 0
	s_add_i32 s62, s62, 2
	s_add_u32 s60, s60, 0x100
	s_addc_u32 s61, s61, 0
	s_cmpk_gt_u32 s62, 0x55
	s_mov_b64 s[26:27], s[28:29]
	s_barrier
	s_cbranch_scc0 .LBB0_785

; #define PG8_STAGE(bufoff, gbase, voff) do { _Pragma("unroll") for (int _i = 0; _i < 2; ++_i) \
;         __builtin_amdgcn_global_load_lds((const unsigned*)((const char*)(gbase) + (voff)[_i]), (LAS unsigned*)(lds + (bufoff) + ldsw + _i * 8192), 16, 0, 0); } while (0)
; #define PG8_LDA(dst, b, h) do { _Pragma("unroll") for (int m = 0; m < 4; ++m) _Pragma("unroll") for (int k = 0; k < 2; ++k) dst[m][k] = *(const LAS bf16x8*)(lds + PG8_SA(b, h) + aoff + m * 2048 + k * 1024); } while (0)
; #define PG8_LDB(dst, b, h) do { _Pragma("unroll") for (int n = 0; n < 2; ++n) _Pragma("unroll") for (int k = 0; k < 2; ++k) dst[n][k] = *(const LAS bf16x8*)(lds + PG8_SB(b, h) + boff + n * 2048 + k * 1024); } while (0)
; #define PG8_SCHED __builtin_amdgcn_sched_barrier(0)
; template <class Epi>
; DI void gemm_phase(LAS unsigned char* lds, int wid, int K, int lda, int ldb, bool bperm, const Sched3& S, const Epi& E) {
;     ...
;             const bool last = (t == nt - 2);
;             const char* a1 = cA + (size_t)(t + 1) * kstep;
;             const char* a2 = last ? nA : cA + (size_t)(t + 2) * kstep; const char* b2 = last ? nB : cB + (size_t)(t + 2) * kstep;
;             const char* a3 = a2 + kstep; const char* b3 = b2 + kstep; const size_t h2 = last ? nhA : hA;
;             PG8_LDB(B0, 0, 0); PG8_SCHED; PG8_LDA(At, 0, 0); PG8_STAGE(PG8_SA(1, 1), a1 + hA, voffA);
.LBB0_872:
	s_add_u32 s36, s36, 0x80080
	s_addc_u32 s37, s37, 0
	s_add_u32 s19, s38, 0x100
	s_nop 0
	s_addc_u32 s21, s39, 0
	s_mov_b32 s27, -2
	s_waitcnt lgkmcnt(0)
	ds_read_b128 v[128:131], v189
	ds_read_b128 v[132:135], v189 offset:1024
	ds_read_b128 v[136:139], v189 offset:2048
	ds_read_b128 v[140:143], v189 offset:3072
	s_add_u32 s38, s36, 0xfff80080
	s_addc_u32 s39, s37, -1
	s_cmp_eq_u32 s27, 28
	s_cselect_b32 s41, s29, s39
	s_cselect_b32 s40, s28, s38
	s_cselect_b32 s39, s31, s21
	s_cselect_b32 s38, s30, s19

; #define PG8_STAGE(bufoff, gbase, voff) do { _Pragma("unroll") for (int _i = 0; _i < 2; ++_i) \
;         __builtin_amdgcn_global_load_lds((const unsigned*)((const char*)(gbase) + (voff)[_i]), (LAS unsigned*)(lds + (bufoff) + ldsw + _i * 8192), 16, 0, 0); } while (0)
; #define PG8_LDA(dst, b, h) do { _Pragma("unroll") for (int m = 0; m < 4; ++m) _Pragma("unroll") for (int k = 0; k < 2; ++k) dst[m][k] = *(const LAS bf16x8*)(lds + PG8_SA(b, h) + aoff + m * 2048 + k * 1024); } while (0)
; #define PG8_LDB(dst, b, h) do { _Pragma("unroll") for (int n = 0; n < 2; ++n) _Pragma("unroll") for (int k = 0; k < 2; ++k) dst[n][k] = *(const LAS bf16x8*)(lds + PG8_SB(b, h) + boff + n * 2048 + k * 1024); } while (0)
; #define PG8_SCHED __builtin_amdgcn_sched_barrier(0)
; template <class Epi>
; DI void gemm_phase(LAS unsigned char* lds, int wid, int K, int lda, int ldb, bool bperm, const Sched3& S, const Epi& E) {
;     ...
;             PG8_LDB(B0, 0, 0); PG8_SCHED; PG8_LDA(At, 0, 0); PG8_STAGE(PG8_SA(1, 1), a1 + hA, voffA);
	s_add_i32 m0, s48, 0xc000
	ds_read_b128 v[180:183], v195
	ds_read_b128 v[190:193], v195 offset:1024
	ds_read_b128 v[200:203], v195 offset:2048
	ds_read_b128 v[204:207], v195 offset:3072
	ds_read_b128 v[208:211], v195 offset:4096
	ds_read_b128 v[212:215], v195 offset:5120
	ds_read_b128 v[216:219], v195 offset:6144
	ds_read_b128 v[224:227], v195 offset:7168
	global_load_lds_dwordx4 v160, s[36:37]

; #define PG8_STAGE(bufoff, gbase, voff) do { _Pragma("unroll") for (int _i = 0; _i < 2; ++_i) \
;         __builtin_amdgcn_global_load_lds((const unsigned*)((const char*)(gbase) + (voff)[_i]), (LAS unsigned*)(lds + (bufoff) + ldsw + _i * 8192), 16, 0, 0); } while (0)
; #define PG8_LDA(dst, b, h) do { _Pragma("unroll") for (int m = 0; m < 4; ++m) _Pragma("unroll") for (int k = 0; k < 2; ++k) dst[m][k] = *(const LAS bf16x8*)(lds + PG8_SA(b, h) + aoff + m * 2048 + k * 1024); } while (0)
; #define PG8_LDB(dst, b, h) do { _Pragma("unroll") for (int n = 0; n < 2; ++n) _Pragma("unroll") for (int k = 0; k < 2; ++k) dst[n][k] = *(const LAS bf16x8*)(lds + PG8_SB(b, h) + boff + n * 2048 + k * 1024); } while (0)
; #define PG8_MMA(ai, bj, At, Bt) do { __builtin_amdgcn_s_setprio(1); _Pragma("unroll") for (int m = 0; m < 4; ++m) _Pragma("unroll") for (int n = 0; n < 2; ++n) _Pragma("unroll") for (int k = 0; k < 2; ++k) \
;         acc[ai][bj][m][n] = __builtin_amdgcn_mfma_f32_16x16x32_bf16(Bt[n][k], At[m][k], acc[ai][bj][m][n], 0, 0, 0); __builtin_amdgcn_s_setprio(0); } while (0)
; #define PG8_WAIT_L(n) asm volatile("s_waitcnt lgkmcnt(" #n ")" ::: "memory")
; #define PG8_BAR __builtin_amdgcn_s_barrier()
; #define PG8_SCHED __builtin_amdgcn_sched_barrier(0)
; template <class Epi>
; DI void gemm_phase(LAS unsigned char* lds, int wid, int K, int lda, int ldb, bool bperm, const Sched3& S, const Epi& E) {
;     ...
;             PG8_LDB(B0, 0, 0); PG8_SCHED; PG8_LDA(At, 0, 0); PG8_STAGE(PG8_SA(1, 1), a1 + hA, voffA);
;             PG8_WAIT_L(8); PG8_BAR; PG8_WAIT_L(0); PG8_MMA(0, 0, At, B0); PG8_BAR; PG8_SCHED;
;             PG8_LDB(B1, 0, 1); PG8_STAGE(PG8_SB(0, 0), b2, voffB);
	s_add_i32 m0, s48, 0xe000
	s_nop 0
	global_load_lds_dwordx4 v162, s[36:37]
	s_waitcnt lgkmcnt(8)
	s_barrier
	s_waitcnt lgkmcnt(0)
	s_setprio 1
	s_waitcnt lgkmcnt(0)
	v_mfma_f32_16x16x32_bf16 v[124:127], v[128:131], v[180:183], 0
	v_mfma_f32_16x16x32_bf16 v[120:123], v[136:139], v[180:183], 0
	v_mfma_f32_16x16x32_bf16 v[108:111], v[128:131], v[200:203], 0
	v_mfma_f32_16x16x32_bf16 v[104:107], v[136:139], v[200:203], 0
	v_mfma_f32_16x16x32_bf16 v[92:95], v[128:131], v[208:211], 0
	v_mfma_f32_16x16x32_bf16 v[88:91], v[136:139], v[208:211], 0
	v_mfma_f32_16x16x32_bf16 v[76:79], v[128:131], v[216:219], 0
	v_mfma_f32_16x16x32_bf16 v[72:75], v[136:139], v[216:219], 0
	v_mfma_f32_16x16x32_bf16 v[124:127], v[132:135], v[190:193], v[124:127]
	v_mfma_f32_16x16x32_bf16 v[120:123], v[140:143], v[190:193], v[120:123]
	v_mfma_f32_16x16x32_bf16 v[108:111], v[132:135], v[204:207], v[108:111]
	v_mfma_f32_16x16x32_bf16 v[104:107], v[140:143], v[204:207], v[104:107]
	v_mfma_f32_16x16x32_bf16 v[92:95], v[132:135], v[212:215], v[92:95]
	v_mfma_f32_16x16x32_bf16 v[88:91], v[140:143], v[212:215], v[88:91]
	v_mfma_f32_16x16x32_bf16 v[76:79], v[132:135], v[224:227], v[76:79]
	v_mfma_f32_16x16x32_bf16 v[72:75], v[140:143], v[224:227], v[72:75]
	s_setprio 0
	s_barrier
	s_add_i32 s64, s59, s47

; #define PG8_STAGE(bufoff, gbase, voff) do { _Pragma("unroll") for (int _i = 0; _i < 2; ++_i) \
;         __builtin_amdgcn_global_load_lds((const unsigned*)((const char*)(gbase) + (voff)[_i]), (LAS unsigned*)(lds + (bufoff) + ldsw + _i * 8192), 16, 0, 0); } while (0)
; #define PG8_LDB(dst, b, h) do { _Pragma("unroll") for (int n = 0; n < 2; ++n) _Pragma("unroll") for (int k = 0; k < 2; ++k) dst[n][k] = *(const LAS bf16x8*)(lds + PG8_SB(b, h) + boff + n * 2048 + k * 1024); } while (0)
; template <class Epi>
; DI void gemm_phase(LAS unsigned char* lds, int wid, int K, int lda, int ldb, bool bperm, const Sched3& S, const Epi& E) {
;     ...
;             PG8_LDB(B1, 0, 1); PG8_STAGE(PG8_SB(0, 0), b2, voffB);
	s_mov_b32 m0, s64
	ds_read_b128 v[228:231], v197
	ds_read_b128 v[232:235], v197 offset:1024
	ds_read_b128 v[236:239], v197 offset:2048
	ds_read_b128 v[240:243], v197 offset:3072
	global_load_lds_dwordx4 v146, s[38:39]

; #define PG8_STAGE(bufoff, gbase, voff) do { _Pragma("unroll") for (int _i = 0; _i < 2; ++_i) \
;         __builtin_amdgcn_global_load_lds((const unsigned*)((const char*)(gbase) + (voff)[_i]), (LAS unsigned*)(lds + (bufoff) + ldsw + _i * 8192), 16, 0, 0); } while (0)
; #define PG8_LDA(dst, b, h) do { _Pragma("unroll") for (int m = 0; m < 4; ++m) _Pragma("unroll") for (int k = 0; k < 2; ++k) dst[m][k] = *(const LAS bf16x8*)(lds + PG8_SA(b, h) + aoff + m * 2048 + k * 1024); } while (0)
; #define PG8_LDB(dst, b, h) do { _Pragma("unroll") for (int n = 0; n < 2; ++n) _Pragma("unroll") for (int k = 0; k < 2; ++k) dst[n][k] = *(const LAS bf16x8*)(lds + PG8_SB(b, h) + boff + n * 2048 + k * 1024); } while (0)
; #define PG8_MMA(ai, bj, At, Bt) do { __builtin_amdgcn_s_setprio(1); _Pragma("unroll") for (int m = 0; m < 4; ++m) _Pragma("unroll") for (int n = 0; n < 2; ++n) _Pragma("unroll") for (int k = 0; k < 2; ++k) \
;         acc[ai][bj][m][n] = __builtin_amdgcn_mfma_f32_16x16x32_bf16(Bt[n][k], At[m][k], acc[ai][bj][m][n], 0, 0, 0); __builtin_amdgcn_s_setprio(0); } while (0)
; #define PG8_WAIT_L(n) asm volatile("s_waitcnt lgkmcnt(" #n ")" ::: "memory")
; #define PG8_BAR __builtin_amdgcn_s_barrier()
; #define PG8_SCHED __builtin_amdgcn_sched_barrier(0)
; template <class Epi>
; DI void gemm_phase(LAS unsigned char* lds, int wid, int K, int lda, int ldb, bool bperm, const Sched3& S, const Epi& E) {
;     ...
;             PG8_LDB(B1, 0, 1); PG8_STAGE(PG8_SB(0, 0), b2, voffB);
;             PG8_BAR; PG8_WAIT_L(0); PG8_MMA(0, 1, At, B1); PG8_BAR;
;             PG8_LDA(At, 0, 1); PG8_STAGE(PG8_SA(0, 0), a2, voffA);
;             PG8_BAR; PG8_WAIT_L(0); if (full) PG8_MMA(1, 0, At, B0); PG8_BAR; PG8_SCHED;
;             PG8_STAGE(PG8_SB(0, 1), b2 + hstepB, voffB);
	s_add_i32 m0, s64, 0x2000
	s_nop 0
	global_load_lds_dwordx4 v150, s[38:39]
	s_barrier
	s_waitcnt lgkmcnt(0)
	s_setprio 1
	s_waitcnt lgkmcnt(0)
	v_mfma_f32_16x16x32_bf16 v[116:119], v[228:231], v[180:183], 0
	v_mfma_f32_16x16x32_bf16 v[112:115], v[236:239], v[180:183], 0
	v_mfma_f32_16x16x32_bf16 v[100:103], v[228:231], v[200:203], 0
	v_mfma_f32_16x16x32_bf16 v[96:99], v[236:239], v[200:203], 0
	v_mfma_f32_16x16x32_bf16 v[84:87], v[228:231], v[208:211], 0
	v_mfma_f32_16x16x32_bf16 v[80:83], v[236:239], v[208:211], 0
	v_mfma_f32_16x16x32_bf16 v[68:71], v[228:231], v[216:219], 0
	v_mfma_f32_16x16x32_bf16 v[64:67], v[236:239], v[216:219], 0
	v_mfma_f32_16x16x32_bf16 v[116:119], v[232:235], v[190:193], v[116:119]
	v_mfma_f32_16x16x32_bf16 v[112:115], v[240:243], v[190:193], v[112:115]
	v_mfma_f32_16x16x32_bf16 v[100:103], v[232:235], v[204:207], v[100:103]
	v_mfma_f32_16x16x32_bf16 v[96:99], v[240:243], v[204:207], v[96:99]
	v_mfma_f32_16x16x32_bf16 v[84:87], v[232:235], v[212:215], v[84:87]
	v_mfma_f32_16x16x32_bf16 v[80:83], v[240:243], v[212:215], v[80:83]
	v_mfma_f32_16x16x32_bf16 v[68:71], v[232:235], v[224:227], v[68:71]
	v_mfma_f32_16x16x32_bf16 v[64:67], v[240:243], v[224:227], v[64:67]
	s_setprio 0
	s_mov_b32 m0, s48
	s_mov_b64 s[100:101], s[40:41]
	s_barrier
	ds_read_b128 v[180:183], v195 offset:16384
	ds_read_b128 v[190:193], v195 offset:17408
	ds_read_b128 v[200:203], v195 offset:18432
	ds_read_b128 v[204:207], v195 offset:19456
	ds_read_b128 v[208:211], v195 offset:20480
	ds_read_b128 v[212:215], v195 offset:21504
	ds_read_b128 v[216:219], v195 offset:22528
	ds_read_b128 v[224:227], v195 offset:23552
	global_load_lds_dwordx4 v144, s[40:41]
	s_mov_b64 s[100:101], s[40:41]
	s_mov_b32 m0, s49
	s_nop 0
	global_load_lds_dwordx4 v148, s[40:41]
	s_barrier
	s_waitcnt lgkmcnt(0)
	s_setprio 1
	s_waitcnt lgkmcnt(0)
	v_mfma_f32_16x16x32_bf16 v[60:63], v[128:131], v[180:183], 0
	v_mfma_f32_16x16x32_bf16 v[56:59], v[136:139], v[180:183], 0
	v_mfma_f32_16x16x32_bf16 v[44:47], v[128:131], v[200:203], 0
	v_mfma_f32_16x16x32_bf16 v[40:43], v[136:139], v[200:203], 0
	v_mfma_f32_16x16x32_bf16 v[28:31], v[128:131], v[208:211], 0
	v_mfma_f32_16x16x32_bf16 v[24:27], v[136:139], v[208:211], 0
	v_mfma_f32_16x16x32_bf16 v[12:15], v[128:131], v[216:219], 0
	v_mfma_f32_16x16x32_bf16 v[8:11], v[136:139], v[216:219], 0
	v_mfma_f32_16x16x32_bf16 v[60:63], v[132:135], v[190:193], v[60:63]
	v_mfma_f32_16x16x32_bf16 v[56:59], v[140:143], v[190:193], v[56:59]
	v_mfma_f32_16x16x32_bf16 v[44:47], v[132:135], v[204:207], v[44:47]
	v_mfma_f32_16x16x32_bf16 v[40:43], v[140:143], v[204:207], v[40:43]
	v_mfma_f32_16x16x32_bf16 v[28:31], v[132:135], v[212:215], v[28:31]
	v_mfma_f32_16x16x32_bf16 v[24:27], v[140:143], v[212:215], v[24:27]
	v_mfma_f32_16x16x32_bf16 v[12:15], v[132:135], v[224:227], v[12:15]
	v_mfma_f32_16x16x32_bf16 v[8:11], v[140:143], v[224:227], v[8:11]
	s_setprio 0
	s_barrier
	s_add_u32 s64, s38, 0x80000
	s_addc_u32 s65, s39, 0
	s_add_i32 s66, s60, s47

; #define PG8_STAGE(bufoff, gbase, voff) do { _Pragma("unroll") for (int _i = 0; _i < 2; ++_i) \
;         __builtin_amdgcn_global_load_lds((const unsigned*)((const char*)(gbase) + (voff)[_i]), (LAS unsigned*)(lds + (bufoff) + ldsw + _i * 8192), 16, 0, 0); } while (0)
; template <class Epi>
; DI void gemm_phase(LAS unsigned char* lds, int wid, int K, int lda, int ldb, bool bperm, const Sched3& S, const Epi& E) {
;     ...
;             PG8_STAGE(PG8_SB(0, 1), b2 + hstepB, voffB);
	s_mov_b32 m0, s66
	s_nop 0
	global_load_lds_dwordx4 v146, s[64:65]

; #define PG8_STAGE(bufoff, gbase, voff) do { _Pragma("unroll") for (int _i = 0; _i < 2; ++_i) \
;         __builtin_amdgcn_global_load_lds((const unsigned*)((const char*)(gbase) + (voff)[_i]), (LAS unsigned*)(lds + (bufoff) + ldsw + _i * 8192), 16, 0, 0); } while (0)
; #define PG8_LDA(dst, b, h) do { _Pragma("unroll") for (int m = 0; m < 4; ++m) _Pragma("unroll") for (int k = 0; k < 2; ++k) dst[m][k] = *(const LAS bf16x8*)(lds + PG8_SA(b, h) + aoff + m * 2048 + k * 1024); } while (0)
; #define PG8_LDB(dst, b, h) do { _Pragma("unroll") for (int n = 0; n < 2; ++n) _Pragma("unroll") for (int k = 0; k < 2; ++k) dst[n][k] = *(const LAS bf16x8*)(lds + PG8_SB(b, h) + boff + n * 2048 + k * 1024); } while (0)
; #define PG8_MMA(ai, bj, At, Bt) do { __builtin_amdgcn_s_setprio(1); _Pragma("unroll") for (int m = 0; m < 4; ++m) _Pragma("unroll") for (int n = 0; n < 2; ++n) _Pragma("unroll") for (int k = 0; k < 2; ++k) \
;         acc[ai][bj][m][n] = __builtin_amdgcn_mfma_f32_16x16x32_bf16(Bt[n][k], At[m][k], acc[ai][bj][m][n], 0, 0, 0); __builtin_amdgcn_s_setprio(0); } while (0)
; #define PG8_WAIT_V(n) asm volatile("s_waitcnt vmcnt(" #n ")" ::: "memory")
; #define PG8_BAR __builtin_amdgcn_s_barrier()
; #define PG8_SCHED __builtin_amdgcn_sched_barrier(0)
; template <class Epi>
; DI void gemm_phase(LAS unsigned char* lds, int wid, int K, int lda, int ldb, bool bperm, const Sched3& S, const Epi& E) {
;     ...
;             PG8_STAGE(PG8_SB(0, 1), b2 + hstepB, voffB);
;             PG8_WAIT_V(6); PG8_BAR; if (full) PG8_MMA(1, 1, At, B1); PG8_BAR;
;             PG8_LDB(B0, 1, 0); PG8_SCHED; PG8_LDA(At, 1, 0); PG8_STAGE(PG8_SA(0, 1), a2 + h2, voffA);
	s_add_i32 m0, s66, 0x2000
	s_nop 0
	global_load_lds_dwordx4 v150, s[64:65]
	s_waitcnt vmcnt(6)
	s_barrier
	s_setprio 1
	v_mfma_f32_16x16x32_bf16 v[52:55], v[228:231], v[180:183], 0
	v_mfma_f32_16x16x32_bf16 v[48:51], v[236:239], v[180:183], 0
	v_mfma_f32_16x16x32_bf16 v[36:39], v[228:231], v[200:203], 0
	v_mfma_f32_16x16x32_bf16 v[32:35], v[236:239], v[200:203], 0
	v_mfma_f32_16x16x32_bf16 v[20:23], v[228:231], v[208:211], 0
	v_mfma_f32_16x16x32_bf16 v[16:19], v[236:239], v[208:211], 0
	v_mfma_f32_16x16x32_bf16 v[4:7], v[228:231], v[216:219], 0
	v_mfma_f32_16x16x32_bf16 v[0:3], v[236:239], v[216:219], 0
	v_mfma_f32_16x16x32_bf16 v[52:55], v[232:235], v[190:193], v[52:55]
	v_mfma_f32_16x16x32_bf16 v[48:51], v[240:243], v[190:193], v[48:51]
	v_mfma_f32_16x16x32_bf16 v[36:39], v[232:235], v[204:207], v[36:39]
	v_mfma_f32_16x16x32_bf16 v[32:35], v[240:243], v[204:207], v[32:35]
	v_mfma_f32_16x16x32_bf16 v[20:23], v[232:235], v[212:215], v[20:23]
	v_mfma_f32_16x16x32_bf16 v[16:19], v[240:243], v[212:215], v[16:19]
	v_mfma_f32_16x16x32_bf16 v[4:7], v[232:235], v[224:227], v[4:7]
	v_mfma_f32_16x16x32_bf16 v[0:3], v[240:243], v[224:227], v[0:3]
	s_setprio 0
	s_add_i32 s64, 0, 0x18000
	v_add_u32_e32 v140, s64, v171
	s_barrier
	ds_read_b128 v[128:131], v140
	ds_read_b128 v[132:135], v140 offset:1024
	ds_read_b128 v[136:139], v140 offset:2048
	ds_read_b128 v[140:143], v140 offset:3072
	s_add_u32 s40, s40, 0x80000
	s_addc_u32 s41, s41, 0
	s_mov_b32 m0, s50

; #define PG8_STAGE(bufoff, gbase, voff) do { _Pragma("unroll") for (int _i = 0; _i < 2; ++_i) \
;         __builtin_amdgcn_global_load_lds((const unsigned*)((const char*)(gbase) + (voff)[_i]), (LAS unsigned*)(lds + (bufoff) + ldsw + _i * 8192), 16, 0, 0); } while (0)
; #define PG8_LDA(dst, b, h) do { _Pragma("unroll") for (int m = 0; m < 4; ++m) _Pragma("unroll") for (int k = 0; k < 2; ++k) dst[m][k] = *(const LAS bf16x8*)(lds + PG8_SA(b, h) + aoff + m * 2048 + k * 1024); } while (0)
; #define PG8_LDB(dst, b, h) do { _Pragma("unroll") for (int n = 0; n < 2; ++n) _Pragma("unroll") for (int k = 0; k < 2; ++k) dst[n][k] = *(const LAS bf16x8*)(lds + PG8_SB(b, h) + boff + n * 2048 + k * 1024); } while (0)
; #define PG8_SCHED __builtin_amdgcn_sched_barrier(0)
; template <class Epi>
; DI void gemm_phase(LAS unsigned char* lds, int wid, int K, int lda, int ldb, bool bperm, const Sched3& S, const Epi& E) {
;     ...
;             PG8_LDB(B0, 1, 0); PG8_SCHED; PG8_LDA(At, 1, 0); PG8_STAGE(PG8_SA(0, 1), a2 + h2, voffA);
	ds_read_b128 v[180:183], v195 offset:32768
	ds_read_b128 v[190:193], v195 offset:33792
	ds_read_b128 v[200:203], v195 offset:34816
	ds_read_b128 v[204:207], v195 offset:35840
	ds_read_b128 v[208:211], v195 offset:36864
	ds_read_b128 v[212:215], v195 offset:37888
	ds_read_b128 v[216:219], v195 offset:38912
	ds_read_b128 v[224:227], v195 offset:39936
	global_load_lds_dwordx4 v144, s[40:41]

; #define PG8_STAGE(bufoff, gbase, voff) do { _Pragma("unroll") for (int _i = 0; _i < 2; ++_i) \
;         __builtin_amdgcn_global_load_lds((const unsigned*)((const char*)(gbase) + (voff)[_i]), (LAS unsigned*)(lds + (bufoff) + ldsw + _i * 8192), 16, 0, 0); } while (0)
; #define PG8_LDA(dst, b, h) do { _Pragma("unroll") for (int m = 0; m < 4; ++m) _Pragma("unroll") for (int k = 0; k < 2; ++k) dst[m][k] = *(const LAS bf16x8*)(lds + PG8_SA(b, h) + aoff + m * 2048 + k * 1024); } while (0)
; #define PG8_LDB(dst, b, h) do { _Pragma("unroll") for (int n = 0; n < 2; ++n) _Pragma("unroll") for (int k = 0; k < 2; ++k) dst[n][k] = *(const LAS bf16x8*)(lds + PG8_SB(b, h) + boff + n * 2048 + k * 1024); } while (0)
; #define PG8_MMA(ai, bj, At, Bt) do { __builtin_amdgcn_s_setprio(1); _Pragma("unroll") for (int m = 0; m < 4; ++m) _Pragma("unroll") for (int n = 0; n < 2; ++n) _Pragma("unroll") for (int k = 0; k < 2; ++k) \
;         acc[ai][bj][m][n] = __builtin_amdgcn_mfma_f32_16x16x32_bf16(Bt[n][k], At[m][k], acc[ai][bj][m][n], 0, 0, 0); __builtin_amdgcn_s_setprio(0); } while (0)
; #define PG8_WAIT_L(n) asm volatile("s_waitcnt lgkmcnt(" #n ")" ::: "memory")
; #define PG8_BAR __builtin_amdgcn_s_barrier()
; #define PG8_SCHED __builtin_amdgcn_sched_barrier(0)
; template <class Epi>
; DI void gemm_phase(LAS unsigned char* lds, int wid, int K, int lda, int ldb, bool bperm, const Sched3& S, const Epi& E) {
;     ...
;             PG8_LDB(B0, 1, 0); PG8_SCHED; PG8_LDA(At, 1, 0); PG8_STAGE(PG8_SA(0, 1), a2 + h2, voffA);
;             PG8_WAIT_L(8); PG8_BAR; PG8_WAIT_L(0); PG8_MMA(0, 0, At, B0); PG8_BAR; PG8_SCHED;
;             PG8_LDB(B1, 1, 1); PG8_STAGE(PG8_SB(1, 0), b3, voffB);
	s_mov_b32 m0, s51
	s_nop 0
	global_load_lds_dwordx4 v148, s[40:41]
	s_waitcnt lgkmcnt(8)
	s_barrier
	s_waitcnt lgkmcnt(0)
	s_setprio 1
	s_waitcnt lgkmcnt(0)
	v_mfma_f32_16x16x32_bf16 v[124:127], v[128:131], v[180:183], v[124:127]
	v_mfma_f32_16x16x32_bf16 v[120:123], v[136:139], v[180:183], v[120:123]
	v_mfma_f32_16x16x32_bf16 v[108:111], v[128:131], v[200:203], v[108:111]
	v_mfma_f32_16x16x32_bf16 v[104:107], v[136:139], v[200:203], v[104:107]
	v_mfma_f32_16x16x32_bf16 v[92:95], v[128:131], v[208:211], v[92:95]
	v_mfma_f32_16x16x32_bf16 v[88:91], v[136:139], v[208:211], v[88:91]
	v_mfma_f32_16x16x32_bf16 v[76:79], v[128:131], v[216:219], v[76:79]
	v_mfma_f32_16x16x32_bf16 v[72:75], v[136:139], v[216:219], v[72:75]
	v_mfma_f32_16x16x32_bf16 v[124:127], v[132:135], v[190:193], v[124:127]
	v_mfma_f32_16x16x32_bf16 v[120:123], v[140:143], v[190:193], v[120:123]
	v_mfma_f32_16x16x32_bf16 v[108:111], v[132:135], v[204:207], v[108:111]
	v_mfma_f32_16x16x32_bf16 v[104:107], v[140:143], v[204:207], v[104:107]
	v_mfma_f32_16x16x32_bf16 v[92:95], v[132:135], v[212:215], v[92:95]
	v_mfma_f32_16x16x32_bf16 v[88:91], v[140:143], v[212:215], v[88:91]
	v_mfma_f32_16x16x32_bf16 v[76:79], v[132:135], v[224:227], v[76:79]
	v_mfma_f32_16x16x32_bf16 v[72:75], v[140:143], v[224:227], v[72:75]
	s_setprio 0
	s_barrier
	s_add_i32 s40, 0, 0x1c000
	s_add_i32 s41, s64, s47
	v_add_u32_e32 v152, s40, v171

; #define PG8_STAGE(bufoff, gbase, voff) do { _Pragma("unroll") for (int _i = 0; _i < 2; ++_i) \
;         __builtin_amdgcn_global_load_lds((const unsigned*)((const char*)(gbase) + (voff)[_i]), (LAS unsigned*)(lds + (bufoff) + ldsw + _i * 8192), 16, 0, 0); } while (0)
; #define PG8_LDB(dst, b, h) do { _Pragma("unroll") for (int n = 0; n < 2; ++n) _Pragma("unroll") for (int k = 0; k < 2; ++k) dst[n][k] = *(const LAS bf16x8*)(lds + PG8_SB(b, h) + boff + n * 2048 + k * 1024); } while (0)
; template <class Epi>
; DI void gemm_phase(LAS unsigned char* lds, int wid, int K, int lda, int ldb, bool bperm, const Sched3& S, const Epi& E) {
;     ...
;             PG8_LDB(B1, 1, 1); PG8_STAGE(PG8_SB(1, 0), b3, voffB);
	s_sub_i32 m0, s41, 0x80
	ds_read_b128 v[228:231], v152
	ds_read_b128 v[232:235], v152 offset:1024
	ds_read_b128 v[236:239], v152 offset:2048
	ds_read_b128 v[240:243], v152 offset:3072
	global_load_lds_dwordx4 v146, s[38:39] offset:128

; #define PG8_STAGE(bufoff, gbase, voff) do { _Pragma("unroll") for (int _i = 0; _i < 2; ++_i) \
;         __builtin_amdgcn_global_load_lds((const unsigned*)((const char*)(gbase) + (voff)[_i]), (LAS unsigned*)(lds + (bufoff) + ldsw + _i * 8192), 16, 0, 0); } while (0)
; #define PG8_LDA(dst, b, h) do { _Pragma("unroll") for (int m = 0; m < 4; ++m) _Pragma("unroll") for (int k = 0; k < 2; ++k) dst[m][k] = *(const LAS bf16x8*)(lds + PG8_SA(b, h) + aoff + m * 2048 + k * 1024); } while (0)
; #define PG8_LDB(dst, b, h) do { _Pragma("unroll") for (int n = 0; n < 2; ++n) _Pragma("unroll") for (int k = 0; k < 2; ++k) dst[n][k] = *(const LAS bf16x8*)(lds + PG8_SB(b, h) + boff + n * 2048 + k * 1024); } while (0)
; #define PG8_MMA(ai, bj, At, Bt) do { __builtin_amdgcn_s_setprio(1); _Pragma("unroll") for (int m = 0; m < 4; ++m) _Pragma("unroll") for (int n = 0; n < 2; ++n) _Pragma("unroll") for (int k = 0; k < 2; ++k) \
;         acc[ai][bj][m][n] = __builtin_amdgcn_mfma_f32_16x16x32_bf16(Bt[n][k], At[m][k], acc[ai][bj][m][n], 0, 0, 0); __builtin_amdgcn_s_setprio(0); } while (0)
; #define PG8_WAIT_L(n) asm volatile("s_waitcnt lgkmcnt(" #n ")" ::: "memory")
; #define PG8_BAR __builtin_amdgcn_s_barrier()
; template <class Epi>
; DI void gemm_phase(LAS unsigned char* lds, int wid, int K, int lda, int ldb, bool bperm, const Sched3& S, const Epi& E) {
;     ...
;             PG8_LDB(B1, 1, 1); PG8_STAGE(PG8_SB(1, 0), b3, voffB);
;             PG8_BAR; PG8_WAIT_L(0); PG8_MMA(0, 1, At, B1); PG8_BAR;
;             PG8_LDA(At, 1, 1); PG8_STAGE(PG8_SA(1, 0), a3, voffA);
	s_add_i32 m0, s41, 0x1f80
	s_nop 0
	global_load_lds_dwordx4 v150, s[38:39] offset:128
	s_barrier
	s_waitcnt lgkmcnt(0)
	s_setprio 1
	s_waitcnt lgkmcnt(0)
	v_mfma_f32_16x16x32_bf16 v[116:119], v[228:231], v[180:183], v[116:119]
	v_mfma_f32_16x16x32_bf16 v[112:115], v[236:239], v[180:183], v[112:115]
	v_mfma_f32_16x16x32_bf16 v[100:103], v[228:231], v[200:203], v[100:103]
	v_mfma_f32_16x16x32_bf16 v[96:99], v[236:239], v[200:203], v[96:99]
	v_mfma_f32_16x16x32_bf16 v[84:87], v[228:231], v[208:211], v[84:87]
	v_mfma_f32_16x16x32_bf16 v[80:83], v[236:239], v[208:211], v[80:83]
	v_mfma_f32_16x16x32_bf16 v[68:71], v[228:231], v[216:219], v[68:71]
	v_mfma_f32_16x16x32_bf16 v[64:67], v[236:239], v[216:219], v[64:67]
	v_mfma_f32_16x16x32_bf16 v[116:119], v[232:235], v[190:193], v[116:119]
	v_mfma_f32_16x16x32_bf16 v[112:115], v[240:243], v[190:193], v[112:115]
	v_mfma_f32_16x16x32_bf16 v[100:103], v[232:235], v[204:207], v[100:103]
	v_mfma_f32_16x16x32_bf16 v[96:99], v[240:243], v[204:207], v[96:99]
	v_mfma_f32_16x16x32_bf16 v[84:87], v[232:235], v[212:215], v[84:87]
	v_mfma_f32_16x16x32_bf16 v[80:83], v[240:243], v[212:215], v[80:83]
	v_mfma_f32_16x16x32_bf16 v[68:71], v[232:235], v[224:227], v[68:71]
	v_mfma_f32_16x16x32_bf16 v[64:67], v[240:243], v[224:227], v[64:67]
	s_setprio 0
	s_sub_i32 m0, s53, 0x80

; #define PG8_STAGE(bufoff, gbase, voff) do { _Pragma("unroll") for (int _i = 0; _i < 2; ++_i) \
;         __builtin_amdgcn_global_load_lds((const unsigned*)((const char*)(gbase) + (voff)[_i]), (LAS unsigned*)(lds + (bufoff) + ldsw + _i * 8192), 16, 0, 0); } while (0)
; #define PG8_LDA(dst, b, h) do { _Pragma("unroll") for (int m = 0; m < 4; ++m) _Pragma("unroll") for (int k = 0; k < 2; ++k) dst[m][k] = *(const LAS bf16x8*)(lds + PG8_SA(b, h) + aoff + m * 2048 + k * 1024); } while (0)
; template <class Epi>
; DI void gemm_phase(LAS unsigned char* lds, int wid, int K, int lda, int ldb, bool bperm, const Sched3& S, const Epi& E) {
;     ...
;             PG8_LDA(At, 1, 1); PG8_STAGE(PG8_SA(1, 0), a3, voffA);
	s_barrier
	ds_read_b128 v[180:183], v195 offset:49152
	ds_read_b128 v[190:193], v195 offset:50176
	ds_read_b128 v[200:203], v195 offset:51200
	ds_read_b128 v[204:207], v195 offset:52224
	ds_read_b128 v[208:211], v195 offset:53248
	ds_read_b128 v[212:215], v195 offset:54272
	ds_read_b128 v[216:219], v195 offset:55296
	ds_read_b128 v[224:227], v195 offset:56320
	global_load_lds_dwordx4 v144, s[100:101] offset:128

; #define PG8_STAGE(bufoff, gbase, voff) do { _Pragma("unroll") for (int _i = 0; _i < 2; ++_i) \
;         __builtin_amdgcn_global_load_lds((const unsigned*)((const char*)(gbase) + (voff)[_i]), (LAS unsigned*)(lds + (bufoff) + ldsw + _i * 8192), 16, 0, 0); } while (0)
; #define PG8_LDA(dst, b, h) do { _Pragma("unroll") for (int m = 0; m < 4; ++m) _Pragma("unroll") for (int k = 0; k < 2; ++k) dst[m][k] = *(const LAS bf16x8*)(lds + PG8_SA(b, h) + aoff + m * 2048 + k * 1024); } while (0)
; #define PG8_MMA(ai, bj, At, Bt) do { __builtin_amdgcn_s_setprio(1); _Pragma("unroll") for (int m = 0; m < 4; ++m) _Pragma("unroll") for (int n = 0; n < 2; ++n) _Pragma("unroll") for (int k = 0; k < 2; ++k) \
;         acc[ai][bj][m][n] = __builtin_amdgcn_mfma_f32_16x16x32_bf16(Bt[n][k], At[m][k], acc[ai][bj][m][n], 0, 0, 0); __builtin_amdgcn_s_setprio(0); } while (0)
; #define PG8_WAIT_L(n) asm volatile("s_waitcnt lgkmcnt(" #n ")" ::: "memory")
; #define PG8_BAR __builtin_amdgcn_s_barrier()
; #define PG8_SCHED __builtin_amdgcn_sched_barrier(0)
; template <class Epi>
; DI void gemm_phase(LAS unsigned char* lds, int wid, int K, int lda, int ldb, bool bperm, const Sched3& S, const Epi& E) {
;     ...
;             PG8_LDA(At, 1, 1); PG8_STAGE(PG8_SA(1, 0), a3, voffA);
;             PG8_BAR; PG8_WAIT_L(0); if (full) PG8_MMA(1, 0, At, B0); PG8_BAR; PG8_SCHED;
;             PG8_STAGE(PG8_SB(1, 1), b3 + hstepB, voffB);
	s_sub_i32 m0, s54, 0x80
	s_nop 0
	global_load_lds_dwordx4 v148, s[100:101] offset:128
	s_barrier
	s_waitcnt lgkmcnt(0)
	s_setprio 1
	s_waitcnt lgkmcnt(0)
	v_mfma_f32_16x16x32_bf16 v[60:63], v[128:131], v[180:183], v[60:63]
	v_mfma_f32_16x16x32_bf16 v[56:59], v[136:139], v[180:183], v[56:59]
	v_mfma_f32_16x16x32_bf16 v[44:47], v[128:131], v[200:203], v[44:47]
	v_mfma_f32_16x16x32_bf16 v[40:43], v[136:139], v[200:203], v[40:43]
	v_mfma_f32_16x16x32_bf16 v[28:31], v[128:131], v[208:211], v[28:31]
	v_mfma_f32_16x16x32_bf16 v[24:27], v[136:139], v[208:211], v[24:27]
	v_mfma_f32_16x16x32_bf16 v[12:15], v[128:131], v[216:219], v[12:15]
	v_mfma_f32_16x16x32_bf16 v[8:11], v[136:139], v[216:219], v[8:11]
	v_mfma_f32_16x16x32_bf16 v[60:63], v[132:135], v[190:193], v[60:63]
	v_mfma_f32_16x16x32_bf16 v[56:59], v[140:143], v[190:193], v[56:59]
	v_mfma_f32_16x16x32_bf16 v[44:47], v[132:135], v[204:207], v[44:47]
	v_mfma_f32_16x16x32_bf16 v[40:43], v[140:143], v[204:207], v[40:43]
	v_mfma_f32_16x16x32_bf16 v[28:31], v[132:135], v[212:215], v[28:31]
	v_mfma_f32_16x16x32_bf16 v[24:27], v[140:143], v[212:215], v[24:27]
	v_mfma_f32_16x16x32_bf16 v[12:15], v[132:135], v[224:227], v[12:15]
	v_mfma_f32_16x16x32_bf16 v[8:11], v[140:143], v[224:227], v[8:11]
	s_setprio 0
	s_barrier
	s_add_u32 s38, s38, 0x80080
	s_addc_u32 s39, s39, 0
	s_add_i32 s40, s40, s47

; #define PG8_STAGE(bufoff, gbase, voff) do { _Pragma("unroll") for (int _i = 0; _i < 2; ++_i) \
;         __builtin_amdgcn_global_load_lds((const unsigned*)((const char*)(gbase) + (voff)[_i]), (LAS unsigned*)(lds + (bufoff) + ldsw + _i * 8192), 16, 0, 0); } while (0)
; template <class Epi>
; DI void gemm_phase(LAS unsigned char* lds, int wid, int K, int lda, int ldb, bool bperm, const Sched3& S, const Epi& E) {
;     ...
;             PG8_STAGE(PG8_SB(1, 1), b3 + hstepB, voffB);
	s_mov_b32 m0, s40
	s_nop 0
	global_load_lds_dwordx4 v146, s[38:39]

; #define PG8_STAGE(bufoff, gbase, voff) do { _Pragma("unroll") for (int _i = 0; _i < 2; ++_i) \
;         __builtin_amdgcn_global_load_lds((const unsigned*)((const char*)(gbase) + (voff)[_i]), (LAS unsigned*)(lds + (bufoff) + ldsw + _i * 8192), 16, 0, 0); } while (0)
; #define PG8_LDA(dst, b, h) do { _Pragma("unroll") for (int m = 0; m < 4; ++m) _Pragma("unroll") for (int k = 0; k < 2; ++k) dst[m][k] = *(const LAS bf16x8*)(lds + PG8_SA(b, h) + aoff + m * 2048 + k * 1024); } while (0)
; #define PG8_LDB(dst, b, h) do { _Pragma("unroll") for (int n = 0; n < 2; ++n) _Pragma("unroll") for (int k = 0; k < 2; ++k) dst[n][k] = *(const LAS bf16x8*)(lds + PG8_SB(b, h) + boff + n * 2048 + k * 1024); } while (0)
; #define PG8_MMA(ai, bj, At, Bt) do { __builtin_amdgcn_s_setprio(1); _Pragma("unroll") for (int m = 0; m < 4; ++m) _Pragma("unroll") for (int n = 0; n < 2; ++n) _Pragma("unroll") for (int k = 0; k < 2; ++k) \
;         acc[ai][bj][m][n] = __builtin_amdgcn_mfma_f32_16x16x32_bf16(Bt[n][k], At[m][k], acc[ai][bj][m][n], 0, 0, 0); __builtin_amdgcn_s_setprio(0); } while (0)
; #define PG8_WAIT_V(n) asm volatile("s_waitcnt vmcnt(" #n ")" ::: "memory")
; #define PG8_BAR __builtin_amdgcn_s_barrier()
; #define PG8_SCHED __builtin_amdgcn_sched_barrier(0)
; template <class Epi>
; DI void gemm_phase(LAS unsigned char* lds, int wid, int K, int lda, int ldb, bool bperm, const Sched3& S, const Epi& E) {
;     ...
;             const bool last = (t == nt - 2);
;             const char* a1 = cA + (size_t)(t + 1) * kstep;
;             const char* a2 = last ? nA : cA + (size_t)(t + 2) * kstep; const char* b2 = last ? nB : cB + (size_t)(t + 2) * kstep;
;             const char* a3 = a2 + kstep; const char* b3 = b2 + kstep; const size_t h2 = last ? nhA : hA;
;             PG8_LDB(B0, 0, 0); PG8_SCHED; PG8_LDA(At, 0, 0); PG8_STAGE(PG8_SA(1, 1), a1 + hA, voffA);
;     ...
;             PG8_STAGE(PG8_SB(1, 1), b3 + hstepB, voffB);
;             PG8_WAIT_V(6); PG8_BAR; if (full) PG8_MMA(1, 1, At, B1); PG8_BAR;
	s_add_i32 m0, s40, 0x2000
	s_nop 0
	global_load_lds_dwordx4 v150, s[38:39]
	s_waitcnt vmcnt(6)
	s_barrier
	s_setprio 1
	v_mfma_f32_16x16x32_bf16 v[52:55], v[228:231], v[180:183], v[52:55]
	v_mfma_f32_16x16x32_bf16 v[48:51], v[236:239], v[180:183], v[48:51]
	v_mfma_f32_16x16x32_bf16 v[36:39], v[228:231], v[200:203], v[36:39]
	v_mfma_f32_16x16x32_bf16 v[32:35], v[236:239], v[200:203], v[32:35]
	v_mfma_f32_16x16x32_bf16 v[20:23], v[228:231], v[208:211], v[20:23]
	v_mfma_f32_16x16x32_bf16 v[16:19], v[236:239], v[208:211], v[16:19]
	v_mfma_f32_16x16x32_bf16 v[4:7], v[228:231], v[216:219], v[4:7]
	v_mfma_f32_16x16x32_bf16 v[0:3], v[236:239], v[216:219], v[0:3]
	v_mfma_f32_16x16x32_bf16 v[52:55], v[232:235], v[190:193], v[52:55]
	v_mfma_f32_16x16x32_bf16 v[48:51], v[240:243], v[190:193], v[48:51]
	v_mfma_f32_16x16x32_bf16 v[36:39], v[232:235], v[204:207], v[36:39]
	v_mfma_f32_16x16x32_bf16 v[32:35], v[240:243], v[204:207], v[32:35]
	v_mfma_f32_16x16x32_bf16 v[20:23], v[232:235], v[212:215], v[20:23]
	v_mfma_f32_16x16x32_bf16 v[16:19], v[240:243], v[212:215], v[16:19]
	v_mfma_f32_16x16x32_bf16 v[4:7], v[232:235], v[224:227], v[4:7]
	v_mfma_f32_16x16x32_bf16 v[0:3], v[240:243], v[224:227], v[0:3]
	s_setprio 0
	s_add_i32 s27, s27, 2
	s_add_u32 s36, s36, 0x100
	s_addc_u32 s37, s37, 0
	s_add_u32 s19, s19, 0x100
	s_addc_u32 s21, s21, 0
	s_cmp_gt_u32 s27, 29
	s_barrier
	s_cbranch_scc0 .LBB0_873
	s_branch .Lpeel_4_exit
.LBB0_873:
	ds_read_b128 v[128:131], v189
	ds_read_b128 v[132:135], v189 offset:1024
	ds_read_b128 v[136:139], v189 offset:2048
	ds_read_b128 v[140:143], v189 offset:3072
	s_add_u32 s38, s36, 0xfff80080
	s_addc_u32 s39, s37, -1
	s_cmp_eq_u32 s27, 28
	s_cselect_b32 s41, s29, s39
	s_cselect_b32 s40, s28, s38
	s_cselect_b32 s39, s31, s21
	s_cselect_b32 s38, s30, s19

; #define PG8_STAGE(bufoff, gbase, voff) do { _Pragma("unroll") for (int _i = 0; _i < 2; ++_i) \
;         __builtin_amdgcn_global_load_lds((const unsigned*)((const char*)(gbase) + (voff)[_i]), (LAS unsigned*)(lds + (bufoff) + ldsw + _i * 8192), 16, 0, 0); } while (0)
; #define PG8_LDA(dst, b, h) do { _Pragma("unroll") for (int m = 0; m < 4; ++m) _Pragma("unroll") for (int k = 0; k < 2; ++k) dst[m][k] = *(const LAS bf16x8*)(lds + PG8_SA(b, h) + aoff + m * 2048 + k * 1024); } while (0)
; #define PG8_LDB(dst, b, h) do { _Pragma("unroll") for (int n = 0; n < 2; ++n) _Pragma("unroll") for (int k = 0; k < 2; ++k) dst[n][k] = *(const LAS bf16x8*)(lds + PG8_SB(b, h) + boff + n * 2048 + k * 1024); } while (0)
; #define PG8_SCHED __builtin_amdgcn_sched_barrier(0)
; template <class Epi>
; DI void gemm_phase(LAS unsigned char* lds, int wid, int K, int lda, int ldb, bool bperm, const Sched3& S, const Epi& E) {
;     ...
;             PG8_LDB(B0, 0, 0); PG8_SCHED; PG8_LDA(At, 0, 0); PG8_STAGE(PG8_SA(1, 1), a1 + hA, voffA);
	s_add_i32 m0, s48, 0xc000
	ds_read_b128 v[180:183], v195
	ds_read_b128 v[190:193], v195 offset:1024
	ds_read_b128 v[200:203], v195 offset:2048
	ds_read_b128 v[204:207], v195 offset:3072
	ds_read_b128 v[208:211], v195 offset:4096
	ds_read_b128 v[212:215], v195 offset:5120
	ds_read_b128 v[216:219], v195 offset:6144
	ds_read_b128 v[224:227], v195 offset:7168
	global_load_lds_dwordx4 v160, s[36:37]

; #define PG8_STAGE(bufoff, gbase, voff) do { _Pragma("unroll") for (int _i = 0; _i < 2; ++_i) \
;         __builtin_amdgcn_global_load_lds((const unsigned*)((const char*)(gbase) + (voff)[_i]), (LAS unsigned*)(lds + (bufoff) + ldsw + _i * 8192), 16, 0, 0); } while (0)
; #define PG8_LDA(dst, b, h) do { _Pragma("unroll") for (int m = 0; m < 4; ++m) _Pragma("unroll") for (int k = 0; k < 2; ++k) dst[m][k] = *(const LAS bf16x8*)(lds + PG8_SA(b, h) + aoff + m * 2048 + k * 1024); } while (0)
; #define PG8_LDB(dst, b, h) do { _Pragma("unroll") for (int n = 0; n < 2; ++n) _Pragma("unroll") for (int k = 0; k < 2; ++k) dst[n][k] = *(const LAS bf16x8*)(lds + PG8_SB(b, h) + boff + n * 2048 + k * 1024); } while (0)
; #define PG8_MMA(ai, bj, At, Bt) do { __builtin_amdgcn_s_setprio(1); _Pragma("unroll") for (int m = 0; m < 4; ++m) _Pragma("unroll") for (int n = 0; n < 2; ++n) _Pragma("unroll") for (int k = 0; k < 2; ++k) \
;         acc[ai][bj][m][n] = __builtin_amdgcn_mfma_f32_16x16x32_bf16(Bt[n][k], At[m][k], acc[ai][bj][m][n], 0, 0, 0); __builtin_amdgcn_s_setprio(0); } while (0)
; #define PG8_WAIT_L(n) asm volatile("s_waitcnt lgkmcnt(" #n ")" ::: "memory")
; #define PG8_BAR __builtin_amdgcn_s_barrier()
; #define PG8_SCHED __builtin_amdgcn_sched_barrier(0)
; template <class Epi>
; DI void gemm_phase(LAS unsigned char* lds, int wid, int K, int lda, int ldb, bool bperm, const Sched3& S, const Epi& E) {
;     ...
;             PG8_LDB(B0, 0, 0); PG8_SCHED; PG8_LDA(At, 0, 0); PG8_STAGE(PG8_SA(1, 1), a1 + hA, voffA);
;             PG8_WAIT_L(8); PG8_BAR; PG8_WAIT_L(0); PG8_MMA(0, 0, At, B0); PG8_BAR; PG8_SCHED;
;             PG8_LDB(B1, 0, 1); PG8_STAGE(PG8_SB(0, 0), b2, voffB);
	s_add_i32 m0, s48, 0xe000
	s_nop 0
	global_load_lds_dwordx4 v162, s[36:37]
	s_waitcnt lgkmcnt(8)
	s_barrier
	s_waitcnt lgkmcnt(0)
	s_setprio 1
	s_waitcnt lgkmcnt(0)
	v_mfma_f32_16x16x32_bf16 v[124:127], v[128:131], v[180:183], v[124:127]
	v_mfma_f32_16x16x32_bf16 v[120:123], v[136:139], v[180:183], v[120:123]
	v_mfma_f32_16x16x32_bf16 v[108:111], v[128:131], v[200:203], v[108:111]
	v_mfma_f32_16x16x32_bf16 v[104:107], v[136:139], v[200:203], v[104:107]
	v_mfma_f32_16x16x32_bf16 v[92:95], v[128:131], v[208:211], v[92:95]
	v_mfma_f32_16x16x32_bf16 v[88:91], v[136:139], v[208:211], v[88:91]
	v_mfma_f32_16x16x32_bf16 v[76:79], v[128:131], v[216:219], v[76:79]
	v_mfma_f32_16x16x32_bf16 v[72:75], v[136:139], v[216:219], v[72:75]
	v_mfma_f32_16x16x32_bf16 v[124:127], v[132:135], v[190:193], v[124:127]
	v_mfma_f32_16x16x32_bf16 v[120:123], v[140:143], v[190:193], v[120:123]
	v_mfma_f32_16x16x32_bf16 v[108:111], v[132:135], v[204:207], v[108:111]
	v_mfma_f32_16x16x32_bf16 v[104:107], v[140:143], v[204:207], v[104:107]
	v_mfma_f32_16x16x32_bf16 v[92:95], v[132:135], v[212:215], v[92:95]
	v_mfma_f32_16x16x32_bf16 v[88:91], v[140:143], v[212:215], v[88:91]
	v_mfma_f32_16x16x32_bf16 v[76:79], v[132:135], v[224:227], v[76:79]
	v_mfma_f32_16x16x32_bf16 v[72:75], v[140:143], v[224:227], v[72:75]
	s_setprio 0
	s_barrier
	s_add_i32 s64, s59, s47

; #define PG8_STAGE(bufoff, gbase, voff) do { _Pragma("unroll") for (int _i = 0; _i < 2; ++_i) \
;         __builtin_amdgcn_global_load_lds((const unsigned*)((const char*)(gbase) + (voff)[_i]), (LAS unsigned*)(lds + (bufoff) + ldsw + _i * 8192), 16, 0, 0); } while (0)
; #define PG8_LDB(dst, b, h) do { _Pragma("unroll") for (int n = 0; n < 2; ++n) _Pragma("unroll") for (int k = 0; k < 2; ++k) dst[n][k] = *(const LAS bf16x8*)(lds + PG8_SB(b, h) + boff + n * 2048 + k * 1024); } while (0)
; template <class Epi>
; DI void gemm_phase(LAS unsigned char* lds, int wid, int K, int lda, int ldb, bool bperm, const Sched3& S, const Epi& E) {
;     ...
;             PG8_LDB(B1, 0, 1); PG8_STAGE(PG8_SB(0, 0), b2, voffB);
	s_mov_b32 m0, s64
	ds_read_b128 v[228:231], v197
	ds_read_b128 v[232:235], v197 offset:1024
	ds_read_b128 v[236:239], v197 offset:2048
	ds_read_b128 v[240:243], v197 offset:3072
	global_load_lds_dwordx4 v146, s[38:39]

; #define PG8_STAGE(bufoff, gbase, voff) do { _Pragma("unroll") for (int _i = 0; _i < 2; ++_i) \
;         __builtin_amdgcn_global_load_lds((const unsigned*)((const char*)(gbase) + (voff)[_i]), (LAS unsigned*)(lds + (bufoff) + ldsw + _i * 8192), 16, 0, 0); } while (0)
; #define PG8_LDA(dst, b, h) do { _Pragma("unroll") for (int m = 0; m < 4; ++m) _Pragma("unroll") for (int k = 0; k < 2; ++k) dst[m][k] = *(const LAS bf16x8*)(lds + PG8_SA(b, h) + aoff + m * 2048 + k * 1024); } while (0)
; #define PG8_LDB(dst, b, h) do { _Pragma("unroll") for (int n = 0; n < 2; ++n) _Pragma("unroll") for (int k = 0; k < 2; ++k) dst[n][k] = *(const LAS bf16x8*)(lds + PG8_SB(b, h) + boff + n * 2048 + k * 1024); } while (0)
; #define PG8_MMA(ai, bj, At, Bt) do { __builtin_amdgcn_s_setprio(1); _Pragma("unroll") for (int m = 0; m < 4; ++m) _Pragma("unroll") for (int n = 0; n < 2; ++n) _Pragma("unroll") for (int k = 0; k < 2; ++k) \
;         acc[ai][bj][m][n] = __builtin_amdgcn_mfma_f32_16x16x32_bf16(Bt[n][k], At[m][k], acc[ai][bj][m][n], 0, 0, 0); __builtin_amdgcn_s_setprio(0); } while (0)
; #define PG8_WAIT_L(n) asm volatile("s_waitcnt lgkmcnt(" #n ")" ::: "memory")
; #define PG8_BAR __builtin_amdgcn_s_barrier()
; #define PG8_SCHED __builtin_amdgcn_sched_barrier(0)
; template <class Epi>
; DI void gemm_phase(LAS unsigned char* lds, int wid, int K, int lda, int ldb, bool bperm, const Sched3& S, const Epi& E) {
;     ...
;             PG8_LDB(B1, 0, 1); PG8_STAGE(PG8_SB(0, 0), b2, voffB);
;             PG8_BAR; PG8_WAIT_L(0); PG8_MMA(0, 1, At, B1); PG8_BAR;
;             PG8_LDA(At, 0, 1); PG8_STAGE(PG8_SA(0, 0), a2, voffA);
;             PG8_BAR; PG8_WAIT_L(0); if (full) PG8_MMA(1, 0, At, B0); PG8_BAR; PG8_SCHED;
;             PG8_STAGE(PG8_SB(0, 1), b2 + hstepB, voffB);
	s_add_i32 m0, s64, 0x2000
	s_nop 0
	global_load_lds_dwordx4 v150, s[38:39]
	s_barrier
	s_waitcnt lgkmcnt(0)
	s_setprio 1
	s_waitcnt lgkmcnt(0)
	v_mfma_f32_16x16x32_bf16 v[116:119], v[228:231], v[180:183], v[116:119]
	v_mfma_f32_16x16x32_bf16 v[112:115], v[236:239], v[180:183], v[112:115]
	v_mfma_f32_16x16x32_bf16 v[100:103], v[228:231], v[200:203], v[100:103]
	v_mfma_f32_16x16x32_bf16 v[96:99], v[236:239], v[200:203], v[96:99]
	v_mfma_f32_16x16x32_bf16 v[84:87], v[228:231], v[208:211], v[84:87]
	v_mfma_f32_16x16x32_bf16 v[80:83], v[236:239], v[208:211], v[80:83]
	v_mfma_f32_16x16x32_bf16 v[68:71], v[228:231], v[216:219], v[68:71]
	v_mfma_f32_16x16x32_bf16 v[64:67], v[236:239], v[216:219], v[64:67]
	v_mfma_f32_16x16x32_bf16 v[116:119], v[232:235], v[190:193], v[116:119]
	v_mfma_f32_16x16x32_bf16 v[112:115], v[240:243], v[190:193], v[112:115]
	v_mfma_f32_16x16x32_bf16 v[100:103], v[232:235], v[204:207], v[100:103]
	v_mfma_f32_16x16x32_bf16 v[96:99], v[240:243], v[204:207], v[96:99]
	v_mfma_f32_16x16x32_bf16 v[84:87], v[232:235], v[212:215], v[84:87]
	v_mfma_f32_16x16x32_bf16 v[80:83], v[240:243], v[212:215], v[80:83]
	v_mfma_f32_16x16x32_bf16 v[68:71], v[232:235], v[224:227], v[68:71]
	v_mfma_f32_16x16x32_bf16 v[64:67], v[240:243], v[224:227], v[64:67]
	s_setprio 0
	s_mov_b32 m0, s48
	s_mov_b64 s[100:101], s[40:41]
	s_barrier
	ds_read_b128 v[180:183], v195 offset:16384
	ds_read_b128 v[190:193], v195 offset:17408
	ds_read_b128 v[200:203], v195 offset:18432
	ds_read_b128 v[204:207], v195 offset:19456
	ds_read_b128 v[208:211], v195 offset:20480
	ds_read_b128 v[212:215], v195 offset:21504
	ds_read_b128 v[216:219], v195 offset:22528
	ds_read_b128 v[224:227], v195 offset:23552
	global_load_lds_dwordx4 v144, s[40:41]
	s_mov_b64 s[100:101], s[40:41]
	s_mov_b32 m0, s49
	s_nop 0
	global_load_lds_dwordx4 v148, s[40:41]
	s_barrier
	s_waitcnt lgkmcnt(0)
	s_setprio 1
	s_waitcnt lgkmcnt(0)
	v_mfma_f32_16x16x32_bf16 v[60:63], v[128:131], v[180:183], v[60:63]
	v_mfma_f32_16x16x32_bf16 v[56:59], v[136:139], v[180:183], v[56:59]
	v_mfma_f32_16x16x32_bf16 v[44:47], v[128:131], v[200:203], v[44:47]
	v_mfma_f32_16x16x32_bf16 v[40:43], v[136:139], v[200:203], v[40:43]
	v_mfma_f32_16x16x32_bf16 v[28:31], v[128:131], v[208:211], v[28:31]
	v_mfma_f32_16x16x32_bf16 v[24:27], v[136:139], v[208:211], v[24:27]
	v_mfma_f32_16x16x32_bf16 v[12:15], v[128:131], v[216:219], v[12:15]
	v_mfma_f32_16x16x32_bf16 v[8:11], v[136:139], v[216:219], v[8:11]
	v_mfma_f32_16x16x32_bf16 v[60:63], v[132:135], v[190:193], v[60:63]
	v_mfma_f32_16x16x32_bf16 v[56:59], v[140:143], v[190:193], v[56:59]
	v_mfma_f32_16x16x32_bf16 v[44:47], v[132:135], v[204:207], v[44:47]
	v_mfma_f32_16x16x32_bf16 v[40:43], v[140:143], v[204:207], v[40:43]
	v_mfma_f32_16x16x32_bf16 v[28:31], v[132:135], v[212:215], v[28:31]
	v_mfma_f32_16x16x32_bf16 v[24:27], v[140:143], v[212:215], v[24:27]
	v_mfma_f32_16x16x32_bf16 v[12:15], v[132:135], v[224:227], v[12:15]
	v_mfma_f32_16x16x32_bf16 v[8:11], v[140:143], v[224:227], v[8:11]
	s_setprio 0
	s_barrier
	s_add_u32 s64, s38, 0x80000
	s_addc_u32 s65, s39, 0
	s_add_i32 s66, s60, s47

; #define PG8_STAGE(bufoff, gbase, voff) do { _Pragma("unroll") for (int _i = 0; _i < 2; ++_i) \
;         __builtin_amdgcn_global_load_lds((const unsigned*)((const char*)(gbase) + (voff)[_i]), (LAS unsigned*)(lds + (bufoff) + ldsw + _i * 8192), 16, 0, 0); } while (0)
; template <class Epi>
; DI void gemm_phase(LAS unsigned char* lds, int wid, int K, int lda, int ldb, bool bperm, const Sched3& S, const Epi& E) {
;     ...
;             PG8_STAGE(PG8_SB(0, 1), b2 + hstepB, voffB);
	s_mov_b32 m0, s66
	s_nop 0
	global_load_lds_dwordx4 v146, s[64:65]

; #define PG8_STAGE(bufoff, gbase, voff) do { _Pragma("unroll") for (int _i = 0; _i < 2; ++_i) \
;         __builtin_amdgcn_global_load_lds((const unsigned*)((const char*)(gbase) + (voff)[_i]), (LAS unsigned*)(lds + (bufoff) + ldsw + _i * 8192), 16, 0, 0); } while (0)
; #define PG8_LDA(dst, b, h) do { _Pragma("unroll") for (int m = 0; m < 4; ++m) _Pragma("unroll") for (int k = 0; k < 2; ++k) dst[m][k] = *(const LAS bf16x8*)(lds + PG8_SA(b, h) + aoff + m * 2048 + k * 1024); } while (0)
; #define PG8_LDB(dst, b, h) do { _Pragma("unroll") for (int n = 0; n < 2; ++n) _Pragma("unroll") for (int k = 0; k < 2; ++k) dst[n][k] = *(const LAS bf16x8*)(lds + PG8_SB(b, h) + boff + n * 2048 + k * 1024); } while (0)
; #define PG8_MMA(ai, bj, At, Bt) do { __builtin_amdgcn_s_setprio(1); _Pragma("unroll") for (int m = 0; m < 4; ++m) _Pragma("unroll") for (int n = 0; n < 2; ++n) _Pragma("unroll") for (int k = 0; k < 2; ++k) \
;         acc[ai][bj][m][n] = __builtin_amdgcn_mfma_f32_16x16x32_bf16(Bt[n][k], At[m][k], acc[ai][bj][m][n], 0, 0, 0); __builtin_amdgcn_s_setprio(0); } while (0)
; #define PG8_WAIT_V(n) asm volatile("s_waitcnt vmcnt(" #n ")" ::: "memory")
; #define PG8_BAR __builtin_amdgcn_s_barrier()
; #define PG8_SCHED __builtin_amdgcn_sched_barrier(0)
; template <class Epi>
; DI void gemm_phase(LAS unsigned char* lds, int wid, int K, int lda, int ldb, bool bperm, const Sched3& S, const Epi& E) {
;     ...
;             PG8_STAGE(PG8_SB(0, 1), b2 + hstepB, voffB);
;             PG8_WAIT_V(6); PG8_BAR; if (full) PG8_MMA(1, 1, At, B1); PG8_BAR;
;             PG8_LDB(B0, 1, 0); PG8_SCHED; PG8_LDA(At, 1, 0); PG8_STAGE(PG8_SA(0, 1), a2 + h2, voffA);
	s_add_i32 m0, s66, 0x2000
	s_nop 0
	global_load_lds_dwordx4 v150, s[64:65]
	s_waitcnt vmcnt(6)
	s_barrier
	s_setprio 1
	v_mfma_f32_16x16x32_bf16 v[52:55], v[228:231], v[180:183], v[52:55]
	v_mfma_f32_16x16x32_bf16 v[48:51], v[236:239], v[180:183], v[48:51]
	v_mfma_f32_16x16x32_bf16 v[36:39], v[228:231], v[200:203], v[36:39]
	v_mfma_f32_16x16x32_bf16 v[32:35], v[236:239], v[200:203], v[32:35]
	v_mfma_f32_16x16x32_bf16 v[20:23], v[228:231], v[208:211], v[20:23]
	v_mfma_f32_16x16x32_bf16 v[16:19], v[236:239], v[208:211], v[16:19]
	v_mfma_f32_16x16x32_bf16 v[4:7], v[228:231], v[216:219], v[4:7]
	v_mfma_f32_16x16x32_bf16 v[0:3], v[236:239], v[216:219], v[0:3]
	v_mfma_f32_16x16x32_bf16 v[52:55], v[232:235], v[190:193], v[52:55]
	v_mfma_f32_16x16x32_bf16 v[48:51], v[240:243], v[190:193], v[48:51]
	v_mfma_f32_16x16x32_bf16 v[36:39], v[232:235], v[204:207], v[36:39]
	v_mfma_f32_16x16x32_bf16 v[32:35], v[240:243], v[204:207], v[32:35]
	v_mfma_f32_16x16x32_bf16 v[20:23], v[232:235], v[212:215], v[20:23]
	v_mfma_f32_16x16x32_bf16 v[16:19], v[240:243], v[212:215], v[16:19]
	v_mfma_f32_16x16x32_bf16 v[4:7], v[232:235], v[224:227], v[4:7]
	v_mfma_f32_16x16x32_bf16 v[0:3], v[240:243], v[224:227], v[0:3]
	s_setprio 0
	s_add_i32 s64, 0, 0x18000
	v_add_u32_e32 v140, s64, v171
	s_barrier
	ds_read_b128 v[128:131], v140
	ds_read_b128 v[132:135], v140 offset:1024
	ds_read_b128 v[136:139], v140 offset:2048
	ds_read_b128 v[140:143], v140 offset:3072
	s_add_u32 s40, s40, 0x80000
	s_addc_u32 s41, s41, 0
	s_mov_b32 m0, s50

; #define PG8_STAGE(bufoff, gbase, voff) do { _Pragma("unroll") for (int _i = 0; _i < 2; ++_i) \
;         __builtin_amdgcn_global_load_lds((const unsigned*)((const char*)(gbase) + (voff)[_i]), (LAS unsigned*)(lds + (bufoff) + ldsw + _i * 8192), 16, 0, 0); } while (0)
; #define PG8_LDA(dst, b, h) do { _Pragma("unroll") for (int m = 0; m < 4; ++m) _Pragma("unroll") for (int k = 0; k < 2; ++k) dst[m][k] = *(const LAS bf16x8*)(lds + PG8_SA(b, h) + aoff + m * 2048 + k * 1024); } while (0)
; #define PG8_LDB(dst, b, h) do { _Pragma("unroll") for (int n = 0; n < 2; ++n) _Pragma("unroll") for (int k = 0; k < 2; ++k) dst[n][k] = *(const LAS bf16x8*)(lds + PG8_SB(b, h) + boff + n * 2048 + k * 1024); } while (0)
; #define PG8_SCHED __builtin_amdgcn_sched_barrier(0)
; template <class Epi>
; DI void gemm_phase(LAS unsigned char* lds, int wid, int K, int lda, int ldb, bool bperm, const Sched3& S, const Epi& E) {
;     ...
;             PG8_LDB(B0, 1, 0); PG8_SCHED; PG8_LDA(At, 1, 0); PG8_STAGE(PG8_SA(0, 1), a2 + h2, voffA);
	ds_read_b128 v[180:183], v195 offset:32768
	ds_read_b128 v[190:193], v195 offset:33792
	ds_read_b128 v[200:203], v195 offset:34816
	ds_read_b128 v[204:207], v195 offset:35840
	ds_read_b128 v[208:211], v195 offset:36864
	ds_read_b128 v[212:215], v195 offset:37888
	ds_read_b128 v[216:219], v195 offset:38912
	ds_read_b128 v[224:227], v195 offset:39936
	global_load_lds_dwordx4 v144, s[40:41]

; #define PG8_STAGE(bufoff, gbase, voff) do { _Pragma("unroll") for (int _i = 0; _i < 2; ++_i) \
;         __builtin_amdgcn_global_load_lds((const unsigned*)((const char*)(gbase) + (voff)[_i]), (LAS unsigned*)(lds + (bufoff) + ldsw + _i * 8192), 16, 0, 0); } while (0)
; #define PG8_LDA(dst, b, h) do { _Pragma("unroll") for (int m = 0; m < 4; ++m) _Pragma("unroll") for (int k = 0; k < 2; ++k) dst[m][k] = *(const LAS bf16x8*)(lds + PG8_SA(b, h) + aoff + m * 2048 + k * 1024); } while (0)
; #define PG8_LDB(dst, b, h) do { _Pragma("unroll") for (int n = 0; n < 2; ++n) _Pragma("unroll") for (int k = 0; k < 2; ++k) dst[n][k] = *(const LAS bf16x8*)(lds + PG8_SB(b, h) + boff + n * 2048 + k * 1024); } while (0)
; #define PG8_MMA(ai, bj, At, Bt) do { __builtin_amdgcn_s_setprio(1); _Pragma("unroll") for (int m = 0; m < 4; ++m) _Pragma("unroll") for (int n = 0; n < 2; ++n) _Pragma("unroll") for (int k = 0; k < 2; ++k) \
;         acc[ai][bj][m][n] = __builtin_amdgcn_mfma_f32_16x16x32_bf16(Bt[n][k], At[m][k], acc[ai][bj][m][n], 0, 0, 0); __builtin_amdgcn_s_setprio(0); } while (0)
; #define PG8_WAIT_L(n) asm volatile("s_waitcnt lgkmcnt(" #n ")" ::: "memory")
; #define PG8_BAR __builtin_amdgcn_s_barrier()
; #define PG8_SCHED __builtin_amdgcn_sched_barrier(0)
; template <class Epi>
; DI void gemm_phase(LAS unsigned char* lds, int wid, int K, int lda, int ldb, bool bperm, const Sched3& S, const Epi& E) {
;     ...
;             PG8_LDB(B0, 1, 0); PG8_SCHED; PG8_LDA(At, 1, 0); PG8_STAGE(PG8_SA(0, 1), a2 + h2, voffA);
;             PG8_WAIT_L(8); PG8_BAR; PG8_WAIT_L(0); PG8_MMA(0, 0, At, B0); PG8_BAR; PG8_SCHED;
;             PG8_LDB(B1, 1, 1); PG8_STAGE(PG8_SB(1, 0), b3, voffB);
	s_mov_b32 m0, s51
	s_nop 0
	global_load_lds_dwordx4 v148, s[40:41]
	s_waitcnt lgkmcnt(8)
	s_barrier
	s_waitcnt lgkmcnt(0)
	s_setprio 1
	s_waitcnt lgkmcnt(0)
	v_mfma_f32_16x16x32_bf16 v[124:127], v[128:131], v[180:183], v[124:127]
	v_mfma_f32_16x16x32_bf16 v[120:123], v[136:139], v[180:183], v[120:123]
	v_mfma_f32_16x16x32_bf16 v[108:111], v[128:131], v[200:203], v[108:111]
	v_mfma_f32_16x16x32_bf16 v[104:107], v[136:139], v[200:203], v[104:107]
	v_mfma_f32_16x16x32_bf16 v[92:95], v[128:131], v[208:211], v[92:95]
	v_mfma_f32_16x16x32_bf16 v[88:91], v[136:139], v[208:211], v[88:91]
	v_mfma_f32_16x16x32_bf16 v[76:79], v[128:131], v[216:219], v[76:79]
	v_mfma_f32_16x16x32_bf16 v[72:75], v[136:139], v[216:219], v[72:75]
	v_mfma_f32_16x16x32_bf16 v[124:127], v[132:135], v[190:193], v[124:127]
	v_mfma_f32_16x16x32_bf16 v[120:123], v[140:143], v[190:193], v[120:123]
	v_mfma_f32_16x16x32_bf16 v[108:111], v[132:135], v[204:207], v[108:111]
	v_mfma_f32_16x16x32_bf16 v[104:107], v[140:143], v[204:207], v[104:107]
	v_mfma_f32_16x16x32_bf16 v[92:95], v[132:135], v[212:215], v[92:95]
	v_mfma_f32_16x16x32_bf16 v[88:91], v[140:143], v[212:215], v[88:91]
	v_mfma_f32_16x16x32_bf16 v[76:79], v[132:135], v[224:227], v[76:79]
	v_mfma_f32_16x16x32_bf16 v[72:75], v[140:143], v[224:227], v[72:75]
	s_setprio 0
	s_barrier
	s_add_i32 s40, 0, 0x1c000
	s_add_i32 s41, s64, s47
	v_add_u32_e32 v152, s40, v171

; #define PG8_STAGE(bufoff, gbase, voff) do { _Pragma("unroll") for (int _i = 0; _i < 2; ++_i) \
;         __builtin_amdgcn_global_load_lds((const unsigned*)((const char*)(gbase) + (voff)[_i]), (LAS unsigned*)(lds + (bufoff) + ldsw + _i * 8192), 16, 0, 0); } while (0)
; #define PG8_LDB(dst, b, h) do { _Pragma("unroll") for (int n = 0; n < 2; ++n) _Pragma("unroll") for (int k = 0; k < 2; ++k) dst[n][k] = *(const LAS bf16x8*)(lds + PG8_SB(b, h) + boff + n * 2048 + k * 1024); } while (0)
; template <class Epi>
; DI void gemm_phase(LAS unsigned char* lds, int wid, int K, int lda, int ldb, bool bperm, const Sched3& S, const Epi& E) {
;     ...
;             PG8_LDB(B1, 1, 1); PG8_STAGE(PG8_SB(1, 0), b3, voffB);
	s_sub_i32 m0, s41, 0x80
	ds_read_b128 v[228:231], v152
	ds_read_b128 v[232:235], v152 offset:1024
	ds_read_b128 v[236:239], v152 offset:2048
	ds_read_b128 v[240:243], v152 offset:3072
	global_load_lds_dwordx4 v146, s[38:39] offset:128

; #define PG8_STAGE(bufoff, gbase, voff) do { _Pragma("unroll") for (int _i = 0; _i < 2; ++_i) \
;         __builtin_amdgcn_global_load_lds((const unsigned*)((const char*)(gbase) + (voff)[_i]), (LAS unsigned*)(lds + (bufoff) + ldsw + _i * 8192), 16, 0, 0); } while (0)
; #define PG8_LDA(dst, b, h) do { _Pragma("unroll") for (int m = 0; m < 4; ++m) _Pragma("unroll") for (int k = 0; k < 2; ++k) dst[m][k] = *(const LAS bf16x8*)(lds + PG8_SA(b, h) + aoff + m * 2048 + k * 1024); } while (0)
; #define PG8_LDB(dst, b, h) do { _Pragma("unroll") for (int n = 0; n < 2; ++n) _Pragma("unroll") for (int k = 0; k < 2; ++k) dst[n][k] = *(const LAS bf16x8*)(lds + PG8_SB(b, h) + boff + n * 2048 + k * 1024); } while (0)
; #define PG8_MMA(ai, bj, At, Bt) do { __builtin_amdgcn_s_setprio(1); _Pragma("unroll") for (int m = 0; m < 4; ++m) _Pragma("unroll") for (int n = 0; n < 2; ++n) _Pragma("unroll") for (int k = 0; k < 2; ++k) \
;         acc[ai][bj][m][n] = __builtin_amdgcn_mfma_f32_16x16x32_bf16(Bt[n][k], At[m][k], acc[ai][bj][m][n], 0, 0, 0); __builtin_amdgcn_s_setprio(0); } while (0)
; #define PG8_WAIT_L(n) asm volatile("s_waitcnt lgkmcnt(" #n ")" ::: "memory")
; #define PG8_BAR __builtin_amdgcn_s_barrier()
; template <class Epi>
; DI void gemm_phase(LAS unsigned char* lds, int wid, int K, int lda, int ldb, bool bperm, const Sched3& S, const Epi& E) {
;     ...
;             PG8_LDB(B1, 1, 1); PG8_STAGE(PG8_SB(1, 0), b3, voffB);
;             PG8_BAR; PG8_WAIT_L(0); PG8_MMA(0, 1, At, B1); PG8_BAR;
;             PG8_LDA(At, 1, 1); PG8_STAGE(PG8_SA(1, 0), a3, voffA);
	s_add_i32 m0, s41, 0x1f80
	s_nop 0
	global_load_lds_dwordx4 v150, s[38:39] offset:128
	s_barrier
	s_waitcnt lgkmcnt(0)
	s_setprio 1
	s_waitcnt lgkmcnt(0)
	v_mfma_f32_16x16x32_bf16 v[116:119], v[228:231], v[180:183], v[116:119]
	v_mfma_f32_16x16x32_bf16 v[112:115], v[236:239], v[180:183], v[112:115]
	v_mfma_f32_16x16x32_bf16 v[100:103], v[228:231], v[200:203], v[100:103]
	v_mfma_f32_16x16x32_bf16 v[96:99], v[236:239], v[200:203], v[96:99]
	v_mfma_f32_16x16x32_bf16 v[84:87], v[228:231], v[208:211], v[84:87]
	v_mfma_f32_16x16x32_bf16 v[80:83], v[236:239], v[208:211], v[80:83]
	v_mfma_f32_16x16x32_bf16 v[68:71], v[228:231], v[216:219], v[68:71]
	v_mfma_f32_16x16x32_bf16 v[64:67], v[236:239], v[216:219], v[64:67]
	v_mfma_f32_16x16x32_bf16 v[116:119], v[232:235], v[190:193], v[116:119]
	v_mfma_f32_16x16x32_bf16 v[112:115], v[240:243], v[190:193], v[112:115]
	v_mfma_f32_16x16x32_bf16 v[100:103], v[232:235], v[204:207], v[100:103]
	v_mfma_f32_16x16x32_bf16 v[96:99], v[240:243], v[204:207], v[96:99]
	v_mfma_f32_16x16x32_bf16 v[84:87], v[232:235], v[212:215], v[84:87]
	v_mfma_f32_16x16x32_bf16 v[80:83], v[240:243], v[212:215], v[80:83]
	v_mfma_f32_16x16x32_bf16 v[68:71], v[232:235], v[224:227], v[68:71]
	v_mfma_f32_16x16x32_bf16 v[64:67], v[240:243], v[224:227], v[64:67]
	s_setprio 0
	s_sub_i32 m0, s53, 0x80

; #define PG8_STAGE(bufoff, gbase, voff) do { _Pragma("unroll") for (int _i = 0; _i < 2; ++_i) \
;         __builtin_amdgcn_global_load_lds((const unsigned*)((const char*)(gbase) + (voff)[_i]), (LAS unsigned*)(lds + (bufoff) + ldsw + _i * 8192), 16, 0, 0); } while (0)
; #define PG8_LDA(dst, b, h) do { _Pragma("unroll") for (int m = 0; m < 4; ++m) _Pragma("unroll") for (int k = 0; k < 2; ++k) dst[m][k] = *(const LAS bf16x8*)(lds + PG8_SA(b, h) + aoff + m * 2048 + k * 1024); } while (0)
; template <class Epi>
; DI void gemm_phase(LAS unsigned char* lds, int wid, int K, int lda, int ldb, bool bperm, const Sched3& S, const Epi& E) {
;     ...
;             PG8_LDA(At, 1, 1); PG8_STAGE(PG8_SA(1, 0), a3, voffA);
	s_barrier
	ds_read_b128 v[180:183], v195 offset:49152
	ds_read_b128 v[190:193], v195 offset:50176
	ds_read_b128 v[200:203], v195 offset:51200
	ds_read_b128 v[204:207], v195 offset:52224
	ds_read_b128 v[208:211], v195 offset:53248
	ds_read_b128 v[212:215], v195 offset:54272
	ds_read_b128 v[216:219], v195 offset:55296
	ds_read_b128 v[224:227], v195 offset:56320
	global_load_lds_dwordx4 v144, s[100:101] offset:128

; #define PG8_STAGE(bufoff, gbase, voff) do { _Pragma("unroll") for (int _i = 0; _i < 2; ++_i) \
;         __builtin_amdgcn_global_load_lds((const unsigned*)((const char*)(gbase) + (voff)[_i]), (LAS unsigned*)(lds + (bufoff) + ldsw + _i * 8192), 16, 0, 0); } while (0)
; #define PG8_LDA(dst, b, h) do { _Pragma("unroll") for (int m = 0; m < 4; ++m) _Pragma("unroll") for (int k = 0; k < 2; ++k) dst[m][k] = *(const LAS bf16x8*)(lds + PG8_SA(b, h) + aoff + m * 2048 + k * 1024); } while (0)
; #define PG8_MMA(ai, bj, At, Bt) do { __builtin_amdgcn_s_setprio(1); _Pragma("unroll") for (int m = 0; m < 4; ++m) _Pragma("unroll") for (int n = 0; n < 2; ++n) _Pragma("unroll") for (int k = 0; k < 2; ++k) \
;         acc[ai][bj][m][n] = __builtin_amdgcn_mfma_f32_16x16x32_bf16(Bt[n][k], At[m][k], acc[ai][bj][m][n], 0, 0, 0); __builtin_amdgcn_s_setprio(0); } while (0)
; #define PG8_WAIT_L(n) asm volatile("s_waitcnt lgkmcnt(" #n ")" ::: "memory")
; #define PG8_BAR __builtin_amdgcn_s_barrier()
; #define PG8_SCHED __builtin_amdgcn_sched_barrier(0)
; template <class Epi>
; DI void gemm_phase(LAS unsigned char* lds, int wid, int K, int lda, int ldb, bool bperm, const Sched3& S, const Epi& E) {
;     ...
;             PG8_LDA(At, 1, 1); PG8_STAGE(PG8_SA(1, 0), a3, voffA);
;             PG8_BAR; PG8_WAIT_L(0); if (full) PG8_MMA(1, 0, At, B0); PG8_BAR; PG8_SCHED;
;             PG8_STAGE(PG8_SB(1, 1), b3 + hstepB, voffB);
	s_sub_i32 m0, s54, 0x80
	s_nop 0
	global_load_lds_dwordx4 v148, s[100:101] offset:128
	s_barrier
	s_waitcnt lgkmcnt(0)
	s_setprio 1
	s_waitcnt lgkmcnt(0)
	v_mfma_f32_16x16x32_bf16 v[60:63], v[128:131], v[180:183], v[60:63]
	v_mfma_f32_16x16x32_bf16 v[56:59], v[136:139], v[180:183], v[56:59]
	v_mfma_f32_16x16x32_bf16 v[44:47], v[128:131], v[200:203], v[44:47]
	v_mfma_f32_16x16x32_bf16 v[40:43], v[136:139], v[200:203], v[40:43]
	v_mfma_f32_16x16x32_bf16 v[28:31], v[128:131], v[208:211], v[28:31]
	v_mfma_f32_16x16x32_bf16 v[24:27], v[136:139], v[208:211], v[24:27]
	v_mfma_f32_16x16x32_bf16 v[12:15], v[128:131], v[216:219], v[12:15]
	v_mfma_f32_16x16x32_bf16 v[8:11], v[136:139], v[216:219], v[8:11]
	v_mfma_f32_16x16x32_bf16 v[60:63], v[132:135], v[190:193], v[60:63]
	v_mfma_f32_16x16x32_bf16 v[56:59], v[140:143], v[190:193], v[56:59]
	v_mfma_f32_16x16x32_bf16 v[44:47], v[132:135], v[204:207], v[44:47]
	v_mfma_f32_16x16x32_bf16 v[40:43], v[140:143], v[204:207], v[40:43]
	v_mfma_f32_16x16x32_bf16 v[28:31], v[132:135], v[212:215], v[28:31]
	v_mfma_f32_16x16x32_bf16 v[24:27], v[140:143], v[212:215], v[24:27]
	v_mfma_f32_16x16x32_bf16 v[12:15], v[132:135], v[224:227], v[12:15]
	v_mfma_f32_16x16x32_bf16 v[8:11], v[140:143], v[224:227], v[8:11]
	s_setprio 0
	s_barrier
	s_add_u32 s38, s38, 0x80080
	s_addc_u32 s39, s39, 0
	s_add_i32 s40, s40, s47

; #define PG8_STAGE(bufoff, gbase, voff) do { _Pragma("unroll") for (int _i = 0; _i < 2; ++_i) \
;         __builtin_amdgcn_global_load_lds((const unsigned*)((const char*)(gbase) + (voff)[_i]), (LAS unsigned*)(lds + (bufoff) + ldsw + _i * 8192), 16, 0, 0); } while (0)
; template <class Epi>
; DI void gemm_phase(LAS unsigned char* lds, int wid, int K, int lda, int ldb, bool bperm, const Sched3& S, const Epi& E) {
;     ...
;             PG8_STAGE(PG8_SB(1, 1), b3 + hstepB, voffB);
	s_mov_b32 m0, s40
	s_nop 0
	global_load_lds_dwordx4 v146, s[38:39]

; #define PG8_STAGE(bufoff, gbase, voff) do { _Pragma("unroll") for (int _i = 0; _i < 2; ++_i) \
;         __builtin_amdgcn_global_load_lds((const unsigned*)((const char*)(gbase) + (voff)[_i]), (LAS unsigned*)(lds + (bufoff) + ldsw + _i * 8192), 16, 0, 0); } while (0)
; #define PG8_MMA(ai, bj, At, Bt) do { __builtin_amdgcn_s_setprio(1); _Pragma("unroll") for (int m = 0; m < 4; ++m) _Pragma("unroll") for (int n = 0; n < 2; ++n) _Pragma("unroll") for (int k = 0; k < 2; ++k) \
;         acc[ai][bj][m][n] = __builtin_amdgcn_mfma_f32_16x16x32_bf16(Bt[n][k], At[m][k], acc[ai][bj][m][n], 0, 0, 0); __builtin_amdgcn_s_setprio(0); } while (0)
; #define PG8_WAIT_V(n) asm volatile("s_waitcnt vmcnt(" #n ")" ::: "memory")
; #define PG8_BAR __builtin_amdgcn_s_barrier()
; template <class Epi>
; DI void gemm_phase(LAS unsigned char* lds, int wid, int K, int lda, int ldb, bool bperm, const Sched3& S, const Epi& E) {
;     ...
;         for (int t = 0; t < nt; t += 2) {
;     ...
;             PG8_STAGE(PG8_SB(1, 1), b3 + hstepB, voffB);
;             PG8_WAIT_V(6); PG8_BAR; if (full) PG8_MMA(1, 1, At, B1); PG8_BAR;
	s_add_i32 m0, s40, 0x2000
	s_nop 0
	global_load_lds_dwordx4 v150, s[38:39]
	s_waitcnt vmcnt(6)
	s_barrier
	s_setprio 1
	v_mfma_f32_16x16x32_bf16 v[52:55], v[228:231], v[180:183], v[52:55]
	v_mfma_f32_16x16x32_bf16 v[48:51], v[236:239], v[180:183], v[48:51]
	v_mfma_f32_16x16x32_bf16 v[36:39], v[228:231], v[200:203], v[36:39]
	v_mfma_f32_16x16x32_bf16 v[32:35], v[236:239], v[200:203], v[32:35]
	v_mfma_f32_16x16x32_bf16 v[20:23], v[228:231], v[208:211], v[20:23]
	v_mfma_f32_16x16x32_bf16 v[16:19], v[236:239], v[208:211], v[16:19]
	v_mfma_f32_16x16x32_bf16 v[4:7], v[228:231], v[216:219], v[4:7]
	v_mfma_f32_16x16x32_bf16 v[0:3], v[236:239], v[216:219], v[0:3]
	v_mfma_f32_16x16x32_bf16 v[52:55], v[232:235], v[190:193], v[52:55]
	v_mfma_f32_16x16x32_bf16 v[48:51], v[240:243], v[190:193], v[48:51]
	v_mfma_f32_16x16x32_bf16 v[36:39], v[232:235], v[204:207], v[36:39]
	v_mfma_f32_16x16x32_bf16 v[32:35], v[240:243], v[204:207], v[32:35]
	v_mfma_f32_16x16x32_bf16 v[20:23], v[232:235], v[212:215], v[20:23]
	v_mfma_f32_16x16x32_bf16 v[16:19], v[240:243], v[212:215], v[16:19]
	v_mfma_f32_16x16x32_bf16 v[4:7], v[232:235], v[224:227], v[4:7]
	v_mfma_f32_16x16x32_bf16 v[0:3], v[240:243], v[224:227], v[0:3]
	s_setprio 0
	s_add_i32 s27, s27, 2
	s_add_u32 s36, s36, 0x100
	s_addc_u32 s37, s37, 0
	s_add_u32 s19, s19, 0x100
	s_addc_u32 s21, s21, 0
	s_cmp_gt_u32 s27, 29
	s_barrier
	s_cbranch_scc0 .LBB0_873

; #define PG8_STAGE(bufoff, gbase, voff) do { _Pragma("unroll") for (int _i = 0; _i < 2; ++_i) \
;         __builtin_amdgcn_global_load_lds((const unsigned*)((const char*)(gbase) + (voff)[_i]), (LAS unsigned*)(lds + (bufoff) + ldsw + _i * 8192), 16, 0, 0); } while (0)
; #define PG8_LDA(dst, b, h) do { _Pragma("unroll") for (int m = 0; m < 4; ++m) _Pragma("unroll") for (int k = 0; k < 2; ++k) dst[m][k] = *(const LAS bf16x8*)(lds + PG8_SA(b, h) + aoff + m * 2048 + k * 1024); } while (0)
; #define PG8_LDB(dst, b, h) do { _Pragma("unroll") for (int n = 0; n < 2; ++n) _Pragma("unroll") for (int k = 0; k < 2; ++k) dst[n][k] = *(const LAS bf16x8*)(lds + PG8_SB(b, h) + boff + n * 2048 + k * 1024); } while (0)
; #define PG8_SCHED __builtin_amdgcn_sched_barrier(0)
; template <class Epi>
; DI void gemm_phase(LAS unsigned char* lds, int wid, int K, int lda, int ldb, bool bperm, const Sched3& S, const Epi& E) {
;     ...
;         const char* nA = has_next ? nxt.A : cA; const char* nB = has_next ? nxt.B : cB; const size_t nhA = has_next ? (nxt.half ? (size_t)0 : hstepA) : hA; const bool full = (cur.half == 0);
;         for (int t = 0; t < nt; t += 2) {
;             const bool last = (t == nt - 2);
;             const char* a1 = cA + (size_t)(t + 1) * kstep;
;             const char* a2 = last ? nA : cA + (size_t)(t + 2) * kstep; const char* b2 = last ? nB : cB + (size_t)(t + 2) * kstep;
;             const char* a3 = a2 + kstep; const char* b3 = b2 + kstep; const size_t h2 = last ? nhA : hA;
;             PG8_LDB(B0, 0, 0); PG8_SCHED; PG8_LDA(At, 0, 0); PG8_STAGE(PG8_SA(1, 1), a1 + hA, voffA);
.LBB0_995:
	s_xor_b64 s[48:49], s[56:57], -1
	s_and_b64 s[56:57], s[56:57], exec
	s_cselect_b32 s41, s45, s53
	s_cselect_b32 s43, s44, s52
	s_cselect_b32 s51, s47, s55
	s_cselect_b32 s58, s46, s54
	s_add_u32 s52, s52, 0x20080
	s_addc_u32 s53, s53, 0
	s_add_u32 s59, s54, 0x100
	s_nop 0
	s_addc_u32 s60, s55, 0
	s_mov_b32 s61, -2
	ds_read_b128 v[156:159], v182
	ds_read_b128 v[160:163], v182 offset:1024
	ds_read_b128 v[164:167], v182 offset:2048
	ds_read_b128 v[168:171], v182 offset:3072
	s_add_u32 s54, s52, 0xfffe0080
	s_addc_u32 s55, s53, -1
	s_cmp_eq_u32 s61, 4
	s_cselect_b32 s57, s41, s55
	s_cselect_b32 s56, s43, s54
	s_cselect_b32 s55, s51, s60
	s_cselect_b32 s54, s58, s59

; #define PG8_STAGE(bufoff, gbase, voff) do { _Pragma("unroll") for (int _i = 0; _i < 2; ++_i) \
;         __builtin_amdgcn_global_load_lds((const unsigned*)((const char*)(gbase) + (voff)[_i]), (LAS unsigned*)(lds + (bufoff) + ldsw + _i * 8192), 16, 0, 0); } while (0)
; #define PG8_LDA(dst, b, h) do { _Pragma("unroll") for (int m = 0; m < 4; ++m) _Pragma("unroll") for (int k = 0; k < 2; ++k) dst[m][k] = *(const LAS bf16x8*)(lds + PG8_SA(b, h) + aoff + m * 2048 + k * 1024); } while (0)
; #define PG8_LDB(dst, b, h) do { _Pragma("unroll") for (int n = 0; n < 2; ++n) _Pragma("unroll") for (int k = 0; k < 2; ++k) dst[n][k] = *(const LAS bf16x8*)(lds + PG8_SB(b, h) + boff + n * 2048 + k * 1024); } while (0)
; #define PG8_SCHED __builtin_amdgcn_sched_barrier(0)
; template <class Epi>
; DI void gemm_phase(LAS unsigned char* lds, int wid, int K, int lda, int ldb, bool bperm, const Sched3& S, const Epi& E) {
;     ...
;             PG8_LDB(B0, 0, 0); PG8_SCHED; PG8_LDA(At, 0, 0); PG8_STAGE(PG8_SA(1, 1), a1 + hA, voffA);
	s_add_i32 m0, s66, 0xc000
	ds_read_b128 v[172:175], v183
	ds_read_b128 v[186:189], v183 offset:1024
	ds_read_b128 v[190:193], v183 offset:2048
	ds_read_b128 v[194:197], v183 offset:3072
	ds_read_b128 v[198:201], v183 offset:4096
	ds_read_b128 v[202:205], v183 offset:5120
	ds_read_b128 v[206:209], v183 offset:6144
	ds_read_b128 v[210:213], v183 offset:7168
	global_load_lds_dwordx4 v144, s[52:53]

; #define PG8_STAGE(bufoff, gbase, voff) do { _Pragma("unroll") for (int _i = 0; _i < 2; ++_i) \
;         __builtin_amdgcn_global_load_lds((const unsigned*)((const char*)(gbase) + (voff)[_i]), (LAS unsigned*)(lds + (bufoff) + ldsw + _i * 8192), 16, 0, 0); } while (0)
; #define PG8_LDA(dst, b, h) do { _Pragma("unroll") for (int m = 0; m < 4; ++m) _Pragma("unroll") for (int k = 0; k < 2; ++k) dst[m][k] = *(const LAS bf16x8*)(lds + PG8_SA(b, h) + aoff + m * 2048 + k * 1024); } while (0)
; #define PG8_LDB(dst, b, h) do { _Pragma("unroll") for (int n = 0; n < 2; ++n) _Pragma("unroll") for (int k = 0; k < 2; ++k) dst[n][k] = *(const LAS bf16x8*)(lds + PG8_SB(b, h) + boff + n * 2048 + k * 1024); } while (0)
; #define PG8_MMA(ai, bj, At, Bt) do { __builtin_amdgcn_s_setprio(1); _Pragma("unroll") for (int m = 0; m < 4; ++m) _Pragma("unroll") for (int n = 0; n < 2; ++n) _Pragma("unroll") for (int k = 0; k < 2; ++k) \
;         acc[ai][bj][m][n] = __builtin_amdgcn_mfma_f32_16x16x32_bf16(Bt[n][k], At[m][k], acc[ai][bj][m][n], 0, 0, 0); __builtin_amdgcn_s_setprio(0); } while (0)
; #define PG8_WAIT_L(n) asm volatile("s_waitcnt lgkmcnt(" #n ")" ::: "memory")
; #define PG8_BAR __builtin_amdgcn_s_barrier()
; #define PG8_SCHED __builtin_amdgcn_sched_barrier(0)
; template <class Epi>
; DI void gemm_phase(LAS unsigned char* lds, int wid, int K, int lda, int ldb, bool bperm, const Sched3& S, const Epi& E) {
;     ...
;             PG8_LDB(B0, 0, 0); PG8_SCHED; PG8_LDA(At, 0, 0); PG8_STAGE(PG8_SA(1, 1), a1 + hA, voffA);
;             PG8_WAIT_L(8); PG8_BAR; PG8_WAIT_L(0); PG8_MMA(0, 0, At, B0); PG8_BAR; PG8_SCHED;
;             PG8_LDB(B1, 0, 1); PG8_STAGE(PG8_SB(0, 0), b2, voffB);
	s_add_i32 m0, s66, 0xe000
	s_nop 0
	global_load_lds_dwordx4 v146, s[52:53]
	s_waitcnt lgkmcnt(8)
	s_barrier
	s_waitcnt lgkmcnt(0)
	s_setprio 1
	s_waitcnt lgkmcnt(0)
	v_mfma_f32_16x16x32_bf16 v[124:127], v[156:159], v[172:175], 0
	v_mfma_f32_16x16x32_bf16 v[120:123], v[164:167], v[172:175], 0
	v_mfma_f32_16x16x32_bf16 v[116:119], v[156:159], v[190:193], 0
	v_mfma_f32_16x16x32_bf16 v[112:115], v[164:167], v[190:193], 0
	v_mfma_f32_16x16x32_bf16 v[108:111], v[156:159], v[198:201], 0
	v_mfma_f32_16x16x32_bf16 v[104:107], v[164:167], v[198:201], 0
	v_mfma_f32_16x16x32_bf16 v[100:103], v[156:159], v[206:209], 0
	v_mfma_f32_16x16x32_bf16 v[96:99], v[164:167], v[206:209], 0
	v_mfma_f32_16x16x32_bf16 v[124:127], v[160:163], v[186:189], v[124:127]
	v_mfma_f32_16x16x32_bf16 v[120:123], v[168:171], v[186:189], v[120:123]
	v_mfma_f32_16x16x32_bf16 v[116:119], v[160:163], v[194:197], v[116:119]
	v_mfma_f32_16x16x32_bf16 v[112:115], v[168:171], v[194:197], v[112:115]
	v_mfma_f32_16x16x32_bf16 v[108:111], v[160:163], v[202:205], v[108:111]
	v_mfma_f32_16x16x32_bf16 v[104:107], v[168:171], v[202:205], v[104:107]
	v_mfma_f32_16x16x32_bf16 v[100:103], v[160:163], v[210:213], v[100:103]
	v_mfma_f32_16x16x32_bf16 v[96:99], v[168:171], v[210:213], v[96:99]
	s_setprio 0
	s_barrier
	s_add_i32 s62, s76, s65

; #define PG8_STAGE(bufoff, gbase, voff) do { _Pragma("unroll") for (int _i = 0; _i < 2; ++_i) \
;         __builtin_amdgcn_global_load_lds((const unsigned*)((const char*)(gbase) + (voff)[_i]), (LAS unsigned*)(lds + (bufoff) + ldsw + _i * 8192), 16, 0, 0); } while (0)
; #define PG8_LDB(dst, b, h) do { _Pragma("unroll") for (int n = 0; n < 2; ++n) _Pragma("unroll") for (int k = 0; k < 2; ++k) dst[n][k] = *(const LAS bf16x8*)(lds + PG8_SB(b, h) + boff + n * 2048 + k * 1024); } while (0)
; template <class Epi>
; DI void gemm_phase(LAS unsigned char* lds, int wid, int K, int lda, int ldb, bool bperm, const Sched3& S, const Epi& E) {
;     ...
;             PG8_LDB(B1, 0, 1); PG8_STAGE(PG8_SB(0, 0), b2, voffB);
	s_mov_b32 m0, s62
	ds_read_b128 v[214:217], v184
	ds_read_b128 v[218:221], v184 offset:1024
	ds_read_b128 v[224:227], v184 offset:2048
	ds_read_b128 v[228:231], v184 offset:3072
	global_load_lds_dwordx4 v130, s[54:55]

; #define PG8_STAGE(bufoff, gbase, voff) do { _Pragma("unroll") for (int _i = 0; _i < 2; ++_i) \
;         __builtin_amdgcn_global_load_lds((const unsigned*)((const char*)(gbase) + (voff)[_i]), (LAS unsigned*)(lds + (bufoff) + ldsw + _i * 8192), 16, 0, 0); } while (0)
; #define PG8_LDA(dst, b, h) do { _Pragma("unroll") for (int m = 0; m < 4; ++m) _Pragma("unroll") for (int k = 0; k < 2; ++k) dst[m][k] = *(const LAS bf16x8*)(lds + PG8_SA(b, h) + aoff + m * 2048 + k * 1024); } while (0)
; #define PG8_LDB(dst, b, h) do { _Pragma("unroll") for (int n = 0; n < 2; ++n) _Pragma("unroll") for (int k = 0; k < 2; ++k) dst[n][k] = *(const LAS bf16x8*)(lds + PG8_SB(b, h) + boff + n * 2048 + k * 1024); } while (0)
; #define PG8_MMA(ai, bj, At, Bt) do { __builtin_amdgcn_s_setprio(1); _Pragma("unroll") for (int m = 0; m < 4; ++m) _Pragma("unroll") for (int n = 0; n < 2; ++n) _Pragma("unroll") for (int k = 0; k < 2; ++k) \
;         acc[ai][bj][m][n] = __builtin_amdgcn_mfma_f32_16x16x32_bf16(Bt[n][k], At[m][k], acc[ai][bj][m][n], 0, 0, 0); __builtin_amdgcn_s_setprio(0); } while (0)
; #define PG8_WAIT_L(n) asm volatile("s_waitcnt lgkmcnt(" #n ")" ::: "memory")
; #define PG8_BAR __builtin_amdgcn_s_barrier()
; #define PG8_SCHED __builtin_amdgcn_sched_barrier(0)
; template <class Epi>
; DI void gemm_phase(LAS unsigned char* lds, int wid, int K, int lda, int ldb, bool bperm, const Sched3& S, const Epi& E) {
;     ...
;             PG8_LDB(B1, 0, 1); PG8_STAGE(PG8_SB(0, 0), b2, voffB);
;             PG8_BAR; PG8_WAIT_L(0); PG8_MMA(0, 1, At, B1); PG8_BAR;
;             PG8_LDA(At, 0, 1); PG8_STAGE(PG8_SA(0, 0), a2, voffA);
;             PG8_BAR; PG8_WAIT_L(0); if (full) PG8_MMA(1, 0, At, B0); PG8_BAR; PG8_SCHED;
;             PG8_STAGE(PG8_SB(0, 1), b2 + hstepB, voffB);
	s_add_i32 m0, s62, 0x2000
	s_nop 0
	global_load_lds_dwordx4 v134, s[54:55]
	s_barrier
	s_waitcnt lgkmcnt(0)
	s_setprio 1
	s_waitcnt lgkmcnt(0)
	v_mfma_f32_16x16x32_bf16 v[60:63], v[214:217], v[172:175], 0
	v_mfma_f32_16x16x32_bf16 v[56:59], v[224:227], v[172:175], 0
	v_mfma_f32_16x16x32_bf16 v[52:55], v[214:217], v[190:193], 0
	v_mfma_f32_16x16x32_bf16 v[48:51], v[224:227], v[190:193], 0
	v_mfma_f32_16x16x32_bf16 v[44:47], v[214:217], v[198:201], 0
	v_mfma_f32_16x16x32_bf16 v[40:43], v[224:227], v[198:201], 0
	v_mfma_f32_16x16x32_bf16 v[36:39], v[214:217], v[206:209], 0
	v_mfma_f32_16x16x32_bf16 v[32:35], v[224:227], v[206:209], 0
	v_mfma_f32_16x16x32_bf16 v[60:63], v[218:221], v[186:189], v[60:63]
	v_mfma_f32_16x16x32_bf16 v[56:59], v[228:231], v[186:189], v[56:59]
	v_mfma_f32_16x16x32_bf16 v[52:55], v[218:221], v[194:197], v[52:55]
	v_mfma_f32_16x16x32_bf16 v[48:51], v[228:231], v[194:197], v[48:51]
	v_mfma_f32_16x16x32_bf16 v[44:47], v[218:221], v[202:205], v[44:47]
	v_mfma_f32_16x16x32_bf16 v[40:43], v[228:231], v[202:205], v[40:43]
	v_mfma_f32_16x16x32_bf16 v[36:39], v[218:221], v[210:213], v[36:39]
	v_mfma_f32_16x16x32_bf16 v[32:35], v[228:231], v[210:213], v[32:35]
	s_setprio 0
	s_mov_b32 m0, s66
	s_mov_b64 s[100:101], s[56:57]
	s_barrier
	ds_read_b128 v[172:175], v183 offset:16384
	ds_read_b128 v[186:189], v183 offset:17408
	ds_read_b128 v[190:193], v183 offset:18432
	ds_read_b128 v[194:197], v183 offset:19456
	ds_read_b128 v[198:201], v183 offset:20480
	ds_read_b128 v[202:205], v183 offset:21504
	ds_read_b128 v[206:209], v183 offset:22528
	ds_read_b128 v[210:213], v183 offset:23552
	global_load_lds_dwordx4 v128, s[56:57]
	s_mov_b64 s[100:101], s[56:57]
	s_mov_b32 m0, s67
	s_nop 0
	global_load_lds_dwordx4 v132, s[56:57]
	s_barrier
	s_waitcnt lgkmcnt(0)
	s_setprio 1
	s_waitcnt lgkmcnt(0)
	v_mfma_f32_16x16x32_bf16 v[92:95], v[156:159], v[172:175], 0
	v_mfma_f32_16x16x32_bf16 v[88:91], v[164:167], v[172:175], 0
	v_mfma_f32_16x16x32_bf16 v[84:87], v[156:159], v[190:193], 0
	v_mfma_f32_16x16x32_bf16 v[80:83], v[164:167], v[190:193], 0
	v_mfma_f32_16x16x32_bf16 v[76:79], v[156:159], v[198:201], 0
	v_mfma_f32_16x16x32_bf16 v[72:75], v[164:167], v[198:201], 0
	v_mfma_f32_16x16x32_bf16 v[68:71], v[156:159], v[206:209], 0
	v_mfma_f32_16x16x32_bf16 v[64:67], v[164:167], v[206:209], 0
	v_mfma_f32_16x16x32_bf16 v[92:95], v[160:163], v[186:189], v[92:95]
	v_mfma_f32_16x16x32_bf16 v[88:91], v[168:171], v[186:189], v[88:91]
	v_mfma_f32_16x16x32_bf16 v[84:87], v[160:163], v[194:197], v[84:87]
	v_mfma_f32_16x16x32_bf16 v[80:83], v[168:171], v[194:197], v[80:83]
	v_mfma_f32_16x16x32_bf16 v[76:79], v[160:163], v[202:205], v[76:79]
	v_mfma_f32_16x16x32_bf16 v[72:75], v[168:171], v[202:205], v[72:75]
	v_mfma_f32_16x16x32_bf16 v[68:71], v[160:163], v[210:213], v[68:71]
	v_mfma_f32_16x16x32_bf16 v[64:67], v[168:171], v[210:213], v[64:67]
	s_setprio 0
	s_barrier
	s_add_u32 s62, s54, 0x20000
	s_addc_u32 s63, s55, 0
	s_add_i32 s86, s77, s65

; #define PG8_STAGE(bufoff, gbase, voff) do { _Pragma("unroll") for (int _i = 0; _i < 2; ++_i) \
;         __builtin_amdgcn_global_load_lds((const unsigned*)((const char*)(gbase) + (voff)[_i]), (LAS unsigned*)(lds + (bufoff) + ldsw + _i * 8192), 16, 0, 0); } while (0)
; template <class Epi>
; DI void gemm_phase(LAS unsigned char* lds, int wid, int K, int lda, int ldb, bool bperm, const Sched3& S, const Epi& E) {
;     ...
;             PG8_STAGE(PG8_SB(0, 1), b2 + hstepB, voffB);
	s_mov_b32 m0, s86
	s_nop 0
	global_load_lds_dwordx4 v130, s[62:63]

; #define PG8_STAGE(bufoff, gbase, voff) do { _Pragma("unroll") for (int _i = 0; _i < 2; ++_i) \
;         __builtin_amdgcn_global_load_lds((const unsigned*)((const char*)(gbase) + (voff)[_i]), (LAS unsigned*)(lds + (bufoff) + ldsw + _i * 8192), 16, 0, 0); } while (0)
; #define PG8_LDA(dst, b, h) do { _Pragma("unroll") for (int m = 0; m < 4; ++m) _Pragma("unroll") for (int k = 0; k < 2; ++k) dst[m][k] = *(const LAS bf16x8*)(lds + PG8_SA(b, h) + aoff + m * 2048 + k * 1024); } while (0)
; #define PG8_LDB(dst, b, h) do { _Pragma("unroll") for (int n = 0; n < 2; ++n) _Pragma("unroll") for (int k = 0; k < 2; ++k) dst[n][k] = *(const LAS bf16x8*)(lds + PG8_SB(b, h) + boff + n * 2048 + k * 1024); } while (0)
; #define PG8_MMA(ai, bj, At, Bt) do { __builtin_amdgcn_s_setprio(1); _Pragma("unroll") for (int m = 0; m < 4; ++m) _Pragma("unroll") for (int n = 0; n < 2; ++n) _Pragma("unroll") for (int k = 0; k < 2; ++k) \
;         acc[ai][bj][m][n] = __builtin_amdgcn_mfma_f32_16x16x32_bf16(Bt[n][k], At[m][k], acc[ai][bj][m][n], 0, 0, 0); __builtin_amdgcn_s_setprio(0); } while (0)
; #define PG8_WAIT_V(n) asm volatile("s_waitcnt vmcnt(" #n ")" ::: "memory")
; #define PG8_BAR __builtin_amdgcn_s_barrier()
; #define PG8_SCHED __builtin_amdgcn_sched_barrier(0)
; template <class Epi>
; DI void gemm_phase(LAS unsigned char* lds, int wid, int K, int lda, int ldb, bool bperm, const Sched3& S, const Epi& E) {
;     ...
;             PG8_STAGE(PG8_SB(0, 1), b2 + hstepB, voffB);
;             PG8_WAIT_V(6); PG8_BAR; if (full) PG8_MMA(1, 1, At, B1); PG8_BAR;
;             PG8_LDB(B0, 1, 0); PG8_SCHED; PG8_LDA(At, 1, 0); PG8_STAGE(PG8_SA(0, 1), a2 + h2, voffA);
	s_add_i32 m0, s86, 0x2000
	s_nop 0
	global_load_lds_dwordx4 v134, s[62:63]
	s_waitcnt vmcnt(6)
	s_barrier
	s_setprio 1
	v_mfma_f32_16x16x32_bf16 v[28:31], v[214:217], v[172:175], 0
	v_mfma_f32_16x16x32_bf16 v[24:27], v[224:227], v[172:175], 0
	v_mfma_f32_16x16x32_bf16 v[20:23], v[214:217], v[190:193], 0
	v_mfma_f32_16x16x32_bf16 v[16:19], v[224:227], v[190:193], 0
	v_mfma_f32_16x16x32_bf16 v[12:15], v[214:217], v[198:201], 0
	v_mfma_f32_16x16x32_bf16 v[8:11], v[224:227], v[198:201], 0
	v_mfma_f32_16x16x32_bf16 v[4:7], v[214:217], v[206:209], 0
	v_mfma_f32_16x16x32_bf16 v[0:3], v[224:227], v[206:209], 0
	v_mfma_f32_16x16x32_bf16 v[28:31], v[218:221], v[186:189], v[28:31]
	v_mfma_f32_16x16x32_bf16 v[24:27], v[228:231], v[186:189], v[24:27]
	v_mfma_f32_16x16x32_bf16 v[20:23], v[218:221], v[194:197], v[20:23]
	v_mfma_f32_16x16x32_bf16 v[16:19], v[228:231], v[194:197], v[16:19]
	v_mfma_f32_16x16x32_bf16 v[12:15], v[218:221], v[202:205], v[12:15]
	v_mfma_f32_16x16x32_bf16 v[8:11], v[228:231], v[202:205], v[8:11]
	v_mfma_f32_16x16x32_bf16 v[4:7], v[218:221], v[210:213], v[4:7]
	v_mfma_f32_16x16x32_bf16 v[0:3], v[228:231], v[210:213], v[0:3]
	s_setprio 0
	s_add_i32 s62, 0, 0x18000
	v_add_u32_e32 v136, s62, v179
	s_barrier
	ds_read_b128 v[156:159], v136
	ds_read_b128 v[160:163], v136 offset:1024
	ds_read_b128 v[164:167], v136 offset:2048
	ds_read_b128 v[168:171], v136 offset:3072
	s_add_u32 s56, s56, 0x20000
	s_addc_u32 s57, s57, 0
	s_mov_b32 m0, s68

; #define PG8_STAGE(bufoff, gbase, voff) do { _Pragma("unroll") for (int _i = 0; _i < 2; ++_i) \
;         __builtin_amdgcn_global_load_lds((const unsigned*)((const char*)(gbase) + (voff)[_i]), (LAS unsigned*)(lds + (bufoff) + ldsw + _i * 8192), 16, 0, 0); } while (0)
; #define PG8_LDA(dst, b, h) do { _Pragma("unroll") for (int m = 0; m < 4; ++m) _Pragma("unroll") for (int k = 0; k < 2; ++k) dst[m][k] = *(const LAS bf16x8*)(lds + PG8_SA(b, h) + aoff + m * 2048 + k * 1024); } while (0)
; #define PG8_LDB(dst, b, h) do { _Pragma("unroll") for (int n = 0; n < 2; ++n) _Pragma("unroll") for (int k = 0; k < 2; ++k) dst[n][k] = *(const LAS bf16x8*)(lds + PG8_SB(b, h) + boff + n * 2048 + k * 1024); } while (0)
; #define PG8_SCHED __builtin_amdgcn_sched_barrier(0)
; template <class Epi>
; DI void gemm_phase(LAS unsigned char* lds, int wid, int K, int lda, int ldb, bool bperm, const Sched3& S, const Epi& E) {
;     ...
;             PG8_LDB(B0, 1, 0); PG8_SCHED; PG8_LDA(At, 1, 0); PG8_STAGE(PG8_SA(0, 1), a2 + h2, voffA);
	ds_read_b128 v[172:175], v183 offset:32768
	ds_read_b128 v[186:189], v183 offset:33792
	ds_read_b128 v[190:193], v183 offset:34816
	ds_read_b128 v[194:197], v183 offset:35840
	ds_read_b128 v[198:201], v183 offset:36864
	ds_read_b128 v[202:205], v183 offset:37888
	ds_read_b128 v[206:209], v183 offset:38912
	ds_read_b128 v[210:213], v183 offset:39936
	global_load_lds_dwordx4 v128, s[56:57]

; #define PG8_STAGE(bufoff, gbase, voff) do { _Pragma("unroll") for (int _i = 0; _i < 2; ++_i) \
;         __builtin_amdgcn_global_load_lds((const unsigned*)((const char*)(gbase) + (voff)[_i]), (LAS unsigned*)(lds + (bufoff) + ldsw + _i * 8192), 16, 0, 0); } while (0)
; #define PG8_LDA(dst, b, h) do { _Pragma("unroll") for (int m = 0; m < 4; ++m) _Pragma("unroll") for (int k = 0; k < 2; ++k) dst[m][k] = *(const LAS bf16x8*)(lds + PG8_SA(b, h) + aoff + m * 2048 + k * 1024); } while (0)
; #define PG8_LDB(dst, b, h) do { _Pragma("unroll") for (int n = 0; n < 2; ++n) _Pragma("unroll") for (int k = 0; k < 2; ++k) dst[n][k] = *(const LAS bf16x8*)(lds + PG8_SB(b, h) + boff + n * 2048 + k * 1024); } while (0)
; #define PG8_MMA(ai, bj, At, Bt) do { __builtin_amdgcn_s_setprio(1); _Pragma("unroll") for (int m = 0; m < 4; ++m) _Pragma("unroll") for (int n = 0; n < 2; ++n) _Pragma("unroll") for (int k = 0; k < 2; ++k) \
;         acc[ai][bj][m][n] = __builtin_amdgcn_mfma_f32_16x16x32_bf16(Bt[n][k], At[m][k], acc[ai][bj][m][n], 0, 0, 0); __builtin_amdgcn_s_setprio(0); } while (0)
; #define PG8_WAIT_L(n) asm volatile("s_waitcnt lgkmcnt(" #n ")" ::: "memory")
; #define PG8_BAR __builtin_amdgcn_s_barrier()
; #define PG8_SCHED __builtin_amdgcn_sched_barrier(0)
; template <class Epi>
; DI void gemm_phase(LAS unsigned char* lds, int wid, int K, int lda, int ldb, bool bperm, const Sched3& S, const Epi& E) {
;     ...
;             PG8_LDB(B0, 1, 0); PG8_SCHED; PG8_LDA(At, 1, 0); PG8_STAGE(PG8_SA(0, 1), a2 + h2, voffA);
;             PG8_WAIT_L(8); PG8_BAR; PG8_WAIT_L(0); PG8_MMA(0, 0, At, B0); PG8_BAR; PG8_SCHED;
;             PG8_LDB(B1, 1, 1); PG8_STAGE(PG8_SB(1, 0), b3, voffB);
	s_mov_b32 m0, s69
	s_nop 0
	global_load_lds_dwordx4 v132, s[56:57]
	s_waitcnt lgkmcnt(8)
	s_barrier
	s_waitcnt lgkmcnt(0)
	s_setprio 1
	s_waitcnt lgkmcnt(0)
	v_mfma_f32_16x16x32_bf16 v[124:127], v[156:159], v[172:175], v[124:127]
	v_mfma_f32_16x16x32_bf16 v[120:123], v[164:167], v[172:175], v[120:123]
	v_mfma_f32_16x16x32_bf16 v[116:119], v[156:159], v[190:193], v[116:119]
	v_mfma_f32_16x16x32_bf16 v[112:115], v[164:167], v[190:193], v[112:115]
	v_mfma_f32_16x16x32_bf16 v[108:111], v[156:159], v[198:201], v[108:111]
	v_mfma_f32_16x16x32_bf16 v[104:107], v[164:167], v[198:201], v[104:107]
	v_mfma_f32_16x16x32_bf16 v[100:103], v[156:159], v[206:209], v[100:103]
	v_mfma_f32_16x16x32_bf16 v[96:99], v[164:167], v[206:209], v[96:99]
	v_mfma_f32_16x16x32_bf16 v[124:127], v[160:163], v[186:189], v[124:127]
	v_mfma_f32_16x16x32_bf16 v[120:123], v[168:171], v[186:189], v[120:123]
	v_mfma_f32_16x16x32_bf16 v[116:119], v[160:163], v[194:197], v[116:119]
	v_mfma_f32_16x16x32_bf16 v[112:115], v[168:171], v[194:197], v[112:115]
	v_mfma_f32_16x16x32_bf16 v[108:111], v[160:163], v[202:205], v[108:111]
	v_mfma_f32_16x16x32_bf16 v[104:107], v[168:171], v[202:205], v[104:107]
	v_mfma_f32_16x16x32_bf16 v[100:103], v[160:163], v[210:213], v[100:103]
	v_mfma_f32_16x16x32_bf16 v[96:99], v[168:171], v[210:213], v[96:99]
	s_setprio 0
	s_barrier
	s_add_i32 s56, 0, 0x1c000
	s_add_i32 s57, s62, s65
	v_add_u32_e32 v136, s56, v179

; #define PG8_STAGE(bufoff, gbase, voff) do { _Pragma("unroll") for (int _i = 0; _i < 2; ++_i) \
;         __builtin_amdgcn_global_load_lds((const unsigned*)((const char*)(gbase) + (voff)[_i]), (LAS unsigned*)(lds + (bufoff) + ldsw + _i * 8192), 16, 0, 0); } while (0)
; #define PG8_LDB(dst, b, h) do { _Pragma("unroll") for (int n = 0; n < 2; ++n) _Pragma("unroll") for (int k = 0; k < 2; ++k) dst[n][k] = *(const LAS bf16x8*)(lds + PG8_SB(b, h) + boff + n * 2048 + k * 1024); } while (0)
; template <class Epi>
; DI void gemm_phase(LAS unsigned char* lds, int wid, int K, int lda, int ldb, bool bperm, const Sched3& S, const Epi& E) {
;     ...
;             PG8_LDB(B1, 1, 1); PG8_STAGE(PG8_SB(1, 0), b3, voffB);
	s_sub_i32 m0, s57, 0x80
	ds_read_b128 v[214:217], v136
	ds_read_b128 v[218:221], v136 offset:1024
	ds_read_b128 v[224:227], v136 offset:2048
	ds_read_b128 v[228:231], v136 offset:3072
	global_load_lds_dwordx4 v130, s[54:55] offset:128

; #define PG8_STAGE(bufoff, gbase, voff) do { _Pragma("unroll") for (int _i = 0; _i < 2; ++_i) \
;         __builtin_amdgcn_global_load_lds((const unsigned*)((const char*)(gbase) + (voff)[_i]), (LAS unsigned*)(lds + (bufoff) + ldsw + _i * 8192), 16, 0, 0); } while (0)
; #define PG8_LDA(dst, b, h) do { _Pragma("unroll") for (int m = 0; m < 4; ++m) _Pragma("unroll") for (int k = 0; k < 2; ++k) dst[m][k] = *(const LAS bf16x8*)(lds + PG8_SA(b, h) + aoff + m * 2048 + k * 1024); } while (0)
; #define PG8_LDB(dst, b, h) do { _Pragma("unroll") for (int n = 0; n < 2; ++n) _Pragma("unroll") for (int k = 0; k < 2; ++k) dst[n][k] = *(const LAS bf16x8*)(lds + PG8_SB(b, h) + boff + n * 2048 + k * 1024); } while (0)
; #define PG8_MMA(ai, bj, At, Bt) do { __builtin_amdgcn_s_setprio(1); _Pragma("unroll") for (int m = 0; m < 4; ++m) _Pragma("unroll") for (int n = 0; n < 2; ++n) _Pragma("unroll") for (int k = 0; k < 2; ++k) \
;         acc[ai][bj][m][n] = __builtin_amdgcn_mfma_f32_16x16x32_bf16(Bt[n][k], At[m][k], acc[ai][bj][m][n], 0, 0, 0); __builtin_amdgcn_s_setprio(0); } while (0)
; #define PG8_WAIT_L(n) asm volatile("s_waitcnt lgkmcnt(" #n ")" ::: "memory")
; #define PG8_BAR __builtin_amdgcn_s_barrier()
; template <class Epi>
; DI void gemm_phase(LAS unsigned char* lds, int wid, int K, int lda, int ldb, bool bperm, const Sched3& S, const Epi& E) {
;     ...
;             PG8_LDB(B1, 1, 1); PG8_STAGE(PG8_SB(1, 0), b3, voffB);
;             PG8_BAR; PG8_WAIT_L(0); PG8_MMA(0, 1, At, B1); PG8_BAR;
;             PG8_LDA(At, 1, 1); PG8_STAGE(PG8_SA(1, 0), a3, voffA);
	s_add_i32 m0, s57, 0x1f80
	s_nop 0
	global_load_lds_dwordx4 v134, s[54:55] offset:128
	s_barrier
	s_waitcnt lgkmcnt(0)
	s_setprio 1
	s_waitcnt lgkmcnt(0)
	v_mfma_f32_16x16x32_bf16 v[60:63], v[214:217], v[172:175], v[60:63]
	v_mfma_f32_16x16x32_bf16 v[56:59], v[224:227], v[172:175], v[56:59]
	v_mfma_f32_16x16x32_bf16 v[52:55], v[214:217], v[190:193], v[52:55]
	v_mfma_f32_16x16x32_bf16 v[48:51], v[224:227], v[190:193], v[48:51]
	v_mfma_f32_16x16x32_bf16 v[44:47], v[214:217], v[198:201], v[44:47]
	v_mfma_f32_16x16x32_bf16 v[40:43], v[224:227], v[198:201], v[40:43]
	v_mfma_f32_16x16x32_bf16 v[36:39], v[214:217], v[206:209], v[36:39]
	v_mfma_f32_16x16x32_bf16 v[32:35], v[224:227], v[206:209], v[32:35]
	v_mfma_f32_16x16x32_bf16 v[60:63], v[218:221], v[186:189], v[60:63]
	v_mfma_f32_16x16x32_bf16 v[56:59], v[228:231], v[186:189], v[56:59]
	v_mfma_f32_16x16x32_bf16 v[52:55], v[218:221], v[194:197], v[52:55]
	v_mfma_f32_16x16x32_bf16 v[48:51], v[228:231], v[194:197], v[48:51]
	v_mfma_f32_16x16x32_bf16 v[44:47], v[218:221], v[202:205], v[44:47]
	v_mfma_f32_16x16x32_bf16 v[40:43], v[228:231], v[202:205], v[40:43]
	v_mfma_f32_16x16x32_bf16 v[36:39], v[218:221], v[210:213], v[36:39]
	v_mfma_f32_16x16x32_bf16 v[32:35], v[228:231], v[210:213], v[32:35]
	s_setprio 0
	s_sub_i32 m0, s72, 0x80

; #define PG8_STAGE(bufoff, gbase, voff) do { _Pragma("unroll") for (int _i = 0; _i < 2; ++_i) \
;         __builtin_amdgcn_global_load_lds((const unsigned*)((const char*)(gbase) + (voff)[_i]), (LAS unsigned*)(lds + (bufoff) + ldsw + _i * 8192), 16, 0, 0); } while (0)
; #define PG8_LDA(dst, b, h) do { _Pragma("unroll") for (int m = 0; m < 4; ++m) _Pragma("unroll") for (int k = 0; k < 2; ++k) dst[m][k] = *(const LAS bf16x8*)(lds + PG8_SA(b, h) + aoff + m * 2048 + k * 1024); } while (0)
; template <class Epi>
; DI void gemm_phase(LAS unsigned char* lds, int wid, int K, int lda, int ldb, bool bperm, const Sched3& S, const Epi& E) {
;     ...
;             PG8_LDA(At, 1, 1); PG8_STAGE(PG8_SA(1, 0), a3, voffA);
	s_barrier
	ds_read_b128 v[172:175], v183 offset:49152
	ds_read_b128 v[186:189], v183 offset:50176
	ds_read_b128 v[190:193], v183 offset:51200
	ds_read_b128 v[194:197], v183 offset:52224
	ds_read_b128 v[198:201], v183 offset:53248
	ds_read_b128 v[202:205], v183 offset:54272
	ds_read_b128 v[206:209], v183 offset:55296
	ds_read_b128 v[210:213], v183 offset:56320
	global_load_lds_dwordx4 v128, s[100:101] offset:128

; #define PG8_STAGE(bufoff, gbase, voff) do { _Pragma("unroll") for (int _i = 0; _i < 2; ++_i) \
;         __builtin_amdgcn_global_load_lds((const unsigned*)((const char*)(gbase) + (voff)[_i]), (LAS unsigned*)(lds + (bufoff) + ldsw + _i * 8192), 16, 0, 0); } while (0)
; #define PG8_LDA(dst, b, h) do { _Pragma("unroll") for (int m = 0; m < 4; ++m) _Pragma("unroll") for (int k = 0; k < 2; ++k) dst[m][k] = *(const LAS bf16x8*)(lds + PG8_SA(b, h) + aoff + m * 2048 + k * 1024); } while (0)
; #define PG8_MMA(ai, bj, At, Bt) do { __builtin_amdgcn_s_setprio(1); _Pragma("unroll") for (int m = 0; m < 4; ++m) _Pragma("unroll") for (int n = 0; n < 2; ++n) _Pragma("unroll") for (int k = 0; k < 2; ++k) \
;         acc[ai][bj][m][n] = __builtin_amdgcn_mfma_f32_16x16x32_bf16(Bt[n][k], At[m][k], acc[ai][bj][m][n], 0, 0, 0); __builtin_amdgcn_s_setprio(0); } while (0)
; #define PG8_WAIT_L(n) asm volatile("s_waitcnt lgkmcnt(" #n ")" ::: "memory")
; #define PG8_BAR __builtin_amdgcn_s_barrier()
; #define PG8_SCHED __builtin_amdgcn_sched_barrier(0)
; template <class Epi>
; DI void gemm_phase(LAS unsigned char* lds, int wid, int K, int lda, int ldb, bool bperm, const Sched3& S, const Epi& E) {
;     ...
;             PG8_LDA(At, 1, 1); PG8_STAGE(PG8_SA(1, 0), a3, voffA);
;             PG8_BAR; PG8_WAIT_L(0); if (full) PG8_MMA(1, 0, At, B0); PG8_BAR; PG8_SCHED;
;             PG8_STAGE(PG8_SB(1, 1), b3 + hstepB, voffB);
	s_sub_i32 m0, s73, 0x80
	s_nop 0
	global_load_lds_dwordx4 v132, s[100:101] offset:128
	s_barrier
	s_waitcnt lgkmcnt(0)
	s_setprio 1
	s_waitcnt lgkmcnt(0)
	v_mfma_f32_16x16x32_bf16 v[92:95], v[156:159], v[172:175], v[92:95]
	v_mfma_f32_16x16x32_bf16 v[88:91], v[164:167], v[172:175], v[88:91]
	v_mfma_f32_16x16x32_bf16 v[84:87], v[156:159], v[190:193], v[84:87]
	v_mfma_f32_16x16x32_bf16 v[80:83], v[164:167], v[190:193], v[80:83]
	v_mfma_f32_16x16x32_bf16 v[76:79], v[156:159], v[198:201], v[76:79]
	v_mfma_f32_16x16x32_bf16 v[72:75], v[164:167], v[198:201], v[72:75]
	v_mfma_f32_16x16x32_bf16 v[68:71], v[156:159], v[206:209], v[68:71]
	v_mfma_f32_16x16x32_bf16 v[64:67], v[164:167], v[206:209], v[64:67]
	v_mfma_f32_16x16x32_bf16 v[92:95], v[160:163], v[186:189], v[92:95]
	v_mfma_f32_16x16x32_bf16 v[88:91], v[168:171], v[186:189], v[88:91]
	v_mfma_f32_16x16x32_bf16 v[84:87], v[160:163], v[194:197], v[84:87]
	v_mfma_f32_16x16x32_bf16 v[80:83], v[168:171], v[194:197], v[80:83]
	v_mfma_f32_16x16x32_bf16 v[76:79], v[160:163], v[202:205], v[76:79]
	v_mfma_f32_16x16x32_bf16 v[72:75], v[168:171], v[202:205], v[72:75]
	v_mfma_f32_16x16x32_bf16 v[68:71], v[160:163], v[210:213], v[68:71]
	v_mfma_f32_16x16x32_bf16 v[64:67], v[168:171], v[210:213], v[64:67]
	s_setprio 0
	s_barrier
	s_add_u32 s54, s54, 0x20080
	s_addc_u32 s55, s55, 0
	s_add_i32 s56, s56, s65

; #define PG8_STAGE(bufoff, gbase, voff) do { _Pragma("unroll") for (int _i = 0; _i < 2; ++_i) \
;         __builtin_amdgcn_global_load_lds((const unsigned*)((const char*)(gbase) + (voff)[_i]), (LAS unsigned*)(lds + (bufoff) + ldsw + _i * 8192), 16, 0, 0); } while (0)
; template <class Epi>
; DI void gemm_phase(LAS unsigned char* lds, int wid, int K, int lda, int ldb, bool bperm, const Sched3& S, const Epi& E) {
;     ...
;             PG8_STAGE(PG8_SB(1, 1), b3 + hstepB, voffB);
	s_mov_b32 m0, s56
	s_nop 0
	global_load_lds_dwordx4 v130, s[54:55]

; #define PG8_STAGE(bufoff, gbase, voff) do { _Pragma("unroll") for (int _i = 0; _i < 2; ++_i) \
;         __builtin_amdgcn_global_load_lds((const unsigned*)((const char*)(gbase) + (voff)[_i]), (LAS unsigned*)(lds + (bufoff) + ldsw + _i * 8192), 16, 0, 0); } while (0)
; #define PG8_LDA(dst, b, h) do { _Pragma("unroll") for (int m = 0; m < 4; ++m) _Pragma("unroll") for (int k = 0; k < 2; ++k) dst[m][k] = *(const LAS bf16x8*)(lds + PG8_SA(b, h) + aoff + m * 2048 + k * 1024); } while (0)
; #define PG8_LDB(dst, b, h) do { _Pragma("unroll") for (int n = 0; n < 2; ++n) _Pragma("unroll") for (int k = 0; k < 2; ++k) dst[n][k] = *(const LAS bf16x8*)(lds + PG8_SB(b, h) + boff + n * 2048 + k * 1024); } while (0)
; #define PG8_MMA(ai, bj, At, Bt) do { __builtin_amdgcn_s_setprio(1); _Pragma("unroll") for (int m = 0; m < 4; ++m) _Pragma("unroll") for (int n = 0; n < 2; ++n) _Pragma("unroll") for (int k = 0; k < 2; ++k) \
;         acc[ai][bj][m][n] = __builtin_amdgcn_mfma_f32_16x16x32_bf16(Bt[n][k], At[m][k], acc[ai][bj][m][n], 0, 0, 0); __builtin_amdgcn_s_setprio(0); } while (0)
; #define PG8_WAIT_V(n) asm volatile("s_waitcnt vmcnt(" #n ")" ::: "memory")
; #define PG8_BAR __builtin_amdgcn_s_barrier()
; #define PG8_SCHED __builtin_amdgcn_sched_barrier(0)
; template <class Epi>
; DI void gemm_phase(LAS unsigned char* lds, int wid, int K, int lda, int ldb, bool bperm, const Sched3& S, const Epi& E) {
;     ...
;             const bool last = (t == nt - 2);
;             const char* a1 = cA + (size_t)(t + 1) * kstep;
;             const char* a2 = last ? nA : cA + (size_t)(t + 2) * kstep; const char* b2 = last ? nB : cB + (size_t)(t + 2) * kstep;
;             const char* a3 = a2 + kstep; const char* b3 = b2 + kstep; const size_t h2 = last ? nhA : hA;
;             PG8_LDB(B0, 0, 0); PG8_SCHED; PG8_LDA(At, 0, 0); PG8_STAGE(PG8_SA(1, 1), a1 + hA, voffA);
;     ...
;             PG8_STAGE(PG8_SB(1, 1), b3 + hstepB, voffB);
;             PG8_WAIT_V(6); PG8_BAR; if (full) PG8_MMA(1, 1, At, B1); PG8_BAR;
	s_add_i32 m0, s56, 0x2000
	s_nop 0
	global_load_lds_dwordx4 v134, s[54:55]
	s_waitcnt vmcnt(6)
	s_barrier
	s_setprio 1
	v_mfma_f32_16x16x32_bf16 v[28:31], v[214:217], v[172:175], v[28:31]
	v_mfma_f32_16x16x32_bf16 v[24:27], v[224:227], v[172:175], v[24:27]
	v_mfma_f32_16x16x32_bf16 v[20:23], v[214:217], v[190:193], v[20:23]
	v_mfma_f32_16x16x32_bf16 v[16:19], v[224:227], v[190:193], v[16:19]
	v_mfma_f32_16x16x32_bf16 v[12:15], v[214:217], v[198:201], v[12:15]
	v_mfma_f32_16x16x32_bf16 v[8:11], v[224:227], v[198:201], v[8:11]
	v_mfma_f32_16x16x32_bf16 v[4:7], v[214:217], v[206:209], v[4:7]
	v_mfma_f32_16x16x32_bf16 v[0:3], v[224:227], v[206:209], v[0:3]
	v_mfma_f32_16x16x32_bf16 v[28:31], v[218:221], v[186:189], v[28:31]
	v_mfma_f32_16x16x32_bf16 v[24:27], v[228:231], v[186:189], v[24:27]
	v_mfma_f32_16x16x32_bf16 v[20:23], v[218:221], v[194:197], v[20:23]
	v_mfma_f32_16x16x32_bf16 v[16:19], v[228:231], v[194:197], v[16:19]
	v_mfma_f32_16x16x32_bf16 v[12:15], v[218:221], v[202:205], v[12:15]
	v_mfma_f32_16x16x32_bf16 v[8:11], v[228:231], v[202:205], v[8:11]
	v_mfma_f32_16x16x32_bf16 v[4:7], v[218:221], v[210:213], v[4:7]
	v_mfma_f32_16x16x32_bf16 v[0:3], v[228:231], v[210:213], v[0:3]
	s_setprio 0
	s_add_i32 s61, s61, 2
	s_add_u32 s52, s52, 0x100
	s_addc_u32 s53, s53, 0
	s_add_u32 s59, s59, 0x100
	s_addc_u32 s60, s60, 0
	s_cmp_gt_u32 s61, 5
	s_barrier
	s_cbranch_scc0 .LBB0_996
	s_branch .Lpeel_5_exit
.LBB0_996:
	ds_read_b128 v[156:159], v182
	ds_read_b128 v[160:163], v182 offset:1024
	ds_read_b128 v[164:167], v182 offset:2048
	ds_read_b128 v[168:171], v182 offset:3072
	s_add_u32 s54, s52, 0xfffe0080
	s_addc_u32 s55, s53, -1
	s_cmp_eq_u32 s61, 4
	s_cselect_b32 s57, s41, s55
	s_cselect_b32 s56, s43, s54
	s_cselect_b32 s55, s51, s60
	s_cselect_b32 s54, s58, s59

; #define PG8_STAGE(bufoff, gbase, voff) do { _Pragma("unroll") for (int _i = 0; _i < 2; ++_i) \
;         __builtin_amdgcn_global_load_lds((const unsigned*)((const char*)(gbase) + (voff)[_i]), (LAS unsigned*)(lds + (bufoff) + ldsw + _i * 8192), 16, 0, 0); } while (0)
; #define PG8_LDA(dst, b, h) do { _Pragma("unroll") for (int m = 0; m < 4; ++m) _Pragma("unroll") for (int k = 0; k < 2; ++k) dst[m][k] = *(const LAS bf16x8*)(lds + PG8_SA(b, h) + aoff + m * 2048 + k * 1024); } while (0)
; #define PG8_LDB(dst, b, h) do { _Pragma("unroll") for (int n = 0; n < 2; ++n) _Pragma("unroll") for (int k = 0; k < 2; ++k) dst[n][k] = *(const LAS bf16x8*)(lds + PG8_SB(b, h) + boff + n * 2048 + k * 1024); } while (0)
; #define PG8_SCHED __builtin_amdgcn_sched_barrier(0)
; template <class Epi>
; DI void gemm_phase(LAS unsigned char* lds, int wid, int K, int lda, int ldb, bool bperm, const Sched3& S, const Epi& E) {
;     ...
;             PG8_LDB(B0, 0, 0); PG8_SCHED; PG8_LDA(At, 0, 0); PG8_STAGE(PG8_SA(1, 1), a1 + hA, voffA);
	s_add_i32 m0, s66, 0xc000
	ds_read_b128 v[172:175], v183
	ds_read_b128 v[186:189], v183 offset:1024
	ds_read_b128 v[190:193], v183 offset:2048
	ds_read_b128 v[194:197], v183 offset:3072
	ds_read_b128 v[198:201], v183 offset:4096
	ds_read_b128 v[202:205], v183 offset:5120
	ds_read_b128 v[206:209], v183 offset:6144
	ds_read_b128 v[210:213], v183 offset:7168
	global_load_lds_dwordx4 v144, s[52:53]

; #define PG8_STAGE(bufoff, gbase, voff) do { _Pragma("unroll") for (int _i = 0; _i < 2; ++_i) \
;         __builtin_amdgcn_global_load_lds((const unsigned*)((const char*)(gbase) + (voff)[_i]), (LAS unsigned*)(lds + (bufoff) + ldsw + _i * 8192), 16, 0, 0); } while (0)
; #define PG8_LDA(dst, b, h) do { _Pragma("unroll") for (int m = 0; m < 4; ++m) _Pragma("unroll") for (int k = 0; k < 2; ++k) dst[m][k] = *(const LAS bf16x8*)(lds + PG8_SA(b, h) + aoff + m * 2048 + k * 1024); } while (0)
; #define PG8_LDB(dst, b, h) do { _Pragma("unroll") for (int n = 0; n < 2; ++n) _Pragma("unroll") for (int k = 0; k < 2; ++k) dst[n][k] = *(const LAS bf16x8*)(lds + PG8_SB(b, h) + boff + n * 2048 + k * 1024); } while (0)
; #define PG8_MMA(ai, bj, At, Bt) do { __builtin_amdgcn_s_setprio(1); _Pragma("unroll") for (int m = 0; m < 4; ++m) _Pragma("unroll") for (int n = 0; n < 2; ++n) _Pragma("unroll") for (int k = 0; k < 2; ++k) \
;         acc[ai][bj][m][n] = __builtin_amdgcn_mfma_f32_16x16x32_bf16(Bt[n][k], At[m][k], acc[ai][bj][m][n], 0, 0, 0); __builtin_amdgcn_s_setprio(0); } while (0)
; #define PG8_WAIT_L(n) asm volatile("s_waitcnt lgkmcnt(" #n ")" ::: "memory")
; #define PG8_BAR __builtin_amdgcn_s_barrier()
; #define PG8_SCHED __builtin_amdgcn_sched_barrier(0)
; template <class Epi>
; DI void gemm_phase(LAS unsigned char* lds, int wid, int K, int lda, int ldb, bool bperm, const Sched3& S, const Epi& E) {
;     ...
;             PG8_LDB(B0, 0, 0); PG8_SCHED; PG8_LDA(At, 0, 0); PG8_STAGE(PG8_SA(1, 1), a1 + hA, voffA);
;             PG8_WAIT_L(8); PG8_BAR; PG8_WAIT_L(0); PG8_MMA(0, 0, At, B0); PG8_BAR; PG8_SCHED;
;             PG8_LDB(B1, 0, 1); PG8_STAGE(PG8_SB(0, 0), b2, voffB);
	s_add_i32 m0, s66, 0xe000
	s_nop 0
	global_load_lds_dwordx4 v146, s[52:53]
	s_waitcnt lgkmcnt(8)
	s_barrier
	s_waitcnt lgkmcnt(0)
	s_setprio 1
	s_waitcnt lgkmcnt(0)
	v_mfma_f32_16x16x32_bf16 v[124:127], v[156:159], v[172:175], v[124:127]
	v_mfma_f32_16x16x32_bf16 v[120:123], v[164:167], v[172:175], v[120:123]
	v_mfma_f32_16x16x32_bf16 v[116:119], v[156:159], v[190:193], v[116:119]
	v_mfma_f32_16x16x32_bf16 v[112:115], v[164:167], v[190:193], v[112:115]
	v_mfma_f32_16x16x32_bf16 v[108:111], v[156:159], v[198:201], v[108:111]
	v_mfma_f32_16x16x32_bf16 v[104:107], v[164:167], v[198:201], v[104:107]
	v_mfma_f32_16x16x32_bf16 v[100:103], v[156:159], v[206:209], v[100:103]
	v_mfma_f32_16x16x32_bf16 v[96:99], v[164:167], v[206:209], v[96:99]
	v_mfma_f32_16x16x32_bf16 v[124:127], v[160:163], v[186:189], v[124:127]
	v_mfma_f32_16x16x32_bf16 v[120:123], v[168:171], v[186:189], v[120:123]
	v_mfma_f32_16x16x32_bf16 v[116:119], v[160:163], v[194:197], v[116:119]
	v_mfma_f32_16x16x32_bf16 v[112:115], v[168:171], v[194:197], v[112:115]
	v_mfma_f32_16x16x32_bf16 v[108:111], v[160:163], v[202:205], v[108:111]
	v_mfma_f32_16x16x32_bf16 v[104:107], v[168:171], v[202:205], v[104:107]
	v_mfma_f32_16x16x32_bf16 v[100:103], v[160:163], v[210:213], v[100:103]
	v_mfma_f32_16x16x32_bf16 v[96:99], v[168:171], v[210:213], v[96:99]
	s_setprio 0
	s_barrier
	s_add_i32 s62, s76, s65

; #define PG8_STAGE(bufoff, gbase, voff) do { _Pragma("unroll") for (int _i = 0; _i < 2; ++_i) \
;         __builtin_amdgcn_global_load_lds((const unsigned*)((const char*)(gbase) + (voff)[_i]), (LAS unsigned*)(lds + (bufoff) + ldsw + _i * 8192), 16, 0, 0); } while (0)
; #define PG8_LDA(dst, b, h) do { _Pragma("unroll") for (int m = 0; m < 4; ++m) _Pragma("unroll") for (int k = 0; k < 2; ++k) dst[m][k] = *(const LAS bf16x8*)(lds + PG8_SA(b, h) + aoff + m * 2048 + k * 1024); } while (0)
; #define PG8_LDB(dst, b, h) do { _Pragma("unroll") for (int n = 0; n < 2; ++n) _Pragma("unroll") for (int k = 0; k < 2; ++k) dst[n][k] = *(const LAS bf16x8*)(lds + PG8_SB(b, h) + boff + n * 2048 + k * 1024); } while (0)
; #define PG8_WAIT_V(n) asm volatile("s_waitcnt vmcnt(" #n ")" ::: "memory")
; #define PG8_WAIT_L(n) asm volatile("s_waitcnt lgkmcnt(" #n ")" ::: "memory")
; #define PG8_BAR __builtin_amdgcn_s_barrier()
; #define PG8_SCHED __builtin_amdgcn_sched_barrier(0)
; template <class Epi>
; DI void gemm_phase(LAS unsigned char* lds, int wid, int K, int lda, int ldb, bool bperm, const Sched3& S, const Epi& E) {
;     ...
;             PG8_LDB(B0, 0, 0); PG8_SCHED; PG8_LDA(At, 0, 0); PG8_STAGE(PG8_SA(1, 1), a1 + hA, voffA);
;             PG8_WAIT_L(8); PG8_BAR; PG8_WAIT_L(0); PG8_MMA(0, 0, At, B0); PG8_BAR; PG8_SCHED;
;             PG8_LDB(B1, 0, 1); PG8_STAGE(PG8_SB(0, 0), b2, voffB);
;             PG8_BAR; PG8_WAIT_L(0); PG8_MMA(0, 1, At, B1); PG8_BAR;
;             PG8_LDA(At, 0, 1); PG8_STAGE(PG8_SA(0, 0), a2, voffA);
;             PG8_BAR; PG8_WAIT_L(0); if (full) PG8_MMA(1, 0, At, B0); PG8_BAR; PG8_SCHED;
;             PG8_STAGE(PG8_SB(0, 1), b2 + hstepB, voffB);
;             PG8_WAIT_V(6); PG8_BAR; if (full) PG8_MMA(1, 1, At, B1); PG8_BAR;
;             PG8_LDB(B0, 1, 0); PG8_SCHED; PG8_LDA(At, 1, 0); PG8_STAGE(PG8_SA(0, 1), a2 + h2, voffA);
;             PG8_WAIT_L(8); PG8_BAR; PG8_WAIT_L(0); PG8_MMA(0, 0, At, B0); PG8_BAR; PG8_SCHED;
;             PG8_LDB(B1, 1, 1); PG8_STAGE(PG8_SB(1, 0), b3, voffB);
;             PG8_BAR; PG8_WAIT_L(0); PG8_MMA(0, 1, At, B1); PG8_BAR;
;             PG8_LDA(At, 1, 1); PG8_STAGE(PG8_SA(1, 0), a3, voffA);
;             PG8_BAR; PG8_WAIT_L(0); if (full) PG8_MMA(1, 0, At, B0); PG8_BAR; PG8_SCHED;
;             PG8_STAGE(PG8_SB(1, 1), b3 + hstepB, voffB);
;             PG8_WAIT_V(6); PG8_BAR; if (full) PG8_MMA(1, 1, At, B1); PG8_BAR;
	s_mov_b32 m0, s62
	ds_read_b128 v[214:217], v184
	ds_read_b128 v[218:221], v184 offset:1024
	ds_read_b128 v[224:227], v184 offset:2048
	ds_read_b128 v[228:231], v184 offset:3072
	global_load_lds_dwordx4 v130, s[54:55]

; #define PG8_STAGE(bufoff, gbase, voff) do { _Pragma("unroll") for (int _i = 0; _i < 2; ++_i) \
;         __builtin_amdgcn_global_load_lds((const unsigned*)((const char*)(gbase) + (voff)[_i]), (LAS unsigned*)(lds + (bufoff) + ldsw + _i * 8192), 16, 0, 0); } while (0)
; #define PG8_LDA(dst, b, h) do { _Pragma("unroll") for (int m = 0; m < 4; ++m) _Pragma("unroll") for (int k = 0; k < 2; ++k) dst[m][k] = *(const LAS bf16x8*)(lds + PG8_SA(b, h) + aoff + m * 2048 + k * 1024); } while (0)
; #define PG8_LDB(dst, b, h) do { _Pragma("unroll") for (int n = 0; n < 2; ++n) _Pragma("unroll") for (int k = 0; k < 2; ++k) dst[n][k] = *(const LAS bf16x8*)(lds + PG8_SB(b, h) + boff + n * 2048 + k * 1024); } while (0)
; #define PG8_WAIT_V(n) asm volatile("s_waitcnt vmcnt(" #n ")" ::: "memory")
; #define PG8_WAIT_L(n) asm volatile("s_waitcnt lgkmcnt(" #n ")" ::: "memory")
; #define PG8_BAR __builtin_amdgcn_s_barrier()
; #define PG8_SCHED __builtin_amdgcn_sched_barrier(0)
; template <class Epi>
; DI void gemm_phase(LAS unsigned char* lds, int wid, int K, int lda, int ldb, bool bperm, const Sched3& S, const Epi& E) {
;     ...
;             PG8_LDB(B0, 0, 0); PG8_SCHED; PG8_LDA(At, 0, 0); PG8_STAGE(PG8_SA(1, 1), a1 + hA, voffA);
;             PG8_WAIT_L(8); PG8_BAR; PG8_WAIT_L(0); PG8_MMA(0, 0, At, B0); PG8_BAR; PG8_SCHED;
;             PG8_LDB(B1, 0, 1); PG8_STAGE(PG8_SB(0, 0), b2, voffB);
;             PG8_BAR; PG8_WAIT_L(0); PG8_MMA(0, 1, At, B1); PG8_BAR;
;             PG8_LDA(At, 0, 1); PG8_STAGE(PG8_SA(0, 0), a2, voffA);
;             PG8_BAR; PG8_WAIT_L(0); if (full) PG8_MMA(1, 0, At, B0); PG8_BAR; PG8_SCHED;
;             PG8_STAGE(PG8_SB(0, 1), b2 + hstepB, voffB);
;             PG8_WAIT_V(6); PG8_BAR; if (full) PG8_MMA(1, 1, At, B1); PG8_BAR;
;             PG8_LDB(B0, 1, 0); PG8_SCHED; PG8_LDA(At, 1, 0); PG8_STAGE(PG8_SA(0, 1), a2 + h2, voffA);
;             PG8_WAIT_L(8); PG8_BAR; PG8_WAIT_L(0); PG8_MMA(0, 0, At, B0); PG8_BAR; PG8_SCHED;
;             PG8_LDB(B1, 1, 1); PG8_STAGE(PG8_SB(1, 0), b3, voffB);
;             PG8_BAR; PG8_WAIT_L(0); PG8_MMA(0, 1, At, B1); PG8_BAR;
;             PG8_LDA(At, 1, 1); PG8_STAGE(PG8_SA(1, 0), a3, voffA);
;             PG8_BAR; PG8_WAIT_L(0); if (full) PG8_MMA(1, 0, At, B0); PG8_BAR; PG8_SCHED;
;             PG8_STAGE(PG8_SB(1, 1), b3 + hstepB, voffB);
;             PG8_WAIT_V(6); PG8_BAR; if (full) PG8_MMA(1, 1, At, B1); PG8_BAR;
	s_add_i32 m0, s62, 0x2000
	s_nop 0
	global_load_lds_dwordx4 v134, s[54:55]
	s_barrier
	s_waitcnt lgkmcnt(0)
	s_setprio 1
	s_waitcnt lgkmcnt(0)
	v_mfma_f32_16x16x32_bf16 v[60:63], v[214:217], v[172:175], v[60:63]
	v_mfma_f32_16x16x32_bf16 v[56:59], v[224:227], v[172:175], v[56:59]
	v_mfma_f32_16x16x32_bf16 v[52:55], v[214:217], v[190:193], v[52:55]
	v_mfma_f32_16x16x32_bf16 v[48:51], v[224:227], v[190:193], v[48:51]
	v_mfma_f32_16x16x32_bf16 v[44:47], v[214:217], v[198:201], v[44:47]
	v_mfma_f32_16x16x32_bf16 v[40:43], v[224:227], v[198:201], v[40:43]
	v_mfma_f32_16x16x32_bf16 v[36:39], v[214:217], v[206:209], v[36:39]
	v_mfma_f32_16x16x32_bf16 v[32:35], v[224:227], v[206:209], v[32:35]
	v_mfma_f32_16x16x32_bf16 v[60:63], v[218:221], v[186:189], v[60:63]
	v_mfma_f32_16x16x32_bf16 v[56:59], v[228:231], v[186:189], v[56:59]
	v_mfma_f32_16x16x32_bf16 v[52:55], v[218:221], v[194:197], v[52:55]
	v_mfma_f32_16x16x32_bf16 v[48:51], v[228:231], v[194:197], v[48:51]
	v_mfma_f32_16x16x32_bf16 v[44:47], v[218:221], v[202:205], v[44:47]
	v_mfma_f32_16x16x32_bf16 v[40:43], v[228:231], v[202:205], v[40:43]
	v_mfma_f32_16x16x32_bf16 v[36:39], v[218:221], v[210:213], v[36:39]
	v_mfma_f32_16x16x32_bf16 v[32:35], v[228:231], v[210:213], v[32:35]
	s_setprio 0
	s_mov_b32 m0, s66
	s_mov_b64 s[100:101], s[56:57]
	s_barrier
	ds_read_b128 v[172:175], v183 offset:16384
	ds_read_b128 v[186:189], v183 offset:17408
	ds_read_b128 v[190:193], v183 offset:18432
	ds_read_b128 v[194:197], v183 offset:19456
	ds_read_b128 v[198:201], v183 offset:20480
	ds_read_b128 v[202:205], v183 offset:21504
	ds_read_b128 v[206:209], v183 offset:22528
	ds_read_b128 v[210:213], v183 offset:23552
	global_load_lds_dwordx4 v128, s[56:57]
	s_mov_b64 s[100:101], s[56:57]
	s_mov_b32 m0, s67
	s_nop 0
	global_load_lds_dwordx4 v132, s[56:57]
	s_barrier
	s_waitcnt lgkmcnt(0)
	s_setprio 1
	s_waitcnt lgkmcnt(0)
	v_mfma_f32_16x16x32_bf16 v[92:95], v[156:159], v[172:175], v[92:95]
	v_mfma_f32_16x16x32_bf16 v[88:91], v[164:167], v[172:175], v[88:91]
	v_mfma_f32_16x16x32_bf16 v[84:87], v[156:159], v[190:193], v[84:87]
	v_mfma_f32_16x16x32_bf16 v[80:83], v[164:167], v[190:193], v[80:83]
	v_mfma_f32_16x16x32_bf16 v[76:79], v[156:159], v[198:201], v[76:79]
	v_mfma_f32_16x16x32_bf16 v[72:75], v[164:167], v[198:201], v[72:75]
	v_mfma_f32_16x16x32_bf16 v[68:71], v[156:159], v[206:209], v[68:71]
	v_mfma_f32_16x16x32_bf16 v[64:67], v[164:167], v[206:209], v[64:67]
	v_mfma_f32_16x16x32_bf16 v[92:95], v[160:163], v[186:189], v[92:95]
	v_mfma_f32_16x16x32_bf16 v[88:91], v[168:171], v[186:189], v[88:91]
	v_mfma_f32_16x16x32_bf16 v[84:87], v[160:163], v[194:197], v[84:87]
	v_mfma_f32_16x16x32_bf16 v[80:83], v[168:171], v[194:197], v[80:83]
	v_mfma_f32_16x16x32_bf16 v[76:79], v[160:163], v[202:205], v[76:79]
	v_mfma_f32_16x16x32_bf16 v[72:75], v[168:171], v[202:205], v[72:75]
	v_mfma_f32_16x16x32_bf16 v[68:71], v[160:163], v[210:213], v[68:71]
	v_mfma_f32_16x16x32_bf16 v[64:67], v[168:171], v[210:213], v[64:67]
	s_setprio 0
	s_barrier
	s_add_u32 s62, s54, 0x20000
	s_addc_u32 s63, s55, 0
	s_add_i32 s86, s77, s65

; #define PG8_STAGE(bufoff, gbase, voff) do { _Pragma("unroll") for (int _i = 0; _i < 2; ++_i) \
;         __builtin_amdgcn_global_load_lds((const unsigned*)((const char*)(gbase) + (voff)[_i]), (LAS unsigned*)(lds + (bufoff) + ldsw + _i * 8192), 16, 0, 0); } while (0)
; #define PG8_LDA(dst, b, h) do { _Pragma("unroll") for (int m = 0; m < 4; ++m) _Pragma("unroll") for (int k = 0; k < 2; ++k) dst[m][k] = *(const LAS bf16x8*)(lds + PG8_SA(b, h) + aoff + m * 2048 + k * 1024); } while (0)
; #define PG8_LDB(dst, b, h) do { _Pragma("unroll") for (int n = 0; n < 2; ++n) _Pragma("unroll") for (int k = 0; k < 2; ++k) dst[n][k] = *(const LAS bf16x8*)(lds + PG8_SB(b, h) + boff + n * 2048 + k * 1024); } while (0)
; #define PG8_WAIT_V(n) asm volatile("s_waitcnt vmcnt(" #n ")" ::: "memory")
; #define PG8_WAIT_L(n) asm volatile("s_waitcnt lgkmcnt(" #n ")" ::: "memory")
; #define PG8_BAR __builtin_amdgcn_s_barrier()
; #define PG8_SCHED __builtin_amdgcn_sched_barrier(0)
; template <class Epi>
; DI void gemm_phase(LAS unsigned char* lds, int wid, int K, int lda, int ldb, bool bperm, const Sched3& S, const Epi& E) {
;     ...
;             PG8_LDB(B0, 0, 0); PG8_SCHED; PG8_LDA(At, 0, 0); PG8_STAGE(PG8_SA(1, 1), a1 + hA, voffA);
;             PG8_WAIT_L(8); PG8_BAR; PG8_WAIT_L(0); PG8_MMA(0, 0, At, B0); PG8_BAR; PG8_SCHED;
;             PG8_LDB(B1, 0, 1); PG8_STAGE(PG8_SB(0, 0), b2, voffB);
;             PG8_BAR; PG8_WAIT_L(0); PG8_MMA(0, 1, At, B1); PG8_BAR;
;             PG8_LDA(At, 0, 1); PG8_STAGE(PG8_SA(0, 0), a2, voffA);
;             PG8_BAR; PG8_WAIT_L(0); if (full) PG8_MMA(1, 0, At, B0); PG8_BAR; PG8_SCHED;
;             PG8_STAGE(PG8_SB(0, 1), b2 + hstepB, voffB);
;             PG8_WAIT_V(6); PG8_BAR; if (full) PG8_MMA(1, 1, At, B1); PG8_BAR;
;             PG8_LDB(B0, 1, 0); PG8_SCHED; PG8_LDA(At, 1, 0); PG8_STAGE(PG8_SA(0, 1), a2 + h2, voffA);
;             PG8_WAIT_L(8); PG8_BAR; PG8_WAIT_L(0); PG8_MMA(0, 0, At, B0); PG8_BAR; PG8_SCHED;
;             PG8_LDB(B1, 1, 1); PG8_STAGE(PG8_SB(1, 0), b3, voffB);
;             PG8_BAR; PG8_WAIT_L(0); PG8_MMA(0, 1, At, B1); PG8_BAR;
;             PG8_LDA(At, 1, 1); PG8_STAGE(PG8_SA(1, 0), a3, voffA);
;             PG8_BAR; PG8_WAIT_L(0); if (full) PG8_MMA(1, 0, At, B0); PG8_BAR; PG8_SCHED;
;             PG8_STAGE(PG8_SB(1, 1), b3 + hstepB, voffB);
;             PG8_WAIT_V(6); PG8_BAR; if (full) PG8_MMA(1, 1, At, B1); PG8_BAR;
	s_mov_b32 m0, s86
	s_nop 0
	global_load_lds_dwordx4 v130, s[62:63]

; #define PG8_STAGE(bufoff, gbase, voff) do { _Pragma("unroll") for (int _i = 0; _i < 2; ++_i) \
;         __builtin_amdgcn_global_load_lds((const unsigned*)((const char*)(gbase) + (voff)[_i]), (LAS unsigned*)(lds + (bufoff) + ldsw + _i * 8192), 16, 0, 0); } while (0)
; #define PG8_LDA(dst, b, h) do { _Pragma("unroll") for (int m = 0; m < 4; ++m) _Pragma("unroll") for (int k = 0; k < 2; ++k) dst[m][k] = *(const LAS bf16x8*)(lds + PG8_SA(b, h) + aoff + m * 2048 + k * 1024); } while (0)
; #define PG8_LDB(dst, b, h) do { _Pragma("unroll") for (int n = 0; n < 2; ++n) _Pragma("unroll") for (int k = 0; k < 2; ++k) dst[n][k] = *(const LAS bf16x8*)(lds + PG8_SB(b, h) + boff + n * 2048 + k * 1024); } while (0)
; #define PG8_WAIT_V(n) asm volatile("s_waitcnt vmcnt(" #n ")" ::: "memory")
; #define PG8_WAIT_L(n) asm volatile("s_waitcnt lgkmcnt(" #n ")" ::: "memory")
; #define PG8_BAR __builtin_amdgcn_s_barrier()
; #define PG8_SCHED __builtin_amdgcn_sched_barrier(0)
; template <class Epi>
; DI void gemm_phase(LAS unsigned char* lds, int wid, int K, int lda, int ldb, bool bperm, const Sched3& S, const Epi& E) {
;     ...
;             PG8_LDB(B0, 0, 0); PG8_SCHED; PG8_LDA(At, 0, 0); PG8_STAGE(PG8_SA(1, 1), a1 + hA, voffA);
;             PG8_WAIT_L(8); PG8_BAR; PG8_WAIT_L(0); PG8_MMA(0, 0, At, B0); PG8_BAR; PG8_SCHED;
;             PG8_LDB(B1, 0, 1); PG8_STAGE(PG8_SB(0, 0), b2, voffB);
;             PG8_BAR; PG8_WAIT_L(0); PG8_MMA(0, 1, At, B1); PG8_BAR;
;             PG8_LDA(At, 0, 1); PG8_STAGE(PG8_SA(0, 0), a2, voffA);
;             PG8_BAR; PG8_WAIT_L(0); if (full) PG8_MMA(1, 0, At, B0); PG8_BAR; PG8_SCHED;
;             PG8_STAGE(PG8_SB(0, 1), b2 + hstepB, voffB);
;             PG8_WAIT_V(6); PG8_BAR; if (full) PG8_MMA(1, 1, At, B1); PG8_BAR;
;             PG8_LDB(B0, 1, 0); PG8_SCHED; PG8_LDA(At, 1, 0); PG8_STAGE(PG8_SA(0, 1), a2 + h2, voffA);
;             PG8_WAIT_L(8); PG8_BAR; PG8_WAIT_L(0); PG8_MMA(0, 0, At, B0); PG8_BAR; PG8_SCHED;
;             PG8_LDB(B1, 1, 1); PG8_STAGE(PG8_SB(1, 0), b3, voffB);
;             PG8_BAR; PG8_WAIT_L(0); PG8_MMA(0, 1, At, B1); PG8_BAR;
;             PG8_LDA(At, 1, 1); PG8_STAGE(PG8_SA(1, 0), a3, voffA);
;             PG8_BAR; PG8_WAIT_L(0); if (full) PG8_MMA(1, 0, At, B0); PG8_BAR; PG8_SCHED;
;             PG8_STAGE(PG8_SB(1, 1), b3 + hstepB, voffB);
;             PG8_WAIT_V(6); PG8_BAR; if (full) PG8_MMA(1, 1, At, B1); PG8_BAR;
	s_add_i32 m0, s86, 0x2000
	s_nop 0
	global_load_lds_dwordx4 v134, s[62:63]
	s_waitcnt vmcnt(6)
	s_barrier
	s_setprio 1
	v_mfma_f32_16x16x32_bf16 v[28:31], v[214:217], v[172:175], v[28:31]
	v_mfma_f32_16x16x32_bf16 v[24:27], v[224:227], v[172:175], v[24:27]
	v_mfma_f32_16x16x32_bf16 v[20:23], v[214:217], v[190:193], v[20:23]
	v_mfma_f32_16x16x32_bf16 v[16:19], v[224:227], v[190:193], v[16:19]
	v_mfma_f32_16x16x32_bf16 v[12:15], v[214:217], v[198:201], v[12:15]
	v_mfma_f32_16x16x32_bf16 v[8:11], v[224:227], v[198:201], v[8:11]
	v_mfma_f32_16x16x32_bf16 v[4:7], v[214:217], v[206:209], v[4:7]
	v_mfma_f32_16x16x32_bf16 v[0:3], v[224:227], v[206:209], v[0:3]
	v_mfma_f32_16x16x32_bf16 v[28:31], v[218:221], v[186:189], v[28:31]
	v_mfma_f32_16x16x32_bf16 v[24:27], v[228:231], v[186:189], v[24:27]
	v_mfma_f32_16x16x32_bf16 v[20:23], v[218:221], v[194:197], v[20:23]
	v_mfma_f32_16x16x32_bf16 v[16:19], v[228:231], v[194:197], v[16:19]
	v_mfma_f32_16x16x32_bf16 v[12:15], v[218:221], v[202:205], v[12:15]
	v_mfma_f32_16x16x32_bf16 v[8:11], v[228:231], v[202:205], v[8:11]
	v_mfma_f32_16x16x32_bf16 v[4:7], v[218:221], v[210:213], v[4:7]
	v_mfma_f32_16x16x32_bf16 v[0:3], v[228:231], v[210:213], v[0:3]
	s_setprio 0
	s_add_i32 s62, 0, 0x18000
	v_add_u32_e32 v136, s62, v179
	s_barrier
	ds_read_b128 v[156:159], v136
	ds_read_b128 v[160:163], v136 offset:1024
	ds_read_b128 v[164:167], v136 offset:2048
	ds_read_b128 v[168:171], v136 offset:3072
	s_add_u32 s56, s56, 0x20000
	s_addc_u32 s57, s57, 0
	s_mov_b32 m0, s68

; #define PG8_STAGE(bufoff, gbase, voff) do { _Pragma("unroll") for (int _i = 0; _i < 2; ++_i) \
;         __builtin_amdgcn_global_load_lds((const unsigned*)((const char*)(gbase) + (voff)[_i]), (LAS unsigned*)(lds + (bufoff) + ldsw + _i * 8192), 16, 0, 0); } while (0)
; #define PG8_LDA(dst, b, h) do { _Pragma("unroll") for (int m = 0; m < 4; ++m) _Pragma("unroll") for (int k = 0; k < 2; ++k) dst[m][k] = *(const LAS bf16x8*)(lds + PG8_SA(b, h) + aoff + m * 2048 + k * 1024); } while (0)
; #define PG8_LDB(dst, b, h) do { _Pragma("unroll") for (int n = 0; n < 2; ++n) _Pragma("unroll") for (int k = 0; k < 2; ++k) dst[n][k] = *(const LAS bf16x8*)(lds + PG8_SB(b, h) + boff + n * 2048 + k * 1024); } while (0)
; #define PG8_WAIT_V(n) asm volatile("s_waitcnt vmcnt(" #n ")" ::: "memory")
; #define PG8_WAIT_L(n) asm volatile("s_waitcnt lgkmcnt(" #n ")" ::: "memory")
; #define PG8_BAR __builtin_amdgcn_s_barrier()
; #define PG8_SCHED __builtin_amdgcn_sched_barrier(0)
; template <class Epi>
; DI void gemm_phase(LAS unsigned char* lds, int wid, int K, int lda, int ldb, bool bperm, const Sched3& S, const Epi& E) {
;     ...
;             PG8_LDB(B0, 0, 0); PG8_SCHED; PG8_LDA(At, 0, 0); PG8_STAGE(PG8_SA(1, 1), a1 + hA, voffA);
;             PG8_WAIT_L(8); PG8_BAR; PG8_WAIT_L(0); PG8_MMA(0, 0, At, B0); PG8_BAR; PG8_SCHED;
;             PG8_LDB(B1, 0, 1); PG8_STAGE(PG8_SB(0, 0), b2, voffB);
;             PG8_BAR; PG8_WAIT_L(0); PG8_MMA(0, 1, At, B1); PG8_BAR;
;             PG8_LDA(At, 0, 1); PG8_STAGE(PG8_SA(0, 0), a2, voffA);
;             PG8_BAR; PG8_WAIT_L(0); if (full) PG8_MMA(1, 0, At, B0); PG8_BAR; PG8_SCHED;
;             PG8_STAGE(PG8_SB(0, 1), b2 + hstepB, voffB);
;             PG8_WAIT_V(6); PG8_BAR; if (full) PG8_MMA(1, 1, At, B1); PG8_BAR;
;             PG8_LDB(B0, 1, 0); PG8_SCHED; PG8_LDA(At, 1, 0); PG8_STAGE(PG8_SA(0, 1), a2 + h2, voffA);
;             PG8_WAIT_L(8); PG8_BAR; PG8_WAIT_L(0); PG8_MMA(0, 0, At, B0); PG8_BAR; PG8_SCHED;
;             PG8_LDB(B1, 1, 1); PG8_STAGE(PG8_SB(1, 0), b3, voffB);
;             PG8_BAR; PG8_WAIT_L(0); PG8_MMA(0, 1, At, B1); PG8_BAR;
;             PG8_LDA(At, 1, 1); PG8_STAGE(PG8_SA(1, 0), a3, voffA);
;             PG8_BAR; PG8_WAIT_L(0); if (full) PG8_MMA(1, 0, At, B0); PG8_BAR; PG8_SCHED;
;             PG8_STAGE(PG8_SB(1, 1), b3 + hstepB, voffB);
;             PG8_WAIT_V(6); PG8_BAR; if (full) PG8_MMA(1, 1, At, B1); PG8_BAR;
	ds_read_b128 v[172:175], v183 offset:32768
	ds_read_b128 v[186:189], v183 offset:33792
	ds_read_b128 v[190:193], v183 offset:34816
	ds_read_b128 v[194:197], v183 offset:35840
	ds_read_b128 v[198:201], v183 offset:36864
	ds_read_b128 v[202:205], v183 offset:37888
	ds_read_b128 v[206:209], v183 offset:38912
	ds_read_b128 v[210:213], v183 offset:39936
	global_load_lds_dwordx4 v128, s[56:57]

; #define PG8_STAGE(bufoff, gbase, voff) do { _Pragma("unroll") for (int _i = 0; _i < 2; ++_i) \
;         __builtin_amdgcn_global_load_lds((const unsigned*)((const char*)(gbase) + (voff)[_i]), (LAS unsigned*)(lds + (bufoff) + ldsw + _i * 8192), 16, 0, 0); } while (0)
; #define PG8_LDA(dst, b, h) do { _Pragma("unroll") for (int m = 0; m < 4; ++m) _Pragma("unroll") for (int k = 0; k < 2; ++k) dst[m][k] = *(const LAS bf16x8*)(lds + PG8_SA(b, h) + aoff + m * 2048 + k * 1024); } while (0)
; #define PG8_LDB(dst, b, h) do { _Pragma("unroll") for (int n = 0; n < 2; ++n) _Pragma("unroll") for (int k = 0; k < 2; ++k) dst[n][k] = *(const LAS bf16x8*)(lds + PG8_SB(b, h) + boff + n * 2048 + k * 1024); } while (0)
; #define PG8_WAIT_V(n) asm volatile("s_waitcnt vmcnt(" #n ")" ::: "memory")
; #define PG8_WAIT_L(n) asm volatile("s_waitcnt lgkmcnt(" #n ")" ::: "memory")
; #define PG8_BAR __builtin_amdgcn_s_barrier()
; #define PG8_SCHED __builtin_amdgcn_sched_barrier(0)
; template <class Epi>
; DI void gemm_phase(LAS unsigned char* lds, int wid, int K, int lda, int ldb, bool bperm, const Sched3& S, const Epi& E) {
;     ...
;             PG8_LDB(B0, 0, 0); PG8_SCHED; PG8_LDA(At, 0, 0); PG8_STAGE(PG8_SA(1, 1), a1 + hA, voffA);
;             PG8_WAIT_L(8); PG8_BAR; PG8_WAIT_L(0); PG8_MMA(0, 0, At, B0); PG8_BAR; PG8_SCHED;
;             PG8_LDB(B1, 0, 1); PG8_STAGE(PG8_SB(0, 0), b2, voffB);
;             PG8_BAR; PG8_WAIT_L(0); PG8_MMA(0, 1, At, B1); PG8_BAR;
;             PG8_LDA(At, 0, 1); PG8_STAGE(PG8_SA(0, 0), a2, voffA);
;             PG8_BAR; PG8_WAIT_L(0); if (full) PG8_MMA(1, 0, At, B0); PG8_BAR; PG8_SCHED;
;             PG8_STAGE(PG8_SB(0, 1), b2 + hstepB, voffB);
;             PG8_WAIT_V(6); PG8_BAR; if (full) PG8_MMA(1, 1, At, B1); PG8_BAR;
;             PG8_LDB(B0, 1, 0); PG8_SCHED; PG8_LDA(At, 1, 0); PG8_STAGE(PG8_SA(0, 1), a2 + h2, voffA);
;             PG8_WAIT_L(8); PG8_BAR; PG8_WAIT_L(0); PG8_MMA(0, 0, At, B0); PG8_BAR; PG8_SCHED;
;             PG8_LDB(B1, 1, 1); PG8_STAGE(PG8_SB(1, 0), b3, voffB);
;             PG8_BAR; PG8_WAIT_L(0); PG8_MMA(0, 1, At, B1); PG8_BAR;
;             PG8_LDA(At, 1, 1); PG8_STAGE(PG8_SA(1, 0), a3, voffA);
;             PG8_BAR; PG8_WAIT_L(0); if (full) PG8_MMA(1, 0, At, B0); PG8_BAR; PG8_SCHED;
;             PG8_STAGE(PG8_SB(1, 1), b3 + hstepB, voffB);
;             PG8_WAIT_V(6); PG8_BAR; if (full) PG8_MMA(1, 1, At, B1); PG8_BAR;
	s_mov_b32 m0, s69
	s_nop 0
	global_load_lds_dwordx4 v132, s[56:57]
	s_waitcnt lgkmcnt(8)
	s_barrier
	s_waitcnt lgkmcnt(0)
	s_setprio 1
	s_waitcnt lgkmcnt(0)
	v_mfma_f32_16x16x32_bf16 v[124:127], v[156:159], v[172:175], v[124:127]
	v_mfma_f32_16x16x32_bf16 v[120:123], v[164:167], v[172:175], v[120:123]
	v_mfma_f32_16x16x32_bf16 v[116:119], v[156:159], v[190:193], v[116:119]
	v_mfma_f32_16x16x32_bf16 v[112:115], v[164:167], v[190:193], v[112:115]
	v_mfma_f32_16x16x32_bf16 v[108:111], v[156:159], v[198:201], v[108:111]
	v_mfma_f32_16x16x32_bf16 v[104:107], v[164:167], v[198:201], v[104:107]
	v_mfma_f32_16x16x32_bf16 v[100:103], v[156:159], v[206:209], v[100:103]
	v_mfma_f32_16x16x32_bf16 v[96:99], v[164:167], v[206:209], v[96:99]
	v_mfma_f32_16x16x32_bf16 v[124:127], v[160:163], v[186:189], v[124:127]
	v_mfma_f32_16x16x32_bf16 v[120:123], v[168:171], v[186:189], v[120:123]
	v_mfma_f32_16x16x32_bf16 v[116:119], v[160:163], v[194:197], v[116:119]
	v_mfma_f32_16x16x32_bf16 v[112:115], v[168:171], v[194:197], v[112:115]
	v_mfma_f32_16x16x32_bf16 v[108:111], v[160:163], v[202:205], v[108:111]
	v_mfma_f32_16x16x32_bf16 v[104:107], v[168:171], v[202:205], v[104:107]
	v_mfma_f32_16x16x32_bf16 v[100:103], v[160:163], v[210:213], v[100:103]
	v_mfma_f32_16x16x32_bf16 v[96:99], v[168:171], v[210:213], v[96:99]
	s_setprio 0
	s_barrier
	s_add_i32 s56, 0, 0x1c000
	s_add_i32 s57, s62, s65
	v_add_u32_e32 v136, s56, v179

; #define PG8_STAGE(bufoff, gbase, voff) do { _Pragma("unroll") for (int _i = 0; _i < 2; ++_i) \
;         __builtin_amdgcn_global_load_lds((const unsigned*)((const char*)(gbase) + (voff)[_i]), (LAS unsigned*)(lds + (bufoff) + ldsw + _i * 8192), 16, 0, 0); } while (0)
; #define PG8_LDA(dst, b, h) do { _Pragma("unroll") for (int m = 0; m < 4; ++m) _Pragma("unroll") for (int k = 0; k < 2; ++k) dst[m][k] = *(const LAS bf16x8*)(lds + PG8_SA(b, h) + aoff + m * 2048 + k * 1024); } while (0)
; #define PG8_LDB(dst, b, h) do { _Pragma("unroll") for (int n = 0; n < 2; ++n) _Pragma("unroll") for (int k = 0; k < 2; ++k) dst[n][k] = *(const LAS bf16x8*)(lds + PG8_SB(b, h) + boff + n * 2048 + k * 1024); } while (0)
; #define PG8_WAIT_V(n) asm volatile("s_waitcnt vmcnt(" #n ")" ::: "memory")
; #define PG8_WAIT_L(n) asm volatile("s_waitcnt lgkmcnt(" #n ")" ::: "memory")
; #define PG8_BAR __builtin_amdgcn_s_barrier()
; #define PG8_SCHED __builtin_amdgcn_sched_barrier(0)
; template <class Epi>
; DI void gemm_phase(LAS unsigned char* lds, int wid, int K, int lda, int ldb, bool bperm, const Sched3& S, const Epi& E) {
;     ...
;             PG8_LDB(B0, 0, 0); PG8_SCHED; PG8_LDA(At, 0, 0); PG8_STAGE(PG8_SA(1, 1), a1 + hA, voffA);
;             PG8_WAIT_L(8); PG8_BAR; PG8_WAIT_L(0); PG8_MMA(0, 0, At, B0); PG8_BAR; PG8_SCHED;
;             PG8_LDB(B1, 0, 1); PG8_STAGE(PG8_SB(0, 0), b2, voffB);
;             PG8_BAR; PG8_WAIT_L(0); PG8_MMA(0, 1, At, B1); PG8_BAR;
;             PG8_LDA(At, 0, 1); PG8_STAGE(PG8_SA(0, 0), a2, voffA);
;             PG8_BAR; PG8_WAIT_L(0); if (full) PG8_MMA(1, 0, At, B0); PG8_BAR; PG8_SCHED;
;             PG8_STAGE(PG8_SB(0, 1), b2 + hstepB, voffB);
;             PG8_WAIT_V(6); PG8_BAR; if (full) PG8_MMA(1, 1, At, B1); PG8_BAR;
;             PG8_LDB(B0, 1, 0); PG8_SCHED; PG8_LDA(At, 1, 0); PG8_STAGE(PG8_SA(0, 1), a2 + h2, voffA);
;             PG8_WAIT_L(8); PG8_BAR; PG8_WAIT_L(0); PG8_MMA(0, 0, At, B0); PG8_BAR; PG8_SCHED;
;             PG8_LDB(B1, 1, 1); PG8_STAGE(PG8_SB(1, 0), b3, voffB);
;             PG8_BAR; PG8_WAIT_L(0); PG8_MMA(0, 1, At, B1); PG8_BAR;
;             PG8_LDA(At, 1, 1); PG8_STAGE(PG8_SA(1, 0), a3, voffA);
;             PG8_BAR; PG8_WAIT_L(0); if (full) PG8_MMA(1, 0, At, B0); PG8_BAR; PG8_SCHED;
;             PG8_STAGE(PG8_SB(1, 1), b3 + hstepB, voffB);
;             PG8_WAIT_V(6); PG8_BAR; if (full) PG8_MMA(1, 1, At, B1); PG8_BAR;
	s_sub_i32 m0, s57, 0x80
	ds_read_b128 v[214:217], v136
	ds_read_b128 v[218:221], v136 offset:1024
	ds_read_b128 v[224:227], v136 offset:2048
	ds_read_b128 v[228:231], v136 offset:3072
	global_load_lds_dwordx4 v130, s[54:55] offset:128

; #define PG8_STAGE(bufoff, gbase, voff) do { _Pragma("unroll") for (int _i = 0; _i < 2; ++_i) \
;         __builtin_amdgcn_global_load_lds((const unsigned*)((const char*)(gbase) + (voff)[_i]), (LAS unsigned*)(lds + (bufoff) + ldsw + _i * 8192), 16, 0, 0); } while (0)
; #define PG8_LDA(dst, b, h) do { _Pragma("unroll") for (int m = 0; m < 4; ++m) _Pragma("unroll") for (int k = 0; k < 2; ++k) dst[m][k] = *(const LAS bf16x8*)(lds + PG8_SA(b, h) + aoff + m * 2048 + k * 1024); } while (0)
; #define PG8_LDB(dst, b, h) do { _Pragma("unroll") for (int n = 0; n < 2; ++n) _Pragma("unroll") for (int k = 0; k < 2; ++k) dst[n][k] = *(const LAS bf16x8*)(lds + PG8_SB(b, h) + boff + n * 2048 + k * 1024); } while (0)
; #define PG8_WAIT_V(n) asm volatile("s_waitcnt vmcnt(" #n ")" ::: "memory")
; #define PG8_WAIT_L(n) asm volatile("s_waitcnt lgkmcnt(" #n ")" ::: "memory")
; #define PG8_BAR __builtin_amdgcn_s_barrier()
; #define PG8_SCHED __builtin_amdgcn_sched_barrier(0)
; template <class Epi>
; DI void gemm_phase(LAS unsigned char* lds, int wid, int K, int lda, int ldb, bool bperm, const Sched3& S, const Epi& E) {
;     ...
;             PG8_LDB(B0, 0, 0); PG8_SCHED; PG8_LDA(At, 0, 0); PG8_STAGE(PG8_SA(1, 1), a1 + hA, voffA);
;             PG8_WAIT_L(8); PG8_BAR; PG8_WAIT_L(0); PG8_MMA(0, 0, At, B0); PG8_BAR; PG8_SCHED;
;             PG8_LDB(B1, 0, 1); PG8_STAGE(PG8_SB(0, 0), b2, voffB);
;             PG8_BAR; PG8_WAIT_L(0); PG8_MMA(0, 1, At, B1); PG8_BAR;
;             PG8_LDA(At, 0, 1); PG8_STAGE(PG8_SA(0, 0), a2, voffA);
;             PG8_BAR; PG8_WAIT_L(0); if (full) PG8_MMA(1, 0, At, B0); PG8_BAR; PG8_SCHED;
;             PG8_STAGE(PG8_SB(0, 1), b2 + hstepB, voffB);
;             PG8_WAIT_V(6); PG8_BAR; if (full) PG8_MMA(1, 1, At, B1); PG8_BAR;
;             PG8_LDB(B0, 1, 0); PG8_SCHED; PG8_LDA(At, 1, 0); PG8_STAGE(PG8_SA(0, 1), a2 + h2, voffA);
;             PG8_WAIT_L(8); PG8_BAR; PG8_WAIT_L(0); PG8_MMA(0, 0, At, B0); PG8_BAR; PG8_SCHED;
;             PG8_LDB(B1, 1, 1); PG8_STAGE(PG8_SB(1, 0), b3, voffB);
;             PG8_BAR; PG8_WAIT_L(0); PG8_MMA(0, 1, At, B1); PG8_BAR;
;             PG8_LDA(At, 1, 1); PG8_STAGE(PG8_SA(1, 0), a3, voffA);
;             PG8_BAR; PG8_WAIT_L(0); if (full) PG8_MMA(1, 0, At, B0); PG8_BAR; PG8_SCHED;
;             PG8_STAGE(PG8_SB(1, 1), b3 + hstepB, voffB);
;             PG8_WAIT_V(6); PG8_BAR; if (full) PG8_MMA(1, 1, At, B1); PG8_BAR;
	s_add_i32 m0, s57, 0x1f80
	s_nop 0
	global_load_lds_dwordx4 v134, s[54:55] offset:128
	s_barrier
	s_waitcnt lgkmcnt(0)
	s_setprio 1
	s_waitcnt lgkmcnt(0)
	v_mfma_f32_16x16x32_bf16 v[60:63], v[214:217], v[172:175], v[60:63]
	v_mfma_f32_16x16x32_bf16 v[56:59], v[224:227], v[172:175], v[56:59]
	v_mfma_f32_16x16x32_bf16 v[52:55], v[214:217], v[190:193], v[52:55]
	v_mfma_f32_16x16x32_bf16 v[48:51], v[224:227], v[190:193], v[48:51]
	v_mfma_f32_16x16x32_bf16 v[44:47], v[214:217], v[198:201], v[44:47]
	v_mfma_f32_16x16x32_bf16 v[40:43], v[224:227], v[198:201], v[40:43]
	v_mfma_f32_16x16x32_bf16 v[36:39], v[214:217], v[206:209], v[36:39]
	v_mfma_f32_16x16x32_bf16 v[32:35], v[224:227], v[206:209], v[32:35]
	v_mfma_f32_16x16x32_bf16 v[60:63], v[218:221], v[186:189], v[60:63]
	v_mfma_f32_16x16x32_bf16 v[56:59], v[228:231], v[186:189], v[56:59]
	v_mfma_f32_16x16x32_bf16 v[52:55], v[218:221], v[194:197], v[52:55]
	v_mfma_f32_16x16x32_bf16 v[48:51], v[228:231], v[194:197], v[48:51]
	v_mfma_f32_16x16x32_bf16 v[44:47], v[218:221], v[202:205], v[44:47]
	v_mfma_f32_16x16x32_bf16 v[40:43], v[228:231], v[202:205], v[40:43]
	v_mfma_f32_16x16x32_bf16 v[36:39], v[218:221], v[210:213], v[36:39]
	v_mfma_f32_16x16x32_bf16 v[32:35], v[228:231], v[210:213], v[32:35]
	s_setprio 0
	s_sub_i32 m0, s72, 0x80

; #define PG8_STAGE(bufoff, gbase, voff) do { _Pragma("unroll") for (int _i = 0; _i < 2; ++_i) \
;         __builtin_amdgcn_global_load_lds((const unsigned*)((const char*)(gbase) + (voff)[_i]), (LAS unsigned*)(lds + (bufoff) + ldsw + _i * 8192), 16, 0, 0); } while (0)
; #define PG8_LDA(dst, b, h) do { _Pragma("unroll") for (int m = 0; m < 4; ++m) _Pragma("unroll") for (int k = 0; k < 2; ++k) dst[m][k] = *(const LAS bf16x8*)(lds + PG8_SA(b, h) + aoff + m * 2048 + k * 1024); } while (0)
; #define PG8_LDB(dst, b, h) do { _Pragma("unroll") for (int n = 0; n < 2; ++n) _Pragma("unroll") for (int k = 0; k < 2; ++k) dst[n][k] = *(const LAS bf16x8*)(lds + PG8_SB(b, h) + boff + n * 2048 + k * 1024); } while (0)
; #define PG8_WAIT_V(n) asm volatile("s_waitcnt vmcnt(" #n ")" ::: "memory")
; #define PG8_WAIT_L(n) asm volatile("s_waitcnt lgkmcnt(" #n ")" ::: "memory")
; #define PG8_BAR __builtin_amdgcn_s_barrier()
; #define PG8_SCHED __builtin_amdgcn_sched_barrier(0)
; template <class Epi>
; DI void gemm_phase(LAS unsigned char* lds, int wid, int K, int lda, int ldb, bool bperm, const Sched3& S, const Epi& E) {
;     ...
;             PG8_LDB(B0, 0, 0); PG8_SCHED; PG8_LDA(At, 0, 0); PG8_STAGE(PG8_SA(1, 1), a1 + hA, voffA);
;             PG8_WAIT_L(8); PG8_BAR; PG8_WAIT_L(0); PG8_MMA(0, 0, At, B0); PG8_BAR; PG8_SCHED;
;             PG8_LDB(B1, 0, 1); PG8_STAGE(PG8_SB(0, 0), b2, voffB);
;             PG8_BAR; PG8_WAIT_L(0); PG8_MMA(0, 1, At, B1); PG8_BAR;
;             PG8_LDA(At, 0, 1); PG8_STAGE(PG8_SA(0, 0), a2, voffA);
;             PG8_BAR; PG8_WAIT_L(0); if (full) PG8_MMA(1, 0, At, B0); PG8_BAR; PG8_SCHED;
;             PG8_STAGE(PG8_SB(0, 1), b2 + hstepB, voffB);
;             PG8_WAIT_V(6); PG8_BAR; if (full) PG8_MMA(1, 1, At, B1); PG8_BAR;
;             PG8_LDB(B0, 1, 0); PG8_SCHED; PG8_LDA(At, 1, 0); PG8_STAGE(PG8_SA(0, 1), a2 + h2, voffA);
;             PG8_WAIT_L(8); PG8_BAR; PG8_WAIT_L(0); PG8_MMA(0, 0, At, B0); PG8_BAR; PG8_SCHED;
;             PG8_LDB(B1, 1, 1); PG8_STAGE(PG8_SB(1, 0), b3, voffB);
;             PG8_BAR; PG8_WAIT_L(0); PG8_MMA(0, 1, At, B1); PG8_BAR;
;             PG8_LDA(At, 1, 1); PG8_STAGE(PG8_SA(1, 0), a3, voffA);
;             PG8_BAR; PG8_WAIT_L(0); if (full) PG8_MMA(1, 0, At, B0); PG8_BAR; PG8_SCHED;
;             PG8_STAGE(PG8_SB(1, 1), b3 + hstepB, voffB);
;             PG8_WAIT_V(6); PG8_BAR; if (full) PG8_MMA(1, 1, At, B1); PG8_BAR;
	s_barrier
	ds_read_b128 v[172:175], v183 offset:49152
	ds_read_b128 v[186:189], v183 offset:50176
	ds_read_b128 v[190:193], v183 offset:51200
	ds_read_b128 v[194:197], v183 offset:52224
	ds_read_b128 v[198:201], v183 offset:53248
	ds_read_b128 v[202:205], v183 offset:54272
	ds_read_b128 v[206:209], v183 offset:55296
	ds_read_b128 v[210:213], v183 offset:56320
	global_load_lds_dwordx4 v128, s[100:101] offset:128

; #define PG8_STAGE(bufoff, gbase, voff) do { _Pragma("unroll") for (int _i = 0; _i < 2; ++_i) \
;         __builtin_amdgcn_global_load_lds((const unsigned*)((const char*)(gbase) + (voff)[_i]), (LAS unsigned*)(lds + (bufoff) + ldsw + _i * 8192), 16, 0, 0); } while (0)
; #define PG8_LDA(dst, b, h) do { _Pragma("unroll") for (int m = 0; m < 4; ++m) _Pragma("unroll") for (int k = 0; k < 2; ++k) dst[m][k] = *(const LAS bf16x8*)(lds + PG8_SA(b, h) + aoff + m * 2048 + k * 1024); } while (0)
; #define PG8_LDB(dst, b, h) do { _Pragma("unroll") for (int n = 0; n < 2; ++n) _Pragma("unroll") for (int k = 0; k < 2; ++k) dst[n][k] = *(const LAS bf16x8*)(lds + PG8_SB(b, h) + boff + n * 2048 + k * 1024); } while (0)
; #define PG8_WAIT_V(n) asm volatile("s_waitcnt vmcnt(" #n ")" ::: "memory")
; #define PG8_WAIT_L(n) asm volatile("s_waitcnt lgkmcnt(" #n ")" ::: "memory")
; #define PG8_BAR __builtin_amdgcn_s_barrier()
; #define PG8_SCHED __builtin_amdgcn_sched_barrier(0)
; template <class Epi>
; DI void gemm_phase(LAS unsigned char* lds, int wid, int K, int lda, int ldb, bool bperm, const Sched3& S, const Epi& E) {
;     ...
;             PG8_LDB(B0, 0, 0); PG8_SCHED; PG8_LDA(At, 0, 0); PG8_STAGE(PG8_SA(1, 1), a1 + hA, voffA);
;             PG8_WAIT_L(8); PG8_BAR; PG8_WAIT_L(0); PG8_MMA(0, 0, At, B0); PG8_BAR; PG8_SCHED;
;             PG8_LDB(B1, 0, 1); PG8_STAGE(PG8_SB(0, 0), b2, voffB);
;             PG8_BAR; PG8_WAIT_L(0); PG8_MMA(0, 1, At, B1); PG8_BAR;
;             PG8_LDA(At, 0, 1); PG8_STAGE(PG8_SA(0, 0), a2, voffA);
;             PG8_BAR; PG8_WAIT_L(0); if (full) PG8_MMA(1, 0, At, B0); PG8_BAR; PG8_SCHED;
;             PG8_STAGE(PG8_SB(0, 1), b2 + hstepB, voffB);
;             PG8_WAIT_V(6); PG8_BAR; if (full) PG8_MMA(1, 1, At, B1); PG8_BAR;
;             PG8_LDB(B0, 1, 0); PG8_SCHED; PG8_LDA(At, 1, 0); PG8_STAGE(PG8_SA(0, 1), a2 + h2, voffA);
;             PG8_WAIT_L(8); PG8_BAR; PG8_WAIT_L(0); PG8_MMA(0, 0, At, B0); PG8_BAR; PG8_SCHED;
;             PG8_LDB(B1, 1, 1); PG8_STAGE(PG8_SB(1, 0), b3, voffB);
;             PG8_BAR; PG8_WAIT_L(0); PG8_MMA(0, 1, At, B1); PG8_BAR;
;             PG8_LDA(At, 1, 1); PG8_STAGE(PG8_SA(1, 0), a3, voffA);
;             PG8_BAR; PG8_WAIT_L(0); if (full) PG8_MMA(1, 0, At, B0); PG8_BAR; PG8_SCHED;
;             PG8_STAGE(PG8_SB(1, 1), b3 + hstepB, voffB);
;             PG8_WAIT_V(6); PG8_BAR; if (full) PG8_MMA(1, 1, At, B1); PG8_BAR;
	s_sub_i32 m0, s73, 0x80
	s_nop 0
	global_load_lds_dwordx4 v132, s[100:101] offset:128
	s_barrier
	s_waitcnt lgkmcnt(0)
	s_setprio 1
	s_waitcnt lgkmcnt(0)
	v_mfma_f32_16x16x32_bf16 v[92:95], v[156:159], v[172:175], v[92:95]
	v_mfma_f32_16x16x32_bf16 v[88:91], v[164:167], v[172:175], v[88:91]
	v_mfma_f32_16x16x32_bf16 v[84:87], v[156:159], v[190:193], v[84:87]
	v_mfma_f32_16x16x32_bf16 v[80:83], v[164:167], v[190:193], v[80:83]
	v_mfma_f32_16x16x32_bf16 v[76:79], v[156:159], v[198:201], v[76:79]
	v_mfma_f32_16x16x32_bf16 v[72:75], v[164:167], v[198:201], v[72:75]
	v_mfma_f32_16x16x32_bf16 v[68:71], v[156:159], v[206:209], v[68:71]
	v_mfma_f32_16x16x32_bf16 v[64:67], v[164:167], v[206:209], v[64:67]
	v_mfma_f32_16x16x32_bf16 v[92:95], v[160:163], v[186:189], v[92:95]
	v_mfma_f32_16x16x32_bf16 v[88:91], v[168:171], v[186:189], v[88:91]
	v_mfma_f32_16x16x32_bf16 v[84:87], v[160:163], v[194:197], v[84:87]
	v_mfma_f32_16x16x32_bf16 v[80:83], v[168:171], v[194:197], v[80:83]
	v_mfma_f32_16x16x32_bf16 v[76:79], v[160:163], v[202:205], v[76:79]
	v_mfma_f32_16x16x32_bf16 v[72:75], v[168:171], v[202:205], v[72:75]
	v_mfma_f32_16x16x32_bf16 v[68:71], v[160:163], v[210:213], v[68:71]
	v_mfma_f32_16x16x32_bf16 v[64:67], v[168:171], v[210:213], v[64:67]
	s_setprio 0
	s_barrier
	s_add_u32 s54, s54, 0x20080
	s_addc_u32 s55, s55, 0
	s_add_i32 s56, s56, s65

; #define PG8_STAGE(bufoff, gbase, voff) do { _Pragma("unroll") for (int _i = 0; _i < 2; ++_i) \
;         __builtin_amdgcn_global_load_lds((const unsigned*)((const char*)(gbase) + (voff)[_i]), (LAS unsigned*)(lds + (bufoff) + ldsw + _i * 8192), 16, 0, 0); } while (0)
; #define PG8_LDA(dst, b, h) do { _Pragma("unroll") for (int m = 0; m < 4; ++m) _Pragma("unroll") for (int k = 0; k < 2; ++k) dst[m][k] = *(const LAS bf16x8*)(lds + PG8_SA(b, h) + aoff + m * 2048 + k * 1024); } while (0)
; #define PG8_LDB(dst, b, h) do { _Pragma("unroll") for (int n = 0; n < 2; ++n) _Pragma("unroll") for (int k = 0; k < 2; ++k) dst[n][k] = *(const LAS bf16x8*)(lds + PG8_SB(b, h) + boff + n * 2048 + k * 1024); } while (0)
; #define PG8_WAIT_V(n) asm volatile("s_waitcnt vmcnt(" #n ")" ::: "memory")
; #define PG8_WAIT_L(n) asm volatile("s_waitcnt lgkmcnt(" #n ")" ::: "memory")
; #define PG8_BAR __builtin_amdgcn_s_barrier()
; #define PG8_SCHED __builtin_amdgcn_sched_barrier(0)
; template <class Epi>
; DI void gemm_phase(LAS unsigned char* lds, int wid, int K, int lda, int ldb, bool bperm, const Sched3& S, const Epi& E) {
;     ...
;             PG8_LDB(B0, 0, 0); PG8_SCHED; PG8_LDA(At, 0, 0); PG8_STAGE(PG8_SA(1, 1), a1 + hA, voffA);
;             PG8_WAIT_L(8); PG8_BAR; PG8_WAIT_L(0); PG8_MMA(0, 0, At, B0); PG8_BAR; PG8_SCHED;
;             PG8_LDB(B1, 0, 1); PG8_STAGE(PG8_SB(0, 0), b2, voffB);
;             PG8_BAR; PG8_WAIT_L(0); PG8_MMA(0, 1, At, B1); PG8_BAR;
;             PG8_LDA(At, 0, 1); PG8_STAGE(PG8_SA(0, 0), a2, voffA);
;             PG8_BAR; PG8_WAIT_L(0); if (full) PG8_MMA(1, 0, At, B0); PG8_BAR; PG8_SCHED;
;             PG8_STAGE(PG8_SB(0, 1), b2 + hstepB, voffB);
;             PG8_WAIT_V(6); PG8_BAR; if (full) PG8_MMA(1, 1, At, B1); PG8_BAR;
;             PG8_LDB(B0, 1, 0); PG8_SCHED; PG8_LDA(At, 1, 0); PG8_STAGE(PG8_SA(0, 1), a2 + h2, voffA);
;             PG8_WAIT_L(8); PG8_BAR; PG8_WAIT_L(0); PG8_MMA(0, 0, At, B0); PG8_BAR; PG8_SCHED;
;             PG8_LDB(B1, 1, 1); PG8_STAGE(PG8_SB(1, 0), b3, voffB);
;             PG8_BAR; PG8_WAIT_L(0); PG8_MMA(0, 1, At, B1); PG8_BAR;
;             PG8_LDA(At, 1, 1); PG8_STAGE(PG8_SA(1, 0), a3, voffA);
;             PG8_BAR; PG8_WAIT_L(0); if (full) PG8_MMA(1, 0, At, B0); PG8_BAR; PG8_SCHED;
;             PG8_STAGE(PG8_SB(1, 1), b3 + hstepB, voffB);
;             PG8_WAIT_V(6); PG8_BAR; if (full) PG8_MMA(1, 1, At, B1); PG8_BAR;
	s_mov_b32 m0, s56
	s_nop 0
	global_load_lds_dwordx4 v130, s[54:55]

; #define PG8_STAGE(bufoff, gbase, voff) do { _Pragma("unroll") for (int _i = 0; _i < 2; ++_i) \
;         __builtin_amdgcn_global_load_lds((const unsigned*)((const char*)(gbase) + (voff)[_i]), (LAS unsigned*)(lds + (bufoff) + ldsw + _i * 8192), 16, 0, 0); } while (0)
; #define PG8_LDA(dst, b, h) do { _Pragma("unroll") for (int m = 0; m < 4; ++m) _Pragma("unroll") for (int k = 0; k < 2; ++k) dst[m][k] = *(const LAS bf16x8*)(lds + PG8_SA(b, h) + aoff + m * 2048 + k * 1024); } while (0)
; #define PG8_WAIT_V(n) asm volatile("s_waitcnt vmcnt(" #n ")" ::: "memory")
; template <class Epi>
; DI void gemm_phase(LAS unsigned char* lds, int wid, int K, int lda, int ldb, bool bperm, const Sched3& S, const Epi& E) {
;     ...
;         for (int t = 0; t < nt; t += 2) {
;             const bool last = (t == nt - 2);
;             const char* a1 = cA + (size_t)(t + 1) * kstep;
;             const char* a2 = last ? nA : cA + (size_t)(t + 2) * kstep; const char* b2 = last ? nB : cB + (size_t)(t + 2) * kstep;
;             const char* a3 = a2 + kstep; const char* b3 = b2 + kstep; const size_t h2 = last ? nhA : hA;
;             PG8_LDB(B0, 0, 0); PG8_SCHED; PG8_LDA(At, 0, 0); PG8_STAGE(PG8_SA(1, 1), a1 + hA, voffA);
;             PG8_WAIT_L(8); PG8_BAR; PG8_WAIT_L(0); PG8_MMA(0, 0, At, B0); PG8_BAR; PG8_SCHED;
;             PG8_LDB(B1, 0, 1); PG8_STAGE(PG8_SB(0, 0), b2, voffB);
;             PG8_BAR; PG8_WAIT_L(0); PG8_MMA(0, 1, At, B1); PG8_BAR;
;             PG8_LDA(At, 0, 1); PG8_STAGE(PG8_SA(0, 0), a2, voffA);
;             PG8_BAR; PG8_WAIT_L(0); if (full) PG8_MMA(1, 0, At, B0); PG8_BAR; PG8_SCHED;
;             PG8_STAGE(PG8_SB(0, 1), b2 + hstepB, voffB);
;             PG8_WAIT_V(6); PG8_BAR; if (full) PG8_MMA(1, 1, At, B1); PG8_BAR;
;             PG8_LDB(B0, 1, 0); PG8_SCHED; PG8_LDA(At, 1, 0); PG8_STAGE(PG8_SA(0, 1), a2 + h2, voffA);
;             PG8_WAIT_L(8); PG8_BAR; PG8_WAIT_L(0); PG8_MMA(0, 0, At, B0); PG8_BAR; PG8_SCHED;
;             PG8_LDB(B1, 1, 1); PG8_STAGE(PG8_SB(1, 0), b3, voffB);
;             PG8_BAR; PG8_WAIT_L(0); PG8_MMA(0, 1, At, B1); PG8_BAR;
;             PG8_LDA(At, 1, 1); PG8_STAGE(PG8_SA(1, 0), a3, voffA);
;             PG8_BAR; PG8_WAIT_L(0); if (full) PG8_MMA(1, 0, At, B0); PG8_BAR; PG8_SCHED;
;             PG8_STAGE(PG8_SB(1, 1), b3 + hstepB, voffB);
;             PG8_WAIT_V(6); PG8_BAR; if (full) PG8_MMA(1, 1, At, B1); PG8_BAR;
	s_add_i32 m0, s56, 0x2000
	s_nop 0
	global_load_lds_dwordx4 v134, s[54:55]
	s_waitcnt vmcnt(6)
	s_barrier
	s_setprio 1
	v_mfma_f32_16x16x32_bf16 v[28:31], v[214:217], v[172:175], v[28:31]
	v_mfma_f32_16x16x32_bf16 v[24:27], v[224:227], v[172:175], v[24:27]
	v_mfma_f32_16x16x32_bf16 v[20:23], v[214:217], v[190:193], v[20:23]
	v_mfma_f32_16x16x32_bf16 v[16:19], v[224:227], v[190:193], v[16:19]
	v_mfma_f32_16x16x32_bf16 v[12:15], v[214:217], v[198:201], v[12:15]
	v_mfma_f32_16x16x32_bf16 v[8:11], v[224:227], v[198:201], v[8:11]
	v_mfma_f32_16x16x32_bf16 v[4:7], v[214:217], v[206:209], v[4:7]
	v_mfma_f32_16x16x32_bf16 v[0:3], v[224:227], v[206:209], v[0:3]
	v_mfma_f32_16x16x32_bf16 v[28:31], v[218:221], v[186:189], v[28:31]
	v_mfma_f32_16x16x32_bf16 v[24:27], v[228:231], v[186:189], v[24:27]
	v_mfma_f32_16x16x32_bf16 v[20:23], v[218:221], v[194:197], v[20:23]
	v_mfma_f32_16x16x32_bf16 v[16:19], v[228:231], v[194:197], v[16:19]
	v_mfma_f32_16x16x32_bf16 v[12:15], v[218:221], v[202:205], v[12:15]
	v_mfma_f32_16x16x32_bf16 v[8:11], v[228:231], v[202:205], v[8:11]
	v_mfma_f32_16x16x32_bf16 v[4:7], v[218:221], v[210:213], v[4:7]
	v_mfma_f32_16x16x32_bf16 v[0:3], v[228:231], v[210:213], v[0:3]
	s_setprio 0
	s_add_i32 s61, s61, 2
	s_add_u32 s52, s52, 0x100
	s_addc_u32 s53, s53, 0
	s_add_u32 s59, s59, 0x100
	s_addc_u32 s60, s60, 0
	s_cmp_gt_u32 s61, 5
	s_barrier
	s_cbranch_scc0 .LBB0_996

; #define PG8_STAGE(bufoff, gbase, voff) do { _Pragma("unroll") for (int _i = 0; _i < 2; ++_i) \
;         __builtin_amdgcn_global_load_lds((const unsigned*)((const char*)(gbase) + (voff)[_i]), (LAS unsigned*)(lds + (bufoff) + ldsw + _i * 8192), 16, 0, 0); } while (0)
; #define PG8_LDA(dst, b, h) do { _Pragma("unroll") for (int m = 0; m < 4; ++m) _Pragma("unroll") for (int k = 0; k < 2; ++k) dst[m][k] = *(const LAS bf16x8*)(lds + PG8_SA(b, h) + aoff + m * 2048 + k * 1024); } while (0)
; #define PG8_LDB(dst, b, h) do { _Pragma("unroll") for (int n = 0; n < 2; ++n) _Pragma("unroll") for (int k = 0; k < 2; ++k) dst[n][k] = *(const LAS bf16x8*)(lds + PG8_SB(b, h) + boff + n * 2048 + k * 1024); } while (0)
; #define PG8_SCHED __builtin_amdgcn_sched_barrier(0)
; template <class Epi>
; DI void gemm_phase(LAS unsigned char* lds, int wid, int K, int lda, int ldb, bool bperm, const Sched3& S, const Epi& E) {
;     ...
;         const char* nA = has_next ? nxt.A : cA; const char* nB = has_next ? nxt.B : cB; const size_t nhA = has_next ? (nxt.half ? (size_t)0 : hstepA) : hA; const bool full = (cur.half == 0);
;         for (int t = 0; t < nt; t += 2) {
;             const bool last = (t == nt - 2);
;             const char* a1 = cA + (size_t)(t + 1) * kstep;
;             const char* a2 = last ? nA : cA + (size_t)(t + 2) * kstep; const char* b2 = last ? nB : cB + (size_t)(t + 2) * kstep;
;             const char* a3 = a2 + kstep; const char* b3 = b2 + kstep; const size_t h2 = last ? nhA : hA;
;             PG8_LDB(B0, 0, 0); PG8_SCHED; PG8_LDA(At, 0, 0); PG8_STAGE(PG8_SA(1, 1), a1 + hA, voffA);
.LBB0_1175:
	s_add_u32 s36, s36, 0x80080
	s_addc_u32 s37, s37, 0
	s_add_u32 s19, s38, 0x100
	s_nop 0
	s_addc_u32 s21, s39, 0
	s_mov_b32 s27, -2
	s_waitcnt lgkmcnt(0)
	ds_read_b128 v[128:131], v185
	ds_read_b128 v[132:135], v185 offset:1024
	ds_read_b128 v[136:139], v185 offset:2048
	ds_read_b128 v[140:143], v185 offset:3072
	s_add_u32 s38, s36, 0xfff80080
	s_addc_u32 s39, s37, -1
	s_cmp_eq_u32 s27, 28
	s_cselect_b32 s41, s29, s39
	s_cselect_b32 s40, s28, s38
	s_cselect_b32 s39, s31, s21
	s_cselect_b32 s38, s30, s19

; #define PG8_STAGE(bufoff, gbase, voff) do { _Pragma("unroll") for (int _i = 0; _i < 2; ++_i) \
;         __builtin_amdgcn_global_load_lds((const unsigned*)((const char*)(gbase) + (voff)[_i]), (LAS unsigned*)(lds + (bufoff) + ldsw + _i * 8192), 16, 0, 0); } while (0)
; #define PG8_LDA(dst, b, h) do { _Pragma("unroll") for (int m = 0; m < 4; ++m) _Pragma("unroll") for (int k = 0; k < 2; ++k) dst[m][k] = *(const LAS bf16x8*)(lds + PG8_SA(b, h) + aoff + m * 2048 + k * 1024); } while (0)
; #define PG8_LDB(dst, b, h) do { _Pragma("unroll") for (int n = 0; n < 2; ++n) _Pragma("unroll") for (int k = 0; k < 2; ++k) dst[n][k] = *(const LAS bf16x8*)(lds + PG8_SB(b, h) + boff + n * 2048 + k * 1024); } while (0)
; #define PG8_WAIT_V(n) asm volatile("s_waitcnt vmcnt(" #n ")" ::: "memory")
; #define PG8_WAIT_L(n) asm volatile("s_waitcnt lgkmcnt(" #n ")" ::: "memory")
; #define PG8_BAR __builtin_amdgcn_s_barrier()
; #define PG8_SCHED __builtin_amdgcn_sched_barrier(0)
; template <class Epi>
; DI void gemm_phase(LAS unsigned char* lds, int wid, int K, int lda, int ldb, bool bperm, const Sched3& S, const Epi& E) {
;     ...
;             PG8_LDB(B0, 0, 0); PG8_SCHED; PG8_LDA(At, 0, 0); PG8_STAGE(PG8_SA(1, 1), a1 + hA, voffA);
;             PG8_WAIT_L(8); PG8_BAR; PG8_WAIT_L(0); PG8_MMA(0, 0, At, B0); PG8_BAR; PG8_SCHED;
;             PG8_LDB(B1, 0, 1); PG8_STAGE(PG8_SB(0, 0), b2, voffB);
;             PG8_BAR; PG8_WAIT_L(0); PG8_MMA(0, 1, At, B1); PG8_BAR;
;             PG8_LDA(At, 0, 1); PG8_STAGE(PG8_SA(0, 0), a2, voffA);
;             PG8_BAR; PG8_WAIT_L(0); if (full) PG8_MMA(1, 0, At, B0); PG8_BAR; PG8_SCHED;
;             PG8_STAGE(PG8_SB(0, 1), b2 + hstepB, voffB);
;             PG8_WAIT_V(6); PG8_BAR; if (full) PG8_MMA(1, 1, At, B1); PG8_BAR;
;             PG8_LDB(B0, 1, 0); PG8_SCHED; PG8_LDA(At, 1, 0); PG8_STAGE(PG8_SA(0, 1), a2 + h2, voffA);
;             PG8_WAIT_L(8); PG8_BAR; PG8_WAIT_L(0); PG8_MMA(0, 0, At, B0); PG8_BAR; PG8_SCHED;
;             PG8_LDB(B1, 1, 1); PG8_STAGE(PG8_SB(1, 0), b3, voffB);
;             PG8_BAR; PG8_WAIT_L(0); PG8_MMA(0, 1, At, B1); PG8_BAR;
;             PG8_LDA(At, 1, 1); PG8_STAGE(PG8_SA(1, 0), a3, voffA);
;             PG8_BAR; PG8_WAIT_L(0); if (full) PG8_MMA(1, 0, At, B0); PG8_BAR; PG8_SCHED;
;             PG8_STAGE(PG8_SB(1, 1), b3 + hstepB, voffB);
;             PG8_WAIT_V(6); PG8_BAR; if (full) PG8_MMA(1, 1, At, B1); PG8_BAR;
	s_add_i32 m0, s48, 0xc000
	ds_read_b128 v[144:147], v186
	ds_read_b128 v[148:151], v186 offset:1024
	ds_read_b128 v[162:165], v186 offset:2048
	ds_read_b128 v[166:169], v186 offset:3072
	ds_read_b128 v[170:173], v186 offset:4096
	ds_read_b128 v[174:177], v186 offset:5120
	ds_read_b128 v[188:191], v186 offset:6144
	ds_read_b128 v[192:195], v186 offset:7168
	global_load_lds_dwordx4 v156, s[36:37]

; #define PG8_STAGE(bufoff, gbase, voff) do { _Pragma("unroll") for (int _i = 0; _i < 2; ++_i) \
;         __builtin_amdgcn_global_load_lds((const unsigned*)((const char*)(gbase) + (voff)[_i]), (LAS unsigned*)(lds + (bufoff) + ldsw + _i * 8192), 16, 0, 0); } while (0)
; #define PG8_LDA(dst, b, h) do { _Pragma("unroll") for (int m = 0; m < 4; ++m) _Pragma("unroll") for (int k = 0; k < 2; ++k) dst[m][k] = *(const LAS bf16x8*)(lds + PG8_SA(b, h) + aoff + m * 2048 + k * 1024); } while (0)
; #define PG8_LDB(dst, b, h) do { _Pragma("unroll") for (int n = 0; n < 2; ++n) _Pragma("unroll") for (int k = 0; k < 2; ++k) dst[n][k] = *(const LAS bf16x8*)(lds + PG8_SB(b, h) + boff + n * 2048 + k * 1024); } while (0)
; #define PG8_WAIT_V(n) asm volatile("s_waitcnt vmcnt(" #n ")" ::: "memory")
; #define PG8_WAIT_L(n) asm volatile("s_waitcnt lgkmcnt(" #n ")" ::: "memory")
; #define PG8_BAR __builtin_amdgcn_s_barrier()
; #define PG8_SCHED __builtin_amdgcn_sched_barrier(0)
; template <class Epi>
; DI void gemm_phase(LAS unsigned char* lds, int wid, int K, int lda, int ldb, bool bperm, const Sched3& S, const Epi& E) {
;     ...
;             PG8_LDB(B0, 0, 0); PG8_SCHED; PG8_LDA(At, 0, 0); PG8_STAGE(PG8_SA(1, 1), a1 + hA, voffA);
;             PG8_WAIT_L(8); PG8_BAR; PG8_WAIT_L(0); PG8_MMA(0, 0, At, B0); PG8_BAR; PG8_SCHED;
;             PG8_LDB(B1, 0, 1); PG8_STAGE(PG8_SB(0, 0), b2, voffB);
;             PG8_BAR; PG8_WAIT_L(0); PG8_MMA(0, 1, At, B1); PG8_BAR;
;             PG8_LDA(At, 0, 1); PG8_STAGE(PG8_SA(0, 0), a2, voffA);
;             PG8_BAR; PG8_WAIT_L(0); if (full) PG8_MMA(1, 0, At, B0); PG8_BAR; PG8_SCHED;
;             PG8_STAGE(PG8_SB(0, 1), b2 + hstepB, voffB);
;             PG8_WAIT_V(6); PG8_BAR; if (full) PG8_MMA(1, 1, At, B1); PG8_BAR;
;             PG8_LDB(B0, 1, 0); PG8_SCHED; PG8_LDA(At, 1, 0); PG8_STAGE(PG8_SA(0, 1), a2 + h2, voffA);
;             PG8_WAIT_L(8); PG8_BAR; PG8_WAIT_L(0); PG8_MMA(0, 0, At, B0); PG8_BAR; PG8_SCHED;
;             PG8_LDB(B1, 1, 1); PG8_STAGE(PG8_SB(1, 0), b3, voffB);
;             PG8_BAR; PG8_WAIT_L(0); PG8_MMA(0, 1, At, B1); PG8_BAR;
;             PG8_LDA(At, 1, 1); PG8_STAGE(PG8_SA(1, 0), a3, voffA);
;             PG8_BAR; PG8_WAIT_L(0); if (full) PG8_MMA(1, 0, At, B0); PG8_BAR; PG8_SCHED;
;             PG8_STAGE(PG8_SB(1, 1), b3 + hstepB, voffB);
;             PG8_WAIT_V(6); PG8_BAR; if (full) PG8_MMA(1, 1, At, B1); PG8_BAR;
	s_add_i32 m0, s48, 0xe000
	s_nop 0
	global_load_lds_dwordx4 v158, s[36:37]
	s_waitcnt lgkmcnt(8)
	s_barrier
	s_waitcnt lgkmcnt(0)
	s_setprio 1
	s_waitcnt lgkmcnt(0)
	v_mfma_f32_16x16x32_bf16 v[124:127], v[128:131], v[144:147], 0
	v_mfma_f32_16x16x32_bf16 v[120:123], v[136:139], v[144:147], 0
	v_mfma_f32_16x16x32_bf16 v[108:111], v[128:131], v[162:165], 0
	v_mfma_f32_16x16x32_bf16 v[104:107], v[136:139], v[162:165], 0
	v_mfma_f32_16x16x32_bf16 v[92:95], v[128:131], v[170:173], 0
	v_mfma_f32_16x16x32_bf16 v[88:91], v[136:139], v[170:173], 0
	v_mfma_f32_16x16x32_bf16 v[76:79], v[128:131], v[188:191], 0
	v_mfma_f32_16x16x32_bf16 v[72:75], v[136:139], v[188:191], 0
	v_mfma_f32_16x16x32_bf16 v[124:127], v[132:135], v[148:151], v[124:127]
	v_mfma_f32_16x16x32_bf16 v[120:123], v[140:143], v[148:151], v[120:123]
	v_mfma_f32_16x16x32_bf16 v[108:111], v[132:135], v[166:169], v[108:111]
	v_mfma_f32_16x16x32_bf16 v[104:107], v[140:143], v[166:169], v[104:107]
	v_mfma_f32_16x16x32_bf16 v[92:95], v[132:135], v[174:177], v[92:95]
	v_mfma_f32_16x16x32_bf16 v[88:91], v[140:143], v[174:177], v[88:91]
	v_mfma_f32_16x16x32_bf16 v[76:79], v[132:135], v[192:195], v[76:79]
	v_mfma_f32_16x16x32_bf16 v[72:75], v[140:143], v[192:195], v[72:75]
	s_setprio 0
	s_barrier
	s_add_i32 s61, s57, s47

; #define PG8_STAGE(bufoff, gbase, voff) do { _Pragma("unroll") for (int _i = 0; _i < 2; ++_i) \
;         __builtin_amdgcn_global_load_lds((const unsigned*)((const char*)(gbase) + (voff)[_i]), (LAS unsigned*)(lds + (bufoff) + ldsw + _i * 8192), 16, 0, 0); } while (0)
; #define PG8_LDA(dst, b, h) do { _Pragma("unroll") for (int m = 0; m < 4; ++m) _Pragma("unroll") for (int k = 0; k < 2; ++k) dst[m][k] = *(const LAS bf16x8*)(lds + PG8_SA(b, h) + aoff + m * 2048 + k * 1024); } while (0)
; #define PG8_LDB(dst, b, h) do { _Pragma("unroll") for (int n = 0; n < 2; ++n) _Pragma("unroll") for (int k = 0; k < 2; ++k) dst[n][k] = *(const LAS bf16x8*)(lds + PG8_SB(b, h) + boff + n * 2048 + k * 1024); } while (0)
; #define PG8_WAIT_V(n) asm volatile("s_waitcnt vmcnt(" #n ")" ::: "memory")
; #define PG8_WAIT_L(n) asm volatile("s_waitcnt lgkmcnt(" #n ")" ::: "memory")
; #define PG8_BAR __builtin_amdgcn_s_barrier()
; #define PG8_SCHED __builtin_amdgcn_sched_barrier(0)
; template <class Epi>
; DI void gemm_phase(LAS unsigned char* lds, int wid, int K, int lda, int ldb, bool bperm, const Sched3& S, const Epi& E) {
;     ...
;             PG8_LDB(B0, 0, 0); PG8_SCHED; PG8_LDA(At, 0, 0); PG8_STAGE(PG8_SA(1, 1), a1 + hA, voffA);
;             PG8_WAIT_L(8); PG8_BAR; PG8_WAIT_L(0); PG8_MMA(0, 0, At, B0); PG8_BAR; PG8_SCHED;
;             PG8_LDB(B1, 0, 1); PG8_STAGE(PG8_SB(0, 0), b2, voffB);
;             PG8_BAR; PG8_WAIT_L(0); PG8_MMA(0, 1, At, B1); PG8_BAR;
;             PG8_LDA(At, 0, 1); PG8_STAGE(PG8_SA(0, 0), a2, voffA);
;             PG8_BAR; PG8_WAIT_L(0); if (full) PG8_MMA(1, 0, At, B0); PG8_BAR; PG8_SCHED;
;             PG8_STAGE(PG8_SB(0, 1), b2 + hstepB, voffB);
;             PG8_WAIT_V(6); PG8_BAR; if (full) PG8_MMA(1, 1, At, B1); PG8_BAR;
;             PG8_LDB(B0, 1, 0); PG8_SCHED; PG8_LDA(At, 1, 0); PG8_STAGE(PG8_SA(0, 1), a2 + h2, voffA);
;             PG8_WAIT_L(8); PG8_BAR; PG8_WAIT_L(0); PG8_MMA(0, 0, At, B0); PG8_BAR; PG8_SCHED;
;             PG8_LDB(B1, 1, 1); PG8_STAGE(PG8_SB(1, 0), b3, voffB);
;             PG8_BAR; PG8_WAIT_L(0); PG8_MMA(0, 1, At, B1); PG8_BAR;
;             PG8_LDA(At, 1, 1); PG8_STAGE(PG8_SA(1, 0), a3, voffA);
;             PG8_BAR; PG8_WAIT_L(0); if (full) PG8_MMA(1, 0, At, B0); PG8_BAR; PG8_SCHED;
;             PG8_STAGE(PG8_SB(1, 1), b3 + hstepB, voffB);
;             PG8_WAIT_V(6); PG8_BAR; if (full) PG8_MMA(1, 1, At, B1); PG8_BAR;
	s_mov_b32 m0, s61
	ds_read_b128 v[196:199], v187
	ds_read_b128 v[200:203], v187 offset:1024
	ds_read_b128 v[204:207], v187 offset:2048
	ds_read_b128 v[208:211], v187 offset:3072
	global_load_lds_dwordx4 v152, s[38:39]

; #define PG8_STAGE(bufoff, gbase, voff) do { _Pragma("unroll") for (int _i = 0; _i < 2; ++_i) \
;         __builtin_amdgcn_global_load_lds((const unsigned*)((const char*)(gbase) + (voff)[_i]), (LAS unsigned*)(lds + (bufoff) + ldsw + _i * 8192), 16, 0, 0); } while (0)
; #define PG8_LDA(dst, b, h) do { _Pragma("unroll") for (int m = 0; m < 4; ++m) _Pragma("unroll") for (int k = 0; k < 2; ++k) dst[m][k] = *(const LAS bf16x8*)(lds + PG8_SA(b, h) + aoff + m * 2048 + k * 1024); } while (0)
; #define PG8_LDB(dst, b, h) do { _Pragma("unroll") for (int n = 0; n < 2; ++n) _Pragma("unroll") for (int k = 0; k < 2; ++k) dst[n][k] = *(const LAS bf16x8*)(lds + PG8_SB(b, h) + boff + n * 2048 + k * 1024); } while (0)
; #define PG8_WAIT_V(n) asm volatile("s_waitcnt vmcnt(" #n ")" ::: "memory")
; #define PG8_WAIT_L(n) asm volatile("s_waitcnt lgkmcnt(" #n ")" ::: "memory")
; #define PG8_BAR __builtin_amdgcn_s_barrier()
; #define PG8_SCHED __builtin_amdgcn_sched_barrier(0)
; template <class Epi>
; DI void gemm_phase(LAS unsigned char* lds, int wid, int K, int lda, int ldb, bool bperm, const Sched3& S, const Epi& E) {
;     ...
;             PG8_LDB(B0, 0, 0); PG8_SCHED; PG8_LDA(At, 0, 0); PG8_STAGE(PG8_SA(1, 1), a1 + hA, voffA);
;             PG8_WAIT_L(8); PG8_BAR; PG8_WAIT_L(0); PG8_MMA(0, 0, At, B0); PG8_BAR; PG8_SCHED;
;             PG8_LDB(B1, 0, 1); PG8_STAGE(PG8_SB(0, 0), b2, voffB);
;             PG8_BAR; PG8_WAIT_L(0); PG8_MMA(0, 1, At, B1); PG8_BAR;
;             PG8_LDA(At, 0, 1); PG8_STAGE(PG8_SA(0, 0), a2, voffA);
;             PG8_BAR; PG8_WAIT_L(0); if (full) PG8_MMA(1, 0, At, B0); PG8_BAR; PG8_SCHED;
;             PG8_STAGE(PG8_SB(0, 1), b2 + hstepB, voffB);
;             PG8_WAIT_V(6); PG8_BAR; if (full) PG8_MMA(1, 1, At, B1); PG8_BAR;
;             PG8_LDB(B0, 1, 0); PG8_SCHED; PG8_LDA(At, 1, 0); PG8_STAGE(PG8_SA(0, 1), a2 + h2, voffA);
;             PG8_WAIT_L(8); PG8_BAR; PG8_WAIT_L(0); PG8_MMA(0, 0, At, B0); PG8_BAR; PG8_SCHED;
;             PG8_LDB(B1, 1, 1); PG8_STAGE(PG8_SB(1, 0), b3, voffB);
;             PG8_BAR; PG8_WAIT_L(0); PG8_MMA(0, 1, At, B1); PG8_BAR;
;             PG8_LDA(At, 1, 1); PG8_STAGE(PG8_SA(1, 0), a3, voffA);
;             PG8_BAR; PG8_WAIT_L(0); if (full) PG8_MMA(1, 0, At, B0); PG8_BAR; PG8_SCHED;
;             PG8_STAGE(PG8_SB(1, 1), b3 + hstepB, voffB);
;             PG8_WAIT_V(6); PG8_BAR; if (full) PG8_MMA(1, 1, At, B1); PG8_BAR;
	s_add_i32 m0, s61, 0x2000
	s_nop 0
	global_load_lds_dwordx4 v154, s[38:39]
	s_barrier
	s_waitcnt lgkmcnt(0)
	s_setprio 1
	s_waitcnt lgkmcnt(0)
	v_mfma_f32_16x16x32_bf16 v[116:119], v[196:199], v[144:147], 0
	v_mfma_f32_16x16x32_bf16 v[112:115], v[204:207], v[144:147], 0
	v_mfma_f32_16x16x32_bf16 v[100:103], v[196:199], v[162:165], 0
	v_mfma_f32_16x16x32_bf16 v[96:99], v[204:207], v[162:165], 0
	v_mfma_f32_16x16x32_bf16 v[84:87], v[196:199], v[170:173], 0
	v_mfma_f32_16x16x32_bf16 v[80:83], v[204:207], v[170:173], 0
	v_mfma_f32_16x16x32_bf16 v[68:71], v[196:199], v[188:191], 0
	v_mfma_f32_16x16x32_bf16 v[64:67], v[204:207], v[188:191], 0
	v_mfma_f32_16x16x32_bf16 v[116:119], v[200:203], v[148:151], v[116:119]
	v_mfma_f32_16x16x32_bf16 v[112:115], v[208:211], v[148:151], v[112:115]
	v_mfma_f32_16x16x32_bf16 v[100:103], v[200:203], v[166:169], v[100:103]
	v_mfma_f32_16x16x32_bf16 v[96:99], v[208:211], v[166:169], v[96:99]
	v_mfma_f32_16x16x32_bf16 v[84:87], v[200:203], v[174:177], v[84:87]
	v_mfma_f32_16x16x32_bf16 v[80:83], v[208:211], v[174:177], v[80:83]
	v_mfma_f32_16x16x32_bf16 v[68:71], v[200:203], v[192:195], v[68:71]
	v_mfma_f32_16x16x32_bf16 v[64:67], v[208:211], v[192:195], v[64:67]
	s_setprio 0
	s_mov_b32 m0, s48
	s_mov_b64 s[100:101], s[40:41]
	s_barrier
	ds_read_b128 v[144:147], v186 offset:16384
	ds_read_b128 v[148:151], v186 offset:17408
	ds_read_b128 v[162:165], v186 offset:18432
	ds_read_b128 v[166:169], v186 offset:19456
	ds_read_b128 v[170:173], v186 offset:20480
	ds_read_b128 v[174:177], v186 offset:21504
	ds_read_b128 v[188:191], v186 offset:22528
	ds_read_b128 v[192:195], v186 offset:23552
	global_load_lds_dwordx4 v152, s[40:41]
	s_mov_b64 s[100:101], s[40:41]
	s_mov_b32 m0, s49
	s_nop 0
	global_load_lds_dwordx4 v154, s[40:41]
	s_barrier
	s_waitcnt lgkmcnt(0)
	s_setprio 1
	s_waitcnt lgkmcnt(0)
	v_mfma_f32_16x16x32_bf16 v[60:63], v[128:131], v[144:147], 0
	v_mfma_f32_16x16x32_bf16 v[56:59], v[136:139], v[144:147], 0
	v_mfma_f32_16x16x32_bf16 v[44:47], v[128:131], v[162:165], 0
	v_mfma_f32_16x16x32_bf16 v[40:43], v[136:139], v[162:165], 0
	v_mfma_f32_16x16x32_bf16 v[28:31], v[128:131], v[170:173], 0
	v_mfma_f32_16x16x32_bf16 v[24:27], v[136:139], v[170:173], 0
	v_mfma_f32_16x16x32_bf16 v[12:15], v[128:131], v[188:191], 0
	v_mfma_f32_16x16x32_bf16 v[8:11], v[136:139], v[188:191], 0
	v_mfma_f32_16x16x32_bf16 v[60:63], v[132:135], v[148:151], v[60:63]
	v_mfma_f32_16x16x32_bf16 v[56:59], v[140:143], v[148:151], v[56:59]
	v_mfma_f32_16x16x32_bf16 v[44:47], v[132:135], v[166:169], v[44:47]
	v_mfma_f32_16x16x32_bf16 v[40:43], v[140:143], v[166:169], v[40:43]
	v_mfma_f32_16x16x32_bf16 v[28:31], v[132:135], v[174:177], v[28:31]
	v_mfma_f32_16x16x32_bf16 v[24:27], v[140:143], v[174:177], v[24:27]
	v_mfma_f32_16x16x32_bf16 v[12:15], v[132:135], v[192:195], v[12:15]
	v_mfma_f32_16x16x32_bf16 v[8:11], v[140:143], v[192:195], v[8:11]
	s_setprio 0
	s_barrier
	s_add_u32 s62, s38, 0x80000
	s_addc_u32 s63, s39, 0
	s_add_i32 s61, s58, s47

; #define PG8_STAGE(bufoff, gbase, voff) do { _Pragma("unroll") for (int _i = 0; _i < 2; ++_i) \
;         __builtin_amdgcn_global_load_lds((const unsigned*)((const char*)(gbase) + (voff)[_i]), (LAS unsigned*)(lds + (bufoff) + ldsw + _i * 8192), 16, 0, 0); } while (0)
; #define PG8_LDA(dst, b, h) do { _Pragma("unroll") for (int m = 0; m < 4; ++m) _Pragma("unroll") for (int k = 0; k < 2; ++k) dst[m][k] = *(const LAS bf16x8*)(lds + PG8_SA(b, h) + aoff + m * 2048 + k * 1024); } while (0)
; #define PG8_LDB(dst, b, h) do { _Pragma("unroll") for (int n = 0; n < 2; ++n) _Pragma("unroll") for (int k = 0; k < 2; ++k) dst[n][k] = *(const LAS bf16x8*)(lds + PG8_SB(b, h) + boff + n * 2048 + k * 1024); } while (0)
; #define PG8_WAIT_V(n) asm volatile("s_waitcnt vmcnt(" #n ")" ::: "memory")
; #define PG8_WAIT_L(n) asm volatile("s_waitcnt lgkmcnt(" #n ")" ::: "memory")
; #define PG8_BAR __builtin_amdgcn_s_barrier()
; #define PG8_SCHED __builtin_amdgcn_sched_barrier(0)
; template <class Epi>
; DI void gemm_phase(LAS unsigned char* lds, int wid, int K, int lda, int ldb, bool bperm, const Sched3& S, const Epi& E) {
;     ...
;             PG8_LDB(B0, 0, 0); PG8_SCHED; PG8_LDA(At, 0, 0); PG8_STAGE(PG8_SA(1, 1), a1 + hA, voffA);
;             PG8_WAIT_L(8); PG8_BAR; PG8_WAIT_L(0); PG8_MMA(0, 0, At, B0); PG8_BAR; PG8_SCHED;
;             PG8_LDB(B1, 0, 1); PG8_STAGE(PG8_SB(0, 0), b2, voffB);
;             PG8_BAR; PG8_WAIT_L(0); PG8_MMA(0, 1, At, B1); PG8_BAR;
;             PG8_LDA(At, 0, 1); PG8_STAGE(PG8_SA(0, 0), a2, voffA);
;             PG8_BAR; PG8_WAIT_L(0); if (full) PG8_MMA(1, 0, At, B0); PG8_BAR; PG8_SCHED;
;             PG8_STAGE(PG8_SB(0, 1), b2 + hstepB, voffB);
;             PG8_WAIT_V(6); PG8_BAR; if (full) PG8_MMA(1, 1, At, B1); PG8_BAR;
;             PG8_LDB(B0, 1, 0); PG8_SCHED; PG8_LDA(At, 1, 0); PG8_STAGE(PG8_SA(0, 1), a2 + h2, voffA);
;             PG8_WAIT_L(8); PG8_BAR; PG8_WAIT_L(0); PG8_MMA(0, 0, At, B0); PG8_BAR; PG8_SCHED;
;             PG8_LDB(B1, 1, 1); PG8_STAGE(PG8_SB(1, 0), b3, voffB);
;             PG8_BAR; PG8_WAIT_L(0); PG8_MMA(0, 1, At, B1); PG8_BAR;
;             PG8_LDA(At, 1, 1); PG8_STAGE(PG8_SA(1, 0), a3, voffA);
;             PG8_BAR; PG8_WAIT_L(0); if (full) PG8_MMA(1, 0, At, B0); PG8_BAR; PG8_SCHED;
;             PG8_STAGE(PG8_SB(1, 1), b3 + hstepB, voffB);
;             PG8_WAIT_V(6); PG8_BAR; if (full) PG8_MMA(1, 1, At, B1); PG8_BAR;
	s_mov_b32 m0, s61
	s_nop 0
	global_load_lds_dwordx4 v152, s[62:63]

; #define PG8_STAGE(bufoff, gbase, voff) do { _Pragma("unroll") for (int _i = 0; _i < 2; ++_i) \
;         __builtin_amdgcn_global_load_lds((const unsigned*)((const char*)(gbase) + (voff)[_i]), (LAS unsigned*)(lds + (bufoff) + ldsw + _i * 8192), 16, 0, 0); } while (0)
; #define PG8_LDA(dst, b, h) do { _Pragma("unroll") for (int m = 0; m < 4; ++m) _Pragma("unroll") for (int k = 0; k < 2; ++k) dst[m][k] = *(const LAS bf16x8*)(lds + PG8_SA(b, h) + aoff + m * 2048 + k * 1024); } while (0)
; #define PG8_LDB(dst, b, h) do { _Pragma("unroll") for (int n = 0; n < 2; ++n) _Pragma("unroll") for (int k = 0; k < 2; ++k) dst[n][k] = *(const LAS bf16x8*)(lds + PG8_SB(b, h) + boff + n * 2048 + k * 1024); } while (0)
; #define PG8_WAIT_V(n) asm volatile("s_waitcnt vmcnt(" #n ")" ::: "memory")
; #define PG8_WAIT_L(n) asm volatile("s_waitcnt lgkmcnt(" #n ")" ::: "memory")
; #define PG8_BAR __builtin_amdgcn_s_barrier()
; #define PG8_SCHED __builtin_amdgcn_sched_barrier(0)
; template <class Epi>
; DI void gemm_phase(LAS unsigned char* lds, int wid, int K, int lda, int ldb, bool bperm, const Sched3& S, const Epi& E) {
;     ...
;             PG8_LDB(B0, 0, 0); PG8_SCHED; PG8_LDA(At, 0, 0); PG8_STAGE(PG8_SA(1, 1), a1 + hA, voffA);
;             PG8_WAIT_L(8); PG8_BAR; PG8_WAIT_L(0); PG8_MMA(0, 0, At, B0); PG8_BAR; PG8_SCHED;
;             PG8_LDB(B1, 0, 1); PG8_STAGE(PG8_SB(0, 0), b2, voffB);
;             PG8_BAR; PG8_WAIT_L(0); PG8_MMA(0, 1, At, B1); PG8_BAR;
;             PG8_LDA(At, 0, 1); PG8_STAGE(PG8_SA(0, 0), a2, voffA);
;             PG8_BAR; PG8_WAIT_L(0); if (full) PG8_MMA(1, 0, At, B0); PG8_BAR; PG8_SCHED;
;             PG8_STAGE(PG8_SB(0, 1), b2 + hstepB, voffB);
;             PG8_WAIT_V(6); PG8_BAR; if (full) PG8_MMA(1, 1, At, B1); PG8_BAR;
;             PG8_LDB(B0, 1, 0); PG8_SCHED; PG8_LDA(At, 1, 0); PG8_STAGE(PG8_SA(0, 1), a2 + h2, voffA);
;             PG8_WAIT_L(8); PG8_BAR; PG8_WAIT_L(0); PG8_MMA(0, 0, At, B0); PG8_BAR; PG8_SCHED;
;             PG8_LDB(B1, 1, 1); PG8_STAGE(PG8_SB(1, 0), b3, voffB);
;             PG8_BAR; PG8_WAIT_L(0); PG8_MMA(0, 1, At, B1); PG8_BAR;
;             PG8_LDA(At, 1, 1); PG8_STAGE(PG8_SA(1, 0), a3, voffA);
;             PG8_BAR; PG8_WAIT_L(0); if (full) PG8_MMA(1, 0, At, B0); PG8_BAR; PG8_SCHED;
;             PG8_STAGE(PG8_SB(1, 1), b3 + hstepB, voffB);
;             PG8_WAIT_V(6); PG8_BAR; if (full) PG8_MMA(1, 1, At, B1); PG8_BAR;
	s_add_i32 m0, s61, 0x2000
	s_nop 0
	global_load_lds_dwordx4 v154, s[62:63]
	s_waitcnt vmcnt(6)
	s_barrier
	s_setprio 1
	v_mfma_f32_16x16x32_bf16 v[52:55], v[196:199], v[144:147], 0
	v_mfma_f32_16x16x32_bf16 v[48:51], v[204:207], v[144:147], 0
	v_mfma_f32_16x16x32_bf16 v[36:39], v[196:199], v[162:165], 0
	v_mfma_f32_16x16x32_bf16 v[32:35], v[204:207], v[162:165], 0
	v_mfma_f32_16x16x32_bf16 v[20:23], v[196:199], v[170:173], 0
	v_mfma_f32_16x16x32_bf16 v[16:19], v[204:207], v[170:173], 0
	v_mfma_f32_16x16x32_bf16 v[4:7], v[196:199], v[188:191], 0
	v_mfma_f32_16x16x32_bf16 v[0:3], v[204:207], v[188:191], 0
	v_mfma_f32_16x16x32_bf16 v[52:55], v[200:203], v[148:151], v[52:55]
	v_mfma_f32_16x16x32_bf16 v[48:51], v[208:211], v[148:151], v[48:51]
	v_mfma_f32_16x16x32_bf16 v[36:39], v[200:203], v[166:169], v[36:39]
	v_mfma_f32_16x16x32_bf16 v[32:35], v[208:211], v[166:169], v[32:35]
	v_mfma_f32_16x16x32_bf16 v[20:23], v[200:203], v[174:177], v[20:23]
	v_mfma_f32_16x16x32_bf16 v[16:19], v[208:211], v[174:177], v[16:19]
	v_mfma_f32_16x16x32_bf16 v[4:7], v[200:203], v[192:195], v[4:7]
	v_mfma_f32_16x16x32_bf16 v[0:3], v[208:211], v[192:195], v[0:3]
	s_setprio 0
	s_add_i32 s61, 0, 0x18000
	v_add_u32_e32 v140, s61, v181
	s_barrier
	ds_read_b128 v[128:131], v140
	ds_read_b128 v[132:135], v140 offset:1024
	ds_read_b128 v[136:139], v140 offset:2048
	ds_read_b128 v[140:143], v140 offset:3072
	s_add_u32 s40, s40, 0x80000
	s_addc_u32 s41, s41, 0
	s_mov_b32 m0, s50

; #define PG8_STAGE(bufoff, gbase, voff) do { _Pragma("unroll") for (int _i = 0; _i < 2; ++_i) \
;         __builtin_amdgcn_global_load_lds((const unsigned*)((const char*)(gbase) + (voff)[_i]), (LAS unsigned*)(lds + (bufoff) + ldsw + _i * 8192), 16, 0, 0); } while (0)
; #define PG8_LDA(dst, b, h) do { _Pragma("unroll") for (int m = 0; m < 4; ++m) _Pragma("unroll") for (int k = 0; k < 2; ++k) dst[m][k] = *(const LAS bf16x8*)(lds + PG8_SA(b, h) + aoff + m * 2048 + k * 1024); } while (0)
; #define PG8_LDB(dst, b, h) do { _Pragma("unroll") for (int n = 0; n < 2; ++n) _Pragma("unroll") for (int k = 0; k < 2; ++k) dst[n][k] = *(const LAS bf16x8*)(lds + PG8_SB(b, h) + boff + n * 2048 + k * 1024); } while (0)
; #define PG8_WAIT_V(n) asm volatile("s_waitcnt vmcnt(" #n ")" ::: "memory")
; #define PG8_WAIT_L(n) asm volatile("s_waitcnt lgkmcnt(" #n ")" ::: "memory")
; #define PG8_BAR __builtin_amdgcn_s_barrier()
; #define PG8_SCHED __builtin_amdgcn_sched_barrier(0)
; template <class Epi>
; DI void gemm_phase(LAS unsigned char* lds, int wid, int K, int lda, int ldb, bool bperm, const Sched3& S, const Epi& E) {
;     ...
;             PG8_LDB(B0, 0, 0); PG8_SCHED; PG8_LDA(At, 0, 0); PG8_STAGE(PG8_SA(1, 1), a1 + hA, voffA);
;             PG8_WAIT_L(8); PG8_BAR; PG8_WAIT_L(0); PG8_MMA(0, 0, At, B0); PG8_BAR; PG8_SCHED;
;             PG8_LDB(B1, 0, 1); PG8_STAGE(PG8_SB(0, 0), b2, voffB);
;             PG8_BAR; PG8_WAIT_L(0); PG8_MMA(0, 1, At, B1); PG8_BAR;
;             PG8_LDA(At, 0, 1); PG8_STAGE(PG8_SA(0, 0), a2, voffA);
;             PG8_BAR; PG8_WAIT_L(0); if (full) PG8_MMA(1, 0, At, B0); PG8_BAR; PG8_SCHED;
;             PG8_STAGE(PG8_SB(0, 1), b2 + hstepB, voffB);
;             PG8_WAIT_V(6); PG8_BAR; if (full) PG8_MMA(1, 1, At, B1); PG8_BAR;
;             PG8_LDB(B0, 1, 0); PG8_SCHED; PG8_LDA(At, 1, 0); PG8_STAGE(PG8_SA(0, 1), a2 + h2, voffA);
;             PG8_WAIT_L(8); PG8_BAR; PG8_WAIT_L(0); PG8_MMA(0, 0, At, B0); PG8_BAR; PG8_SCHED;
;             PG8_LDB(B1, 1, 1); PG8_STAGE(PG8_SB(1, 0), b3, voffB);
;             PG8_BAR; PG8_WAIT_L(0); PG8_MMA(0, 1, At, B1); PG8_BAR;
;             PG8_LDA(At, 1, 1); PG8_STAGE(PG8_SA(1, 0), a3, voffA);
;             PG8_BAR; PG8_WAIT_L(0); if (full) PG8_MMA(1, 0, At, B0); PG8_BAR; PG8_SCHED;
;             PG8_STAGE(PG8_SB(1, 1), b3 + hstepB, voffB);
;             PG8_WAIT_V(6); PG8_BAR; if (full) PG8_MMA(1, 1, At, B1); PG8_BAR;
	ds_read_b128 v[144:147], v186 offset:32768
	ds_read_b128 v[148:151], v186 offset:33792
	ds_read_b128 v[162:165], v186 offset:34816
	ds_read_b128 v[166:169], v186 offset:35840
	ds_read_b128 v[170:173], v186 offset:36864
	ds_read_b128 v[174:177], v186 offset:37888
	ds_read_b128 v[188:191], v186 offset:38912
	ds_read_b128 v[192:195], v186 offset:39936
	global_load_lds_dwordx4 v152, s[40:41]

; #define PG8_STAGE(bufoff, gbase, voff) do { _Pragma("unroll") for (int _i = 0; _i < 2; ++_i) \
;         __builtin_amdgcn_global_load_lds((const unsigned*)((const char*)(gbase) + (voff)[_i]), (LAS unsigned*)(lds + (bufoff) + ldsw + _i * 8192), 16, 0, 0); } while (0)
; #define PG8_LDA(dst, b, h) do { _Pragma("unroll") for (int m = 0; m < 4; ++m) _Pragma("unroll") for (int k = 0; k < 2; ++k) dst[m][k] = *(const LAS bf16x8*)(lds + PG8_SA(b, h) + aoff + m * 2048 + k * 1024); } while (0)
; #define PG8_LDB(dst, b, h) do { _Pragma("unroll") for (int n = 0; n < 2; ++n) _Pragma("unroll") for (int k = 0; k < 2; ++k) dst[n][k] = *(const LAS bf16x8*)(lds + PG8_SB(b, h) + boff + n * 2048 + k * 1024); } while (0)
; #define PG8_WAIT_V(n) asm volatile("s_waitcnt vmcnt(" #n ")" ::: "memory")
; #define PG8_WAIT_L(n) asm volatile("s_waitcnt lgkmcnt(" #n ")" ::: "memory")
; #define PG8_BAR __builtin_amdgcn_s_barrier()
; #define PG8_SCHED __builtin_amdgcn_sched_barrier(0)
; template <class Epi>
; DI void gemm_phase(LAS unsigned char* lds, int wid, int K, int lda, int ldb, bool bperm, const Sched3& S, const Epi& E) {
;     ...
;             PG8_LDB(B0, 0, 0); PG8_SCHED; PG8_LDA(At, 0, 0); PG8_STAGE(PG8_SA(1, 1), a1 + hA, voffA);
;             PG8_WAIT_L(8); PG8_BAR; PG8_WAIT_L(0); PG8_MMA(0, 0, At, B0); PG8_BAR; PG8_SCHED;
;             PG8_LDB(B1, 0, 1); PG8_STAGE(PG8_SB(0, 0), b2, voffB);
;             PG8_BAR; PG8_WAIT_L(0); PG8_MMA(0, 1, At, B1); PG8_BAR;
;             PG8_LDA(At, 0, 1); PG8_STAGE(PG8_SA(0, 0), a2, voffA);
;             PG8_BAR; PG8_WAIT_L(0); if (full) PG8_MMA(1, 0, At, B0); PG8_BAR; PG8_SCHED;
;             PG8_STAGE(PG8_SB(0, 1), b2 + hstepB, voffB);
;             PG8_WAIT_V(6); PG8_BAR; if (full) PG8_MMA(1, 1, At, B1); PG8_BAR;
;             PG8_LDB(B0, 1, 0); PG8_SCHED; PG8_LDA(At, 1, 0); PG8_STAGE(PG8_SA(0, 1), a2 + h2, voffA);
;             PG8_WAIT_L(8); PG8_BAR; PG8_WAIT_L(0); PG8_MMA(0, 0, At, B0); PG8_BAR; PG8_SCHED;
;             PG8_LDB(B1, 1, 1); PG8_STAGE(PG8_SB(1, 0), b3, voffB);
;             PG8_BAR; PG8_WAIT_L(0); PG8_MMA(0, 1, At, B1); PG8_BAR;
;             PG8_LDA(At, 1, 1); PG8_STAGE(PG8_SA(1, 0), a3, voffA);
;             PG8_BAR; PG8_WAIT_L(0); if (full) PG8_MMA(1, 0, At, B0); PG8_BAR; PG8_SCHED;
;             PG8_STAGE(PG8_SB(1, 1), b3 + hstepB, voffB);
;             PG8_WAIT_V(6); PG8_BAR; if (full) PG8_MMA(1, 1, At, B1); PG8_BAR;
	s_mov_b32 m0, s51
	s_nop 0
	global_load_lds_dwordx4 v154, s[40:41]
	s_waitcnt lgkmcnt(8)
	s_barrier
	s_waitcnt lgkmcnt(0)
	s_setprio 1
	s_waitcnt lgkmcnt(0)
	v_mfma_f32_16x16x32_bf16 v[124:127], v[128:131], v[144:147], v[124:127]
	v_mfma_f32_16x16x32_bf16 v[120:123], v[136:139], v[144:147], v[120:123]
	v_mfma_f32_16x16x32_bf16 v[108:111], v[128:131], v[162:165], v[108:111]
	v_mfma_f32_16x16x32_bf16 v[104:107], v[136:139], v[162:165], v[104:107]
	v_mfma_f32_16x16x32_bf16 v[92:95], v[128:131], v[170:173], v[92:95]
	v_mfma_f32_16x16x32_bf16 v[88:91], v[136:139], v[170:173], v[88:91]
	v_mfma_f32_16x16x32_bf16 v[76:79], v[128:131], v[188:191], v[76:79]
	v_mfma_f32_16x16x32_bf16 v[72:75], v[136:139], v[188:191], v[72:75]
	v_mfma_f32_16x16x32_bf16 v[124:127], v[132:135], v[148:151], v[124:127]
	v_mfma_f32_16x16x32_bf16 v[120:123], v[140:143], v[148:151], v[120:123]
	v_mfma_f32_16x16x32_bf16 v[108:111], v[132:135], v[166:169], v[108:111]
	v_mfma_f32_16x16x32_bf16 v[104:107], v[140:143], v[166:169], v[104:107]
	v_mfma_f32_16x16x32_bf16 v[92:95], v[132:135], v[174:177], v[92:95]
	v_mfma_f32_16x16x32_bf16 v[88:91], v[140:143], v[174:177], v[88:91]
	v_mfma_f32_16x16x32_bf16 v[76:79], v[132:135], v[192:195], v[76:79]
	v_mfma_f32_16x16x32_bf16 v[72:75], v[140:143], v[192:195], v[72:75]
	s_setprio 0
	s_barrier
	s_add_i32 s40, 0, 0x1c000
	s_add_i32 s41, s61, s47
	v_add_u32_e32 v208, s40, v181

; #define PG8_STAGE(bufoff, gbase, voff) do { _Pragma("unroll") for (int _i = 0; _i < 2; ++_i) \
;         __builtin_amdgcn_global_load_lds((const unsigned*)((const char*)(gbase) + (voff)[_i]), (LAS unsigned*)(lds + (bufoff) + ldsw + _i * 8192), 16, 0, 0); } while (0)
; #define PG8_LDA(dst, b, h) do { _Pragma("unroll") for (int m = 0; m < 4; ++m) _Pragma("unroll") for (int k = 0; k < 2; ++k) dst[m][k] = *(const LAS bf16x8*)(lds + PG8_SA(b, h) + aoff + m * 2048 + k * 1024); } while (0)
; #define PG8_LDB(dst, b, h) do { _Pragma("unroll") for (int n = 0; n < 2; ++n) _Pragma("unroll") for (int k = 0; k < 2; ++k) dst[n][k] = *(const LAS bf16x8*)(lds + PG8_SB(b, h) + boff + n * 2048 + k * 1024); } while (0)
; #define PG8_WAIT_V(n) asm volatile("s_waitcnt vmcnt(" #n ")" ::: "memory")
; #define PG8_WAIT_L(n) asm volatile("s_waitcnt lgkmcnt(" #n ")" ::: "memory")
; #define PG8_BAR __builtin_amdgcn_s_barrier()
; #define PG8_SCHED __builtin_amdgcn_sched_barrier(0)
; template <class Epi>
; DI void gemm_phase(LAS unsigned char* lds, int wid, int K, int lda, int ldb, bool bperm, const Sched3& S, const Epi& E) {
;     ...
;             PG8_LDB(B0, 0, 0); PG8_SCHED; PG8_LDA(At, 0, 0); PG8_STAGE(PG8_SA(1, 1), a1 + hA, voffA);
;             PG8_WAIT_L(8); PG8_BAR; PG8_WAIT_L(0); PG8_MMA(0, 0, At, B0); PG8_BAR; PG8_SCHED;
;             PG8_LDB(B1, 0, 1); PG8_STAGE(PG8_SB(0, 0), b2, voffB);
;             PG8_BAR; PG8_WAIT_L(0); PG8_MMA(0, 1, At, B1); PG8_BAR;
;             PG8_LDA(At, 0, 1); PG8_STAGE(PG8_SA(0, 0), a2, voffA);
;             PG8_BAR; PG8_WAIT_L(0); if (full) PG8_MMA(1, 0, At, B0); PG8_BAR; PG8_SCHED;
;             PG8_STAGE(PG8_SB(0, 1), b2 + hstepB, voffB);
;             PG8_WAIT_V(6); PG8_BAR; if (full) PG8_MMA(1, 1, At, B1); PG8_BAR;
;             PG8_LDB(B0, 1, 0); PG8_SCHED; PG8_LDA(At, 1, 0); PG8_STAGE(PG8_SA(0, 1), a2 + h2, voffA);
;             PG8_WAIT_L(8); PG8_BAR; PG8_WAIT_L(0); PG8_MMA(0, 0, At, B0); PG8_BAR; PG8_SCHED;
;             PG8_LDB(B1, 1, 1); PG8_STAGE(PG8_SB(1, 0), b3, voffB);
;             PG8_BAR; PG8_WAIT_L(0); PG8_MMA(0, 1, At, B1); PG8_BAR;
;             PG8_LDA(At, 1, 1); PG8_STAGE(PG8_SA(1, 0), a3, voffA);
;             PG8_BAR; PG8_WAIT_L(0); if (full) PG8_MMA(1, 0, At, B0); PG8_BAR; PG8_SCHED;
;             PG8_STAGE(PG8_SB(1, 1), b3 + hstepB, voffB);
;             PG8_WAIT_V(6); PG8_BAR; if (full) PG8_MMA(1, 1, At, B1); PG8_BAR;
	s_sub_i32 m0, s41, 0x80
	ds_read_b128 v[196:199], v208
	ds_read_b128 v[200:203], v208 offset:1024
	ds_read_b128 v[204:207], v208 offset:2048
	ds_read_b128 v[208:211], v208 offset:3072
	global_load_lds_dwordx4 v152, s[38:39] offset:128

; #define PG8_STAGE(bufoff, gbase, voff) do { _Pragma("unroll") for (int _i = 0; _i < 2; ++_i) \
;         __builtin_amdgcn_global_load_lds((const unsigned*)((const char*)(gbase) + (voff)[_i]), (LAS unsigned*)(lds + (bufoff) + ldsw + _i * 8192), 16, 0, 0); } while (0)
; #define PG8_LDA(dst, b, h) do { _Pragma("unroll") for (int m = 0; m < 4; ++m) _Pragma("unroll") for (int k = 0; k < 2; ++k) dst[m][k] = *(const LAS bf16x8*)(lds + PG8_SA(b, h) + aoff + m * 2048 + k * 1024); } while (0)
; #define PG8_LDB(dst, b, h) do { _Pragma("unroll") for (int n = 0; n < 2; ++n) _Pragma("unroll") for (int k = 0; k < 2; ++k) dst[n][k] = *(const LAS bf16x8*)(lds + PG8_SB(b, h) + boff + n * 2048 + k * 1024); } while (0)
; #define PG8_WAIT_V(n) asm volatile("s_waitcnt vmcnt(" #n ")" ::: "memory")
; #define PG8_WAIT_L(n) asm volatile("s_waitcnt lgkmcnt(" #n ")" ::: "memory")
; #define PG8_BAR __builtin_amdgcn_s_barrier()
; #define PG8_SCHED __builtin_amdgcn_sched_barrier(0)
; template <class Epi>
; DI void gemm_phase(LAS unsigned char* lds, int wid, int K, int lda, int ldb, bool bperm, const Sched3& S, const Epi& E) {
;     ...
;             PG8_LDB(B0, 0, 0); PG8_SCHED; PG8_LDA(At, 0, 0); PG8_STAGE(PG8_SA(1, 1), a1 + hA, voffA);
;             PG8_WAIT_L(8); PG8_BAR; PG8_WAIT_L(0); PG8_MMA(0, 0, At, B0); PG8_BAR; PG8_SCHED;
;             PG8_LDB(B1, 0, 1); PG8_STAGE(PG8_SB(0, 0), b2, voffB);
;             PG8_BAR; PG8_WAIT_L(0); PG8_MMA(0, 1, At, B1); PG8_BAR;
;             PG8_LDA(At, 0, 1); PG8_STAGE(PG8_SA(0, 0), a2, voffA);
;             PG8_BAR; PG8_WAIT_L(0); if (full) PG8_MMA(1, 0, At, B0); PG8_BAR; PG8_SCHED;
;             PG8_STAGE(PG8_SB(0, 1), b2 + hstepB, voffB);
;             PG8_WAIT_V(6); PG8_BAR; if (full) PG8_MMA(1, 1, At, B1); PG8_BAR;
;             PG8_LDB(B0, 1, 0); PG8_SCHED; PG8_LDA(At, 1, 0); PG8_STAGE(PG8_SA(0, 1), a2 + h2, voffA);
;             PG8_WAIT_L(8); PG8_BAR; PG8_WAIT_L(0); PG8_MMA(0, 0, At, B0); PG8_BAR; PG8_SCHED;
;             PG8_LDB(B1, 1, 1); PG8_STAGE(PG8_SB(1, 0), b3, voffB);
;             PG8_BAR; PG8_WAIT_L(0); PG8_MMA(0, 1, At, B1); PG8_BAR;
;             PG8_LDA(At, 1, 1); PG8_STAGE(PG8_SA(1, 0), a3, voffA);
;             PG8_BAR; PG8_WAIT_L(0); if (full) PG8_MMA(1, 0, At, B0); PG8_BAR; PG8_SCHED;
;             PG8_STAGE(PG8_SB(1, 1), b3 + hstepB, voffB);
;             PG8_WAIT_V(6); PG8_BAR; if (full) PG8_MMA(1, 1, At, B1); PG8_BAR;
	s_add_i32 m0, s41, 0x1f80
	s_nop 0
	global_load_lds_dwordx4 v154, s[38:39] offset:128
	s_barrier
	s_waitcnt lgkmcnt(0)
	s_setprio 1
	s_waitcnt lgkmcnt(0)
	v_mfma_f32_16x16x32_bf16 v[116:119], v[196:199], v[144:147], v[116:119]
	v_mfma_f32_16x16x32_bf16 v[112:115], v[204:207], v[144:147], v[112:115]
	v_mfma_f32_16x16x32_bf16 v[100:103], v[196:199], v[162:165], v[100:103]
	v_mfma_f32_16x16x32_bf16 v[96:99], v[204:207], v[162:165], v[96:99]
	v_mfma_f32_16x16x32_bf16 v[84:87], v[196:199], v[170:173], v[84:87]
	v_mfma_f32_16x16x32_bf16 v[80:83], v[204:207], v[170:173], v[80:83]
	v_mfma_f32_16x16x32_bf16 v[68:71], v[196:199], v[188:191], v[68:71]
	v_mfma_f32_16x16x32_bf16 v[64:67], v[204:207], v[188:191], v[64:67]
	v_mfma_f32_16x16x32_bf16 v[116:119], v[200:203], v[148:151], v[116:119]
	v_mfma_f32_16x16x32_bf16 v[112:115], v[208:211], v[148:151], v[112:115]
	v_mfma_f32_16x16x32_bf16 v[100:103], v[200:203], v[166:169], v[100:103]
	v_mfma_f32_16x16x32_bf16 v[96:99], v[208:211], v[166:169], v[96:99]
	v_mfma_f32_16x16x32_bf16 v[84:87], v[200:203], v[174:177], v[84:87]
	v_mfma_f32_16x16x32_bf16 v[80:83], v[208:211], v[174:177], v[80:83]
	v_mfma_f32_16x16x32_bf16 v[68:71], v[200:203], v[192:195], v[68:71]
	v_mfma_f32_16x16x32_bf16 v[64:67], v[208:211], v[192:195], v[64:67]
	s_setprio 0
	s_sub_i32 m0, s53, 0x80

; #define PG8_STAGE(bufoff, gbase, voff) do { _Pragma("unroll") for (int _i = 0; _i < 2; ++_i) \
;         __builtin_amdgcn_global_load_lds((const unsigned*)((const char*)(gbase) + (voff)[_i]), (LAS unsigned*)(lds + (bufoff) + ldsw + _i * 8192), 16, 0, 0); } while (0)
; #define PG8_LDA(dst, b, h) do { _Pragma("unroll") for (int m = 0; m < 4; ++m) _Pragma("unroll") for (int k = 0; k < 2; ++k) dst[m][k] = *(const LAS bf16x8*)(lds + PG8_SA(b, h) + aoff + m * 2048 + k * 1024); } while (0)
; #define PG8_LDB(dst, b, h) do { _Pragma("unroll") for (int n = 0; n < 2; ++n) _Pragma("unroll") for (int k = 0; k < 2; ++k) dst[n][k] = *(const LAS bf16x8*)(lds + PG8_SB(b, h) + boff + n * 2048 + k * 1024); } while (0)
; #define PG8_WAIT_V(n) asm volatile("s_waitcnt vmcnt(" #n ")" ::: "memory")
; #define PG8_WAIT_L(n) asm volatile("s_waitcnt lgkmcnt(" #n ")" ::: "memory")
; #define PG8_BAR __builtin_amdgcn_s_barrier()
; #define PG8_SCHED __builtin_amdgcn_sched_barrier(0)
; template <class Epi>
; DI void gemm_phase(LAS unsigned char* lds, int wid, int K, int lda, int ldb, bool bperm, const Sched3& S, const Epi& E) {
;     ...
;             PG8_LDB(B0, 0, 0); PG8_SCHED; PG8_LDA(At, 0, 0); PG8_STAGE(PG8_SA(1, 1), a1 + hA, voffA);
;             PG8_WAIT_L(8); PG8_BAR; PG8_WAIT_L(0); PG8_MMA(0, 0, At, B0); PG8_BAR; PG8_SCHED;
;             PG8_LDB(B1, 0, 1); PG8_STAGE(PG8_SB(0, 0), b2, voffB);
;             PG8_BAR; PG8_WAIT_L(0); PG8_MMA(0, 1, At, B1); PG8_BAR;
;             PG8_LDA(At, 0, 1); PG8_STAGE(PG8_SA(0, 0), a2, voffA);
;             PG8_BAR; PG8_WAIT_L(0); if (full) PG8_MMA(1, 0, At, B0); PG8_BAR; PG8_SCHED;
;             PG8_STAGE(PG8_SB(0, 1), b2 + hstepB, voffB);
;             PG8_WAIT_V(6); PG8_BAR; if (full) PG8_MMA(1, 1, At, B1); PG8_BAR;
;             PG8_LDB(B0, 1, 0); PG8_SCHED; PG8_LDA(At, 1, 0); PG8_STAGE(PG8_SA(0, 1), a2 + h2, voffA);
;             PG8_WAIT_L(8); PG8_BAR; PG8_WAIT_L(0); PG8_MMA(0, 0, At, B0); PG8_BAR; PG8_SCHED;
;             PG8_LDB(B1, 1, 1); PG8_STAGE(PG8_SB(1, 0), b3, voffB);
;             PG8_BAR; PG8_WAIT_L(0); PG8_MMA(0, 1, At, B1); PG8_BAR;
;             PG8_LDA(At, 1, 1); PG8_STAGE(PG8_SA(1, 0), a3, voffA);
;             PG8_BAR; PG8_WAIT_L(0); if (full) PG8_MMA(1, 0, At, B0); PG8_BAR; PG8_SCHED;
;             PG8_STAGE(PG8_SB(1, 1), b3 + hstepB, voffB);
;             PG8_WAIT_V(6); PG8_BAR; if (full) PG8_MMA(1, 1, At, B1); PG8_BAR;
	s_barrier
	ds_read_b128 v[144:147], v186 offset:49152
	ds_read_b128 v[148:151], v186 offset:50176
	ds_read_b128 v[162:165], v186 offset:51200
	ds_read_b128 v[166:169], v186 offset:52224
	ds_read_b128 v[170:173], v186 offset:53248
	ds_read_b128 v[174:177], v186 offset:54272
	ds_read_b128 v[188:191], v186 offset:55296
	ds_read_b128 v[192:195], v186 offset:56320
	global_load_lds_dwordx4 v152, s[100:101] offset:128

; #define PG8_STAGE(bufoff, gbase, voff) do { _Pragma("unroll") for (int _i = 0; _i < 2; ++_i) \
;         __builtin_amdgcn_global_load_lds((const unsigned*)((const char*)(gbase) + (voff)[_i]), (LAS unsigned*)(lds + (bufoff) + ldsw + _i * 8192), 16, 0, 0); } while (0)
; #define PG8_LDA(dst, b, h) do { _Pragma("unroll") for (int m = 0; m < 4; ++m) _Pragma("unroll") for (int k = 0; k < 2; ++k) dst[m][k] = *(const LAS bf16x8*)(lds + PG8_SA(b, h) + aoff + m * 2048 + k * 1024); } while (0)
; #define PG8_LDB(dst, b, h) do { _Pragma("unroll") for (int n = 0; n < 2; ++n) _Pragma("unroll") for (int k = 0; k < 2; ++k) dst[n][k] = *(const LAS bf16x8*)(lds + PG8_SB(b, h) + boff + n * 2048 + k * 1024); } while (0)
; #define PG8_WAIT_V(n) asm volatile("s_waitcnt vmcnt(" #n ")" ::: "memory")
; #define PG8_WAIT_L(n) asm volatile("s_waitcnt lgkmcnt(" #n ")" ::: "memory")
; #define PG8_BAR __builtin_amdgcn_s_barrier()
; #define PG8_SCHED __builtin_amdgcn_sched_barrier(0)
; template <class Epi>
; DI void gemm_phase(LAS unsigned char* lds, int wid, int K, int lda, int ldb, bool bperm, const Sched3& S, const Epi& E) {
;     ...
;             PG8_LDB(B0, 0, 0); PG8_SCHED; PG8_LDA(At, 0, 0); PG8_STAGE(PG8_SA(1, 1), a1 + hA, voffA);
;             PG8_WAIT_L(8); PG8_BAR; PG8_WAIT_L(0); PG8_MMA(0, 0, At, B0); PG8_BAR; PG8_SCHED;
;             PG8_LDB(B1, 0, 1); PG8_STAGE(PG8_SB(0, 0), b2, voffB);
;             PG8_BAR; PG8_WAIT_L(0); PG8_MMA(0, 1, At, B1); PG8_BAR;
;             PG8_LDA(At, 0, 1); PG8_STAGE(PG8_SA(0, 0), a2, voffA);
;             PG8_BAR; PG8_WAIT_L(0); if (full) PG8_MMA(1, 0, At, B0); PG8_BAR; PG8_SCHED;
;             PG8_STAGE(PG8_SB(0, 1), b2 + hstepB, voffB);
;             PG8_WAIT_V(6); PG8_BAR; if (full) PG8_MMA(1, 1, At, B1); PG8_BAR;
;             PG8_LDB(B0, 1, 0); PG8_SCHED; PG8_LDA(At, 1, 0); PG8_STAGE(PG8_SA(0, 1), a2 + h2, voffA);
;             PG8_WAIT_L(8); PG8_BAR; PG8_WAIT_L(0); PG8_MMA(0, 0, At, B0); PG8_BAR; PG8_SCHED;
;             PG8_LDB(B1, 1, 1); PG8_STAGE(PG8_SB(1, 0), b3, voffB);
;             PG8_BAR; PG8_WAIT_L(0); PG8_MMA(0, 1, At, B1); PG8_BAR;
;             PG8_LDA(At, 1, 1); PG8_STAGE(PG8_SA(1, 0), a3, voffA);
;             PG8_BAR; PG8_WAIT_L(0); if (full) PG8_MMA(1, 0, At, B0); PG8_BAR; PG8_SCHED;
;             PG8_STAGE(PG8_SB(1, 1), b3 + hstepB, voffB);
;             PG8_WAIT_V(6); PG8_BAR; if (full) PG8_MMA(1, 1, At, B1); PG8_BAR;
	s_sub_i32 m0, s54, 0x80
	s_nop 0
	global_load_lds_dwordx4 v154, s[100:101] offset:128
	s_barrier
	s_waitcnt lgkmcnt(0)
	s_setprio 1
	s_waitcnt lgkmcnt(0)
	v_mfma_f32_16x16x32_bf16 v[60:63], v[128:131], v[144:147], v[60:63]
	v_mfma_f32_16x16x32_bf16 v[56:59], v[136:139], v[144:147], v[56:59]
	v_mfma_f32_16x16x32_bf16 v[44:47], v[128:131], v[162:165], v[44:47]
	v_mfma_f32_16x16x32_bf16 v[40:43], v[136:139], v[162:165], v[40:43]
	v_mfma_f32_16x16x32_bf16 v[28:31], v[128:131], v[170:173], v[28:31]
	v_mfma_f32_16x16x32_bf16 v[24:27], v[136:139], v[170:173], v[24:27]
	v_mfma_f32_16x16x32_bf16 v[12:15], v[128:131], v[188:191], v[12:15]
	v_mfma_f32_16x16x32_bf16 v[8:11], v[136:139], v[188:191], v[8:11]
	v_mfma_f32_16x16x32_bf16 v[60:63], v[132:135], v[148:151], v[60:63]
	v_mfma_f32_16x16x32_bf16 v[56:59], v[140:143], v[148:151], v[56:59]
	v_mfma_f32_16x16x32_bf16 v[44:47], v[132:135], v[166:169], v[44:47]
	v_mfma_f32_16x16x32_bf16 v[40:43], v[140:143], v[166:169], v[40:43]
	v_mfma_f32_16x16x32_bf16 v[28:31], v[132:135], v[174:177], v[28:31]
	v_mfma_f32_16x16x32_bf16 v[24:27], v[140:143], v[174:177], v[24:27]
	v_mfma_f32_16x16x32_bf16 v[12:15], v[132:135], v[192:195], v[12:15]
	v_mfma_f32_16x16x32_bf16 v[8:11], v[140:143], v[192:195], v[8:11]
	s_setprio 0
	s_barrier
	s_add_u32 s38, s38, 0x80080
	s_addc_u32 s39, s39, 0
	s_add_i32 s40, s40, s47

; #define PG8_STAGE(bufoff, gbase, voff) do { _Pragma("unroll") for (int _i = 0; _i < 2; ++_i) \
;         __builtin_amdgcn_global_load_lds((const unsigned*)((const char*)(gbase) + (voff)[_i]), (LAS unsigned*)(lds + (bufoff) + ldsw + _i * 8192), 16, 0, 0); } while (0)
; #define PG8_LDA(dst, b, h) do { _Pragma("unroll") for (int m = 0; m < 4; ++m) _Pragma("unroll") for (int k = 0; k < 2; ++k) dst[m][k] = *(const LAS bf16x8*)(lds + PG8_SA(b, h) + aoff + m * 2048 + k * 1024); } while (0)
; #define PG8_LDB(dst, b, h) do { _Pragma("unroll") for (int n = 0; n < 2; ++n) _Pragma("unroll") for (int k = 0; k < 2; ++k) dst[n][k] = *(const LAS bf16x8*)(lds + PG8_SB(b, h) + boff + n * 2048 + k * 1024); } while (0)
; #define PG8_WAIT_V(n) asm volatile("s_waitcnt vmcnt(" #n ")" ::: "memory")
; #define PG8_WAIT_L(n) asm volatile("s_waitcnt lgkmcnt(" #n ")" ::: "memory")
; #define PG8_BAR __builtin_amdgcn_s_barrier()
; #define PG8_SCHED __builtin_amdgcn_sched_barrier(0)
; template <class Epi>
; DI void gemm_phase(LAS unsigned char* lds, int wid, int K, int lda, int ldb, bool bperm, const Sched3& S, const Epi& E) {
;     ...
;             PG8_LDB(B0, 0, 0); PG8_SCHED; PG8_LDA(At, 0, 0); PG8_STAGE(PG8_SA(1, 1), a1 + hA, voffA);
;             PG8_WAIT_L(8); PG8_BAR; PG8_WAIT_L(0); PG8_MMA(0, 0, At, B0); PG8_BAR; PG8_SCHED;
;             PG8_LDB(B1, 0, 1); PG8_STAGE(PG8_SB(0, 0), b2, voffB);
;             PG8_BAR; PG8_WAIT_L(0); PG8_MMA(0, 1, At, B1); PG8_BAR;
;             PG8_LDA(At, 0, 1); PG8_STAGE(PG8_SA(0, 0), a2, voffA);
;             PG8_BAR; PG8_WAIT_L(0); if (full) PG8_MMA(1, 0, At, B0); PG8_BAR; PG8_SCHED;
;             PG8_STAGE(PG8_SB(0, 1), b2 + hstepB, voffB);
;             PG8_WAIT_V(6); PG8_BAR; if (full) PG8_MMA(1, 1, At, B1); PG8_BAR;
;             PG8_LDB(B0, 1, 0); PG8_SCHED; PG8_LDA(At, 1, 0); PG8_STAGE(PG8_SA(0, 1), a2 + h2, voffA);
;             PG8_WAIT_L(8); PG8_BAR; PG8_WAIT_L(0); PG8_MMA(0, 0, At, B0); PG8_BAR; PG8_SCHED;
;             PG8_LDB(B1, 1, 1); PG8_STAGE(PG8_SB(1, 0), b3, voffB);
;             PG8_BAR; PG8_WAIT_L(0); PG8_MMA(0, 1, At, B1); PG8_BAR;
;             PG8_LDA(At, 1, 1); PG8_STAGE(PG8_SA(1, 0), a3, voffA);
;             PG8_BAR; PG8_WAIT_L(0); if (full) PG8_MMA(1, 0, At, B0); PG8_BAR; PG8_SCHED;
;             PG8_STAGE(PG8_SB(1, 1), b3 + hstepB, voffB);
;             PG8_WAIT_V(6); PG8_BAR; if (full) PG8_MMA(1, 1, At, B1); PG8_BAR;
	s_mov_b32 m0, s40
	s_nop 0
	global_load_lds_dwordx4 v152, s[38:39]

; #define PG8_STAGE(bufoff, gbase, voff) do { _Pragma("unroll") for (int _i = 0; _i < 2; ++_i) \
;         __builtin_amdgcn_global_load_lds((const unsigned*)((const char*)(gbase) + (voff)[_i]), (LAS unsigned*)(lds + (bufoff) + ldsw + _i * 8192), 16, 0, 0); } while (0)
; #define PG8_LDA(dst, b, h) do { _Pragma("unroll") for (int m = 0; m < 4; ++m) _Pragma("unroll") for (int k = 0; k < 2; ++k) dst[m][k] = *(const LAS bf16x8*)(lds + PG8_SA(b, h) + aoff + m * 2048 + k * 1024); } while (0)
; #define PG8_WAIT_V(n) asm volatile("s_waitcnt vmcnt(" #n ")" ::: "memory")
; template <class Epi>
; DI void gemm_phase(LAS unsigned char* lds, int wid, int K, int lda, int ldb, bool bperm, const Sched3& S, const Epi& E) {
;     ...
;         for (int t = 0; t < nt; t += 2) {
;             const bool last = (t == nt - 2);
;             const char* a1 = cA + (size_t)(t + 1) * kstep;
;             const char* a2 = last ? nA : cA + (size_t)(t + 2) * kstep; const char* b2 = last ? nB : cB + (size_t)(t + 2) * kstep;
;             const char* a3 = a2 + kstep; const char* b3 = b2 + kstep; const size_t h2 = last ? nhA : hA;
;             PG8_LDB(B0, 0, 0); PG8_SCHED; PG8_LDA(At, 0, 0); PG8_STAGE(PG8_SA(1, 1), a1 + hA, voffA);
;             PG8_WAIT_L(8); PG8_BAR; PG8_WAIT_L(0); PG8_MMA(0, 0, At, B0); PG8_BAR; PG8_SCHED;
;             PG8_LDB(B1, 0, 1); PG8_STAGE(PG8_SB(0, 0), b2, voffB);
;             PG8_BAR; PG8_WAIT_L(0); PG8_MMA(0, 1, At, B1); PG8_BAR;
;             PG8_LDA(At, 0, 1); PG8_STAGE(PG8_SA(0, 0), a2, voffA);
;             PG8_BAR; PG8_WAIT_L(0); if (full) PG8_MMA(1, 0, At, B0); PG8_BAR; PG8_SCHED;
;             PG8_STAGE(PG8_SB(0, 1), b2 + hstepB, voffB);
;             PG8_WAIT_V(6); PG8_BAR; if (full) PG8_MMA(1, 1, At, B1); PG8_BAR;
;             PG8_LDB(B0, 1, 0); PG8_SCHED; PG8_LDA(At, 1, 0); PG8_STAGE(PG8_SA(0, 1), a2 + h2, voffA);
;             PG8_WAIT_L(8); PG8_BAR; PG8_WAIT_L(0); PG8_MMA(0, 0, At, B0); PG8_BAR; PG8_SCHED;
;             PG8_LDB(B1, 1, 1); PG8_STAGE(PG8_SB(1, 0), b3, voffB);
;             PG8_BAR; PG8_WAIT_L(0); PG8_MMA(0, 1, At, B1); PG8_BAR;
;             PG8_LDA(At, 1, 1); PG8_STAGE(PG8_SA(1, 0), a3, voffA);
;             PG8_BAR; PG8_WAIT_L(0); if (full) PG8_MMA(1, 0, At, B0); PG8_BAR; PG8_SCHED;
;             PG8_STAGE(PG8_SB(1, 1), b3 + hstepB, voffB);
;             PG8_WAIT_V(6); PG8_BAR; if (full) PG8_MMA(1, 1, At, B1); PG8_BAR;
	s_add_i32 m0, s40, 0x2000
	s_nop 0
	global_load_lds_dwordx4 v154, s[38:39]
	s_waitcnt vmcnt(6)
	s_barrier
	s_setprio 1
	v_mfma_f32_16x16x32_bf16 v[52:55], v[196:199], v[144:147], v[52:55]
	v_mfma_f32_16x16x32_bf16 v[48:51], v[204:207], v[144:147], v[48:51]
	v_mfma_f32_16x16x32_bf16 v[36:39], v[196:199], v[162:165], v[36:39]
	v_mfma_f32_16x16x32_bf16 v[32:35], v[204:207], v[162:165], v[32:35]
	v_mfma_f32_16x16x32_bf16 v[20:23], v[196:199], v[170:173], v[20:23]
	v_mfma_f32_16x16x32_bf16 v[16:19], v[204:207], v[170:173], v[16:19]
	v_mfma_f32_16x16x32_bf16 v[4:7], v[196:199], v[188:191], v[4:7]
	v_mfma_f32_16x16x32_bf16 v[0:3], v[204:207], v[188:191], v[0:3]
	v_mfma_f32_16x16x32_bf16 v[52:55], v[200:203], v[148:151], v[52:55]
	v_mfma_f32_16x16x32_bf16 v[48:51], v[208:211], v[148:151], v[48:51]
	v_mfma_f32_16x16x32_bf16 v[36:39], v[200:203], v[166:169], v[36:39]
	v_mfma_f32_16x16x32_bf16 v[32:35], v[208:211], v[166:169], v[32:35]
	v_mfma_f32_16x16x32_bf16 v[20:23], v[200:203], v[174:177], v[20:23]
	v_mfma_f32_16x16x32_bf16 v[16:19], v[208:211], v[174:177], v[16:19]
	v_mfma_f32_16x16x32_bf16 v[4:7], v[200:203], v[192:195], v[4:7]
	v_mfma_f32_16x16x32_bf16 v[0:3], v[208:211], v[192:195], v[0:3]
	s_setprio 0
	s_add_i32 s27, s27, 2
	s_add_u32 s36, s36, 0x100
	s_addc_u32 s37, s37, 0
	s_add_u32 s19, s19, 0x100
	s_addc_u32 s21, s21, 0
	s_cmp_gt_u32 s27, 29
	s_barrier
	s_cbranch_scc0 .LBB0_1176
	s_branch .Lpeel_6_exit
.LBB0_1176:
	ds_read_b128 v[128:131], v185
	ds_read_b128 v[132:135], v185 offset:1024
	ds_read_b128 v[136:139], v185 offset:2048
	ds_read_b128 v[140:143], v185 offset:3072
	s_add_u32 s38, s36, 0xfff80080
	s_addc_u32 s39, s37, -1
	s_cmp_eq_u32 s27, 28
	s_cselect_b32 s41, s29, s39
	s_cselect_b32 s40, s28, s38
	s_cselect_b32 s39, s31, s21
	s_cselect_b32 s38, s30, s19

; #define PG8_STAGE(bufoff, gbase, voff) do { _Pragma("unroll") for (int _i = 0; _i < 2; ++_i) \
;         __builtin_amdgcn_global_load_lds((const unsigned*)((const char*)(gbase) + (voff)[_i]), (LAS unsigned*)(lds + (bufoff) + ldsw + _i * 8192), 16, 0, 0); } while (0)
; #define PG8_LDA(dst, b, h) do { _Pragma("unroll") for (int m = 0; m < 4; ++m) _Pragma("unroll") for (int k = 0; k < 2; ++k) dst[m][k] = *(const LAS bf16x8*)(lds + PG8_SA(b, h) + aoff + m * 2048 + k * 1024); } while (0)
; #define PG8_LDB(dst, b, h) do { _Pragma("unroll") for (int n = 0; n < 2; ++n) _Pragma("unroll") for (int k = 0; k < 2; ++k) dst[n][k] = *(const LAS bf16x8*)(lds + PG8_SB(b, h) + boff + n * 2048 + k * 1024); } while (0)
; #define PG8_WAIT_V(n) asm volatile("s_waitcnt vmcnt(" #n ")" ::: "memory")
; #define PG8_WAIT_L(n) asm volatile("s_waitcnt lgkmcnt(" #n ")" ::: "memory")
; #define PG8_BAR __builtin_amdgcn_s_barrier()
; #define PG8_SCHED __builtin_amdgcn_sched_barrier(0)
; template <class Epi>
; DI void gemm_phase(LAS unsigned char* lds, int wid, int K, int lda, int ldb, bool bperm, const Sched3& S, const Epi& E) {
;     ...
;             PG8_LDB(B0, 0, 0); PG8_SCHED; PG8_LDA(At, 0, 0); PG8_STAGE(PG8_SA(1, 1), a1 + hA, voffA);
;             PG8_WAIT_L(8); PG8_BAR; PG8_WAIT_L(0); PG8_MMA(0, 0, At, B0); PG8_BAR; PG8_SCHED;
;             PG8_LDB(B1, 0, 1); PG8_STAGE(PG8_SB(0, 0), b2, voffB);
;             PG8_BAR; PG8_WAIT_L(0); PG8_MMA(0, 1, At, B1); PG8_BAR;
;             PG8_LDA(At, 0, 1); PG8_STAGE(PG8_SA(0, 0), a2, voffA);
;             PG8_BAR; PG8_WAIT_L(0); if (full) PG8_MMA(1, 0, At, B0); PG8_BAR; PG8_SCHED;
;             PG8_STAGE(PG8_SB(0, 1), b2 + hstepB, voffB);
;             PG8_WAIT_V(6); PG8_BAR; if (full) PG8_MMA(1, 1, At, B1); PG8_BAR;
;             PG8_LDB(B0, 1, 0); PG8_SCHED; PG8_LDA(At, 1, 0); PG8_STAGE(PG8_SA(0, 1), a2 + h2, voffA);
;             PG8_WAIT_L(8); PG8_BAR; PG8_WAIT_L(0); PG8_MMA(0, 0, At, B0); PG8_BAR; PG8_SCHED;
;             PG8_LDB(B1, 1, 1); PG8_STAGE(PG8_SB(1, 0), b3, voffB);
;             PG8_BAR; PG8_WAIT_L(0); PG8_MMA(0, 1, At, B1); PG8_BAR;
;             PG8_LDA(At, 1, 1); PG8_STAGE(PG8_SA(1, 0), a3, voffA);
;             PG8_BAR; PG8_WAIT_L(0); if (full) PG8_MMA(1, 0, At, B0); PG8_BAR; PG8_SCHED;
;             PG8_STAGE(PG8_SB(1, 1), b3 + hstepB, voffB);
;             PG8_WAIT_V(6); PG8_BAR; if (full) PG8_MMA(1, 1, At, B1); PG8_BAR;
	s_add_i32 m0, s48, 0xc000
	ds_read_b128 v[144:147], v186
	ds_read_b128 v[148:151], v186 offset:1024
	ds_read_b128 v[162:165], v186 offset:2048
	ds_read_b128 v[166:169], v186 offset:3072
	ds_read_b128 v[170:173], v186 offset:4096
	ds_read_b128 v[174:177], v186 offset:5120
	ds_read_b128 v[188:191], v186 offset:6144
	ds_read_b128 v[192:195], v186 offset:7168
	global_load_lds_dwordx4 v156, s[36:37]

; #define PG8_STAGE(bufoff, gbase, voff) do { _Pragma("unroll") for (int _i = 0; _i < 2; ++_i) \
;         __builtin_amdgcn_global_load_lds((const unsigned*)((const char*)(gbase) + (voff)[_i]), (LAS unsigned*)(lds + (bufoff) + ldsw + _i * 8192), 16, 0, 0); } while (0)
; #define PG8_LDA(dst, b, h) do { _Pragma("unroll") for (int m = 0; m < 4; ++m) _Pragma("unroll") for (int k = 0; k < 2; ++k) dst[m][k] = *(const LAS bf16x8*)(lds + PG8_SA(b, h) + aoff + m * 2048 + k * 1024); } while (0)
; #define PG8_LDB(dst, b, h) do { _Pragma("unroll") for (int n = 0; n < 2; ++n) _Pragma("unroll") for (int k = 0; k < 2; ++k) dst[n][k] = *(const LAS bf16x8*)(lds + PG8_SB(b, h) + boff + n * 2048 + k * 1024); } while (0)
; #define PG8_WAIT_V(n) asm volatile("s_waitcnt vmcnt(" #n ")" ::: "memory")
; #define PG8_WAIT_L(n) asm volatile("s_waitcnt lgkmcnt(" #n ")" ::: "memory")
; #define PG8_BAR __builtin_amdgcn_s_barrier()
; #define PG8_SCHED __builtin_amdgcn_sched_barrier(0)
; template <class Epi>
; DI void gemm_phase(LAS unsigned char* lds, int wid, int K, int lda, int ldb, bool bperm, const Sched3& S, const Epi& E) {
;     ...
;             PG8_LDB(B0, 0, 0); PG8_SCHED; PG8_LDA(At, 0, 0); PG8_STAGE(PG8_SA(1, 1), a1 + hA, voffA);
;             PG8_WAIT_L(8); PG8_BAR; PG8_WAIT_L(0); PG8_MMA(0, 0, At, B0); PG8_BAR; PG8_SCHED;
;             PG8_LDB(B1, 0, 1); PG8_STAGE(PG8_SB(0, 0), b2, voffB);
;             PG8_BAR; PG8_WAIT_L(0); PG8_MMA(0, 1, At, B1); PG8_BAR;
;             PG8_LDA(At, 0, 1); PG8_STAGE(PG8_SA(0, 0), a2, voffA);
;             PG8_BAR; PG8_WAIT_L(0); if (full) PG8_MMA(1, 0, At, B0); PG8_BAR; PG8_SCHED;
;             PG8_STAGE(PG8_SB(0, 1), b2 + hstepB, voffB);
;             PG8_WAIT_V(6); PG8_BAR; if (full) PG8_MMA(1, 1, At, B1); PG8_BAR;
;             PG8_LDB(B0, 1, 0); PG8_SCHED; PG8_LDA(At, 1, 0); PG8_STAGE(PG8_SA(0, 1), a2 + h2, voffA);
;             PG8_WAIT_L(8); PG8_BAR; PG8_WAIT_L(0); PG8_MMA(0, 0, At, B0); PG8_BAR; PG8_SCHED;
;             PG8_LDB(B1, 1, 1); PG8_STAGE(PG8_SB(1, 0), b3, voffB);
;             PG8_BAR; PG8_WAIT_L(0); PG8_MMA(0, 1, At, B1); PG8_BAR;
;             PG8_LDA(At, 1, 1); PG8_STAGE(PG8_SA(1, 0), a3, voffA);
;             PG8_BAR; PG8_WAIT_L(0); if (full) PG8_MMA(1, 0, At, B0); PG8_BAR; PG8_SCHED;
;             PG8_STAGE(PG8_SB(1, 1), b3 + hstepB, voffB);
;             PG8_WAIT_V(6); PG8_BAR; if (full) PG8_MMA(1, 1, At, B1); PG8_BAR;
	s_add_i32 m0, s48, 0xe000
	s_nop 0
	global_load_lds_dwordx4 v158, s[36:37]
	s_waitcnt lgkmcnt(8)
	s_barrier
	s_waitcnt lgkmcnt(0)
	s_setprio 1
	s_waitcnt lgkmcnt(0)
	v_mfma_f32_16x16x32_bf16 v[124:127], v[128:131], v[144:147], v[124:127]
	v_mfma_f32_16x16x32_bf16 v[120:123], v[136:139], v[144:147], v[120:123]
	v_mfma_f32_16x16x32_bf16 v[108:111], v[128:131], v[162:165], v[108:111]
	v_mfma_f32_16x16x32_bf16 v[104:107], v[136:139], v[162:165], v[104:107]
	v_mfma_f32_16x16x32_bf16 v[92:95], v[128:131], v[170:173], v[92:95]
	v_mfma_f32_16x16x32_bf16 v[88:91], v[136:139], v[170:173], v[88:91]
	v_mfma_f32_16x16x32_bf16 v[76:79], v[128:131], v[188:191], v[76:79]
	v_mfma_f32_16x16x32_bf16 v[72:75], v[136:139], v[188:191], v[72:75]
	v_mfma_f32_16x16x32_bf16 v[124:127], v[132:135], v[148:151], v[124:127]
	v_mfma_f32_16x16x32_bf16 v[120:123], v[140:143], v[148:151], v[120:123]
	v_mfma_f32_16x16x32_bf16 v[108:111], v[132:135], v[166:169], v[108:111]
	v_mfma_f32_16x16x32_bf16 v[104:107], v[140:143], v[166:169], v[104:107]
	v_mfma_f32_16x16x32_bf16 v[92:95], v[132:135], v[174:177], v[92:95]
	v_mfma_f32_16x16x32_bf16 v[88:91], v[140:143], v[174:177], v[88:91]
	v_mfma_f32_16x16x32_bf16 v[76:79], v[132:135], v[192:195], v[76:79]
	v_mfma_f32_16x16x32_bf16 v[72:75], v[140:143], v[192:195], v[72:75]
	s_setprio 0
	s_barrier
	s_add_i32 s61, s57, s47

; #define PG8_STAGE(bufoff, gbase, voff) do { _Pragma("unroll") for (int _i = 0; _i < 2; ++_i) \
;         __builtin_amdgcn_global_load_lds((const unsigned*)((const char*)(gbase) + (voff)[_i]), (LAS unsigned*)(lds + (bufoff) + ldsw + _i * 8192), 16, 0, 0); } while (0)
; #define PG8_LDA(dst, b, h) do { _Pragma("unroll") for (int m = 0; m < 4; ++m) _Pragma("unroll") for (int k = 0; k < 2; ++k) dst[m][k] = *(const LAS bf16x8*)(lds + PG8_SA(b, h) + aoff + m * 2048 + k * 1024); } while (0)
; #define PG8_LDB(dst, b, h) do { _Pragma("unroll") for (int n = 0; n < 2; ++n) _Pragma("unroll") for (int k = 0; k < 2; ++k) dst[n][k] = *(const LAS bf16x8*)(lds + PG8_SB(b, h) + boff + n * 2048 + k * 1024); } while (0)
; #define PG8_WAIT_V(n) asm volatile("s_waitcnt vmcnt(" #n ")" ::: "memory")
; #define PG8_WAIT_L(n) asm volatile("s_waitcnt lgkmcnt(" #n ")" ::: "memory")
; #define PG8_BAR __builtin_amdgcn_s_barrier()
; #define PG8_SCHED __builtin_amdgcn_sched_barrier(0)
; template <class Epi>
; DI void gemm_phase(LAS unsigned char* lds, int wid, int K, int lda, int ldb, bool bperm, const Sched3& S, const Epi& E) {
;     ...
;             PG8_LDB(B0, 0, 0); PG8_SCHED; PG8_LDA(At, 0, 0); PG8_STAGE(PG8_SA(1, 1), a1 + hA, voffA);
;             PG8_WAIT_L(8); PG8_BAR; PG8_WAIT_L(0); PG8_MMA(0, 0, At, B0); PG8_BAR; PG8_SCHED;
;             PG8_LDB(B1, 0, 1); PG8_STAGE(PG8_SB(0, 0), b2, voffB);
;             PG8_BAR; PG8_WAIT_L(0); PG8_MMA(0, 1, At, B1); PG8_BAR;
;             PG8_LDA(At, 0, 1); PG8_STAGE(PG8_SA(0, 0), a2, voffA);
;             PG8_BAR; PG8_WAIT_L(0); if (full) PG8_MMA(1, 0, At, B0); PG8_BAR; PG8_SCHED;
;             PG8_STAGE(PG8_SB(0, 1), b2 + hstepB, voffB);
;             PG8_WAIT_V(6); PG8_BAR; if (full) PG8_MMA(1, 1, At, B1); PG8_BAR;
;             PG8_LDB(B0, 1, 0); PG8_SCHED; PG8_LDA(At, 1, 0); PG8_STAGE(PG8_SA(0, 1), a2 + h2, voffA);
;             PG8_WAIT_L(8); PG8_BAR; PG8_WAIT_L(0); PG8_MMA(0, 0, At, B0); PG8_BAR; PG8_SCHED;
;             PG8_LDB(B1, 1, 1); PG8_STAGE(PG8_SB(1, 0), b3, voffB);
;             PG8_BAR; PG8_WAIT_L(0); PG8_MMA(0, 1, At, B1); PG8_BAR;
;             PG8_LDA(At, 1, 1); PG8_STAGE(PG8_SA(1, 0), a3, voffA);
;             PG8_BAR; PG8_WAIT_L(0); if (full) PG8_MMA(1, 0, At, B0); PG8_BAR; PG8_SCHED;
;             PG8_STAGE(PG8_SB(1, 1), b3 + hstepB, voffB);
;             PG8_WAIT_V(6); PG8_BAR; if (full) PG8_MMA(1, 1, At, B1); PG8_BAR;
	s_mov_b32 m0, s61
	ds_read_b128 v[196:199], v187
	ds_read_b128 v[200:203], v187 offset:1024
	ds_read_b128 v[204:207], v187 offset:2048
	ds_read_b128 v[208:211], v187 offset:3072
	global_load_lds_dwordx4 v152, s[38:39]

; #define PG8_STAGE(bufoff, gbase, voff) do { _Pragma("unroll") for (int _i = 0; _i < 2; ++_i) \
;         __builtin_amdgcn_global_load_lds((const unsigned*)((const char*)(gbase) + (voff)[_i]), (LAS unsigned*)(lds + (bufoff) + ldsw + _i * 8192), 16, 0, 0); } while (0)
; #define PG8_LDA(dst, b, h) do { _Pragma("unroll") for (int m = 0; m < 4; ++m) _Pragma("unroll") for (int k = 0; k < 2; ++k) dst[m][k] = *(const LAS bf16x8*)(lds + PG8_SA(b, h) + aoff + m * 2048 + k * 1024); } while (0)
; #define PG8_LDB(dst, b, h) do { _Pragma("unroll") for (int n = 0; n < 2; ++n) _Pragma("unroll") for (int k = 0; k < 2; ++k) dst[n][k] = *(const LAS bf16x8*)(lds + PG8_SB(b, h) + boff + n * 2048 + k * 1024); } while (0)
; #define PG8_WAIT_V(n) asm volatile("s_waitcnt vmcnt(" #n ")" ::: "memory")
; #define PG8_WAIT_L(n) asm volatile("s_waitcnt lgkmcnt(" #n ")" ::: "memory")
; #define PG8_BAR __builtin_amdgcn_s_barrier()
; #define PG8_SCHED __builtin_amdgcn_sched_barrier(0)
; template <class Epi>
; DI void gemm_phase(LAS unsigned char* lds, int wid, int K, int lda, int ldb, bool bperm, const Sched3& S, const Epi& E) {
;     ...
;             PG8_LDB(B0, 0, 0); PG8_SCHED; PG8_LDA(At, 0, 0); PG8_STAGE(PG8_SA(1, 1), a1 + hA, voffA);
;             PG8_WAIT_L(8); PG8_BAR; PG8_WAIT_L(0); PG8_MMA(0, 0, At, B0); PG8_BAR; PG8_SCHED;
;             PG8_LDB(B1, 0, 1); PG8_STAGE(PG8_SB(0, 0), b2, voffB);
;             PG8_BAR; PG8_WAIT_L(0); PG8_MMA(0, 1, At, B1); PG8_BAR;
;             PG8_LDA(At, 0, 1); PG8_STAGE(PG8_SA(0, 0), a2, voffA);
;             PG8_BAR; PG8_WAIT_L(0); if (full) PG8_MMA(1, 0, At, B0); PG8_BAR; PG8_SCHED;
;             PG8_STAGE(PG8_SB(0, 1), b2 + hstepB, voffB);
;             PG8_WAIT_V(6); PG8_BAR; if (full) PG8_MMA(1, 1, At, B1); PG8_BAR;
;             PG8_LDB(B0, 1, 0); PG8_SCHED; PG8_LDA(At, 1, 0); PG8_STAGE(PG8_SA(0, 1), a2 + h2, voffA);
;             PG8_WAIT_L(8); PG8_BAR; PG8_WAIT_L(0); PG8_MMA(0, 0, At, B0); PG8_BAR; PG8_SCHED;
;             PG8_LDB(B1, 1, 1); PG8_STAGE(PG8_SB(1, 0), b3, voffB);
;             PG8_BAR; PG8_WAIT_L(0); PG8_MMA(0, 1, At, B1); PG8_BAR;
;             PG8_LDA(At, 1, 1); PG8_STAGE(PG8_SA(1, 0), a3, voffA);
;             PG8_BAR; PG8_WAIT_L(0); if (full) PG8_MMA(1, 0, At, B0); PG8_BAR; PG8_SCHED;
;             PG8_STAGE(PG8_SB(1, 1), b3 + hstepB, voffB);
;             PG8_WAIT_V(6); PG8_BAR; if (full) PG8_MMA(1, 1, At, B1); PG8_BAR;
	s_add_i32 m0, s61, 0x2000
	s_nop 0
	global_load_lds_dwordx4 v154, s[38:39]
	s_barrier
	s_waitcnt lgkmcnt(0)
	s_setprio 1
	s_waitcnt lgkmcnt(0)
	v_mfma_f32_16x16x32_bf16 v[116:119], v[196:199], v[144:147], v[116:119]
	v_mfma_f32_16x16x32_bf16 v[112:115], v[204:207], v[144:147], v[112:115]
	v_mfma_f32_16x16x32_bf16 v[100:103], v[196:199], v[162:165], v[100:103]
	v_mfma_f32_16x16x32_bf16 v[96:99], v[204:207], v[162:165], v[96:99]
	v_mfma_f32_16x16x32_bf16 v[84:87], v[196:199], v[170:173], v[84:87]
	v_mfma_f32_16x16x32_bf16 v[80:83], v[204:207], v[170:173], v[80:83]
	v_mfma_f32_16x16x32_bf16 v[68:71], v[196:199], v[188:191], v[68:71]
	v_mfma_f32_16x16x32_bf16 v[64:67], v[204:207], v[188:191], v[64:67]
	v_mfma_f32_16x16x32_bf16 v[116:119], v[200:203], v[148:151], v[116:119]
	v_mfma_f32_16x16x32_bf16 v[112:115], v[208:211], v[148:151], v[112:115]
	v_mfma_f32_16x16x32_bf16 v[100:103], v[200:203], v[166:169], v[100:103]
	v_mfma_f32_16x16x32_bf16 v[96:99], v[208:211], v[166:169], v[96:99]
	v_mfma_f32_16x16x32_bf16 v[84:87], v[200:203], v[174:177], v[84:87]
	v_mfma_f32_16x16x32_bf16 v[80:83], v[208:211], v[174:177], v[80:83]
	v_mfma_f32_16x16x32_bf16 v[68:71], v[200:203], v[192:195], v[68:71]
	v_mfma_f32_16x16x32_bf16 v[64:67], v[208:211], v[192:195], v[64:67]
	s_setprio 0
	s_mov_b32 m0, s48
	s_mov_b64 s[100:101], s[40:41]
	s_barrier
	ds_read_b128 v[144:147], v186 offset:16384
	ds_read_b128 v[148:151], v186 offset:17408
	ds_read_b128 v[162:165], v186 offset:18432
	ds_read_b128 v[166:169], v186 offset:19456
	ds_read_b128 v[170:173], v186 offset:20480
	ds_read_b128 v[174:177], v186 offset:21504
	ds_read_b128 v[188:191], v186 offset:22528
	ds_read_b128 v[192:195], v186 offset:23552
	global_load_lds_dwordx4 v152, s[40:41]
	s_mov_b64 s[100:101], s[40:41]
	s_mov_b32 m0, s49
	s_nop 0
	global_load_lds_dwordx4 v154, s[40:41]
	s_barrier
	s_waitcnt lgkmcnt(0)
	s_setprio 1
	s_waitcnt lgkmcnt(0)
	v_mfma_f32_16x16x32_bf16 v[60:63], v[128:131], v[144:147], v[60:63]
	v_mfma_f32_16x16x32_bf16 v[56:59], v[136:139], v[144:147], v[56:59]
	v_mfma_f32_16x16x32_bf16 v[44:47], v[128:131], v[162:165], v[44:47]
	v_mfma_f32_16x16x32_bf16 v[40:43], v[136:139], v[162:165], v[40:43]
	v_mfma_f32_16x16x32_bf16 v[28:31], v[128:131], v[170:173], v[28:31]
	v_mfma_f32_16x16x32_bf16 v[24:27], v[136:139], v[170:173], v[24:27]
	v_mfma_f32_16x16x32_bf16 v[12:15], v[128:131], v[188:191], v[12:15]
	v_mfma_f32_16x16x32_bf16 v[8:11], v[136:139], v[188:191], v[8:11]
	v_mfma_f32_16x16x32_bf16 v[60:63], v[132:135], v[148:151], v[60:63]
	v_mfma_f32_16x16x32_bf16 v[56:59], v[140:143], v[148:151], v[56:59]
	v_mfma_f32_16x16x32_bf16 v[44:47], v[132:135], v[166:169], v[44:47]
	v_mfma_f32_16x16x32_bf16 v[40:43], v[140:143], v[166:169], v[40:43]
	v_mfma_f32_16x16x32_bf16 v[28:31], v[132:135], v[174:177], v[28:31]
	v_mfma_f32_16x16x32_bf16 v[24:27], v[140:143], v[174:177], v[24:27]
	v_mfma_f32_16x16x32_bf16 v[12:15], v[132:135], v[192:195], v[12:15]
	v_mfma_f32_16x16x32_bf16 v[8:11], v[140:143], v[192:195], v[8:11]
	s_setprio 0
	s_barrier
	s_add_u32 s62, s38, 0x80000
	s_addc_u32 s63, s39, 0
	s_add_i32 s61, s58, s47

; #define PG8_STAGE(bufoff, gbase, voff) do { _Pragma("unroll") for (int _i = 0; _i < 2; ++_i) \
;         __builtin_amdgcn_global_load_lds((const unsigned*)((const char*)(gbase) + (voff)[_i]), (LAS unsigned*)(lds + (bufoff) + ldsw + _i * 8192), 16, 0, 0); } while (0)
; #define PG8_LDA(dst, b, h) do { _Pragma("unroll") for (int m = 0; m < 4; ++m) _Pragma("unroll") for (int k = 0; k < 2; ++k) dst[m][k] = *(const LAS bf16x8*)(lds + PG8_SA(b, h) + aoff + m * 2048 + k * 1024); } while (0)
; #define PG8_LDB(dst, b, h) do { _Pragma("unroll") for (int n = 0; n < 2; ++n) _Pragma("unroll") for (int k = 0; k < 2; ++k) dst[n][k] = *(const LAS bf16x8*)(lds + PG8_SB(b, h) + boff + n * 2048 + k * 1024); } while (0)
; #define PG8_WAIT_V(n) asm volatile("s_waitcnt vmcnt(" #n ")" ::: "memory")
; #define PG8_WAIT_L(n) asm volatile("s_waitcnt lgkmcnt(" #n ")" ::: "memory")
; #define PG8_BAR __builtin_amdgcn_s_barrier()
; #define PG8_SCHED __builtin_amdgcn_sched_barrier(0)
; template <class Epi>
; DI void gemm_phase(LAS unsigned char* lds, int wid, int K, int lda, int ldb, bool bperm, const Sched3& S, const Epi& E) {
;     ...
;             PG8_LDB(B0, 0, 0); PG8_SCHED; PG8_LDA(At, 0, 0); PG8_STAGE(PG8_SA(1, 1), a1 + hA, voffA);
;             PG8_WAIT_L(8); PG8_BAR; PG8_WAIT_L(0); PG8_MMA(0, 0, At, B0); PG8_BAR; PG8_SCHED;
;             PG8_LDB(B1, 0, 1); PG8_STAGE(PG8_SB(0, 0), b2, voffB);
;             PG8_BAR; PG8_WAIT_L(0); PG8_MMA(0, 1, At, B1); PG8_BAR;
;             PG8_LDA(At, 0, 1); PG8_STAGE(PG8_SA(0, 0), a2, voffA);
;             PG8_BAR; PG8_WAIT_L(0); if (full) PG8_MMA(1, 0, At, B0); PG8_BAR; PG8_SCHED;
;             PG8_STAGE(PG8_SB(0, 1), b2 + hstepB, voffB);
;             PG8_WAIT_V(6); PG8_BAR; if (full) PG8_MMA(1, 1, At, B1); PG8_BAR;
;             PG8_LDB(B0, 1, 0); PG8_SCHED; PG8_LDA(At, 1, 0); PG8_STAGE(PG8_SA(0, 1), a2 + h2, voffA);
;             PG8_WAIT_L(8); PG8_BAR; PG8_WAIT_L(0); PG8_MMA(0, 0, At, B0); PG8_BAR; PG8_SCHED;
;             PG8_LDB(B1, 1, 1); PG8_STAGE(PG8_SB(1, 0), b3, voffB);
;             PG8_BAR; PG8_WAIT_L(0); PG8_MMA(0, 1, At, B1); PG8_BAR;
;             PG8_LDA(At, 1, 1); PG8_STAGE(PG8_SA(1, 0), a3, voffA);
;             PG8_BAR; PG8_WAIT_L(0); if (full) PG8_MMA(1, 0, At, B0); PG8_BAR; PG8_SCHED;
;             PG8_STAGE(PG8_SB(1, 1), b3 + hstepB, voffB);
;             PG8_WAIT_V(6); PG8_BAR; if (full) PG8_MMA(1, 1, At, B1); PG8_BAR;
	s_mov_b32 m0, s61
	s_nop 0
	global_load_lds_dwordx4 v152, s[62:63]

; #define PG8_STAGE(bufoff, gbase, voff) do { _Pragma("unroll") for (int _i = 0; _i < 2; ++_i) \
;         __builtin_amdgcn_global_load_lds((const unsigned*)((const char*)(gbase) + (voff)[_i]), (LAS unsigned*)(lds + (bufoff) + ldsw + _i * 8192), 16, 0, 0); } while (0)
; #define PG8_LDA(dst, b, h) do { _Pragma("unroll") for (int m = 0; m < 4; ++m) _Pragma("unroll") for (int k = 0; k < 2; ++k) dst[m][k] = *(const LAS bf16x8*)(lds + PG8_SA(b, h) + aoff + m * 2048 + k * 1024); } while (0)
; #define PG8_LDB(dst, b, h) do { _Pragma("unroll") for (int n = 0; n < 2; ++n) _Pragma("unroll") for (int k = 0; k < 2; ++k) dst[n][k] = *(const LAS bf16x8*)(lds + PG8_SB(b, h) + boff + n * 2048 + k * 1024); } while (0)
; #define PG8_WAIT_V(n) asm volatile("s_waitcnt vmcnt(" #n ")" ::: "memory")
; #define PG8_WAIT_L(n) asm volatile("s_waitcnt lgkmcnt(" #n ")" ::: "memory")
; #define PG8_BAR __builtin_amdgcn_s_barrier()
; #define PG8_SCHED __builtin_amdgcn_sched_barrier(0)
; template <class Epi>
; DI void gemm_phase(LAS unsigned char* lds, int wid, int K, int lda, int ldb, bool bperm, const Sched3& S, const Epi& E) {
;     ...
;             PG8_LDB(B0, 0, 0); PG8_SCHED; PG8_LDA(At, 0, 0); PG8_STAGE(PG8_SA(1, 1), a1 + hA, voffA);
;             PG8_WAIT_L(8); PG8_BAR; PG8_WAIT_L(0); PG8_MMA(0, 0, At, B0); PG8_BAR; PG8_SCHED;
;             PG8_LDB(B1, 0, 1); PG8_STAGE(PG8_SB(0, 0), b2, voffB);
;             PG8_BAR; PG8_WAIT_L(0); PG8_MMA(0, 1, At, B1); PG8_BAR;
;             PG8_LDA(At, 0, 1); PG8_STAGE(PG8_SA(0, 0), a2, voffA);
;             PG8_BAR; PG8_WAIT_L(0); if (full) PG8_MMA(1, 0, At, B0); PG8_BAR; PG8_SCHED;
;             PG8_STAGE(PG8_SB(0, 1), b2 + hstepB, voffB);
;             PG8_WAIT_V(6); PG8_BAR; if (full) PG8_MMA(1, 1, At, B1); PG8_BAR;
;             PG8_LDB(B0, 1, 0); PG8_SCHED; PG8_LDA(At, 1, 0); PG8_STAGE(PG8_SA(0, 1), a2 + h2, voffA);
;             PG8_WAIT_L(8); PG8_BAR; PG8_WAIT_L(0); PG8_MMA(0, 0, At, B0); PG8_BAR; PG8_SCHED;
;             PG8_LDB(B1, 1, 1); PG8_STAGE(PG8_SB(1, 0), b3, voffB);
;             PG8_BAR; PG8_WAIT_L(0); PG8_MMA(0, 1, At, B1); PG8_BAR;
;             PG8_LDA(At, 1, 1); PG8_STAGE(PG8_SA(1, 0), a3, voffA);
;             PG8_BAR; PG8_WAIT_L(0); if (full) PG8_MMA(1, 0, At, B0); PG8_BAR; PG8_SCHED;
;             PG8_STAGE(PG8_SB(1, 1), b3 + hstepB, voffB);
;             PG8_WAIT_V(6); PG8_BAR; if (full) PG8_MMA(1, 1, At, B1); PG8_BAR;
	s_add_i32 m0, s61, 0x2000
	s_nop 0
	global_load_lds_dwordx4 v154, s[62:63]
	s_waitcnt vmcnt(6)
	s_barrier
	s_setprio 1
	v_mfma_f32_16x16x32_bf16 v[52:55], v[196:199], v[144:147], v[52:55]
	v_mfma_f32_16x16x32_bf16 v[48:51], v[204:207], v[144:147], v[48:51]
	v_mfma_f32_16x16x32_bf16 v[36:39], v[196:199], v[162:165], v[36:39]
	v_mfma_f32_16x16x32_bf16 v[32:35], v[204:207], v[162:165], v[32:35]
	v_mfma_f32_16x16x32_bf16 v[20:23], v[196:199], v[170:173], v[20:23]
	v_mfma_f32_16x16x32_bf16 v[16:19], v[204:207], v[170:173], v[16:19]
	v_mfma_f32_16x16x32_bf16 v[4:7], v[196:199], v[188:191], v[4:7]
	v_mfma_f32_16x16x32_bf16 v[0:3], v[204:207], v[188:191], v[0:3]
	v_mfma_f32_16x16x32_bf16 v[52:55], v[200:203], v[148:151], v[52:55]
	v_mfma_f32_16x16x32_bf16 v[48:51], v[208:211], v[148:151], v[48:51]
	v_mfma_f32_16x16x32_bf16 v[36:39], v[200:203], v[166:169], v[36:39]
	v_mfma_f32_16x16x32_bf16 v[32:35], v[208:211], v[166:169], v[32:35]
	v_mfma_f32_16x16x32_bf16 v[20:23], v[200:203], v[174:177], v[20:23]
	v_mfma_f32_16x16x32_bf16 v[16:19], v[208:211], v[174:177], v[16:19]
	v_mfma_f32_16x16x32_bf16 v[4:7], v[200:203], v[192:195], v[4:7]
	v_mfma_f32_16x16x32_bf16 v[0:3], v[208:211], v[192:195], v[0:3]
	s_setprio 0
	s_add_i32 s61, 0, 0x18000
	v_add_u32_e32 v140, s61, v181
	s_barrier
	ds_read_b128 v[128:131], v140
	ds_read_b128 v[132:135], v140 offset:1024
	ds_read_b128 v[136:139], v140 offset:2048
	ds_read_b128 v[140:143], v140 offset:3072
	s_add_u32 s40, s40, 0x80000
	s_addc_u32 s41, s41, 0
	s_mov_b32 m0, s50

; #define PG8_STAGE(bufoff, gbase, voff) do { _Pragma("unroll") for (int _i = 0; _i < 2; ++_i) \
;         __builtin_amdgcn_global_load_lds((const unsigned*)((const char*)(gbase) + (voff)[_i]), (LAS unsigned*)(lds + (bufoff) + ldsw + _i * 8192), 16, 0, 0); } while (0)
; #define PG8_LDA(dst, b, h) do { _Pragma("unroll") for (int m = 0; m < 4; ++m) _Pragma("unroll") for (int k = 0; k < 2; ++k) dst[m][k] = *(const LAS bf16x8*)(lds + PG8_SA(b, h) + aoff + m * 2048 + k * 1024); } while (0)
; #define PG8_LDB(dst, b, h) do { _Pragma("unroll") for (int n = 0; n < 2; ++n) _Pragma("unroll") for (int k = 0; k < 2; ++k) dst[n][k] = *(const LAS bf16x8*)(lds + PG8_SB(b, h) + boff + n * 2048 + k * 1024); } while (0)
; #define PG8_WAIT_V(n) asm volatile("s_waitcnt vmcnt(" #n ")" ::: "memory")
; #define PG8_WAIT_L(n) asm volatile("s_waitcnt lgkmcnt(" #n ")" ::: "memory")
; #define PG8_BAR __builtin_amdgcn_s_barrier()
; #define PG8_SCHED __builtin_amdgcn_sched_barrier(0)
; template <class Epi>
; DI void gemm_phase(LAS unsigned char* lds, int wid, int K, int lda, int ldb, bool bperm, const Sched3& S, const Epi& E) {
;     ...
;             PG8_LDB(B0, 0, 0); PG8_SCHED; PG8_LDA(At, 0, 0); PG8_STAGE(PG8_SA(1, 1), a1 + hA, voffA);
;             PG8_WAIT_L(8); PG8_BAR; PG8_WAIT_L(0); PG8_MMA(0, 0, At, B0); PG8_BAR; PG8_SCHED;
;             PG8_LDB(B1, 0, 1); PG8_STAGE(PG8_SB(0, 0), b2, voffB);
;             PG8_BAR; PG8_WAIT_L(0); PG8_MMA(0, 1, At, B1); PG8_BAR;
;             PG8_LDA(At, 0, 1); PG8_STAGE(PG8_SA(0, 0), a2, voffA);
;             PG8_BAR; PG8_WAIT_L(0); if (full) PG8_MMA(1, 0, At, B0); PG8_BAR; PG8_SCHED;
;             PG8_STAGE(PG8_SB(0, 1), b2 + hstepB, voffB);
;             PG8_WAIT_V(6); PG8_BAR; if (full) PG8_MMA(1, 1, At, B1); PG8_BAR;
;             PG8_LDB(B0, 1, 0); PG8_SCHED; PG8_LDA(At, 1, 0); PG8_STAGE(PG8_SA(0, 1), a2 + h2, voffA);
;             PG8_WAIT_L(8); PG8_BAR; PG8_WAIT_L(0); PG8_MMA(0, 0, At, B0); PG8_BAR; PG8_SCHED;
;             PG8_LDB(B1, 1, 1); PG8_STAGE(PG8_SB(1, 0), b3, voffB);
;             PG8_BAR; PG8_WAIT_L(0); PG8_MMA(0, 1, At, B1); PG8_BAR;
;             PG8_LDA(At, 1, 1); PG8_STAGE(PG8_SA(1, 0), a3, voffA);
;             PG8_BAR; PG8_WAIT_L(0); if (full) PG8_MMA(1, 0, At, B0); PG8_BAR; PG8_SCHED;
;             PG8_STAGE(PG8_SB(1, 1), b3 + hstepB, voffB);
;             PG8_WAIT_V(6); PG8_BAR; if (full) PG8_MMA(1, 1, At, B1); PG8_BAR;
	ds_read_b128 v[144:147], v186 offset:32768
	ds_read_b128 v[148:151], v186 offset:33792
	ds_read_b128 v[162:165], v186 offset:34816
	ds_read_b128 v[166:169], v186 offset:35840
	ds_read_b128 v[170:173], v186 offset:36864
	ds_read_b128 v[174:177], v186 offset:37888
	ds_read_b128 v[188:191], v186 offset:38912
	ds_read_b128 v[192:195], v186 offset:39936
	global_load_lds_dwordx4 v152, s[40:41]

; #define PG8_STAGE(bufoff, gbase, voff) do { _Pragma("unroll") for (int _i = 0; _i < 2; ++_i) \
;         __builtin_amdgcn_global_load_lds((const unsigned*)((const char*)(gbase) + (voff)[_i]), (LAS unsigned*)(lds + (bufoff) + ldsw + _i * 8192), 16, 0, 0); } while (0)
; #define PG8_LDA(dst, b, h) do { _Pragma("unroll") for (int m = 0; m < 4; ++m) _Pragma("unroll") for (int k = 0; k < 2; ++k) dst[m][k] = *(const LAS bf16x8*)(lds + PG8_SA(b, h) + aoff + m * 2048 + k * 1024); } while (0)
; #define PG8_LDB(dst, b, h) do { _Pragma("unroll") for (int n = 0; n < 2; ++n) _Pragma("unroll") for (int k = 0; k < 2; ++k) dst[n][k] = *(const LAS bf16x8*)(lds + PG8_SB(b, h) + boff + n * 2048 + k * 1024); } while (0)
; #define PG8_WAIT_V(n) asm volatile("s_waitcnt vmcnt(" #n ")" ::: "memory")
; #define PG8_WAIT_L(n) asm volatile("s_waitcnt lgkmcnt(" #n ")" ::: "memory")
; #define PG8_BAR __builtin_amdgcn_s_barrier()
; #define PG8_SCHED __builtin_amdgcn_sched_barrier(0)
; template <class Epi>
; DI void gemm_phase(LAS unsigned char* lds, int wid, int K, int lda, int ldb, bool bperm, const Sched3& S, const Epi& E) {
;     ...
;             PG8_LDB(B0, 0, 0); PG8_SCHED; PG8_LDA(At, 0, 0); PG8_STAGE(PG8_SA(1, 1), a1 + hA, voffA);
;             PG8_WAIT_L(8); PG8_BAR; PG8_WAIT_L(0); PG8_MMA(0, 0, At, B0); PG8_BAR; PG8_SCHED;
;             PG8_LDB(B1, 0, 1); PG8_STAGE(PG8_SB(0, 0), b2, voffB);
;             PG8_BAR; PG8_WAIT_L(0); PG8_MMA(0, 1, At, B1); PG8_BAR;
;             PG8_LDA(At, 0, 1); PG8_STAGE(PG8_SA(0, 0), a2, voffA);
;             PG8_BAR; PG8_WAIT_L(0); if (full) PG8_MMA(1, 0, At, B0); PG8_BAR; PG8_SCHED;
;             PG8_STAGE(PG8_SB(0, 1), b2 + hstepB, voffB);
;             PG8_WAIT_V(6); PG8_BAR; if (full) PG8_MMA(1, 1, At, B1); PG8_BAR;
;             PG8_LDB(B0, 1, 0); PG8_SCHED; PG8_LDA(At, 1, 0); PG8_STAGE(PG8_SA(0, 1), a2 + h2, voffA);
;             PG8_WAIT_L(8); PG8_BAR; PG8_WAIT_L(0); PG8_MMA(0, 0, At, B0); PG8_BAR; PG8_SCHED;
;             PG8_LDB(B1, 1, 1); PG8_STAGE(PG8_SB(1, 0), b3, voffB);
;             PG8_BAR; PG8_WAIT_L(0); PG8_MMA(0, 1, At, B1); PG8_BAR;
;             PG8_LDA(At, 1, 1); PG8_STAGE(PG8_SA(1, 0), a3, voffA);
;             PG8_BAR; PG8_WAIT_L(0); if (full) PG8_MMA(1, 0, At, B0); PG8_BAR; PG8_SCHED;
;             PG8_STAGE(PG8_SB(1, 1), b3 + hstepB, voffB);
;             PG8_WAIT_V(6); PG8_BAR; if (full) PG8_MMA(1, 1, At, B1); PG8_BAR;
	s_mov_b32 m0, s51
	s_nop 0
	global_load_lds_dwordx4 v154, s[40:41]
	s_waitcnt lgkmcnt(8)
	s_barrier
	s_waitcnt lgkmcnt(0)
	s_setprio 1
	s_waitcnt lgkmcnt(0)
	v_mfma_f32_16x16x32_bf16 v[124:127], v[128:131], v[144:147], v[124:127]
	v_mfma_f32_16x16x32_bf16 v[120:123], v[136:139], v[144:147], v[120:123]
	v_mfma_f32_16x16x32_bf16 v[108:111], v[128:131], v[162:165], v[108:111]
	v_mfma_f32_16x16x32_bf16 v[104:107], v[136:139], v[162:165], v[104:107]
	v_mfma_f32_16x16x32_bf16 v[92:95], v[128:131], v[170:173], v[92:95]
	v_mfma_f32_16x16x32_bf16 v[88:91], v[136:139], v[170:173], v[88:91]
	v_mfma_f32_16x16x32_bf16 v[76:79], v[128:131], v[188:191], v[76:79]
	v_mfma_f32_16x16x32_bf16 v[72:75], v[136:139], v[188:191], v[72:75]
	v_mfma_f32_16x16x32_bf16 v[124:127], v[132:135], v[148:151], v[124:127]
	v_mfma_f32_16x16x32_bf16 v[120:123], v[140:143], v[148:151], v[120:123]
	v_mfma_f32_16x16x32_bf16 v[108:111], v[132:135], v[166:169], v[108:111]
	v_mfma_f32_16x16x32_bf16 v[104:107], v[140:143], v[166:169], v[104:107]
	v_mfma_f32_16x16x32_bf16 v[92:95], v[132:135], v[174:177], v[92:95]
	v_mfma_f32_16x16x32_bf16 v[88:91], v[140:143], v[174:177], v[88:91]
	v_mfma_f32_16x16x32_bf16 v[76:79], v[132:135], v[192:195], v[76:79]
	v_mfma_f32_16x16x32_bf16 v[72:75], v[140:143], v[192:195], v[72:75]
	s_setprio 0
	s_barrier
	s_add_i32 s40, 0, 0x1c000
	s_add_i32 s41, s61, s47
	v_add_u32_e32 v208, s40, v181

; #define PG8_STAGE(bufoff, gbase, voff) do { _Pragma("unroll") for (int _i = 0; _i < 2; ++_i) \
;         __builtin_amdgcn_global_load_lds((const unsigned*)((const char*)(gbase) + (voff)[_i]), (LAS unsigned*)(lds + (bufoff) + ldsw + _i * 8192), 16, 0, 0); } while (0)
; #define PG8_LDA(dst, b, h) do { _Pragma("unroll") for (int m = 0; m < 4; ++m) _Pragma("unroll") for (int k = 0; k < 2; ++k) dst[m][k] = *(const LAS bf16x8*)(lds + PG8_SA(b, h) + aoff + m * 2048 + k * 1024); } while (0)
; #define PG8_LDB(dst, b, h) do { _Pragma("unroll") for (int n = 0; n < 2; ++n) _Pragma("unroll") for (int k = 0; k < 2; ++k) dst[n][k] = *(const LAS bf16x8*)(lds + PG8_SB(b, h) + boff + n * 2048 + k * 1024); } while (0)
; #define PG8_WAIT_V(n) asm volatile("s_waitcnt vmcnt(" #n ")" ::: "memory")
; #define PG8_WAIT_L(n) asm volatile("s_waitcnt lgkmcnt(" #n ")" ::: "memory")
; #define PG8_BAR __builtin_amdgcn_s_barrier()
; #define PG8_SCHED __builtin_amdgcn_sched_barrier(0)
; template <class Epi>
; DI void gemm_phase(LAS unsigned char* lds, int wid, int K, int lda, int ldb, bool bperm, const Sched3& S, const Epi& E) {
;     ...
;             PG8_LDB(B0, 0, 0); PG8_SCHED; PG8_LDA(At, 0, 0); PG8_STAGE(PG8_SA(1, 1), a1 + hA, voffA);
;             PG8_WAIT_L(8); PG8_BAR; PG8_WAIT_L(0); PG8_MMA(0, 0, At, B0); PG8_BAR; PG8_SCHED;
;             PG8_LDB(B1, 0, 1); PG8_STAGE(PG8_SB(0, 0), b2, voffB);
;             PG8_BAR; PG8_WAIT_L(0); PG8_MMA(0, 1, At, B1); PG8_BAR;
;             PG8_LDA(At, 0, 1); PG8_STAGE(PG8_SA(0, 0), a2, voffA);
;             PG8_BAR; PG8_WAIT_L(0); if (full) PG8_MMA(1, 0, At, B0); PG8_BAR; PG8_SCHED;
;             PG8_STAGE(PG8_SB(0, 1), b2 + hstepB, voffB);
;             PG8_WAIT_V(6); PG8_BAR; if (full) PG8_MMA(1, 1, At, B1); PG8_BAR;
;             PG8_LDB(B0, 1, 0); PG8_SCHED; PG8_LDA(At, 1, 0); PG8_STAGE(PG8_SA(0, 1), a2 + h2, voffA);
;             PG8_WAIT_L(8); PG8_BAR; PG8_WAIT_L(0); PG8_MMA(0, 0, At, B0); PG8_BAR; PG8_SCHED;
;             PG8_LDB(B1, 1, 1); PG8_STAGE(PG8_SB(1, 0), b3, voffB);
;             PG8_BAR; PG8_WAIT_L(0); PG8_MMA(0, 1, At, B1); PG8_BAR;
;             PG8_LDA(At, 1, 1); PG8_STAGE(PG8_SA(1, 0), a3, voffA);
;             PG8_BAR; PG8_WAIT_L(0); if (full) PG8_MMA(1, 0, At, B0); PG8_BAR; PG8_SCHED;
;             PG8_STAGE(PG8_SB(1, 1), b3 + hstepB, voffB);
;             PG8_WAIT_V(6); PG8_BAR; if (full) PG8_MMA(1, 1, At, B1); PG8_BAR;
	s_sub_i32 m0, s41, 0x80
	ds_read_b128 v[196:199], v208
	ds_read_b128 v[200:203], v208 offset:1024
	ds_read_b128 v[204:207], v208 offset:2048
	ds_read_b128 v[208:211], v208 offset:3072
	global_load_lds_dwordx4 v152, s[38:39] offset:128

; #define PG8_STAGE(bufoff, gbase, voff) do { _Pragma("unroll") for (int _i = 0; _i < 2; ++_i) \
;         __builtin_amdgcn_global_load_lds((const unsigned*)((const char*)(gbase) + (voff)[_i]), (LAS unsigned*)(lds + (bufoff) + ldsw + _i * 8192), 16, 0, 0); } while (0)
; #define PG8_LDA(dst, b, h) do { _Pragma("unroll") for (int m = 0; m < 4; ++m) _Pragma("unroll") for (int k = 0; k < 2; ++k) dst[m][k] = *(const LAS bf16x8*)(lds + PG8_SA(b, h) + aoff + m * 2048 + k * 1024); } while (0)
; #define PG8_LDB(dst, b, h) do { _Pragma("unroll") for (int n = 0; n < 2; ++n) _Pragma("unroll") for (int k = 0; k < 2; ++k) dst[n][k] = *(const LAS bf16x8*)(lds + PG8_SB(b, h) + boff + n * 2048 + k * 1024); } while (0)
; #define PG8_WAIT_V(n) asm volatile("s_waitcnt vmcnt(" #n ")" ::: "memory")
; #define PG8_WAIT_L(n) asm volatile("s_waitcnt lgkmcnt(" #n ")" ::: "memory")
; #define PG8_BAR __builtin_amdgcn_s_barrier()
; #define PG8_SCHED __builtin_amdgcn_sched_barrier(0)
; template <class Epi>
; DI void gemm_phase(LAS unsigned char* lds, int wid, int K, int lda, int ldb, bool bperm, const Sched3& S, const Epi& E) {
;     ...
;             PG8_LDB(B0, 0, 0); PG8_SCHED; PG8_LDA(At, 0, 0); PG8_STAGE(PG8_SA(1, 1), a1 + hA, voffA);
;             PG8_WAIT_L(8); PG8_BAR; PG8_WAIT_L(0); PG8_MMA(0, 0, At, B0); PG8_BAR; PG8_SCHED;
;             PG8_LDB(B1, 0, 1); PG8_STAGE(PG8_SB(0, 0), b2, voffB);
;             PG8_BAR; PG8_WAIT_L(0); PG8_MMA(0, 1, At, B1); PG8_BAR;
;             PG8_LDA(At, 0, 1); PG8_STAGE(PG8_SA(0, 0), a2, voffA);
;             PG8_BAR; PG8_WAIT_L(0); if (full) PG8_MMA(1, 0, At, B0); PG8_BAR; PG8_SCHED;
;             PG8_STAGE(PG8_SB(0, 1), b2 + hstepB, voffB);
;             PG8_WAIT_V(6); PG8_BAR; if (full) PG8_MMA(1, 1, At, B1); PG8_BAR;
;             PG8_LDB(B0, 1, 0); PG8_SCHED; PG8_LDA(At, 1, 0); PG8_STAGE(PG8_SA(0, 1), a2 + h2, voffA);
;             PG8_WAIT_L(8); PG8_BAR; PG8_WAIT_L(0); PG8_MMA(0, 0, At, B0); PG8_BAR; PG8_SCHED;
;             PG8_LDB(B1, 1, 1); PG8_STAGE(PG8_SB(1, 0), b3, voffB);
;             PG8_BAR; PG8_WAIT_L(0); PG8_MMA(0, 1, At, B1); PG8_BAR;
;             PG8_LDA(At, 1, 1); PG8_STAGE(PG8_SA(1, 0), a3, voffA);
;             PG8_BAR; PG8_WAIT_L(0); if (full) PG8_MMA(1, 0, At, B0); PG8_BAR; PG8_SCHED;
;             PG8_STAGE(PG8_SB(1, 1), b3 + hstepB, voffB);
;             PG8_WAIT_V(6); PG8_BAR; if (full) PG8_MMA(1, 1, At, B1); PG8_BAR;
	s_add_i32 m0, s41, 0x1f80
	s_nop 0
	global_load_lds_dwordx4 v154, s[38:39] offset:128
	s_barrier
	s_waitcnt lgkmcnt(0)
	s_setprio 1
	s_waitcnt lgkmcnt(0)
	v_mfma_f32_16x16x32_bf16 v[116:119], v[196:199], v[144:147], v[116:119]
	v_mfma_f32_16x16x32_bf16 v[112:115], v[204:207], v[144:147], v[112:115]
	v_mfma_f32_16x16x32_bf16 v[100:103], v[196:199], v[162:165], v[100:103]
	v_mfma_f32_16x16x32_bf16 v[96:99], v[204:207], v[162:165], v[96:99]
	v_mfma_f32_16x16x32_bf16 v[84:87], v[196:199], v[170:173], v[84:87]
	v_mfma_f32_16x16x32_bf16 v[80:83], v[204:207], v[170:173], v[80:83]
	v_mfma_f32_16x16x32_bf16 v[68:71], v[196:199], v[188:191], v[68:71]
	v_mfma_f32_16x16x32_bf16 v[64:67], v[204:207], v[188:191], v[64:67]
	v_mfma_f32_16x16x32_bf16 v[116:119], v[200:203], v[148:151], v[116:119]
	v_mfma_f32_16x16x32_bf16 v[112:115], v[208:211], v[148:151], v[112:115]
	v_mfma_f32_16x16x32_bf16 v[100:103], v[200:203], v[166:169], v[100:103]
	v_mfma_f32_16x16x32_bf16 v[96:99], v[208:211], v[166:169], v[96:99]
	v_mfma_f32_16x16x32_bf16 v[84:87], v[200:203], v[174:177], v[84:87]
	v_mfma_f32_16x16x32_bf16 v[80:83], v[208:211], v[174:177], v[80:83]
	v_mfma_f32_16x16x32_bf16 v[68:71], v[200:203], v[192:195], v[68:71]
	v_mfma_f32_16x16x32_bf16 v[64:67], v[208:211], v[192:195], v[64:67]
	s_setprio 0
	s_sub_i32 m0, s53, 0x80

; #define PG8_STAGE(bufoff, gbase, voff) do { _Pragma("unroll") for (int _i = 0; _i < 2; ++_i) \
;         __builtin_amdgcn_global_load_lds((const unsigned*)((const char*)(gbase) + (voff)[_i]), (LAS unsigned*)(lds + (bufoff) + ldsw + _i * 8192), 16, 0, 0); } while (0)
; #define PG8_LDA(dst, b, h) do { _Pragma("unroll") for (int m = 0; m < 4; ++m) _Pragma("unroll") for (int k = 0; k < 2; ++k) dst[m][k] = *(const LAS bf16x8*)(lds + PG8_SA(b, h) + aoff + m * 2048 + k * 1024); } while (0)
; #define PG8_LDB(dst, b, h) do { _Pragma("unroll") for (int n = 0; n < 2; ++n) _Pragma("unroll") for (int k = 0; k < 2; ++k) dst[n][k] = *(const LAS bf16x8*)(lds + PG8_SB(b, h) + boff + n * 2048 + k * 1024); } while (0)
; #define PG8_WAIT_V(n) asm volatile("s_waitcnt vmcnt(" #n ")" ::: "memory")
; #define PG8_WAIT_L(n) asm volatile("s_waitcnt lgkmcnt(" #n ")" ::: "memory")
; #define PG8_BAR __builtin_amdgcn_s_barrier()
; #define PG8_SCHED __builtin_amdgcn_sched_barrier(0)
; template <class Epi>
; DI void gemm_phase(LAS unsigned char* lds, int wid, int K, int lda, int ldb, bool bperm, const Sched3& S, const Epi& E) {
;     ...
;             PG8_LDB(B0, 0, 0); PG8_SCHED; PG8_LDA(At, 0, 0); PG8_STAGE(PG8_SA(1, 1), a1 + hA, voffA);
;             PG8_WAIT_L(8); PG8_BAR; PG8_WAIT_L(0); PG8_MMA(0, 0, At, B0); PG8_BAR; PG8_SCHED;
;             PG8_LDB(B1, 0, 1); PG8_STAGE(PG8_SB(0, 0), b2, voffB);
;             PG8_BAR; PG8_WAIT_L(0); PG8_MMA(0, 1, At, B1); PG8_BAR;
;             PG8_LDA(At, 0, 1); PG8_STAGE(PG8_SA(0, 0), a2, voffA);
;             PG8_BAR; PG8_WAIT_L(0); if (full) PG8_MMA(1, 0, At, B0); PG8_BAR; PG8_SCHED;
;             PG8_STAGE(PG8_SB(0, 1), b2 + hstepB, voffB);
;             PG8_WAIT_V(6); PG8_BAR; if (full) PG8_MMA(1, 1, At, B1); PG8_BAR;
;             PG8_LDB(B0, 1, 0); PG8_SCHED; PG8_LDA(At, 1, 0); PG8_STAGE(PG8_SA(0, 1), a2 + h2, voffA);
;             PG8_WAIT_L(8); PG8_BAR; PG8_WAIT_L(0); PG8_MMA(0, 0, At, B0); PG8_BAR; PG8_SCHED;
;             PG8_LDB(B1, 1, 1); PG8_STAGE(PG8_SB(1, 0), b3, voffB);
;             PG8_BAR; PG8_WAIT_L(0); PG8_MMA(0, 1, At, B1); PG8_BAR;
;             PG8_LDA(At, 1, 1); PG8_STAGE(PG8_SA(1, 0), a3, voffA);
;             PG8_BAR; PG8_WAIT_L(0); if (full) PG8_MMA(1, 0, At, B0); PG8_BAR; PG8_SCHED;
;             PG8_STAGE(PG8_SB(1, 1), b3 + hstepB, voffB);
;             PG8_WAIT_V(6); PG8_BAR; if (full) PG8_MMA(1, 1, At, B1); PG8_BAR;
	s_barrier
	ds_read_b128 v[144:147], v186 offset:49152
	ds_read_b128 v[148:151], v186 offset:50176
	ds_read_b128 v[162:165], v186 offset:51200
	ds_read_b128 v[166:169], v186 offset:52224
	ds_read_b128 v[170:173], v186 offset:53248
	ds_read_b128 v[174:177], v186 offset:54272
	ds_read_b128 v[188:191], v186 offset:55296
	ds_read_b128 v[192:195], v186 offset:56320
	global_load_lds_dwordx4 v152, s[100:101] offset:128

; #define PG8_STAGE(bufoff, gbase, voff) do { _Pragma("unroll") for (int _i = 0; _i < 2; ++_i) \
;         __builtin_amdgcn_global_load_lds((const unsigned*)((const char*)(gbase) + (voff)[_i]), (LAS unsigned*)(lds + (bufoff) + ldsw + _i * 8192), 16, 0, 0); } while (0)
; #define PG8_LDA(dst, b, h) do { _Pragma("unroll") for (int m = 0; m < 4; ++m) _Pragma("unroll") for (int k = 0; k < 2; ++k) dst[m][k] = *(const LAS bf16x8*)(lds + PG8_SA(b, h) + aoff + m * 2048 + k * 1024); } while (0)
; #define PG8_LDB(dst, b, h) do { _Pragma("unroll") for (int n = 0; n < 2; ++n) _Pragma("unroll") for (int k = 0; k < 2; ++k) dst[n][k] = *(const LAS bf16x8*)(lds + PG8_SB(b, h) + boff + n * 2048 + k * 1024); } while (0)
; #define PG8_WAIT_V(n) asm volatile("s_waitcnt vmcnt(" #n ")" ::: "memory")
; #define PG8_WAIT_L(n) asm volatile("s_waitcnt lgkmcnt(" #n ")" ::: "memory")
; #define PG8_BAR __builtin_amdgcn_s_barrier()
; #define PG8_SCHED __builtin_amdgcn_sched_barrier(0)
; template <class Epi>
; DI void gemm_phase(LAS unsigned char* lds, int wid, int K, int lda, int ldb, bool bperm, const Sched3& S, const Epi& E) {
;     ...
;             PG8_LDB(B0, 0, 0); PG8_SCHED; PG8_LDA(At, 0, 0); PG8_STAGE(PG8_SA(1, 1), a1 + hA, voffA);
;             PG8_WAIT_L(8); PG8_BAR; PG8_WAIT_L(0); PG8_MMA(0, 0, At, B0); PG8_BAR; PG8_SCHED;
;             PG8_LDB(B1, 0, 1); PG8_STAGE(PG8_SB(0, 0), b2, voffB);
;             PG8_BAR; PG8_WAIT_L(0); PG8_MMA(0, 1, At, B1); PG8_BAR;
;             PG8_LDA(At, 0, 1); PG8_STAGE(PG8_SA(0, 0), a2, voffA);
;             PG8_BAR; PG8_WAIT_L(0); if (full) PG8_MMA(1, 0, At, B0); PG8_BAR; PG8_SCHED;
;             PG8_STAGE(PG8_SB(0, 1), b2 + hstepB, voffB);
;             PG8_WAIT_V(6); PG8_BAR; if (full) PG8_MMA(1, 1, At, B1); PG8_BAR;
;             PG8_LDB(B0, 1, 0); PG8_SCHED; PG8_LDA(At, 1, 0); PG8_STAGE(PG8_SA(0, 1), a2 + h2, voffA);
;             PG8_WAIT_L(8); PG8_BAR; PG8_WAIT_L(0); PG8_MMA(0, 0, At, B0); PG8_BAR; PG8_SCHED;
;             PG8_LDB(B1, 1, 1); PG8_STAGE(PG8_SB(1, 0), b3, voffB);
;             PG8_BAR; PG8_WAIT_L(0); PG8_MMA(0, 1, At, B1); PG8_BAR;
;             PG8_LDA(At, 1, 1); PG8_STAGE(PG8_SA(1, 0), a3, voffA);
;             PG8_BAR; PG8_WAIT_L(0); if (full) PG8_MMA(1, 0, At, B0); PG8_BAR; PG8_SCHED;
;             PG8_STAGE(PG8_SB(1, 1), b3 + hstepB, voffB);
;             PG8_WAIT_V(6); PG8_BAR; if (full) PG8_MMA(1, 1, At, B1); PG8_BAR;
	s_sub_i32 m0, s54, 0x80
	s_nop 0
	global_load_lds_dwordx4 v154, s[100:101] offset:128
	s_barrier
	s_waitcnt lgkmcnt(0)
	s_setprio 1
	s_waitcnt lgkmcnt(0)
	v_mfma_f32_16x16x32_bf16 v[60:63], v[128:131], v[144:147], v[60:63]
	v_mfma_f32_16x16x32_bf16 v[56:59], v[136:139], v[144:147], v[56:59]
	v_mfma_f32_16x16x32_bf16 v[44:47], v[128:131], v[162:165], v[44:47]
	v_mfma_f32_16x16x32_bf16 v[40:43], v[136:139], v[162:165], v[40:43]
	v_mfma_f32_16x16x32_bf16 v[28:31], v[128:131], v[170:173], v[28:31]
	v_mfma_f32_16x16x32_bf16 v[24:27], v[136:139], v[170:173], v[24:27]
	v_mfma_f32_16x16x32_bf16 v[12:15], v[128:131], v[188:191], v[12:15]
	v_mfma_f32_16x16x32_bf16 v[8:11], v[136:139], v[188:191], v[8:11]
	v_mfma_f32_16x16x32_bf16 v[60:63], v[132:135], v[148:151], v[60:63]
	v_mfma_f32_16x16x32_bf16 v[56:59], v[140:143], v[148:151], v[56:59]
	v_mfma_f32_16x16x32_bf16 v[44:47], v[132:135], v[166:169], v[44:47]
	v_mfma_f32_16x16x32_bf16 v[40:43], v[140:143], v[166:169], v[40:43]
	v_mfma_f32_16x16x32_bf16 v[28:31], v[132:135], v[174:177], v[28:31]
	v_mfma_f32_16x16x32_bf16 v[24:27], v[140:143], v[174:177], v[24:27]
	v_mfma_f32_16x16x32_bf16 v[12:15], v[132:135], v[192:195], v[12:15]
	v_mfma_f32_16x16x32_bf16 v[8:11], v[140:143], v[192:195], v[8:11]
	s_setprio 0
	s_barrier
	s_add_u32 s38, s38, 0x80080
	s_addc_u32 s39, s39, 0
	s_add_i32 s40, s40, s47

; #define PG8_STAGE(bufoff, gbase, voff) do { _Pragma("unroll") for (int _i = 0; _i < 2; ++_i) \
;         __builtin_amdgcn_global_load_lds((const unsigned*)((const char*)(gbase) + (voff)[_i]), (LAS unsigned*)(lds + (bufoff) + ldsw + _i * 8192), 16, 0, 0); } while (0)
; #define PG8_LDA(dst, b, h) do { _Pragma("unroll") for (int m = 0; m < 4; ++m) _Pragma("unroll") for (int k = 0; k < 2; ++k) dst[m][k] = *(const LAS bf16x8*)(lds + PG8_SA(b, h) + aoff + m * 2048 + k * 1024); } while (0)
; #define PG8_LDB(dst, b, h) do { _Pragma("unroll") for (int n = 0; n < 2; ++n) _Pragma("unroll") for (int k = 0; k < 2; ++k) dst[n][k] = *(const LAS bf16x8*)(lds + PG8_SB(b, h) + boff + n * 2048 + k * 1024); } while (0)
; #define PG8_WAIT_V(n) asm volatile("s_waitcnt vmcnt(" #n ")" ::: "memory")
; #define PG8_WAIT_L(n) asm volatile("s_waitcnt lgkmcnt(" #n ")" ::: "memory")
; #define PG8_BAR __builtin_amdgcn_s_barrier()
; #define PG8_SCHED __builtin_amdgcn_sched_barrier(0)
; template <class Epi>
; DI void gemm_phase(LAS unsigned char* lds, int wid, int K, int lda, int ldb, bool bperm, const Sched3& S, const Epi& E) {
;     ...
;             PG8_LDB(B0, 0, 0); PG8_SCHED; PG8_LDA(At, 0, 0); PG8_STAGE(PG8_SA(1, 1), a1 + hA, voffA);
;             PG8_WAIT_L(8); PG8_BAR; PG8_WAIT_L(0); PG8_MMA(0, 0, At, B0); PG8_BAR; PG8_SCHED;
;             PG8_LDB(B1, 0, 1); PG8_STAGE(PG8_SB(0, 0), b2, voffB);
;             PG8_BAR; PG8_WAIT_L(0); PG8_MMA(0, 1, At, B1); PG8_BAR;
;             PG8_LDA(At, 0, 1); PG8_STAGE(PG8_SA(0, 0), a2, voffA);
;             PG8_BAR; PG8_WAIT_L(0); if (full) PG8_MMA(1, 0, At, B0); PG8_BAR; PG8_SCHED;
;             PG8_STAGE(PG8_SB(0, 1), b2 + hstepB, voffB);
;             PG8_WAIT_V(6); PG8_BAR; if (full) PG8_MMA(1, 1, At, B1); PG8_BAR;
;             PG8_LDB(B0, 1, 0); PG8_SCHED; PG8_LDA(At, 1, 0); PG8_STAGE(PG8_SA(0, 1), a2 + h2, voffA);
;             PG8_WAIT_L(8); PG8_BAR; PG8_WAIT_L(0); PG8_MMA(0, 0, At, B0); PG8_BAR; PG8_SCHED;
;             PG8_LDB(B1, 1, 1); PG8_STAGE(PG8_SB(1, 0), b3, voffB);
;             PG8_BAR; PG8_WAIT_L(0); PG8_MMA(0, 1, At, B1); PG8_BAR;
;             PG8_LDA(At, 1, 1); PG8_STAGE(PG8_SA(1, 0), a3, voffA);
;             PG8_BAR; PG8_WAIT_L(0); if (full) PG8_MMA(1, 0, At, B0); PG8_BAR; PG8_SCHED;
;             PG8_STAGE(PG8_SB(1, 1), b3 + hstepB, voffB);
;             PG8_WAIT_V(6); PG8_BAR; if (full) PG8_MMA(1, 1, At, B1); PG8_BAR;
	s_mov_b32 m0, s40
	s_nop 0
	global_load_lds_dwordx4 v152, s[38:39]

; #define PG8_STAGE(bufoff, gbase, voff) do { _Pragma("unroll") for (int _i = 0; _i < 2; ++_i) \
;         __builtin_amdgcn_global_load_lds((const unsigned*)((const char*)(gbase) + (voff)[_i]), (LAS unsigned*)(lds + (bufoff) + ldsw + _i * 8192), 16, 0, 0); } while (0)
; #define PG8_LDA(dst, b, h) do { _Pragma("unroll") for (int m = 0; m < 4; ++m) _Pragma("unroll") for (int k = 0; k < 2; ++k) dst[m][k] = *(const LAS bf16x8*)(lds + PG8_SA(b, h) + aoff + m * 2048 + k * 1024); } while (0)
; #define PG8_WAIT_V(n) asm volatile("s_waitcnt vmcnt(" #n ")" ::: "memory")
; template <class Epi>
; DI void gemm_phase(LAS unsigned char* lds, int wid, int K, int lda, int ldb, bool bperm, const Sched3& S, const Epi& E) {
;     ...
;         for (int t = 0; t < nt; t += 2) {
;             const bool last = (t == nt - 2);
;             const char* a1 = cA + (size_t)(t + 1) * kstep;
;             const char* a2 = last ? nA : cA + (size_t)(t + 2) * kstep; const char* b2 = last ? nB : cB + (size_t)(t + 2) * kstep;
;             const char* a3 = a2 + kstep; const char* b3 = b2 + kstep; const size_t h2 = last ? nhA : hA;
;             PG8_LDB(B0, 0, 0); PG8_SCHED; PG8_LDA(At, 0, 0); PG8_STAGE(PG8_SA(1, 1), a1 + hA, voffA);
;             PG8_WAIT_L(8); PG8_BAR; PG8_WAIT_L(0); PG8_MMA(0, 0, At, B0); PG8_BAR; PG8_SCHED;
;             PG8_LDB(B1, 0, 1); PG8_STAGE(PG8_SB(0, 0), b2, voffB);
;             PG8_BAR; PG8_WAIT_L(0); PG8_MMA(0, 1, At, B1); PG8_BAR;
;             PG8_LDA(At, 0, 1); PG8_STAGE(PG8_SA(0, 0), a2, voffA);
;             PG8_BAR; PG8_WAIT_L(0); if (full) PG8_MMA(1, 0, At, B0); PG8_BAR; PG8_SCHED;
;             PG8_STAGE(PG8_SB(0, 1), b2 + hstepB, voffB);
;             PG8_WAIT_V(6); PG8_BAR; if (full) PG8_MMA(1, 1, At, B1); PG8_BAR;
;             PG8_LDB(B0, 1, 0); PG8_SCHED; PG8_LDA(At, 1, 0); PG8_STAGE(PG8_SA(0, 1), a2 + h2, voffA);
;             PG8_WAIT_L(8); PG8_BAR; PG8_WAIT_L(0); PG8_MMA(0, 0, At, B0); PG8_BAR; PG8_SCHED;
;             PG8_LDB(B1, 1, 1); PG8_STAGE(PG8_SB(1, 0), b3, voffB);
;             PG8_BAR; PG8_WAIT_L(0); PG8_MMA(0, 1, At, B1); PG8_BAR;
;             PG8_LDA(At, 1, 1); PG8_STAGE(PG8_SA(1, 0), a3, voffA);
;             PG8_BAR; PG8_WAIT_L(0); if (full) PG8_MMA(1, 0, At, B0); PG8_BAR; PG8_SCHED;
;             PG8_STAGE(PG8_SB(1, 1), b3 + hstepB, voffB);
;             PG8_WAIT_V(6); PG8_BAR; if (full) PG8_MMA(1, 1, At, B1); PG8_BAR;
	s_add_i32 m0, s40, 0x2000
	s_nop 0
	global_load_lds_dwordx4 v154, s[38:39]
	s_waitcnt vmcnt(6)
	s_barrier
	s_setprio 1
	v_mfma_f32_16x16x32_bf16 v[52:55], v[196:199], v[144:147], v[52:55]
	v_mfma_f32_16x16x32_bf16 v[48:51], v[204:207], v[144:147], v[48:51]
	v_mfma_f32_16x16x32_bf16 v[36:39], v[196:199], v[162:165], v[36:39]
	v_mfma_f32_16x16x32_bf16 v[32:35], v[204:207], v[162:165], v[32:35]
	v_mfma_f32_16x16x32_bf16 v[20:23], v[196:199], v[170:173], v[20:23]
	v_mfma_f32_16x16x32_bf16 v[16:19], v[204:207], v[170:173], v[16:19]
	v_mfma_f32_16x16x32_bf16 v[4:7], v[196:199], v[188:191], v[4:7]
	v_mfma_f32_16x16x32_bf16 v[0:3], v[204:207], v[188:191], v[0:3]
	v_mfma_f32_16x16x32_bf16 v[52:55], v[200:203], v[148:151], v[52:55]
	v_mfma_f32_16x16x32_bf16 v[48:51], v[208:211], v[148:151], v[48:51]
	v_mfma_f32_16x16x32_bf16 v[36:39], v[200:203], v[166:169], v[36:39]
	v_mfma_f32_16x16x32_bf16 v[32:35], v[208:211], v[166:169], v[32:35]
	v_mfma_f32_16x16x32_bf16 v[20:23], v[200:203], v[174:177], v[20:23]
	v_mfma_f32_16x16x32_bf16 v[16:19], v[208:211], v[174:177], v[16:19]
	v_mfma_f32_16x16x32_bf16 v[4:7], v[200:203], v[192:195], v[4:7]
	v_mfma_f32_16x16x32_bf16 v[0:3], v[208:211], v[192:195], v[0:3]
	s_setprio 0
	s_add_i32 s27, s27, 2
	s_add_u32 s36, s36, 0x100
	s_addc_u32 s37, s37, 0
	s_add_u32 s19, s19, 0x100
	s_addc_u32 s21, s21, 0
	s_cmp_gt_u32 s27, 29
	s_barrier
	s_cbranch_scc0 .LBB0_1176
